# f32->bf16 RNE packs use v_cvt_pk_bf16_f32 (own P1/P6/P9 epilogues and the compiler's bit-trick sites; same rounding)
# speedup vs baseline: 1.1214x; 1.0054x over previous
.LBB0_22:
	s_cmpk_gt_i32 s25, 0x103f
	s_mov_b64 s[14:15], -1
	s_cbranch_scc0 .LBB0_24
	v_mov_b32_e32 v21, v13
	v_lshlrev_b64 v[0:1], 12, v[20:21]
	v_lshl_add_u64 v[62:63], v[16:17], 0, v[0:1]
	global_load_dwordx4 v[8:11], v[62:63], off
	global_load_dwordx4 v[4:7], v[62:63], off offset:1024
	global_load_dwordx4 v[46:49], v[62:63], off offset:2048
	global_load_dwordx4 v[0:3], v[62:63], off offset:3072
	global_load_dwordx4 v[50:53], v[18:19], off
	global_load_dwordx4 v[54:57], v[18:19], off offset:1024
	global_load_dwordx4 v[58:61], v[18:19], off offset:2048
	v_cmp_lt_i32_e32 vcc, v38, v37
	global_load_dwordx4 v[62:65], v[18:19], off offset:3072
	s_mov_b64 s[14:15], 0
	v_cndmask_b32_e32 v45, v36, v38, vcc
	v_lshlrev_b32_e32 v45, 2, v45
	v_cmp_lt_i32_e32 vcc, v39, v37
	s_waitcnt vmcnt(7)
	v_mov_b32_e32 v68, v9
	s_waitcnt vmcnt(6)
	v_mov_b32_e32 v69, v5
	v_mov_b32_e32 v66, v8
	v_mov_b32_e32 v67, v4
	s_waitcnt vmcnt(5)
	v_mov_b32_e32 v76, v47
	s_waitcnt vmcnt(4)
	v_mov_b32_e32 v77, v1
	v_pk_mul_f32 v[68:69], v[68:69], v[68:69]
	v_mov_b32_e32 v70, v10
	v_mov_b32_e32 v71, v6
	v_mov_b32_e32 v74, v46
	v_mov_b32_e32 v75, v0
	v_pk_mul_f32 v[76:77], v[76:77], v[76:77]
	v_pk_fma_f32 v[66:67], v[66:67], v[66:67], v[68:69]
	v_mov_b32_e32 v72, v11
	v_mov_b32_e32 v73, v7
	v_mov_b32_e32 v78, v48
	v_mov_b32_e32 v79, v2
	v_pk_fma_f32 v[68:69], v[74:75], v[74:75], v[76:77]
	v_pk_fma_f32 v[66:67], v[70:71], v[70:71], v[66:67]
	v_mov_b32_e32 v80, v49
	v_mov_b32_e32 v81, v3
	v_pk_fma_f32 v[68:69], v[78:79], v[78:79], v[68:69]
	v_pk_fma_f32 v[66:67], v[72:73], v[72:73], v[66:67]
	v_pk_fma_f32 v[68:69], v[80:81], v[80:81], v[68:69]
	v_add_f32_e32 v66, v66, v67
	v_add_f32_e32 v66, v66, v68
	v_add_f32_e32 v66, v66, v69
	ds_bpermute_b32 v45, v45, v66
	v_cndmask_b32_e32 v82, v36, v39, vcc
	v_lshlrev_b32_e32 v67, 2, v82
	v_cmp_lt_i32_e32 vcc, v40, v37
	s_waitcnt vmcnt(3)
	v_mov_b32_e32 v68, v50
	s_waitcnt lgkmcnt(0)
	v_add_f32_e32 v45, v66, v45
	ds_bpermute_b32 v72, v67, v45
	v_cndmask_b32_e32 v83, v36, v40, vcc
	v_lshlrev_b32_e32 v69, 2, v83
	v_lshlrev_b64 v[66:67], 11, v[20:21]
	v_cmp_lt_i32_e32 vcc, v41, v37
	s_waitcnt lgkmcnt(0)
	v_add_f32_e32 v21, v45, v72
	ds_bpermute_b32 v45, v69, v21
	v_cndmask_b32_e32 v84, v36, v41, vcc
	v_lshlrev_b32_e32 v70, 2, v84
	v_cmp_lt_i32_e32 vcc, v42, v37
	s_waitcnt vmcnt(2)
	v_mov_b32_e32 v50, v54
	s_waitcnt lgkmcnt(0)
	v_add_f32_e32 v21, v21, v45
	ds_bpermute_b32 v45, v70, v21
	v_cndmask_b32_e32 v85, v36, v42, vcc
	v_lshlrev_b32_e32 v71, 2, v85
	v_cmp_lt_i32_e32 vcc, v43, v37
	s_waitcnt vmcnt(1)
	v_mov_b32_e32 v54, v58
	s_waitcnt lgkmcnt(0)
	v_add_f32_e32 v21, v21, v45
	ds_bpermute_b32 v45, v71, v21
	v_cndmask_b32_e32 v86, v36, v43, vcc
	v_lshlrev_b32_e32 v73, 2, v86
	v_mov_b32_e32 v58, v8
	v_mov_b32_e32 v8, v9
	s_waitcnt lgkmcnt(0)
	v_add_f32_e32 v21, v21, v45
	ds_bpermute_b32 v45, v73, v21
	v_mov_b32_e32 v9, v11
	v_mov_b32_e32 v11, v48
	v_mov_b32_e32 v48, v4
	v_mov_b32_e32 v69, v52
	s_waitcnt lgkmcnt(0)
	v_add_f32_e32 v21, v21, v45
	v_fmamk_f32 v21, v21, 0x3a800000, v34
	v_mul_f32_e32 v45, 0x4b800000, v21
	v_cmp_gt_f32_e32 vcc, s22, v21
	v_mov_b32_e32 v52, v51
	v_mov_b32_e32 v51, v56
	v_cndmask_b32_e32 v21, v21, v45, vcc
	v_rsq_f32_e32 v21, v21
	v_mov_b32_e32 v56, v55
	v_mov_b32_e32 v55, v60
	v_mov_b32_e32 v60, v59
	v_mul_f32_e32 v4, 0x45800000, v21
	v_cndmask_b32_e32 v4, v21, v4, vcc
	v_mov_b32_e32 v59, v10
	v_mov_b32_e32 v10, v46
	v_mov_b32_e32 v46, v47
	v_mov_b32_e32 v47, v49
	v_mov_b32_e32 v49, v6
	v_mov_b32_e32 v6, v5
	v_pk_mul_f32 v[8:9], v[8:9], v[4:5] op_sel_hi:[1,0]
	v_pk_mul_f32 v[6:7], v[6:7], v[4:5] op_sel_hi:[1,0]
	v_pk_mul_f32 v[58:59], v[58:59], v[4:5] op_sel_hi:[1,0]
	v_pk_mul_f32 v[48:49], v[48:49], v[4:5] op_sel_hi:[1,0]
	v_pk_mul_f32 v[8:9], v[52:53], v[8:9]
	v_pk_mul_f32 v[10:11], v[10:11], v[4:5] op_sel_hi:[1,0]
	v_pk_mul_f32 v[46:47], v[46:47], v[4:5] op_sel_hi:[1,0]
	v_pk_mul_f32 v[58:59], v[68:69], v[58:59]
	v_pk_mul_f32 v[48:49], v[50:51], v[48:49]
	v_pk_mul_f32 v[6:7], v[56:57], v[6:7]
	s_nop 0
	s_nop 0
	v_pk_mul_f32 v[10:11], v[10:11], v[54:55]
	v_pk_mul_f32 v[46:47], v[46:47], v[60:61]
	s_nop 0
	s_nop 0
	s_nop 0
	s_nop 0
	v_cvt_pk_bf16_f32 v9, v9, v9
	v_cvt_pk_bf16_f32 v8, v8, v8
	s_nop 0
	s_nop 0
	s_nop 0
	s_nop 0
	v_cvt_pk_bf16_f32 v21, v58, v58
	v_cvt_pk_bf16_f32 v5, v59, v59
	v_cvt_pk_bf16_f32 v7, v7, v7
	v_cvt_pk_bf16_f32 v6, v6, v6
	v_and_b32_e32 v9, 0xffff0000, v9
	v_and_b32_e32 v8, 0xffff0000, v8
	v_lshl_add_u64 v[66:67], v[14:15], 0, v[66:67]
	s_nop 0
	s_nop 0
	v_cvt_pk_bf16_f32 v45, v48, v48
	v_cvt_pk_bf16_f32 v48, v49, v49
	v_cvt_pk_bf16_f32 v47, v47, v47
	v_cvt_pk_bf16_f32 v46, v46, v46
	v_and_b32_e32 v49, 0xffff0000, v7
	v_and_b32_e32 v50, 0xffff0000, v6
	v_or_b32_sdwa v7, v9, v5 dst_sel:DWORD dst_unused:UNUSED_PAD src0_sel:DWORD src1_sel:WORD_1
	v_or_b32_sdwa v6, v8, v21 dst_sel:DWORD dst_unused:UNUSED_PAD src0_sel:DWORD src1_sel:WORD_1
	v_cvt_pk_bf16_f32 v10, v10, v10
	v_cvt_pk_bf16_f32 v11, v11, v11
	v_or_b32_sdwa v9, v49, v48 dst_sel:DWORD dst_unused:UNUSED_PAD src0_sel:DWORD src1_sel:WORD_1
	v_or_b32_sdwa v8, v50, v45 dst_sel:DWORD dst_unused:UNUSED_PAD src0_sel:DWORD src1_sel:WORD_1
	global_store_dwordx2 v[66:67], v[6:7], off
	global_store_dwordx2 v[66:67], v[8:9], off offset:512
	v_and_b32_e32 v5, 0xffff0000, v47
	v_and_b32_e32 v6, 0xffff0000, v46
	v_or_b32_sdwa v7, v5, v11 dst_sel:DWORD dst_unused:UNUSED_PAD src0_sel:DWORD src1_sel:WORD_1
	v_or_b32_sdwa v6, v6, v10 dst_sel:DWORD dst_unused:UNUSED_PAD src0_sel:DWORD src1_sel:WORD_1
	global_store_dwordx2 v[66:67], v[6:7], off offset:1024
	v_mov_b32_e32 v7, v2
	v_mov_b32_e32 v2, v1
	v_mov_b32_e32 v6, v0
	s_waitcnt vmcnt(3)
	v_mov_b32_e32 v9, v64
	v_pk_mul_f32 v[0:1], v[2:3], v[4:5] op_sel_hi:[1,0]
	v_mov_b32_e32 v64, v63
	v_pk_mul_f32 v[6:7], v[6:7], v[4:5] op_sel_hi:[1,0]
	v_mov_b32_e32 v8, v62
	v_pk_mul_f32 v[0:1], v[0:1], v[64:65]
	v_pk_mul_f32 v[6:7], v[6:7], v[8:9]
	v_and_b32_sdwa v4, v1, v44 dst_sel:DWORD dst_unused:UNUSED_PAD src0_sel:WORD_1 src1_sel:DWORD
	v_and_b32_sdwa v5, v0, v44 dst_sel:DWORD dst_unused:UNUSED_PAD src0_sel:WORD_1 src1_sel:DWORD
	s_nop 0
	s_nop 0
	v_cvt_pk_bf16_f32 v1, v1, v1
	v_cvt_pk_bf16_f32 v0, v0, v0
	v_cvt_pk_bf16_f32 v3, v6, v6
	v_cvt_pk_bf16_f32 v2, v7, v7
	v_and_b32_e32 v1, 0xffff0000, v1
	v_and_b32_e32 v0, 0xffff0000, v0
	v_or_b32_sdwa v1, v1, v2 dst_sel:DWORD dst_unused:UNUSED_PAD src0_sel:DWORD src1_sel:WORD_1
	v_or_b32_sdwa v0, v0, v3 dst_sel:DWORD dst_unused:UNUSED_PAD src0_sel:DWORD src1_sel:WORD_1
	global_store_dwordx2 v[66:67], v[0:1], off offset:1536

.LBB0_33:
	s_and_b32 s14, s20, 0x3c0
	v_mov_b32_e32 v0, 0
	s_cmp_lt_i32 s26, 0
	v_mov_b32_e32 v1, 0
	v_mov_b32_e32 v2, 0
	v_mov_b32_e32 v3, 0
	s_cbranch_scc1 .LBB0_20
	v_add_u32_e32 v21, s26, v24
	v_or_b32_e32 v0, s14, v23
	v_add_u32_e32 v45, s14, v30
	v_mad_u32_u24 v0, v0, s24, v21
	v_mov_b32_e32 v1, v13
	v_or_b32_e32 v2, s14, v25
	v_or_b32_e32 v4, s14, v26
	v_or_b32_e32 v6, s14, v27
	v_or_b32_e32 v8, s14, v28
	v_add_u32_e32 v10, s14, v29
	v_mad_u32_u24 v46, v45, s24, v21
	v_add_u32_e32 v45, s14, v31
	s_waitcnt lgkmcnt(0)
	v_lshl_add_u64 v[0:1], v[0:1], 2, s[8:9]
	v_mad_u32_u24 v2, v2, s24, v21
	v_mov_b32_e32 v3, v13
	v_mad_u32_u24 v4, v4, s24, v21
	v_mov_b32_e32 v5, v13
	v_mad_u32_u24 v6, v6, s24, v21
	v_mov_b32_e32 v7, v13
	v_mad_u32_u24 v8, v8, s24, v21
	v_mov_b32_e32 v9, v13
	v_mad_u32_u24 v10, v10, s24, v21
	v_mov_b32_e32 v11, v13
	v_mov_b32_e32 v47, v13
	v_mad_u32_u24 v48, v45, s24, v21
	v_mov_b32_e32 v49, v13
	s_barrier
	v_lshl_add_u64 v[2:3], v[2:3], 2, s[8:9]
	v_lshl_add_u64 v[4:5], v[4:5], 2, s[8:9]
	v_lshl_add_u64 v[6:7], v[6:7], 2, s[8:9]
	v_lshl_add_u64 v[8:9], v[8:9], 2, s[8:9]
	v_lshl_add_u64 v[10:11], v[10:11], 2, s[8:9]
	v_lshl_add_u64 v[46:47], v[46:47], 2, s[8:9]
	v_lshl_add_u64 v[48:49], v[48:49], 2, s[8:9]
	global_load_dword v21, v[0:1], off
	global_load_dword v45, v[2:3], off
	global_load_dword v50, v[4:5], off
	global_load_dword v51, v[6:7], off
	global_load_dword v52, v[8:9], off
	global_load_dword v53, v[10:11], off
	global_load_dword v54, v[46:47], off
	global_load_dword v55, v[48:49], off
	s_waitcnt vmcnt(7)
	ds_write_b32 v35, v21
	s_waitcnt vmcnt(6)
	ds_write_b32 v35, v45 offset:1056
	s_waitcnt vmcnt(5)
	ds_write_b32 v35, v50 offset:2112
	s_waitcnt vmcnt(4)
	ds_write_b32 v35, v51 offset:3168
	s_waitcnt vmcnt(3)
	ds_write_b32 v35, v52 offset:4224
	s_waitcnt vmcnt(2)
	ds_write_b32 v35, v53 offset:5280
	s_waitcnt vmcnt(1)
	ds_write_b32 v35, v54 offset:6336
	s_waitcnt vmcnt(0)
	ds_write_b32 v35, v55 offset:7392
	s_waitcnt lgkmcnt(0)
	s_barrier
	ds_read2_b32 v[0:1], v32 offset1:66
	ds_read2_b32 v[2:3], v33 offset0:33 offset1:99
	ds_read2_b32 v[4:5], v32 offset0:132 offset1:198
	ds_read2_b32 v[6:7], v33 offset0:165 offset1:231
	s_waitcnt lgkmcnt(3)
	v_and_b32_sdwa v8, v1, v44 dst_sel:DWORD dst_unused:UNUSED_PAD src0_sel:WORD_1 src1_sel:DWORD
	s_waitcnt lgkmcnt(2)
	v_and_b32_sdwa v10, v3, v44 dst_sel:DWORD dst_unused:UNUSED_PAD src0_sel:WORD_1 src1_sel:DWORD
	v_and_b32_sdwa v11, v2, v44 dst_sel:DWORD dst_unused:UNUSED_PAD src0_sel:WORD_1 src1_sel:DWORD
	s_waitcnt lgkmcnt(0)
	v_and_b32_sdwa v46, v7, v44 dst_sel:DWORD dst_unused:UNUSED_PAD src0_sel:WORD_1 src1_sel:DWORD
	v_and_b32_sdwa v47, v6, v44 dst_sel:DWORD dst_unused:UNUSED_PAD src0_sel:WORD_1 src1_sel:DWORD
	v_and_b32_sdwa v9, v0, v44 dst_sel:DWORD dst_unused:UNUSED_PAD src0_sel:WORD_1 src1_sel:DWORD
	s_nop 0
	v_and_b32_sdwa v45, v4, v44 dst_sel:DWORD dst_unused:UNUSED_PAD src0_sel:WORD_1 src1_sel:DWORD
	v_cvt_pk_bf16_f32 v3, v3, v3
	v_cvt_pk_bf16_f32 v2, v2, v2
	v_cvt_pk_bf16_f32 v7, v7, v7
	v_cvt_pk_bf16_f32 v6, v6, v6
	v_cvt_pk_bf16_f32 v0, v0, v0
	v_cvt_pk_bf16_f32 v1, v1, v1
	v_cvt_pk_bf16_f32 v4, v4, v4
	v_cvt_pk_bf16_f32 v5, v5, v5
	v_and_b32_e32 v3, 0xffff0000, v3
	v_and_b32_e32 v2, 0xffff0000, v2
	v_and_b32_e32 v7, 0xffff0000, v7
	v_and_b32_e32 v6, 0xffff0000, v6
	v_or_b32_sdwa v1, v3, v1 dst_sel:DWORD dst_unused:UNUSED_PAD src0_sel:DWORD src1_sel:WORD_1
	v_or_b32_sdwa v0, v2, v0 dst_sel:DWORD dst_unused:UNUSED_PAD src0_sel:DWORD src1_sel:WORD_1
	v_or_b32_sdwa v3, v7, v5 dst_sel:DWORD dst_unused:UNUSED_PAD src0_sel:DWORD src1_sel:WORD_1
	v_or_b32_sdwa v2, v6, v4 dst_sel:DWORD dst_unused:UNUSED_PAD src0_sel:DWORD src1_sel:WORD_1
	s_branch .LBB0_20

.Lgp1_last:
	v_mfma_f32_16x16x32_bf16 v[56:59], v[216:219], v[184:187], v[56:59]
	v_mfma_f32_16x16x32_bf16 v[116:119], v[248:251], v[184:187], v[116:119]
	v_mfma_f32_16x16x32_bf16 v[48:51], v[220:223], v[184:187], v[48:51]
	v_mfma_f32_16x16x32_bf16 v[120:123], v[252:255], v[184:187], v[120:123]
	v_mfma_f32_16x16x32_bf16 v[60:63], v[224:227], v[184:187], v[60:63]
	v_mfma_f32_16x16x32_bf16 v[124:127], v[68:71], v[184:187], v[124:127]
	v_mfma_f32_16x16x32_bf16 v[52:55], v[228:231], v[184:187], v[52:55]
	v_mfma_f32_16x16x32_bf16 v[128:131], v[72:75], v[184:187], v[128:131]
	v_mfma_f32_16x16x32_bf16 v[40:43], v[216:219], v[188:191], v[40:43]
	v_mfma_f32_16x16x32_bf16 v[132:135], v[248:251], v[188:191], v[132:135]
	v_mfma_f32_16x16x32_bf16 v[32:35], v[220:223], v[188:191], v[32:35]
	v_mfma_f32_16x16x32_bf16 v[136:139], v[252:255], v[188:191], v[136:139]
	v_mfma_f32_16x16x32_bf16 v[44:47], v[224:227], v[188:191], v[44:47]
	v_mfma_f32_16x16x32_bf16 v[140:143], v[68:71], v[188:191], v[140:143]
	v_mfma_f32_16x16x32_bf16 v[36:39], v[228:231], v[188:191], v[36:39]
	v_mfma_f32_16x16x32_bf16 v[144:147], v[72:75], v[188:191], v[144:147]
	v_mfma_f32_16x16x32_bf16 v[24:27], v[216:219], v[192:195], v[24:27]
	v_mfma_f32_16x16x32_bf16 v[148:151], v[248:251], v[192:195], v[148:151]
	v_mfma_f32_16x16x32_bf16 v[16:19], v[220:223], v[192:195], v[16:19]
	v_mfma_f32_16x16x32_bf16 v[152:155], v[252:255], v[192:195], v[152:155]
	v_mfma_f32_16x16x32_bf16 v[28:31], v[224:227], v[192:195], v[28:31]
	v_mfma_f32_16x16x32_bf16 v[156:159], v[68:71], v[192:195], v[156:159]
	v_mfma_f32_16x16x32_bf16 v[20:23], v[228:231], v[192:195], v[20:23]
	v_mfma_f32_16x16x32_bf16 v[160:163], v[72:75], v[192:195], v[160:163]
	v_mfma_f32_16x16x32_bf16 v[8:11], v[216:219], v[196:199], v[8:11]
	v_mfma_f32_16x16x32_bf16 v[164:167], v[248:251], v[196:199], v[164:167]
	v_mfma_f32_16x16x32_bf16 v[0:3], v[220:223], v[196:199], v[0:3]
	v_mfma_f32_16x16x32_bf16 v[172:175], v[252:255], v[196:199], v[172:175]
	v_mfma_f32_16x16x32_bf16 v[12:15], v[224:227], v[196:199], v[12:15]
	v_mfma_f32_16x16x32_bf16 v[176:179], v[68:71], v[196:199], v[176:179]
	v_mfma_f32_16x16x32_bf16 v[4:7], v[228:231], v[196:199], v[4:7]
	v_mfma_f32_16x16x32_bf16 v[180:183], v[72:75], v[196:199], v[180:183]
	s_waitcnt lgkmcnt(0)
	v_mfma_f32_16x16x32_bf16 v[56:59], v[232:235], v[200:203], v[56:59]
	v_mfma_f32_16x16x32_bf16 v[116:119], v[96:99], v[200:203], v[116:119]
	v_mfma_f32_16x16x32_bf16 v[48:51], v[236:239], v[200:203], v[48:51]
	v_mfma_f32_16x16x32_bf16 v[120:123], v[100:103], v[200:203], v[120:123]
	v_mfma_f32_16x16x32_bf16 v[60:63], v[240:243], v[200:203], v[60:63]
	v_mfma_f32_16x16x32_bf16 v[124:127], v[104:107], v[200:203], v[124:127]
	v_mfma_f32_16x16x32_bf16 v[52:55], v[244:247], v[200:203], v[52:55]
	v_mfma_f32_16x16x32_bf16 v[128:131], v[112:115], v[200:203], v[128:131]
	v_mfma_f32_16x16x32_bf16 v[40:43], v[232:235], v[204:207], v[40:43]
	v_mfma_f32_16x16x32_bf16 v[132:135], v[96:99], v[204:207], v[132:135]
	v_mfma_f32_16x16x32_bf16 v[32:35], v[236:239], v[204:207], v[32:35]
	v_mfma_f32_16x16x32_bf16 v[136:139], v[100:103], v[204:207], v[136:139]
	v_mfma_f32_16x16x32_bf16 v[44:47], v[240:243], v[204:207], v[44:47]
	v_mfma_f32_16x16x32_bf16 v[140:143], v[104:107], v[204:207], v[140:143]
	v_mfma_f32_16x16x32_bf16 v[36:39], v[244:247], v[204:207], v[36:39]
	v_mfma_f32_16x16x32_bf16 v[144:147], v[112:115], v[204:207], v[144:147]
	v_mfma_f32_16x16x32_bf16 v[24:27], v[232:235], v[208:211], v[24:27]
	v_mfma_f32_16x16x32_bf16 v[148:151], v[96:99], v[208:211], v[148:151]
	v_mfma_f32_16x16x32_bf16 v[16:19], v[236:239], v[208:211], v[16:19]
	v_mfma_f32_16x16x32_bf16 v[152:155], v[100:103], v[208:211], v[152:155]
	v_mfma_f32_16x16x32_bf16 v[28:31], v[240:243], v[208:211], v[28:31]
	v_mfma_f32_16x16x32_bf16 v[156:159], v[104:107], v[208:211], v[156:159]
	v_mfma_f32_16x16x32_bf16 v[20:23], v[244:247], v[208:211], v[20:23]
	v_mfma_f32_16x16x32_bf16 v[160:163], v[112:115], v[208:211], v[160:163]
	v_mfma_f32_16x16x32_bf16 v[8:11], v[232:235], v[212:215], v[8:11]
	v_mfma_f32_16x16x32_bf16 v[164:167], v[96:99], v[212:215], v[164:167]
	v_mfma_f32_16x16x32_bf16 v[0:3], v[236:239], v[212:215], v[0:3]
	v_mfma_f32_16x16x32_bf16 v[172:175], v[100:103], v[212:215], v[172:175]
	v_mfma_f32_16x16x32_bf16 v[12:15], v[240:243], v[212:215], v[12:15]
	v_mfma_f32_16x16x32_bf16 v[176:179], v[104:107], v[212:215], v[176:179]
	v_mfma_f32_16x16x32_bf16 v[4:7], v[244:247], v[212:215], v[4:7]
	v_mfma_f32_16x16x32_bf16 v[180:183], v[112:115], v[212:215], v[180:183]
	s_nop 7
	s_nop 3
	v_lshrrev_b32_e32 v212, 1, v168
	v_and_b32_e32 v212, 0x1c0, v212
	v_and_b32_e32 v213, 15, v168
	v_or_b32_e32 v212, v212, v213
	v_lshl_add_u32 v212, s60, 7, v212
	v_lshlrev_b32_e32 v212, 11, v212
	v_bfe_u32 v213, v168, 4, 2
	v_lshlrev_b32_e32 v209, 3, v213
	v_and_b32_e32 v213, 1, v213
	v_mul_u32_u24_e32 v213, 24, v213
	v_add3_u32 v212, v212, v213, v209
	v_bfe_u32 v213, v168, 6, 1
	s_cmp_lt_u32 s58, 16
	s_cbranch_scc1 .Lep1a_B
	s_sub_u32 s87, s58, 16
	s_lshr_b32 s88, s87, 3
	s_and_b32 s87, s87, 7
	s_lshl_b32 s89, s88, 3
	s_add_u32 s89, s89, 0xe0
	s_load_dwordx2 s[84:85], s[0:1], s89
	s_cmp_eq_u32 s88, 1
	s_cselect_b32 s88, 1, 0
	s_cmp_lt_u32 s87, 4
	s_cselect_b32 s88, s88, 0
	s_mov_b32 s86, 1.0
	s_cmp_eq_u32 s88, 1
	s_cselect_b32 s86, 0x3db504f3, s86
	s_lshl_b32 s87, s87, 8
	v_lshl_add_u32 v208, v213, 7, v212
	v_add_u32_e32 v208, s87, v208
	v_add_u32_e32 v209, 0x8000, v208
	v_add_u32_e32 v210, 0x10000, v208
	v_add_u32_e32 v211, 0x18000, v208
	s_waitcnt lgkmcnt(0)
	v_mul_f32_e32 v184, s86, v56
	v_mul_f32_e32 v185, s86, v57
	v_mul_f32_e32 v186, s86, v58
	v_mul_f32_e32 v187, s86, v59
	v_mul_f32_e32 v188, s86, v48
	v_mul_f32_e32 v189, s86, v49
	v_mul_f32_e32 v190, s86, v50
	v_mul_f32_e32 v191, s86, v51
	v_cvt_pk_bf16_f32 v200, v184, v185
	v_cvt_pk_bf16_f32 v201, v186, v187
	v_cvt_pk_bf16_f32 v202, v188, v189
	v_cvt_pk_bf16_f32 v203, v190, v191
	s_nop 1
	v_permlane16_swap_b32_e32 v200, v202
	v_permlane16_swap_b32_e32 v201, v203
	global_store_dwordx4 v208, v[200:203], s[84:85]
	v_mul_f32_e32 v184, s86, v60
	v_mul_f32_e32 v185, s86, v61
	v_mul_f32_e32 v186, s86, v62
	v_mul_f32_e32 v187, s86, v63
	v_mul_f32_e32 v188, s86, v52
	v_mul_f32_e32 v189, s86, v53
	v_mul_f32_e32 v190, s86, v54
	v_mul_f32_e32 v191, s86, v55
	v_cvt_pk_bf16_f32 v204, v184, v185
	v_cvt_pk_bf16_f32 v205, v186, v187
	v_cvt_pk_bf16_f32 v206, v188, v189
	v_cvt_pk_bf16_f32 v207, v190, v191
	s_nop 1
	v_permlane16_swap_b32_e32 v204, v206
	v_permlane16_swap_b32_e32 v205, v207
	global_store_dwordx4 v208, v[204:207], s[84:85] offset:64
	v_mul_f32_e32 v184, s86, v40
	v_mul_f32_e32 v185, s86, v41
	v_mul_f32_e32 v186, s86, v42
	v_mul_f32_e32 v187, s86, v43
	v_mul_f32_e32 v188, s86, v32
	v_mul_f32_e32 v189, s86, v33
	v_mul_f32_e32 v190, s86, v34
	v_mul_f32_e32 v191, s86, v35
	v_cvt_pk_bf16_f32 v200, v184, v185
	v_cvt_pk_bf16_f32 v201, v186, v187
	v_cvt_pk_bf16_f32 v202, v188, v189
	v_cvt_pk_bf16_f32 v203, v190, v191
	s_nop 1
	v_permlane16_swap_b32_e32 v200, v202
	v_permlane16_swap_b32_e32 v201, v203
	global_store_dwordx4 v209, v[200:203], s[84:85]
	v_mul_f32_e32 v184, s86, v44
	v_mul_f32_e32 v185, s86, v45
	v_mul_f32_e32 v186, s86, v46
	v_mul_f32_e32 v187, s86, v47
	v_mul_f32_e32 v188, s86, v36
	v_mul_f32_e32 v189, s86, v37
	v_mul_f32_e32 v190, s86, v38
	v_mul_f32_e32 v191, s86, v39
	v_cvt_pk_bf16_f32 v204, v184, v185
	v_cvt_pk_bf16_f32 v205, v186, v187
	v_cvt_pk_bf16_f32 v206, v188, v189
	v_cvt_pk_bf16_f32 v207, v190, v191
	s_nop 1
	v_permlane16_swap_b32_e32 v204, v206
	v_permlane16_swap_b32_e32 v205, v207
	global_store_dwordx4 v209, v[204:207], s[84:85] offset:64
	v_mul_f32_e32 v184, s86, v24
	v_mul_f32_e32 v185, s86, v25
	v_mul_f32_e32 v186, s86, v26
	v_mul_f32_e32 v187, s86, v27
	v_mul_f32_e32 v188, s86, v16
	v_mul_f32_e32 v189, s86, v17
	v_mul_f32_e32 v190, s86, v18
	v_mul_f32_e32 v191, s86, v19
	v_cvt_pk_bf16_f32 v200, v184, v185
	v_cvt_pk_bf16_f32 v201, v186, v187
	v_cvt_pk_bf16_f32 v202, v188, v189
	v_cvt_pk_bf16_f32 v203, v190, v191
	s_nop 1
	v_permlane16_swap_b32_e32 v200, v202
	v_permlane16_swap_b32_e32 v201, v203
	global_store_dwordx4 v210, v[200:203], s[84:85]
	v_mul_f32_e32 v184, s86, v28
	v_mul_f32_e32 v185, s86, v29
	v_mul_f32_e32 v186, s86, v30
	v_mul_f32_e32 v187, s86, v31
	v_mul_f32_e32 v188, s86, v20
	v_mul_f32_e32 v189, s86, v21
	v_mul_f32_e32 v190, s86, v22
	v_mul_f32_e32 v191, s86, v23
	v_cvt_pk_bf16_f32 v204, v184, v185
	v_cvt_pk_bf16_f32 v205, v186, v187
	v_cvt_pk_bf16_f32 v206, v188, v189
	v_cvt_pk_bf16_f32 v207, v190, v191
	s_nop 1
	v_permlane16_swap_b32_e32 v204, v206
	v_permlane16_swap_b32_e32 v205, v207
	global_store_dwordx4 v210, v[204:207], s[84:85] offset:64
	v_mul_f32_e32 v184, s86, v8
	v_mul_f32_e32 v185, s86, v9
	v_mul_f32_e32 v186, s86, v10
	v_mul_f32_e32 v187, s86, v11
	v_mul_f32_e32 v188, s86, v0
	v_mul_f32_e32 v189, s86, v1
	v_mul_f32_e32 v190, s86, v2
	v_mul_f32_e32 v191, s86, v3
	v_cvt_pk_bf16_f32 v200, v184, v185
	v_cvt_pk_bf16_f32 v201, v186, v187
	v_cvt_pk_bf16_f32 v202, v188, v189
	v_cvt_pk_bf16_f32 v203, v190, v191
	s_nop 1
	v_permlane16_swap_b32_e32 v200, v202
	v_permlane16_swap_b32_e32 v201, v203
	global_store_dwordx4 v211, v[200:203], s[84:85]
	v_mul_f32_e32 v184, s86, v12
	v_mul_f32_e32 v185, s86, v13
	v_mul_f32_e32 v186, s86, v14
	v_mul_f32_e32 v187, s86, v15
	v_mul_f32_e32 v188, s86, v4
	v_mul_f32_e32 v189, s86, v5
	v_mul_f32_e32 v190, s86, v6
	v_mul_f32_e32 v191, s86, v7
	v_cvt_pk_bf16_f32 v204, v184, v185
	v_cvt_pk_bf16_f32 v205, v186, v187
	v_cvt_pk_bf16_f32 v206, v188, v189
	v_cvt_pk_bf16_f32 v207, v190, v191
	s_nop 1
	v_permlane16_swap_b32_e32 v204, v206
	v_permlane16_swap_b32_e32 v205, v207
	global_store_dwordx4 v211, v[204:207], s[84:85] offset:64
	s_branch .Lep1a_done
.Lep1a_B:
	s_load_dwordx2 s[84:85], s[0:1], 0xd8
	s_lshl_b32 s87, s58, 7
	v_lshl_add_u32 v208, v213, 6, v212
	v_add_u32_e32 v208, s87, v208
	v_add_u32_e32 v209, 0x8000, v208
	v_add_u32_e32 v210, 0x10000, v208
	v_add_u32_e32 v211, 0x18000, v208
	s_waitcnt lgkmcnt(0)
	v_mul_f32_e32 v184, v60, v56
	v_mul_f32_e32 v185, v61, v57
	v_mul_f32_e32 v186, v62, v58
	v_mul_f32_e32 v187, v63, v59
	v_mul_f32_e32 v188, v52, v48
	v_mul_f32_e32 v189, v53, v49
	v_mul_f32_e32 v190, v54, v50
	v_mul_f32_e32 v191, v55, v51
	v_cvt_pk_bf16_f32 v200, v184, v185
	v_cvt_pk_bf16_f32 v201, v186, v187
	v_cvt_pk_bf16_f32 v202, v188, v189
	v_cvt_pk_bf16_f32 v203, v190, v191
	s_nop 1
	v_permlane16_swap_b32_e32 v200, v202
	v_permlane16_swap_b32_e32 v201, v203
	global_store_dwordx4 v208, v[200:203], s[84:85]
	v_mul_f32_e32 v184, v44, v40
	v_mul_f32_e32 v185, v45, v41
	v_mul_f32_e32 v186, v46, v42
	v_mul_f32_e32 v187, v47, v43
	v_mul_f32_e32 v188, v36, v32
	v_mul_f32_e32 v189, v37, v33
	v_mul_f32_e32 v190, v38, v34
	v_mul_f32_e32 v191, v39, v35
	v_cvt_pk_bf16_f32 v204, v184, v185
	v_cvt_pk_bf16_f32 v205, v186, v187
	v_cvt_pk_bf16_f32 v206, v188, v189
	v_cvt_pk_bf16_f32 v207, v190, v191
	s_nop 1
	v_permlane16_swap_b32_e32 v204, v206
	v_permlane16_swap_b32_e32 v205, v207
	global_store_dwordx4 v209, v[204:207], s[84:85]
	v_mul_f32_e32 v184, v28, v24
	v_mul_f32_e32 v185, v29, v25
	v_mul_f32_e32 v186, v30, v26
	v_mul_f32_e32 v187, v31, v27
	v_mul_f32_e32 v188, v20, v16
	v_mul_f32_e32 v189, v21, v17
	v_mul_f32_e32 v190, v22, v18
	v_mul_f32_e32 v191, v23, v19
	v_cvt_pk_bf16_f32 v200, v184, v185
	v_cvt_pk_bf16_f32 v201, v186, v187
	v_cvt_pk_bf16_f32 v202, v188, v189
	v_cvt_pk_bf16_f32 v203, v190, v191
	s_nop 1
	v_permlane16_swap_b32_e32 v200, v202
	v_permlane16_swap_b32_e32 v201, v203
	global_store_dwordx4 v210, v[200:203], s[84:85]
	v_mul_f32_e32 v184, v12, v8
	v_mul_f32_e32 v185, v13, v9
	v_mul_f32_e32 v186, v14, v10
	v_mul_f32_e32 v187, v15, v11
	v_mul_f32_e32 v188, v4, v0
	v_mul_f32_e32 v189, v5, v1
	v_mul_f32_e32 v190, v6, v2
	v_mul_f32_e32 v191, v7, v3
	v_cvt_pk_bf16_f32 v204, v184, v185
	v_cvt_pk_bf16_f32 v205, v186, v187
	v_cvt_pk_bf16_f32 v206, v188, v189
	v_cvt_pk_bf16_f32 v207, v190, v191
	s_nop 1
	v_permlane16_swap_b32_e32 v204, v206
	v_permlane16_swap_b32_e32 v205, v207
	global_store_dwordx4 v211, v[204:207], s[84:85]
.Lep1a_done:
	s_cmp_eq_u32 s95, 1
	s_cbranch_scc0 .Lgp1_single
	v_lshrrev_b32_e32 v212, 1, v168
	v_and_b32_e32 v212, 0x1c0, v212
	v_and_b32_e32 v213, 15, v168
	v_or_b32_e32 v212, v212, v213
	v_lshl_add_u32 v212, s60, 7, v212
	v_lshlrev_b32_e32 v212, 11, v212
	v_bfe_u32 v213, v168, 4, 2
	v_lshlrev_b32_e32 v209, 3, v213
	v_and_b32_e32 v213, 1, v213
	v_mul_u32_u24_e32 v213, 24, v213
	v_add3_u32 v212, v212, v213, v209
	v_bfe_u32 v213, v168, 6, 1
	s_cmp_lt_u32 s83, 16
	s_cbranch_scc1 .Lep1b_B
	s_sub_u32 s87, s83, 16
	s_lshr_b32 s88, s87, 3
	s_and_b32 s87, s87, 7
	s_lshl_b32 s89, s88, 3
	s_add_u32 s89, s89, 0xe0
	s_load_dwordx2 s[84:85], s[0:1], s89
	s_cmp_eq_u32 s88, 1
	s_cselect_b32 s88, 1, 0
	s_cmp_lt_u32 s87, 4
	s_cselect_b32 s88, s88, 0
	s_mov_b32 s86, 1.0
	s_cmp_eq_u32 s88, 1
	s_cselect_b32 s86, 0x3db504f3, s86
	s_lshl_b32 s87, s87, 8
	v_lshl_add_u32 v208, v213, 7, v212
	v_add_u32_e32 v208, s87, v208
	v_add_u32_e32 v209, 0x8000, v208
	v_add_u32_e32 v210, 0x10000, v208
	v_add_u32_e32 v211, 0x18000, v208
	s_waitcnt lgkmcnt(0)
	v_mul_f32_e32 v184, s86, v116
	v_mul_f32_e32 v185, s86, v117
	v_mul_f32_e32 v186, s86, v118
	v_mul_f32_e32 v187, s86, v119
	v_mul_f32_e32 v188, s86, v120
	v_mul_f32_e32 v189, s86, v121
	v_mul_f32_e32 v190, s86, v122
	v_mul_f32_e32 v191, s86, v123
	v_cvt_pk_bf16_f32 v200, v184, v185
	v_cvt_pk_bf16_f32 v201, v186, v187
	v_cvt_pk_bf16_f32 v202, v188, v189
	v_cvt_pk_bf16_f32 v203, v190, v191
	s_nop 1
	v_permlane16_swap_b32_e32 v200, v202
	v_permlane16_swap_b32_e32 v201, v203
	global_store_dwordx4 v208, v[200:203], s[84:85]
	v_mul_f32_e32 v184, s86, v124
	v_mul_f32_e32 v185, s86, v125
	v_mul_f32_e32 v186, s86, v126
	v_mul_f32_e32 v187, s86, v127
	v_mul_f32_e32 v188, s86, v128
	v_mul_f32_e32 v189, s86, v129
	v_mul_f32_e32 v190, s86, v130
	v_mul_f32_e32 v191, s86, v131
	v_cvt_pk_bf16_f32 v204, v184, v185
	v_cvt_pk_bf16_f32 v205, v186, v187
	v_cvt_pk_bf16_f32 v206, v188, v189
	v_cvt_pk_bf16_f32 v207, v190, v191
	s_nop 1
	v_permlane16_swap_b32_e32 v204, v206
	v_permlane16_swap_b32_e32 v205, v207
	global_store_dwordx4 v208, v[204:207], s[84:85] offset:64
	v_mul_f32_e32 v184, s86, v132
	v_mul_f32_e32 v185, s86, v133
	v_mul_f32_e32 v186, s86, v134
	v_mul_f32_e32 v187, s86, v135
	v_mul_f32_e32 v188, s86, v136
	v_mul_f32_e32 v189, s86, v137
	v_mul_f32_e32 v190, s86, v138
	v_mul_f32_e32 v191, s86, v139
	v_cvt_pk_bf16_f32 v200, v184, v185
	v_cvt_pk_bf16_f32 v201, v186, v187
	v_cvt_pk_bf16_f32 v202, v188, v189
	v_cvt_pk_bf16_f32 v203, v190, v191
	s_nop 1
	v_permlane16_swap_b32_e32 v200, v202
	v_permlane16_swap_b32_e32 v201, v203
	global_store_dwordx4 v209, v[200:203], s[84:85]
	v_mul_f32_e32 v184, s86, v140
	v_mul_f32_e32 v185, s86, v141
	v_mul_f32_e32 v186, s86, v142
	v_mul_f32_e32 v187, s86, v143
	v_mul_f32_e32 v188, s86, v144
	v_mul_f32_e32 v189, s86, v145
	v_mul_f32_e32 v190, s86, v146
	v_mul_f32_e32 v191, s86, v147
	v_cvt_pk_bf16_f32 v204, v184, v185
	v_cvt_pk_bf16_f32 v205, v186, v187
	v_cvt_pk_bf16_f32 v206, v188, v189
	v_cvt_pk_bf16_f32 v207, v190, v191
	s_nop 1
	v_permlane16_swap_b32_e32 v204, v206
	v_permlane16_swap_b32_e32 v205, v207
	global_store_dwordx4 v209, v[204:207], s[84:85] offset:64
	v_mul_f32_e32 v184, s86, v148
	v_mul_f32_e32 v185, s86, v149
	v_mul_f32_e32 v186, s86, v150
	v_mul_f32_e32 v187, s86, v151
	v_mul_f32_e32 v188, s86, v152
	v_mul_f32_e32 v189, s86, v153
	v_mul_f32_e32 v190, s86, v154
	v_mul_f32_e32 v191, s86, v155
	v_cvt_pk_bf16_f32 v200, v184, v185
	v_cvt_pk_bf16_f32 v201, v186, v187
	v_cvt_pk_bf16_f32 v202, v188, v189
	v_cvt_pk_bf16_f32 v203, v190, v191
	s_nop 1
	v_permlane16_swap_b32_e32 v200, v202
	v_permlane16_swap_b32_e32 v201, v203
	global_store_dwordx4 v210, v[200:203], s[84:85]
	v_mul_f32_e32 v184, s86, v156
	v_mul_f32_e32 v185, s86, v157
	v_mul_f32_e32 v186, s86, v158
	v_mul_f32_e32 v187, s86, v159
	v_mul_f32_e32 v188, s86, v160
	v_mul_f32_e32 v189, s86, v161
	v_mul_f32_e32 v190, s86, v162
	v_mul_f32_e32 v191, s86, v163
	v_cvt_pk_bf16_f32 v204, v184, v185
	v_cvt_pk_bf16_f32 v205, v186, v187
	v_cvt_pk_bf16_f32 v206, v188, v189
	v_cvt_pk_bf16_f32 v207, v190, v191
	s_nop 1
	v_permlane16_swap_b32_e32 v204, v206
	v_permlane16_swap_b32_e32 v205, v207
	global_store_dwordx4 v210, v[204:207], s[84:85] offset:64
	v_mul_f32_e32 v184, s86, v164
	v_mul_f32_e32 v185, s86, v165
	v_mul_f32_e32 v186, s86, v166
	v_mul_f32_e32 v187, s86, v167
	v_mul_f32_e32 v188, s86, v172
	v_mul_f32_e32 v189, s86, v173
	v_mul_f32_e32 v190, s86, v174
	v_mul_f32_e32 v191, s86, v175
	v_cvt_pk_bf16_f32 v200, v184, v185
	v_cvt_pk_bf16_f32 v201, v186, v187
	v_cvt_pk_bf16_f32 v202, v188, v189
	v_cvt_pk_bf16_f32 v203, v190, v191
	s_nop 1
	v_permlane16_swap_b32_e32 v200, v202
	v_permlane16_swap_b32_e32 v201, v203
	global_store_dwordx4 v211, v[200:203], s[84:85]
	v_mul_f32_e32 v184, s86, v176
	v_mul_f32_e32 v185, s86, v177
	v_mul_f32_e32 v186, s86, v178
	v_mul_f32_e32 v187, s86, v179
	v_mul_f32_e32 v188, s86, v180
	v_mul_f32_e32 v189, s86, v181
	v_mul_f32_e32 v190, s86, v182
	v_mul_f32_e32 v191, s86, v183
	v_cvt_pk_bf16_f32 v204, v184, v185
	v_cvt_pk_bf16_f32 v205, v186, v187
	v_cvt_pk_bf16_f32 v206, v188, v189
	v_cvt_pk_bf16_f32 v207, v190, v191
	s_nop 1
	v_permlane16_swap_b32_e32 v204, v206
	v_permlane16_swap_b32_e32 v205, v207
	global_store_dwordx4 v211, v[204:207], s[84:85] offset:64
	s_branch .Lep1b_done
.Lep1b_B:
	s_load_dwordx2 s[84:85], s[0:1], 0xd8
	s_lshl_b32 s87, s83, 7
	v_lshl_add_u32 v208, v213, 6, v212
	v_add_u32_e32 v208, s87, v208
	v_add_u32_e32 v209, 0x8000, v208
	v_add_u32_e32 v210, 0x10000, v208
	v_add_u32_e32 v211, 0x18000, v208
	s_waitcnt lgkmcnt(0)
	v_mul_f32_e32 v184, v124, v116
	v_mul_f32_e32 v185, v125, v117
	v_mul_f32_e32 v186, v126, v118
	v_mul_f32_e32 v187, v127, v119
	v_mul_f32_e32 v188, v128, v120
	v_mul_f32_e32 v189, v129, v121
	v_mul_f32_e32 v190, v130, v122
	v_mul_f32_e32 v191, v131, v123
	v_cvt_pk_bf16_f32 v200, v184, v185
	v_cvt_pk_bf16_f32 v201, v186, v187
	v_cvt_pk_bf16_f32 v202, v188, v189
	v_cvt_pk_bf16_f32 v203, v190, v191
	s_nop 1
	v_permlane16_swap_b32_e32 v200, v202
	v_permlane16_swap_b32_e32 v201, v203
	global_store_dwordx4 v208, v[200:203], s[84:85]
	v_mul_f32_e32 v184, v140, v132
	v_mul_f32_e32 v185, v141, v133
	v_mul_f32_e32 v186, v142, v134
	v_mul_f32_e32 v187, v143, v135
	v_mul_f32_e32 v188, v144, v136
	v_mul_f32_e32 v189, v145, v137
	v_mul_f32_e32 v190, v146, v138
	v_mul_f32_e32 v191, v147, v139
	v_cvt_pk_bf16_f32 v204, v184, v185
	v_cvt_pk_bf16_f32 v205, v186, v187
	v_cvt_pk_bf16_f32 v206, v188, v189
	v_cvt_pk_bf16_f32 v207, v190, v191
	s_nop 1
	v_permlane16_swap_b32_e32 v204, v206
	v_permlane16_swap_b32_e32 v205, v207
	global_store_dwordx4 v209, v[204:207], s[84:85]
	v_mul_f32_e32 v184, v156, v148
	v_mul_f32_e32 v185, v157, v149
	v_mul_f32_e32 v186, v158, v150
	v_mul_f32_e32 v187, v159, v151
	v_mul_f32_e32 v188, v160, v152
	v_mul_f32_e32 v189, v161, v153
	v_mul_f32_e32 v190, v162, v154
	v_mul_f32_e32 v191, v163, v155
	v_cvt_pk_bf16_f32 v200, v184, v185
	v_cvt_pk_bf16_f32 v201, v186, v187
	v_cvt_pk_bf16_f32 v202, v188, v189
	v_cvt_pk_bf16_f32 v203, v190, v191
	s_nop 1
	v_permlane16_swap_b32_e32 v200, v202
	v_permlane16_swap_b32_e32 v201, v203
	global_store_dwordx4 v210, v[200:203], s[84:85]
	v_mul_f32_e32 v184, v176, v164
	v_mul_f32_e32 v185, v177, v165
	v_mul_f32_e32 v186, v178, v166
	v_mul_f32_e32 v187, v179, v167
	v_mul_f32_e32 v188, v180, v172
	v_mul_f32_e32 v189, v181, v173
	v_mul_f32_e32 v190, v182, v174
	v_mul_f32_e32 v191, v183, v175
	v_cvt_pk_bf16_f32 v204, v184, v185
	v_cvt_pk_bf16_f32 v205, v186, v187
	v_cvt_pk_bf16_f32 v206, v188, v189
	v_cvt_pk_bf16_f32 v207, v190, v191
	s_nop 1
	v_permlane16_swap_b32_e32 v204, v206
	v_permlane16_swap_b32_e32 v205, v207
	global_store_dwordx4 v211, v[204:207], s[84:85]

.LBB0_184:
	s_or_b64 exec, exec, s[6:7]
	v_lshlrev_b64 v[50:51], 1, v[46:47]
	v_lshl_add_u64 v[46:47], s[14:15], 0, v[50:51]
	global_load_dwordx4 v[46:49], v[46:47], off
	s_waitcnt vmcnt(0)
	v_mov_b32_e32 v45, v13
	v_mov_b32_e32 v66, v25
	v_mov_b32_e32 v71, v21
	v_mov_b32_e32 v74, v29
	v_lshlrev_b32_e32 v52, 16, v40
	v_lshlrev_b32_e32 v53, 16, v41
	v_mov_b32_e32 v25, v26
	v_mov_b32_e32 v29, v30
	v_mov_b32_e32 v67, v5
	v_mov_b32_e32 v68, v17
	v_lshlrev_b32_e32 v55, 16, v33
	v_lshlrev_b32_e32 v54, 16, v32
	v_and_b32_e32 v59, 0xffff0000, v41
	v_and_b32_e32 v58, 0xffff0000, v40
	v_lshlrev_b32_e32 v40, 16, v42
	v_and_b32_e32 v65, 0xffff0000, v43
	v_and_b32_e32 v64, 0xffff0000, v42
	v_lshlrev_b32_e32 v41, 16, v43
	v_mov_b32_e32 v17, v18
	v_mov_b32_e32 v13, v14
	v_mov_b32_e32 v21, v22
	v_lshl_add_u64 v[42:43], s[24:25], 0, v[50:51]
	v_pk_fma_f32 v[50:51], v[24:25], v[52:53], v[28:29]
	v_mov_b32_e32 v26, v66
	v_mov_b32_e32 v30, v74
	v_mov_b32_e32 v14, v45
	v_mov_b32_e32 v22, v71
	v_mov_b32_e32 v69, v1
	v_mov_b32_e32 v70, v9
	v_and_b32_e32 v33, 0xffff0000, v33
	v_and_b32_e32 v32, 0xffff0000, v32
	v_lshlrev_b32_e32 v61, 16, v35
	v_lshlrev_b32_e32 v60, 16, v34
	v_and_b32_e32 v35, 0xffff0000, v35
	v_and_b32_e32 v34, 0xffff0000, v34
	v_mov_b32_e32 v5, v6
	v_mov_b32_e32 v18, v68
	v_mov_b32_e32 v6, v67
	v_pk_fma_f32 v[50:51], v[16:17], v[54:55], v[50:51]
	v_pk_fma_f32 v[52:53], v[26:27], v[58:59], v[30:31]
	v_pk_fma_f32 v[54:55], v[14:15], v[64:65], v[22:23]
	v_lshlrev_b32_e32 v57, 16, v37
	v_lshlrev_b32_e32 v56, 16, v36
	v_and_b32_e32 v37, 0xffff0000, v37
	v_and_b32_e32 v36, 0xffff0000, v36
	v_lshlrev_b32_e32 v63, 16, v39
	v_lshlrev_b32_e32 v62, 16, v38
	v_and_b32_e32 v39, 0xffff0000, v39
	v_and_b32_e32 v38, 0xffff0000, v38
	v_mov_b32_e32 v9, v10
	v_mov_b32_e32 v1, v2
	v_mov_b32_e32 v10, v70
	v_pk_fma_f32 v[40:41], v[12:13], v[40:41], v[20:21]
	v_mov_b32_e32 v2, v69
	v_pk_fma_f32 v[32:33], v[18:19], v[32:33], v[52:53]
	v_pk_fma_f32 v[34:35], v[6:7], v[34:35], v[54:55]
	v_pk_fma_f32 v[40:41], v[4:5], v[60:61], v[40:41]
	v_pk_fma_f32 v[32:33], v[10:11], v[36:37], v[32:33]
	v_pk_fma_f32 v[34:35], v[2:3], v[38:39], v[34:35]
	v_pk_fma_f32 v[50:51], v[8:9], v[56:57], v[50:51]
	v_pk_fma_f32 v[40:41], v[0:1], v[62:63], v[40:41]
	v_add_u32_e32 v74, 2, v44
	v_and_b32_e32 v39, 0xffff0000, v47
	v_and_b32_e32 v38, 0xffff0000, v46
	v_lshlrev_b32_e32 v37, 16, v47
	v_lshlrev_b32_e32 v36, 16, v46
	v_lshlrev_b32_e32 v47, 16, v49
	v_lshlrev_b32_e32 v46, 16, v48
	v_pk_mul_f32 v[32:33], v[32:33], v[38:39]
	v_pk_mul_f32 v[36:37], v[50:51], v[36:37]
	v_pk_mul_f32 v[38:39], v[40:41], v[46:47]
	s_nop 0
	s_nop 0
	s_nop 0
	s_nop 0
	v_cvt_pk_bf16_f32 v33, v33, v33
	v_cvt_pk_bf16_f32 v32, v32, v32
	v_and_b32_e32 v49, 0xffff0000, v49
	v_and_b32_e32 v48, 0xffff0000, v48
	v_cvt_pk_bf16_f32 v36, v36, v36
	v_cvt_pk_bf16_f32 v37, v37, v37
	v_and_b32_e32 v33, 0xffff0000, v33
	v_and_b32_e32 v32, 0xffff0000, v32
	v_pk_mul_f32 v[34:35], v[34:35], v[48:49]
	v_or_b32_sdwa v33, v33, v37 dst_sel:DWORD dst_unused:UNUSED_PAD src0_sel:DWORD src1_sel:WORD_1
	v_or_b32_sdwa v32, v32, v36 dst_sel:DWORD dst_unused:UNUSED_PAD src0_sel:DWORD src1_sel:WORD_1
	s_nop 0
	s_nop 0
	v_cvt_pk_bf16_f32 v37, v38, v38
	v_cvt_pk_bf16_f32 v36, v39, v39
	s_nop 0
	s_nop 0
	v_cvt_pk_bf16_f32 v35, v35, v35
	v_cvt_pk_bf16_f32 v34, v34, v34
	v_and_b32_e32 v35, 0xffff0000, v35
	v_and_b32_e32 v34, 0xffff0000, v34
	v_lshlrev_b64 v[46:47], 10, v[74:75]
	v_or_b32_sdwa v35, v35, v36 dst_sel:DWORD dst_unused:UNUSED_PAD src0_sel:DWORD src1_sel:WORD_1
	v_or_b32_sdwa v34, v34, v37 dst_sel:DWORD dst_unused:UNUSED_PAD src0_sel:DWORD src1_sel:WORD_1
	v_or_b32_e32 v46, v46, v72
	global_store_dwordx4 v[42:43], v[32:35], off
	v_lshl_add_u64 v[48:49], v[46:47], 1, s[12:13]
	global_load_dwordx4 v[32:35], v[48:49], off
	v_and_b32_e32 v37, 0x1fff, v74
	v_mov_b32_e32 v36, 0
	v_cmp_ne_u32_e32 vcc, 0, v37
	v_mov_b32_e32 v42, 0
	v_mov_b32_e32 v43, 0
	v_mov_b32_e32 v40, 0
	v_mov_b32_e32 v41, 0
	s_and_saveexec_b64 s[6:7], vcc
	s_cbranch_execz .LBB0_186
	global_load_dwordx4 v[40:43], v[48:49], off offset:-2048

.LBB0_188:
	s_or_b64 exec, exec, s[6:7]
	v_lshlrev_b64 v[46:47], 1, v[46:47]
	v_lshl_add_u64 v[48:49], s[14:15], 0, v[46:47]
	global_load_dwordx4 v[48:51], v[48:49], off
	s_waitcnt vmcnt(1)
	v_lshlrev_b32_e32 v52, 16, v40
	v_and_b32_e32 v59, 0xffff0000, v41
	v_and_b32_e32 v58, 0xffff0000, v40
	v_lshlrev_b32_e32 v53, 16, v41
	v_lshlrev_b32_e32 v40, 16, v42
	v_and_b32_e32 v65, 0xffff0000, v43
	v_and_b32_e32 v64, 0xffff0000, v42
	v_lshlrev_b32_e32 v41, 16, v43
	v_lshlrev_b32_e32 v55, 16, v33
	v_lshlrev_b32_e32 v54, 16, v32
	v_and_b32_e32 v33, 0xffff0000, v33
	v_and_b32_e32 v32, 0xffff0000, v32
	v_lshlrev_b32_e32 v61, 16, v35
	v_lshlrev_b32_e32 v60, 16, v34
	v_and_b32_e32 v35, 0xffff0000, v35
	v_and_b32_e32 v34, 0xffff0000, v34
	v_pk_fma_f32 v[58:59], v[26:27], v[58:59], v[30:31]
	v_pk_fma_f32 v[40:41], v[12:13], v[40:41], v[20:21]
	v_pk_fma_f32 v[64:65], v[14:15], v[64:65], v[22:23]
	v_lshlrev_b32_e32 v57, 16, v37
	v_lshlrev_b32_e32 v56, 16, v36
	v_and_b32_e32 v37, 0xffff0000, v37
	v_and_b32_e32 v36, 0xffff0000, v36
	v_lshlrev_b32_e32 v63, 16, v39
	v_lshlrev_b32_e32 v62, 16, v38
	v_and_b32_e32 v39, 0xffff0000, v39
	v_and_b32_e32 v38, 0xffff0000, v38
	v_pk_fma_f32 v[52:53], v[24:25], v[52:53], v[28:29]
	v_pk_fma_f32 v[32:33], v[18:19], v[32:33], v[58:59]
	v_pk_fma_f32 v[40:41], v[4:5], v[60:61], v[40:41]
	v_pk_fma_f32 v[34:35], v[6:7], v[34:35], v[64:65]
	v_pk_fma_f32 v[52:53], v[16:17], v[54:55], v[52:53]
	v_pk_fma_f32 v[32:33], v[10:11], v[36:37], v[32:33]
	v_pk_fma_f32 v[36:37], v[0:1], v[62:63], v[40:41]
	v_pk_fma_f32 v[34:35], v[2:3], v[38:39], v[34:35]
	v_pk_fma_f32 v[52:53], v[8:9], v[56:57], v[52:53]
	v_add_u32_e32 v74, 4, v44
	v_lshl_add_u64 v[42:43], s[24:25], 0, v[46:47]
	v_lshlrev_b64 v[46:47], 10, v[74:75]
	v_or_b32_e32 v46, v46, v72
	s_waitcnt vmcnt(0)
	v_lshlrev_b32_e32 v39, 16, v49
	v_lshlrev_b32_e32 v38, 16, v48
	v_and_b32_e32 v41, 0xffff0000, v49
	v_and_b32_e32 v40, 0xffff0000, v48
	v_lshlrev_b32_e32 v49, 16, v51
	v_lshlrev_b32_e32 v48, 16, v50
	v_and_b32_e32 v51, 0xffff0000, v51
	v_and_b32_e32 v50, 0xffff0000, v50
	v_pk_mul_f32 v[32:33], v[32:33], v[40:41]
	v_pk_mul_f32 v[34:35], v[34:35], v[50:51]
	v_pk_mul_f32 v[38:39], v[52:53], v[38:39]
	v_pk_mul_f32 v[36:37], v[36:37], v[48:49]
	s_nop 0
	s_nop 0
	s_nop 0
	s_nop 0
	s_nop 0
	s_nop 0
	s_nop 0
	s_nop 0
	v_cvt_pk_bf16_f32 v33, v33, v33
	v_cvt_pk_bf16_f32 v32, v32, v32
	v_cvt_pk_bf16_f32 v35, v35, v35
	v_cvt_pk_bf16_f32 v34, v34, v34
	v_cvt_pk_bf16_f32 v38, v38, v38
	v_cvt_pk_bf16_f32 v39, v39, v39
	v_cvt_pk_bf16_f32 v36, v36, v36
	v_cvt_pk_bf16_f32 v37, v37, v37
	v_and_b32_e32 v33, 0xffff0000, v33
	v_and_b32_e32 v32, 0xffff0000, v32
	v_and_b32_e32 v35, 0xffff0000, v35
	v_and_b32_e32 v34, 0xffff0000, v34
	v_or_b32_sdwa v33, v33, v39 dst_sel:DWORD dst_unused:UNUSED_PAD src0_sel:DWORD src1_sel:WORD_1
	v_or_b32_sdwa v32, v32, v38 dst_sel:DWORD dst_unused:UNUSED_PAD src0_sel:DWORD src1_sel:WORD_1
	v_or_b32_sdwa v35, v35, v37 dst_sel:DWORD dst_unused:UNUSED_PAD src0_sel:DWORD src1_sel:WORD_1
	v_or_b32_sdwa v34, v34, v36 dst_sel:DWORD dst_unused:UNUSED_PAD src0_sel:DWORD src1_sel:WORD_1
	global_store_dwordx4 v[42:43], v[32:35], off
	v_lshl_add_u64 v[48:49], v[46:47], 1, s[12:13]
	global_load_dwordx4 v[32:35], v[48:49], off
	v_and_b32_e32 v37, 0x1fff, v74
	v_mov_b32_e32 v36, 0
	v_cmp_ne_u32_e32 vcc, 0, v37
	v_mov_b32_e32 v42, 0
	v_mov_b32_e32 v43, 0
	v_mov_b32_e32 v40, 0
	v_mov_b32_e32 v41, 0
	s_and_saveexec_b64 s[6:7], vcc
	s_cbranch_execz .LBB0_190
	global_load_dwordx4 v[40:43], v[48:49], off offset:-2048

.LBB0_192:
	s_or_b64 exec, exec, s[6:7]
	v_lshlrev_b64 v[50:51], 1, v[46:47]
	v_lshl_add_u64 v[46:47], s[14:15], 0, v[50:51]
	global_load_dwordx4 v[46:49], v[46:47], off
	s_waitcnt vmcnt(1)
	v_lshlrev_b32_e32 v52, 16, v40
	v_and_b32_e32 v59, 0xffff0000, v41
	v_and_b32_e32 v58, 0xffff0000, v40
	v_lshlrev_b32_e32 v53, 16, v41
	v_lshlrev_b32_e32 v40, 16, v42
	v_and_b32_e32 v65, 0xffff0000, v43
	v_and_b32_e32 v64, 0xffff0000, v42
	v_lshlrev_b32_e32 v41, 16, v43
	v_lshlrev_b32_e32 v55, 16, v33
	v_lshlrev_b32_e32 v54, 16, v32
	v_and_b32_e32 v33, 0xffff0000, v33
	v_and_b32_e32 v32, 0xffff0000, v32
	v_lshlrev_b32_e32 v61, 16, v35
	v_lshlrev_b32_e32 v60, 16, v34
	v_and_b32_e32 v35, 0xffff0000, v35
	v_and_b32_e32 v34, 0xffff0000, v34
	v_lshl_add_u64 v[42:43], s[24:25], 0, v[50:51]
	v_pk_fma_f32 v[50:51], v[24:25], v[52:53], v[28:29]
	v_pk_fma_f32 v[52:53], v[26:27], v[58:59], v[30:31]
	v_pk_fma_f32 v[40:41], v[12:13], v[40:41], v[20:21]
	v_pk_fma_f32 v[58:59], v[14:15], v[64:65], v[22:23]
	v_lshlrev_b32_e32 v57, 16, v37
	v_lshlrev_b32_e32 v56, 16, v36
	v_and_b32_e32 v37, 0xffff0000, v37
	v_and_b32_e32 v36, 0xffff0000, v36
	v_lshlrev_b32_e32 v63, 16, v39
	v_lshlrev_b32_e32 v62, 16, v38
	v_and_b32_e32 v39, 0xffff0000, v39
	v_and_b32_e32 v38, 0xffff0000, v38
	v_pk_fma_f32 v[32:33], v[18:19], v[32:33], v[52:53]
	v_pk_fma_f32 v[40:41], v[4:5], v[60:61], v[40:41]
	v_pk_fma_f32 v[34:35], v[6:7], v[34:35], v[58:59]
	v_pk_fma_f32 v[50:51], v[16:17], v[54:55], v[50:51]
	v_pk_fma_f32 v[32:33], v[10:11], v[36:37], v[32:33]
	v_pk_fma_f32 v[36:37], v[0:1], v[62:63], v[40:41]
	v_pk_fma_f32 v[34:35], v[2:3], v[38:39], v[34:35]
	v_pk_fma_f32 v[50:51], v[8:9], v[56:57], v[50:51]
	v_add_u32_e32 v74, 6, v44
	v_lshlrev_b64 v[44:45], 10, v[74:75]
	v_or_b32_e32 v44, v44, v72
	s_waitcnt vmcnt(0)
	v_lshlrev_b32_e32 v39, 16, v47
	v_lshlrev_b32_e32 v38, 16, v46
	v_and_b32_e32 v41, 0xffff0000, v47
	v_and_b32_e32 v40, 0xffff0000, v46
	v_lshlrev_b32_e32 v47, 16, v49
	v_lshlrev_b32_e32 v46, 16, v48
	v_and_b32_e32 v49, 0xffff0000, v49
	v_and_b32_e32 v48, 0xffff0000, v48
	v_pk_mul_f32 v[32:33], v[32:33], v[40:41]
	v_pk_mul_f32 v[34:35], v[34:35], v[48:49]
	v_pk_mul_f32 v[38:39], v[50:51], v[38:39]
	v_pk_mul_f32 v[36:37], v[36:37], v[46:47]
	s_nop 0
	s_nop 0
	s_nop 0
	s_nop 0
	s_nop 0
	s_nop 0
	s_nop 0
	s_nop 0
	v_cvt_pk_bf16_f32 v33, v33, v33
	v_cvt_pk_bf16_f32 v32, v32, v32
	v_cvt_pk_bf16_f32 v35, v35, v35
	v_cvt_pk_bf16_f32 v34, v34, v34
	v_cvt_pk_bf16_f32 v38, v38, v38
	v_cvt_pk_bf16_f32 v39, v39, v39
	v_cvt_pk_bf16_f32 v36, v36, v36
	v_cvt_pk_bf16_f32 v37, v37, v37
	v_and_b32_e32 v33, 0xffff0000, v33
	v_and_b32_e32 v32, 0xffff0000, v32
	v_and_b32_e32 v35, 0xffff0000, v35
	v_and_b32_e32 v34, 0xffff0000, v34
	v_or_b32_sdwa v33, v33, v39 dst_sel:DWORD dst_unused:UNUSED_PAD src0_sel:DWORD src1_sel:WORD_1
	v_or_b32_sdwa v32, v32, v38 dst_sel:DWORD dst_unused:UNUSED_PAD src0_sel:DWORD src1_sel:WORD_1
	v_or_b32_sdwa v35, v35, v37 dst_sel:DWORD dst_unused:UNUSED_PAD src0_sel:DWORD src1_sel:WORD_1
	v_or_b32_sdwa v34, v34, v36 dst_sel:DWORD dst_unused:UNUSED_PAD src0_sel:DWORD src1_sel:WORD_1
	global_store_dwordx4 v[42:43], v[32:35], off
	v_lshl_add_u64 v[46:47], v[44:45], 1, s[12:13]
	global_load_dwordx4 v[32:35], v[46:47], off
	v_and_b32_e32 v37, 0x1fff, v74
	v_mov_b32_e32 v36, 0
	v_cmp_ne_u32_e32 vcc, 0, v37
	v_mov_b32_e32 v42, 0
	v_mov_b32_e32 v43, 0
	v_mov_b32_e32 v40, 0
	v_mov_b32_e32 v41, 0
	s_and_saveexec_b64 s[6:7], vcc
	s_cbranch_execz .LBB0_194
	global_load_dwordx4 v[40:43], v[46:47], off offset:-2048

.LBB0_196:
	s_or_b64 exec, exec, s[6:7]
	v_lshlrev_b64 v[48:49], 1, v[44:45]
	v_lshl_add_u64 v[44:45], s[14:15], 0, v[48:49]
	global_load_dwordx4 v[44:47], v[44:45], off
	s_waitcnt vmcnt(1)
	v_lshlrev_b32_e32 v50, 16, v40
	v_and_b32_e32 v57, 0xffff0000, v41
	v_and_b32_e32 v56, 0xffff0000, v40
	v_lshlrev_b32_e32 v51, 16, v41
	v_lshlrev_b32_e32 v40, 16, v42
	v_and_b32_e32 v63, 0xffff0000, v43
	v_and_b32_e32 v62, 0xffff0000, v42
	v_lshlrev_b32_e32 v41, 16, v43
	v_lshlrev_b32_e32 v53, 16, v33
	v_lshlrev_b32_e32 v52, 16, v32
	v_and_b32_e32 v33, 0xffff0000, v33
	v_and_b32_e32 v32, 0xffff0000, v32
	v_lshlrev_b32_e32 v59, 16, v35
	v_lshlrev_b32_e32 v58, 16, v34
	v_and_b32_e32 v35, 0xffff0000, v35
	v_and_b32_e32 v34, 0xffff0000, v34
	v_pk_fma_f32 v[24:25], v[24:25], v[50:51], v[28:29]
	v_pk_fma_f32 v[26:27], v[26:27], v[56:57], v[30:31]
	v_pk_fma_f32 v[12:13], v[12:13], v[40:41], v[20:21]
	v_pk_fma_f32 v[14:15], v[14:15], v[62:63], v[22:23]
	v_lshlrev_b32_e32 v55, 16, v37
	v_lshlrev_b32_e32 v54, 16, v36
	v_and_b32_e32 v37, 0xffff0000, v37
	v_and_b32_e32 v36, 0xffff0000, v36
	v_lshlrev_b32_e32 v61, 16, v39
	v_lshlrev_b32_e32 v60, 16, v38
	v_and_b32_e32 v39, 0xffff0000, v39
	v_and_b32_e32 v38, 0xffff0000, v38
	v_pk_fma_f32 v[16:17], v[16:17], v[52:53], v[24:25]
	v_pk_fma_f32 v[18:19], v[18:19], v[32:33], v[26:27]
	v_pk_fma_f32 v[4:5], v[4:5], v[58:59], v[12:13]
	v_pk_fma_f32 v[6:7], v[6:7], v[34:35], v[14:15]
	v_pk_fma_f32 v[8:9], v[8:9], v[54:55], v[16:17]
	v_pk_fma_f32 v[10:11], v[10:11], v[36:37], v[18:19]
	v_pk_fma_f32 v[0:1], v[0:1], v[60:61], v[4:5]
	v_pk_fma_f32 v[2:3], v[2:3], v[38:39], v[6:7]
	v_lshl_add_u64 v[42:43], s[24:25], 0, v[48:49]
	s_mov_b64 s[6:7], 0
	s_waitcnt vmcnt(0)
	v_lshlrev_b32_e32 v5, 16, v45
	v_lshlrev_b32_e32 v4, 16, v44
	v_and_b32_e32 v7, 0xffff0000, v45
	v_and_b32_e32 v6, 0xffff0000, v44
	v_lshlrev_b32_e32 v13, 16, v47
	v_lshlrev_b32_e32 v12, 16, v46
	v_and_b32_e32 v15, 0xffff0000, v47
	v_and_b32_e32 v14, 0xffff0000, v46
	v_pk_mul_f32 v[4:5], v[8:9], v[4:5]
	v_pk_mul_f32 v[6:7], v[10:11], v[6:7]
	v_pk_mul_f32 v[0:1], v[0:1], v[12:13]
	v_pk_mul_f32 v[2:3], v[2:3], v[14:15]
	s_nop 0
	s_nop 0
	v_and_b32_sdwa v10, v7, v143 dst_sel:DWORD dst_unused:UNUSED_PAD src0_sel:WORD_1 src1_sel:DWORD
	v_and_b32_sdwa v11, v6, v143 dst_sel:DWORD dst_unused:UNUSED_PAD src0_sel:WORD_1 src1_sel:DWORD
	v_and_b32_sdwa v12, v1, v143 dst_sel:DWORD dst_unused:UNUSED_PAD src0_sel:WORD_1 src1_sel:DWORD
	v_and_b32_sdwa v13, v0, v143 dst_sel:DWORD dst_unused:UNUSED_PAD src0_sel:WORD_1 src1_sel:DWORD
	v_and_b32_sdwa v14, v3, v143 dst_sel:DWORD dst_unused:UNUSED_PAD src0_sel:WORD_1 src1_sel:DWORD
	v_and_b32_sdwa v15, v2, v143 dst_sel:DWORD dst_unused:UNUSED_PAD src0_sel:WORD_1 src1_sel:DWORD
	v_cvt_pk_bf16_f32 v4, v4, v4
	v_cvt_pk_bf16_f32 v5, v5, v5
	v_cvt_pk_bf16_f32 v7, v7, v7
	v_cvt_pk_bf16_f32 v6, v6, v6
	v_cvt_pk_bf16_f32 v8, v0, v0
	v_cvt_pk_bf16_f32 v9, v1, v1
	v_cvt_pk_bf16_f32 v0, v3, v3
	v_cvt_pk_bf16_f32 v1, v2, v2
	v_and_b32_e32 v2, 0xffff0000, v7
	v_and_b32_e32 v3, 0xffff0000, v6
	v_and_b32_e32 v6, 0xffff0000, v0
	v_and_b32_e32 v7, 0xffff0000, v1
	v_or_b32_sdwa v1, v2, v5 dst_sel:DWORD dst_unused:UNUSED_PAD src0_sel:DWORD src1_sel:WORD_1
	v_or_b32_sdwa v0, v3, v4 dst_sel:DWORD dst_unused:UNUSED_PAD src0_sel:DWORD src1_sel:WORD_1
	v_or_b32_sdwa v3, v6, v9 dst_sel:DWORD dst_unused:UNUSED_PAD src0_sel:DWORD src1_sel:WORD_1
	v_or_b32_sdwa v2, v7, v8 dst_sel:DWORD dst_unused:UNUSED_PAD src0_sel:DWORD src1_sel:WORD_1
	global_store_dwordx4 v[42:43], v[0:3], off

.LBB0_199:
	v_cndmask_b32_e64 v134, v134, 0, s[26:27]
	v_cndmask_b32_e64 v101, v135, 0, s[26:27]
	v_add_f32_e32 v70, v134, v70
	v_add_f32_e32 v71, v101, v71
	v_cndmask_b32_e64 v70, v134, v70, s[6:7]
	v_cndmask_b32_e64 v71, v101, v71, s[6:7]
	v_add_f32_e32 v64, v70, v64
	v_add_f32_e32 v65, v71, v65
	v_cndmask_b32_e64 v64, v70, v64, s[8:9]
	v_cndmask_b32_e64 v65, v71, v65, s[8:9]
	v_add_f32_e32 v66, v64, v66
	v_add_f32_e32 v67, v65, v67
	v_cndmask_b32_e64 v200, v64, v66, s[10:11]
	v_cndmask_b32_e64 v101, v65, v67, s[10:11]
	v_add_f32_e32 v66, v132, v200
	v_add_f32_e32 v67, v133, v101
	v_mul_f32_e32 v66, 0x3fb8aa3b, v66
	v_exp_f32_e32 v70, v66
	v_mul_f32_e32 v66, 0x3fb8aa3b, v67
	v_exp_f32_e32 v71, v66
	v_add_f32_e32 v126, v126, v200
	v_mul_f32_e32 v126, 0x3fb8aa3b, v126
	v_exp_f32_e32 v126, v126
	v_rcp_f32_e32 v132, v71
	v_add_f32_e32 v71, v130, v200
	v_mul_f32_e32 v71, 0x3fb8aa3b, v71
	v_exp_f32_e32 v71, v71
	v_add_f32_e32 v133, v131, v101
	v_rcp_f32_e32 v70, v70
	v_mul_f32_e32 v133, 0x3fb8aa3b, v133
	v_rcp_f32_e32 v196, v71
	v_add_f32_e32 v71, v128, v200
	v_mul_f32_e32 v71, 0x3fb8aa3b, v71
	v_exp_f32_e32 v71, v71
	v_add_f32_e32 v128, v129, v101
	v_mul_f32_e32 v128, 0x3fb8aa3b, v128
	v_add_f32_e32 v127, v127, v101
	v_rcp_f32_e32 v71, v71
	v_exp_f32_e32 v133, v133
	v_exp_f32_e32 v128, v128
	v_mul_f32_e32 v127, 0x3fb8aa3b, v127
	v_rcp_f32_e32 v197, v126
	v_exp_f32_e32 v127, v127
	v_lshlrev_b32_e32 v65, 16, v193
	v_lshlrev_b32_e32 v64, 16, v189
	v_lshlrev_b32_e32 v131, 16, v194
	v_lshlrev_b32_e32 v130, 16, v190
	v_pk_mul_f32 v[64:65], v[70:71], v[64:65]
	v_rcp_f32_e32 v198, v133
	v_rcp_f32_e32 v133, v128
	v_pk_mul_f32 v[64:65], v[100:101], v[64:65] op_sel_hi:[0,1]
	v_pk_mul_f32 v[70:71], v[196:197], v[130:131]
	v_rcp_f32_e32 v199, v127
	v_pk_mul_f32 v[70:71], v[100:101], v[70:71] op_sel_hi:[0,1]
	s_nop 0
	s_nop 0
	v_cvt_pk_bf16_f32 v64, v64, v64
	v_cvt_pk_bf16_f32 v65, v65, v65
	s_nop 0
	s_nop 0
	v_and_b32_e32 v67, 0xffff0000, v193
	v_and_b32_e32 v66, 0xffff0000, v189
	v_cvt_pk_bf16_f32 v71, v71, v71
	v_cvt_pk_bf16_f32 v70, v70, v70
	v_and_b32_e32 v135, 0xffff0000, v194
	v_and_b32_e32 v134, 0xffff0000, v190
	v_and_b32_e32 v71, 0xffff0000, v71
	v_and_b32_e32 v70, 0xffff0000, v70
	v_pk_mul_f32 v[66:67], v[132:133], v[66:67]
	v_or_b32_sdwa v65, v71, v65 dst_sel:DWORD dst_unused:UNUSED_PAD src0_sel:DWORD src1_sel:WORD_1
	v_or_b32_sdwa v64, v70, v64 dst_sel:DWORD dst_unused:UNUSED_PAD src0_sel:DWORD src1_sel:WORD_1
	v_pk_mul_f32 v[66:67], v[74:75], v[66:67] op_sel_hi:[0,1]
	v_pk_mul_f32 v[70:71], v[198:199], v[134:135]
	s_nop 0
	v_pk_mul_f32 v[70:71], v[74:75], v[70:71] op_sel_hi:[0,1]
	s_nop 0
	v_cvt_pk_bf16_f32 v66, v66, v66
	s_nop 0
	v_cvt_pk_bf16_f32 v67, v67, v67
	s_nop 0
	v_cvt_pk_bf16_f32 v70, v70, v70
	v_cvt_pk_bf16_f32 v71, v71, v71
	v_and_b32_e32 v70, 0xffff0000, v70
	v_and_b32_e32 v71, 0xffff0000, v71
	v_or_b32_sdwa v126, v70, v66 dst_sel:DWORD dst_unused:UNUSED_PAD src0_sel:DWORD src1_sel:WORD_1
	v_add_f32_e32 v70, v124, v200
	v_or_b32_sdwa v127, v71, v67 dst_sel:DWORD dst_unused:UNUSED_PAD src0_sel:DWORD src1_sel:WORD_1
	v_add_f32_e32 v71, v125, v101
	v_mul_f32_e32 v70, 0x3fb8aa3b, v70
	v_exp_f32_e32 v124, v70
	v_mul_f32_e32 v70, 0x3fb8aa3b, v71
	v_exp_f32_e32 v125, v70
	v_add_f32_e32 v120, v120, v200
	v_mul_f32_e32 v120, 0x3fb8aa3b, v120
	v_add_f32_e32 v118, v118, v200
	v_rcp_f32_e32 v128, v125
	v_add_f32_e32 v125, v122, v200
	v_mul_f32_e32 v125, 0x3fb8aa3b, v125
	v_exp_f32_e32 v125, v125
	v_exp_f32_e32 v120, v120
	v_mul_f32_e32 v118, 0x3fb8aa3b, v118
	v_exp_f32_e32 v118, v118
	v_add_f32_e32 v119, v119, v101
	v_rcp_f32_e32 v124, v124
	v_add_f32_e32 v129, v123, v101
	v_rcp_f32_e32 v132, v125
	v_add_f32_e32 v121, v121, v101
	v_mul_f32_e32 v119, 0x3fb8aa3b, v119
	v_rcp_f32_e32 v125, v120
	v_mul_f32_e32 v129, 0x3fb8aa3b, v129
	v_mul_f32_e32 v121, 0x3fb8aa3b, v121
	v_exp_f32_e32 v119, v119
	v_rcp_f32_e32 v133, v118
	v_exp_f32_e32 v129, v129
	v_exp_f32_e32 v121, v121
	v_lshlrev_b32_e32 v67, 16, v191
	v_lshlrev_b32_e32 v66, 16, v185
	v_lshlrev_b32_e32 v123, 16, v192
	v_lshlrev_b32_e32 v122, 16, v187
	v_pk_mul_f32 v[66:67], v[124:125], v[66:67]
	v_rcp_f32_e32 v135, v119
	v_pk_mul_f32 v[66:67], v[100:101], v[66:67] op_sel_hi:[0,1]
	v_pk_mul_f32 v[118:119], v[132:133], v[122:123]
	v_rcp_f32_e32 v134, v129
	v_rcp_f32_e32 v129, v121
	v_pk_mul_f32 v[118:119], v[100:101], v[118:119] op_sel_hi:[0,1]
	s_nop 0
	s_nop 0
	v_cvt_pk_bf16_f32 v66, v66, v66
	v_cvt_pk_bf16_f32 v67, v67, v67
	s_nop 0
	s_nop 0
	v_cvt_pk_bf16_f32 v119, v119, v119
	v_cvt_pk_bf16_f32 v118, v118, v118
	v_and_b32_e32 v119, 0xffff0000, v119
	v_and_b32_e32 v118, 0xffff0000, v118
	v_and_b32_e32 v71, 0xffff0000, v191
	v_and_b32_e32 v70, 0xffff0000, v185
	v_or_b32_sdwa v67, v119, v67 dst_sel:DWORD dst_unused:UNUSED_PAD src0_sel:DWORD src1_sel:WORD_1
	v_or_b32_sdwa v66, v118, v66 dst_sel:DWORD dst_unused:UNUSED_PAD src0_sel:DWORD src1_sel:WORD_1
	v_and_b32_e32 v131, 0xffff0000, v192
	v_and_b32_e32 v130, 0xffff0000, v187
	ds_write_b128 v91, v[64:67] offset:34816
	v_pk_mul_f32 v[64:65], v[128:129], v[70:71]
	v_pk_mul_f32 v[66:67], v[134:135], v[130:131]
	v_pk_mul_f32 v[64:65], v[74:75], v[64:65] op_sel_hi:[0,1]
	v_pk_mul_f32 v[66:67], v[74:75], v[66:67] op_sel_hi:[0,1]
	s_nop 0
	s_nop 0
	v_cvt_pk_bf16_f32 v64, v64, v64
	s_nop 0
	v_cvt_pk_bf16_f32 v65, v65, v65
	s_nop 0
	v_cvt_pk_bf16_f32 v66, v66, v66
	v_cvt_pk_bf16_f32 v67, v67, v67
	v_and_b32_e32 v66, 0xffff0000, v66
	v_and_b32_e32 v67, 0xffff0000, v67
	v_or_b32_sdwa v128, v66, v64 dst_sel:DWORD dst_unused:UNUSED_PAD src0_sel:DWORD src1_sel:WORD_1
	v_add_f32_e32 v66, v116, v200
	v_or_b32_sdwa v129, v67, v65 dst_sel:DWORD dst_unused:UNUSED_PAD src0_sel:DWORD src1_sel:WORD_1
	v_add_f32_e32 v67, v117, v101
	v_mul_f32_e32 v66, 0x3fb8aa3b, v66
	v_exp_f32_e32 v70, v66
	v_mul_f32_e32 v66, 0x3fb8aa3b, v67
	v_exp_f32_e32 v71, v66
	v_add_f32_e32 v110, v110, v200
	v_mul_f32_e32 v110, 0x3fb8aa3b, v110
	v_exp_f32_e32 v110, v110
	v_rcp_f32_e32 v116, v71
	v_add_f32_e32 v71, v114, v200
	v_mul_f32_e32 v71, 0x3fb8aa3b, v71
	v_exp_f32_e32 v71, v71
	v_add_f32_e32 v117, v115, v101
	v_rcp_f32_e32 v70, v70
	v_mul_f32_e32 v117, 0x3fb8aa3b, v117
	v_rcp_f32_e32 v120, v71
	v_add_f32_e32 v71, v112, v200
	v_mul_f32_e32 v71, 0x3fb8aa3b, v71
	v_exp_f32_e32 v71, v71
	v_add_f32_e32 v112, v113, v101
	v_mul_f32_e32 v112, 0x3fb8aa3b, v112
	v_add_f32_e32 v111, v111, v101
	v_rcp_f32_e32 v71, v71
	v_exp_f32_e32 v117, v117
	v_exp_f32_e32 v112, v112
	v_mul_f32_e32 v111, 0x3fb8aa3b, v111
	v_rcp_f32_e32 v121, v110
	v_exp_f32_e32 v111, v111
	v_lshlrev_b32_e32 v65, 16, v183
	v_lshlrev_b32_e32 v64, 16, v180
	s_waitcnt vmcnt(14)
	v_lshlrev_b32_e32 v115, 16, v195
	v_lshlrev_b32_e32 v114, 16, v181
	v_pk_mul_f32 v[64:65], v[70:71], v[64:65]
	v_rcp_f32_e32 v122, v117
	v_rcp_f32_e32 v117, v112
	v_pk_mul_f32 v[64:65], v[100:101], v[64:65] op_sel_hi:[0,1]
	v_pk_mul_f32 v[70:71], v[120:121], v[114:115]
	v_rcp_f32_e32 v123, v111
	v_pk_mul_f32 v[70:71], v[100:101], v[70:71] op_sel_hi:[0,1]
	s_nop 0
	s_nop 0
	v_cvt_pk_bf16_f32 v64, v64, v64
	v_cvt_pk_bf16_f32 v65, v65, v65
	s_nop 0
	s_nop 0
	v_and_b32_e32 v67, 0xffff0000, v183
	v_and_b32_e32 v66, 0xffff0000, v180
	v_cvt_pk_bf16_f32 v71, v71, v71
	v_cvt_pk_bf16_f32 v70, v70, v70
	v_and_b32_e32 v119, 0xffff0000, v195
	v_and_b32_e32 v118, 0xffff0000, v181
	v_and_b32_e32 v71, 0xffff0000, v71
	v_and_b32_e32 v70, 0xffff0000, v70
	v_pk_mul_f32 v[66:67], v[116:117], v[66:67]
	v_or_b32_sdwa v65, v71, v65 dst_sel:DWORD dst_unused:UNUSED_PAD src0_sel:DWORD src1_sel:WORD_1
	v_or_b32_sdwa v64, v70, v64 dst_sel:DWORD dst_unused:UNUSED_PAD src0_sel:DWORD src1_sel:WORD_1
	v_pk_mul_f32 v[66:67], v[74:75], v[66:67] op_sel_hi:[0,1]
	v_pk_mul_f32 v[70:71], v[122:123], v[118:119]
	s_nop 0
	v_pk_mul_f32 v[70:71], v[74:75], v[70:71] op_sel_hi:[0,1]
	s_nop 0
	v_cvt_pk_bf16_f32 v66, v66, v66
	s_nop 0
	v_cvt_pk_bf16_f32 v67, v67, v67
	s_nop 0
	v_cvt_pk_bf16_f32 v70, v70, v70
	v_cvt_pk_bf16_f32 v71, v71, v71
	v_and_b32_e32 v70, 0xffff0000, v70
	v_and_b32_e32 v71, 0xffff0000, v71
	v_or_b32_sdwa v110, v70, v66 dst_sel:DWORD dst_unused:UNUSED_PAD src0_sel:DWORD src1_sel:WORD_1
	v_add_f32_e32 v70, v108, v200
	v_or_b32_sdwa v111, v71, v67 dst_sel:DWORD dst_unused:UNUSED_PAD src0_sel:DWORD src1_sel:WORD_1
	v_add_f32_e32 v71, v109, v101
	v_mul_f32_e32 v70, 0x3fb8aa3b, v70
	v_exp_f32_e32 v108, v70
	v_mul_f32_e32 v70, 0x3fb8aa3b, v71
	v_exp_f32_e32 v109, v70
	v_add_f32_e32 v104, v104, v200
	v_mul_f32_e32 v104, 0x3fb8aa3b, v104
	v_add_f32_e32 v102, v102, v200
	v_rcp_f32_e32 v112, v109
	v_add_f32_e32 v109, v106, v200
	v_mul_f32_e32 v109, 0x3fb8aa3b, v109
	v_exp_f32_e32 v109, v109
	v_exp_f32_e32 v104, v104
	v_mul_f32_e32 v102, 0x3fb8aa3b, v102
	v_exp_f32_e32 v102, v102
	v_add_f32_e32 v113, v107, v101
	v_add_f32_e32 v105, v105, v101
	v_add_f32_e32 v101, v103, v101
	v_rcp_f32_e32 v108, v108
	v_rcp_f32_e32 v116, v109
	v_mul_f32_e32 v101, 0x3fb8aa3b, v101
	v_rcp_f32_e32 v109, v104
	v_exp_f32_e32 v101, v101
	v_rcp_f32_e32 v117, v102
	v_mul_f32_e32 v113, 0x3fb8aa3b, v113
	v_mul_f32_e32 v105, 0x3fb8aa3b, v105
	s_waitcnt vmcnt(5)
	v_lshlrev_b32_e32 v67, 16, v188
	v_lshlrev_b32_e32 v66, 16, v184
	v_exp_f32_e32 v113, v113
	v_exp_f32_e32 v105, v105
	s_waitcnt vmcnt(2)
	v_lshlrev_b32_e32 v107, 16, v186
	v_lshlrev_b32_e32 v106, 16, v182
	v_pk_mul_f32 v[66:67], v[108:109], v[66:67]
	v_pk_mul_f32 v[102:103], v[116:117], v[106:107]
	v_pk_mul_f32 v[66:67], v[100:101], v[66:67] op_sel_hi:[0,1]
	v_rcp_f32_e32 v119, v101
	v_pk_mul_f32 v[100:101], v[100:101], v[102:103] op_sel_hi:[0,1]
	s_nop 0
	s_nop 0
	v_rcp_f32_e32 v118, v113
	v_rcp_f32_e32 v113, v105
	v_cvt_pk_bf16_f32 v66, v66, v66
	v_cvt_pk_bf16_f32 v67, v67, v67
	s_nop 0
	s_nop 0
	v_cvt_pk_bf16_f32 v101, v101, v101
	v_cvt_pk_bf16_f32 v100, v100, v100
	v_and_b32_e32 v101, 0xffff0000, v101
	v_and_b32_e32 v100, 0xffff0000, v100
	v_and_b32_e32 v71, 0xffff0000, v188
	v_and_b32_e32 v70, 0xffff0000, v184
	v_or_b32_sdwa v67, v101, v67 dst_sel:DWORD dst_unused:UNUSED_PAD src0_sel:DWORD src1_sel:WORD_1
	v_or_b32_sdwa v66, v100, v66 dst_sel:DWORD dst_unused:UNUSED_PAD src0_sel:DWORD src1_sel:WORD_1
	v_and_b32_e32 v115, 0xffff0000, v186
	v_and_b32_e32 v114, 0xffff0000, v182
	ds_write_b128 v91, v[64:67] offset:34832
	v_pk_mul_f32 v[64:65], v[112:113], v[70:71]
	v_pk_mul_f32 v[66:67], v[118:119], v[114:115]
	v_pk_mul_f32 v[64:65], v[74:75], v[64:65] op_sel_hi:[0,1]
	v_pk_mul_f32 v[66:67], v[74:75], v[66:67] op_sel_hi:[0,1]
	s_nop 0
	s_nop 0
	v_cvt_pk_bf16_f32 v64, v64, v64
	v_cvt_pk_bf16_f32 v65, v65, v65
	s_nop 0
	s_nop 0
	v_cvt_pk_bf16_f32 v67, v67, v67
	v_cvt_pk_bf16_f32 v66, v66, v66
	v_lshlrev_b32_e32 v70, 16, v173
	v_and_b32_e32 v67, 0xffff0000, v67
	v_and_b32_e32 v66, 0xffff0000, v66
	v_or_b32_sdwa v100, v70, v172 dst_sel:DWORD dst_unused:UNUSED_PAD src0_sel:DWORD src1_sel:WORD_0
	v_lshlrev_b32_e32 v70, 16, v175
	v_or_b32_sdwa v113, v67, v65 dst_sel:DWORD dst_unused:UNUSED_PAD src0_sel:DWORD src1_sel:WORD_1
	v_or_b32_sdwa v112, v66, v64 dst_sel:DWORD dst_unused:UNUSED_PAD src0_sel:DWORD src1_sel:WORD_1
	v_lshlrev_b32_e32 v64, 16, v157
	v_lshlrev_b32_e32 v65, 16, v159
	v_lshlrev_b32_e32 v66, 16, v166
	v_lshlrev_b32_e32 v67, 16, v171
	v_or_b32_sdwa v101, v70, v174 dst_sel:DWORD dst_unused:UNUSED_PAD src0_sel:DWORD src1_sel:WORD_0
	v_lshlrev_b32_e32 v70, 16, v177
	v_or_b32_sdwa v64, v64, v156 dst_sel:DWORD dst_unused:UNUSED_PAD src0_sel:DWORD src1_sel:WORD_0
	v_or_b32_sdwa v65, v65, v158 dst_sel:DWORD dst_unused:UNUSED_PAD src0_sel:DWORD src1_sel:WORD_0
	v_or_b32_sdwa v66, v66, v160 dst_sel:DWORD dst_unused:UNUSED_PAD src0_sel:DWORD src1_sel:WORD_0
	v_or_b32_sdwa v67, v67, v170 dst_sel:DWORD dst_unused:UNUSED_PAD src0_sel:DWORD src1_sel:WORD_0
	v_or_b32_sdwa v102, v70, v176 dst_sel:DWORD dst_unused:UNUSED_PAD src0_sel:DWORD src1_sel:WORD_0
	s_waitcnt vmcnt(1)
	v_lshlrev_b32_e32 v70, 16, v179
	v_add_u32_e32 v166, s43, v140
	ds_write_b128 v91, v[126:129] offset:34960
	ds_write_b128 v91, v[110:113] offset:34976
	s_waitcnt lgkmcnt(0)
	s_barrier
	v_or_b32_sdwa v103, v70, v178 dst_sel:DWORD dst_unused:UNUSED_PAD src0_sel:DWORD src1_sel:WORD_0
	ds_write_b128 v144, v[64:67] offset:53248
	ds_write_b128 v144, v[100:103] offset:53264
	s_waitcnt lgkmcnt(0)
	s_barrier
	ds_read_b128 v[64:67], v166 offset:53248
	ds_read2_b32 v[70:71], v145 offset1:16
	ds_read2_b32 v[170:171], v145 offset0:32 offset1:48
	v_add_u32_e32 v172, s44, v140
	ds_read_b128 v[100:103], v172 offset:34816
	ds_read_b128 v[104:107], v172 offset:37120
	ds_read_b128 v[108:111], v166 offset:53312
	ds_read_b128 v[112:115], v172 offset:34880
	ds_read_b128 v[116:119], v172 offset:39424
	ds_read_b128 v[120:123], v172 offset:37184
	ds_read_b128 v[124:127], v166 offset:55552
	ds_read_b128 v[128:131], v172 offset:41728
	ds_read_b128 v[132:135], v172 offset:39488
	s_waitcnt lgkmcnt(10)
	v_mov_b32_e32 v74, v71
	s_waitcnt lgkmcnt(9)
	v_mov_b32_e32 v160, v171
	v_pk_mul_f32 v[62:63], v[62:63], v[70:71] op_sel_hi:[1,0]
	v_pk_mul_f32 v[60:61], v[60:61], v[70:71] op_sel_hi:[1,0]
	v_pk_mul_f32 v[58:59], v[58:59], v[74:75] op_sel_hi:[1,0]
	v_pk_mul_f32 v[56:57], v[56:57], v[74:75] op_sel_hi:[1,0]
	v_pk_mul_f32 v[54:55], v[54:55], v[170:171] op_sel_hi:[1,0]
	v_pk_mul_f32 v[52:53], v[52:53], v[170:171] op_sel_hi:[1,0]
	v_pk_mul_f32 v[46:47], v[46:47], v[160:161] op_sel_hi:[1,0]
	v_pk_mul_f32 v[44:45], v[44:45], v[160:161] op_sel_hi:[1,0]
	s_waitcnt lgkmcnt(8)
	v_mfma_f32_16x16x32_bf16 v[60:63], v[64:67], v[100:103], v[60:63]
	ds_read_b128 v[156:159], v172 offset:41792
	v_pk_mul_f32 v[42:43], v[42:43], v[70:71] op_sel_hi:[1,0]
	v_pk_mul_f32 v[40:41], v[40:41], v[70:71] op_sel_hi:[1,0]
	s_waitcnt lgkmcnt(8)
	v_mfma_f32_16x16x32_bf16 v[56:59], v[64:67], v[104:107], v[56:59]
	v_lshlrev_b32_e32 v70, 16, v147
	v_pk_mul_f32 v[38:39], v[38:39], v[74:75] op_sel_hi:[1,0]
	v_pk_mul_f32 v[36:37], v[36:37], v[74:75] op_sel_hi:[1,0]
	s_waitcnt lgkmcnt(5)
	v_mfma_f32_16x16x32_bf16 v[52:55], v[64:67], v[116:119], v[52:55]
	v_mul_f32_e64 v30, v30, v170
	v_mul_f32_e64 v31, v31, v170
	v_pk_mul_f32 v[28:29], v[28:29], v[170:171] op_sel_hi:[1,0]
	v_pk_mul_f32 v[34:35], v[34:35], v[160:161] op_sel_hi:[1,0]
	s_waitcnt lgkmcnt(2)
	v_mfma_f32_16x16x32_bf16 v[44:47], v[64:67], v[128:131], v[44:47]
	ds_read_b128 v[64:67], v166 offset:55616
	v_pk_mul_f32 v[32:33], v[32:33], v[160:161] op_sel_hi:[1,0]
	s_waitcnt lgkmcnt(0)
	v_mfma_f32_16x16x32_bf16 v[40:43], v[124:127], v[100:103], v[40:43]
	v_or_b32_sdwa v100, v70, v146 dst_sel:DWORD dst_unused:UNUSED_PAD src0_sel:DWORD src1_sel:WORD_0
	v_lshlrev_b32_e32 v70, 16, v149
	v_or_b32_sdwa v101, v70, v148 dst_sel:DWORD dst_unused:UNUSED_PAD src0_sel:DWORD src1_sel:WORD_0
	v_lshlrev_b32_e32 v70, 16, v151
	v_or_b32_sdwa v102, v70, v150 dst_sel:DWORD dst_unused:UNUSED_PAD src0_sel:DWORD src1_sel:WORD_0
	v_lshlrev_b32_e32 v70, 16, v153
	v_mfma_f32_16x16x32_bf16 v[36:39], v[124:127], v[104:107], v[36:39]
	v_or_b32_sdwa v103, v70, v152 dst_sel:DWORD dst_unused:UNUSED_PAD src0_sel:DWORD src1_sel:WORD_0
	v_lshlrev_b32_e32 v70, 16, v155
	v_or_b32_sdwa v104, v70, v154 dst_sel:DWORD dst_unused:UNUSED_PAD src0_sel:DWORD src1_sel:WORD_0
	v_mfma_f32_16x16x32_bf16 v[28:31], v[124:127], v[116:119], v[28:31]
	v_lshlrev_b32_e32 v70, 16, v162
	v_or_b32_sdwa v105, v70, v161 dst_sel:DWORD dst_unused:UNUSED_PAD src0_sel:DWORD src1_sel:WORD_0
	v_lshlrev_b32_e32 v70, 16, v164
	v_mfma_f32_16x16x32_bf16 v[32:35], v[124:127], v[128:131], v[32:35]
	v_or_b32_sdwa v106, v70, v163 dst_sel:DWORD dst_unused:UNUSED_PAD src0_sel:DWORD src1_sel:WORD_0
	s_waitcnt vmcnt(0)
	v_lshlrev_b32_e32 v70, 16, v167
	s_barrier
	v_mfma_f32_16x16x32_bf16 v[40:43], v[64:67], v[112:115], v[40:43]
	v_or_b32_sdwa v107, v70, v165 dst_sel:DWORD dst_unused:UNUSED_PAD src0_sel:DWORD src1_sel:WORD_0
	ds_write_b128 v144, v[100:103] offset:53248
	ds_write_b128 v144, v[104:107] offset:53264
	v_mfma_f32_16x16x32_bf16 v[36:39], v[64:67], v[120:123], v[36:39]
	s_waitcnt lgkmcnt(0)
	s_barrier
	v_mfma_f32_16x16x32_bf16 v[28:31], v[64:67], v[132:135], v[28:31]
	ds_read2_b32 v[70:71], v145 offset1:16
	ds_read2_b32 v[150:151], v145 offset0:32 offset1:48
	ds_read_b128 v[100:103], v172 offset:34816
	v_mfma_f32_16x16x32_bf16 v[32:35], v[64:67], v[156:159], v[32:35]
	ds_read_b128 v[64:67], v166 offset:53248
	s_waitcnt lgkmcnt(3)
	v_mov_b32_e32 v74, v71
	s_waitcnt lgkmcnt(2)
	v_mov_b32_e32 v152, v151
	v_mfma_f32_16x16x32_bf16 v[60:63], v[108:111], v[112:115], v[60:63]
	v_mul_f32_e64 v50, v50, v70
	v_mul_f32_e64 v51, v51, v70
	v_pk_mul_f32 v[48:49], v[48:49], v[70:71] op_sel_hi:[1,0]
	v_pk_mul_f32 v[26:27], v[26:27], v[74:75] op_sel_hi:[1,0]
	v_mfma_f32_16x16x32_bf16 v[56:59], v[108:111], v[120:123], v[56:59]
	v_mul_f32_e64 v24, v24, v74
	v_mul_f32_e64 v25, v25, v74
	v_pk_mul_f32 v[22:23], v[22:23], v[150:151] op_sel_hi:[1,0]
	v_pk_mul_f32 v[20:21], v[20:21], v[150:151] op_sel_hi:[1,0]
	v_mfma_f32_16x16x32_bf16 v[52:55], v[108:111], v[132:135], v[52:55]
	v_mul_f32_e64 v14, v14, v152
	v_mul_f32_e64 v15, v15, v152
	v_pk_mul_f32 v[12:13], v[12:13], v[152:153] op_sel_hi:[1,0]
	v_pk_mul_f32 v[10:11], v[10:11], v[70:71] op_sel_hi:[1,0]
	v_mfma_f32_16x16x32_bf16 v[44:47], v[108:111], v[156:159], v[44:47]
	ds_read_b128 v[104:107], v172 offset:37120
	ds_read_b128 v[108:111], v166 offset:53312
	ds_read_b128 v[112:115], v172 offset:34880
	ds_read_b128 v[116:119], v172 offset:39424
	ds_read_b128 v[120:123], v172 offset:37184
	ds_read_b128 v[124:127], v166 offset:55552
	ds_read_b128 v[128:131], v172 offset:41728
	ds_read_b128 v[132:135], v172 offset:39488
	s_waitcnt lgkmcnt(8)
	v_mfma_f32_16x16x32_bf16 v[48:51], v[64:67], v[100:103], v[48:51]
	ds_read_b128 v[146:149], v172 offset:41792
	v_pk_mul_f32 v[8:9], v[8:9], v[70:71] op_sel_hi:[1,0]
	v_pk_mul_f32 v[6:7], v[6:7], v[74:75] op_sel_hi:[1,0]
	s_waitcnt lgkmcnt(8)
	v_mfma_f32_16x16x32_bf16 v[24:27], v[64:67], v[104:107], v[24:27]
	v_mul_f32_e64 v4, v4, v74
	v_mul_f32_e64 v5, v5, v74
	v_pk_mul_f32 v[2:3], v[2:3], v[150:151] op_sel_hi:[1,0]
	v_pk_mul_f32 v[0:1], v[0:1], v[150:151] op_sel_hi:[1,0]
	s_waitcnt lgkmcnt(5)
	v_mfma_f32_16x16x32_bf16 v[20:23], v[64:67], v[116:119], v[20:23]
	v_mul_f32_e64 v18, v18, v152
	v_mul_f32_e64 v19, v19, v152
	v_pk_mul_f32 v[16:17], v[16:17], v[152:153] op_sel_hi:[1,0]
	s_add_i32 s40, s40, 64
	s_waitcnt lgkmcnt(2)
	v_mfma_f32_16x16x32_bf16 v[12:15], v[64:67], v[128:131], v[12:15]
	ds_read_b128 v[64:67], v166 offset:55616
	s_sub_i32 s45, s45, 64
	v_pk_add_f32 v[92:93], v[92:93], v[68:69]
	v_mfma_f32_16x16x32_bf16 v[8:11], v[124:127], v[100:103], v[8:11]
	s_cmpk_eq_i32 s40, 0x200
	v_mfma_f32_16x16x32_bf16 v[4:7], v[124:127], v[104:107], v[4:7]
	v_mfma_f32_16x16x32_bf16 v[0:3], v[124:127], v[116:119], v[0:3]
	v_mfma_f32_16x16x32_bf16 v[16:19], v[124:127], v[128:131], v[16:19]
	v_mfma_f32_16x16x32_bf16 v[48:51], v[108:111], v[112:115], v[48:51]
	v_mfma_f32_16x16x32_bf16 v[24:27], v[108:111], v[120:123], v[24:27]
	s_waitcnt lgkmcnt(2)
	v_mfma_f32_16x16x32_bf16 v[20:23], v[108:111], v[132:135], v[20:23]
	s_waitcnt lgkmcnt(1)
	v_mfma_f32_16x16x32_bf16 v[12:15], v[108:111], v[146:149], v[12:15]
	s_waitcnt lgkmcnt(0)
	v_mfma_f32_16x16x32_bf16 v[8:11], v[64:67], v[112:115], v[8:11]
	v_mfma_f32_16x16x32_bf16 v[4:7], v[64:67], v[120:123], v[4:7]
	v_mfma_f32_16x16x32_bf16 v[0:3], v[64:67], v[132:135], v[0:3]
	v_mfma_f32_16x16x32_bf16 v[16:19], v[64:67], v[146:149], v[16:19]
	s_cbranch_scc1 .LBB0_202

.LBB0_267:
	s_cmpk_gt_i32 s26, 0x5ff
	s_mov_b64 s[16:17], -1
	s_cbranch_scc0 .LBB0_273
	s_cmpk_gt_u32 s26, 0x9ff
	s_cbranch_scc0 .LBB0_270
	v_mov_b32_e32 v5, v3
	v_lshl_add_u64 v[0:1], v[4:5], 2, s[10:11]
	global_load_dwordx4 v[24:27], v[0:1], off
	global_load_dwordx4 v[28:31], v[0:1], off offset:16
	v_lshl_add_u64 v[8:9], v[4:5], 1, s[14:15]
	s_mov_b64 s[16:17], 0
	s_waitcnt vmcnt(0)
	s_nop 0
	s_nop 0
	s_nop 0
	s_nop 0
	s_nop 0
	v_cvt_pk_bf16_f32 v0, v24, v24
	s_nop 0
	s_nop 0
	s_nop 0
	v_cvt_pk_bf16_f32 v1, v25, v25
	v_cvt_pk_bf16_f32 v7, v29, v29
	v_cvt_pk_bf16_f32 v24, v27, v27
	v_cvt_pk_bf16_f32 v25, v30, v30
	v_lshrrev_b32_e32 v0, 16, v0
	v_cvt_pk_bf16_f32 v5, v26, v26
	v_cvt_pk_bf16_f32 v2, v28, v28
	v_cvt_pk_bf16_f32 v26, v31, v31
	v_and_b32_e32 v7, 0xffff0000, v7
	v_and_b32_e32 v24, 0xffff0000, v24
	v_lshrrev_b32_e32 v25, 16, v25
	v_and_or_b32 v27, v1, s23, v0
	v_or_b32_sdwa v1, v7, v2 dst_sel:DWORD dst_unused:UNUSED_PAD src0_sel:DWORD src1_sel:WORD_1
	v_or_b32_sdwa v0, v24, v5 dst_sel:DWORD dst_unused:UNUSED_PAD src0_sel:DWORD src1_sel:WORD_1
	v_and_or_b32 v2, v26, s23, v25
	global_store_dword v[8:9], v27, off
.LBB0_270:
	s_andn2_b64 vcc, exec, s[16:17]
	s_cbranch_vccnz .LBB0_272
	s_and_b32 s6, s18, 0x1fe0
	s_add_i32 s16, s6, 0xfffff400
	s_and_b32 s6, s20, 0x3c0
	v_or_b32_e32 v5, s16, v12
	v_or_b32_e32 v0, s6, v11
	v_lshl_add_u32 v2, v0, 11, v5
	v_lshl_add_u64 v[0:1], v[2:3], 2, s[8:9]
	v_or_b32_e32 v2, s6, v13
	v_lshl_add_u32 v2, v2, 11, v5
	v_lshl_add_u64 v[8:9], v[2:3], 2, s[8:9]
	v_or_b32_e32 v2, s6, v14
	v_lshl_add_u32 v2, v2, 11, v5
	v_lshl_add_u64 v[24:25], v[2:3], 2, s[8:9]
	v_or_b32_e32 v2, s6, v15
	v_lshl_add_u32 v2, v2, 11, v5
	v_lshl_add_u64 v[26:27], v[2:3], 2, s[8:9]
	v_or_b32_e32 v2, s6, v16
	v_lshl_add_u32 v2, v2, 11, v5
	v_lshl_add_u64 v[28:29], v[2:3], 2, s[8:9]
	v_add_u32_e32 v2, s6, v17
	v_lshl_add_u32 v2, v2, 11, v5
	v_lshl_add_u64 v[30:31], v[2:3], 2, s[8:9]
	v_add_u32_e32 v2, s6, v18
	v_lshl_add_u32 v2, v2, 11, v5
	v_lshl_add_u64 v[32:33], v[2:3], 2, s[8:9]
	v_add_u32_e32 v2, s6, v19
	v_lshl_add_u32 v2, v2, 11, v5
	s_waitcnt vmcnt(0)
	s_barrier
	v_lshl_add_u64 v[34:35], v[2:3], 2, s[8:9]
	global_load_dword v5, v[0:1], off
	global_load_dword v36, v[8:9], off
	global_load_dword v37, v[24:25], off
	global_load_dword v38, v[26:27], off
	global_load_dword v39, v[28:29], off
	global_load_dword v40, v[30:31], off
	global_load_dword v41, v[32:33], off
	global_load_dword v42, v[34:35], off
	v_add_u32_e32 v2, s16, v10
	v_lshlrev_b64 v[0:1], 11, v[2:3]
	s_lshl_b32 s6, s6, 1
	v_lshl_add_u64 v[0:1], s[12:13], 0, v[0:1]
	v_lshl_add_u64 v[28:29], v[0:1], 0, s[6:7]
	v_mov_b32_e32 v7, v3
	s_waitcnt vmcnt(7)
	ds_write_b32 v23, v5
	s_waitcnt vmcnt(6)
	ds_write_b32 v23, v36 offset:1056
	s_waitcnt vmcnt(5)
	ds_write_b32 v23, v37 offset:2112
	s_waitcnt vmcnt(4)
	ds_write_b32 v23, v38 offset:3168
	s_waitcnt vmcnt(3)
	ds_write_b32 v23, v39 offset:4224
	s_waitcnt vmcnt(2)
	ds_write_b32 v23, v40 offset:5280
	s_waitcnt vmcnt(1)
	ds_write_b32 v23, v41 offset:6336
	s_waitcnt vmcnt(0)
	ds_write_b32 v23, v42 offset:7392
	s_waitcnt lgkmcnt(0)
	s_barrier
	ds_read2_b32 v[8:9], v20 offset1:66
	ds_read2_b32 v[24:25], v21 offset0:33 offset1:99
	ds_read2_b32 v[26:27], v20 offset0:132 offset1:198
	ds_read2_b32 v[0:1], v21 offset0:165 offset1:231
	s_waitcnt lgkmcnt(3)
	s_nop 0
	s_waitcnt lgkmcnt(2)
	s_nop 0
	s_nop 0
	s_waitcnt lgkmcnt(0)
	s_nop 0
	s_nop 0
	s_nop 0
	s_nop 0
	s_nop 0
	v_cvt_pk_bf16_f32 v2, v8, v8
	v_cvt_pk_bf16_f32 v5, v24, v24
	v_cvt_pk_bf16_f32 v0, v0, v0
	v_cvt_pk_bf16_f32 v24, v25, v25
	v_cvt_pk_bf16_f32 v25, v27, v27
	v_cvt_pk_bf16_f32 v8, v9, v9
	v_cvt_pk_bf16_f32 v9, v26, v26
	v_cvt_pk_bf16_f32 v26, v1, v1
	v_lshrrev_b32_e32 v1, 16, v2
	v_and_b32_e32 v0, 0xffff0000, v0
	v_and_b32_e32 v2, 0xffff0000, v24
	v_lshrrev_b32_e32 v24, 16, v25
	v_and_or_b32 v5, v5, s23, v1
	v_or_b32_sdwa v1, v0, v9 dst_sel:DWORD dst_unused:UNUSED_PAD src0_sel:DWORD src1_sel:WORD_1
	v_or_b32_sdwa v0, v2, v8 dst_sel:DWORD dst_unused:UNUSED_PAD src0_sel:DWORD src1_sel:WORD_1
	v_and_or_b32 v2, v26, s23, v24
	v_lshl_add_u64 v[8:9], v[28:29], 0, v[6:7]
	global_store_dword v[8:9], v5, off

.LBB0_273:
	s_andn2_b64 vcc, exec, s[16:17]
	s_cbranch_vccnz .LBB0_266
	s_and_b32 s6, s26, 0xfffffe00
	s_cmpk_eq_i32 s6, 0x200
	s_cselect_b32 s6, s24, 0x68
	s_cselect_b32 s16, s25, 0xc0
	s_cmpk_lt_u32 s26, 0x200
	s_cselect_b32 s6, 40, s6
	s_cselect_b32 s16, 0xb0, s16
	s_add_u32 s28, s0, s6
	s_addc_u32 s29, s1, 0
	s_add_u32 s30, s0, s16
	s_addc_u32 s31, s1, 0
	s_load_dwordx2 s[34:35], s[28:29], 0x0
	s_load_dwordx2 s[16:17], s[30:31], 0x0
	s_and_b32 s6, s18, 0x3e0
	s_and_b32 s27, s20, 0x3c0
	v_or_b32_e32 v0, s6, v12
	v_or_b32_e32 v1, s27, v11
	v_lshlrev_b32_e32 v0, 2, v0
	v_lshl_or_b32 v1, v1, 12, v0
	v_or_b32_e32 v2, s27, v13
	v_or_b32_e32 v5, s27, v14
	v_or_b32_e32 v7, s27, v15
	v_or_b32_e32 v8, s27, v16
	v_add_u32_e32 v9, s27, v17
	v_add_u32_e32 v24, s27, v18
	v_add_u32_e32 v25, s27, v19
	s_waitcnt vmcnt(0) lgkmcnt(0)
	s_barrier
	v_lshl_or_b32 v2, v2, 12, v0
	v_lshl_or_b32 v5, v5, 12, v0
	v_lshl_or_b32 v7, v7, 12, v0
	v_lshl_or_b32 v8, v8, 12, v0
	v_lshl_or_b32 v9, v9, 12, v0
	v_lshl_or_b32 v24, v24, 12, v0
	v_lshl_or_b32 v0, v25, 12, v0
	global_load_dword v25, v1, s[34:35]
	global_load_dword v26, v2, s[34:35]
	global_load_dword v27, v5, s[34:35]
	global_load_dword v28, v7, s[34:35]
	global_load_dword v29, v8, s[34:35]
	global_load_dword v30, v9, s[34:35]
	global_load_dword v31, v24, s[34:35]
	global_load_dword v32, v0, s[34:35]
	v_add_lshl_u32 v2, s6, v10, 11
	s_lshl_b32 s6, s27, 1
	v_lshl_add_u64 v[0:1], s[16:17], 0, v[2:3]
	v_mov_b32_e32 v7, v3
	s_waitcnt vmcnt(7)
	ds_write_b32 v23, v25
	s_waitcnt vmcnt(6)
	ds_write_b32 v23, v26 offset:1056
	s_waitcnt vmcnt(5)
	ds_write_b32 v23, v27 offset:2112
	s_waitcnt vmcnt(4)
	ds_write_b32 v23, v28 offset:3168
	s_waitcnt vmcnt(3)
	ds_write_b32 v23, v29 offset:4224
	s_waitcnt vmcnt(2)
	ds_write_b32 v23, v30 offset:5280
	s_waitcnt vmcnt(1)
	ds_write_b32 v23, v31 offset:6336
	s_waitcnt vmcnt(0)
	ds_write_b32 v23, v32 offset:7392
	s_waitcnt lgkmcnt(0)
	s_barrier
	ds_read2_b32 v[8:9], v20 offset1:66
	ds_read2_b32 v[24:25], v21 offset0:33 offset1:99
	ds_read2_b32 v[26:27], v20 offset0:132 offset1:198
	v_lshl_add_u64 v[28:29], v[0:1], 0, s[6:7]
	ds_read2_b32 v[0:1], v21 offset0:165 offset1:231
	s_waitcnt lgkmcnt(3)
	s_nop 0
	s_waitcnt lgkmcnt(2)
	s_nop 0
	s_nop 0
	s_waitcnt lgkmcnt(1)
	s_nop 0
	s_waitcnt lgkmcnt(0)
	s_nop 0
	s_nop 0
	s_nop 0
	s_nop 0
	v_cvt_pk_bf16_f32 v2, v8, v8
	v_cvt_pk_bf16_f32 v5, v24, v24
	v_cvt_pk_bf16_f32 v0, v0, v0
	v_cvt_pk_bf16_f32 v24, v25, v25
	v_cvt_pk_bf16_f32 v25, v27, v27
	v_cvt_pk_bf16_f32 v8, v9, v9
	v_cvt_pk_bf16_f32 v9, v26, v26
	v_cvt_pk_bf16_f32 v26, v1, v1
	v_lshrrev_b32_e32 v1, 16, v2
	v_and_b32_e32 v0, 0xffff0000, v0
	v_and_b32_e32 v2, 0xffff0000, v24
	v_lshrrev_b32_e32 v24, 16, v25
	v_and_or_b32 v5, v5, s23, v1
	v_or_b32_sdwa v1, v0, v9 dst_sel:DWORD dst_unused:UNUSED_PAD src0_sel:DWORD src1_sel:WORD_1
	v_or_b32_sdwa v0, v2, v8 dst_sel:DWORD dst_unused:UNUSED_PAD src0_sel:DWORD src1_sel:WORD_1
	v_and_or_b32 v2, v26, s23, v24
	v_lshl_add_u64 v[8:9], v[28:29], 0, v[6:7]
	global_store_dword v[8:9], v5, off
	s_branch .LBB0_266

.LBB0_334:
	v_cndmask_b32_e64 v216, v216, 0, s[58:59]
	v_cndmask_b32_e64 v215, v215, 0, s[58:59]
	v_add_f32_e32 v70, v215, v70
	v_add_f32_e32 v71, v216, v71
	v_cndmask_b32_e64 v71, v216, v71, s[8:9]
	v_cndmask_b32_e64 v70, v215, v70, s[8:9]
	v_add_f32_e32 v64, v70, v64
	v_add_f32_e32 v65, v71, v65
	v_cndmask_b32_e64 v65, v71, v65, s[10:11]
	v_cndmask_b32_e64 v70, v70, v64, s[10:11]
	v_add_f32_e32 v66, v70, v66
	v_add_f32_e32 v64, v65, v67
	v_cndmask_b32_e64 v64, v65, v64, s[12:13]
	v_cndmask_b32_e64 v65, v70, v66, s[12:13]
	v_add_f32_e32 v66, v122, v65
	v_mul_f32_e32 v66, 0x3fb8aa3b, v66
	v_exp_f32_e32 v66, v66
	v_add_f32_e32 v67, v123, v64
	v_mul_f32_e32 v67, 0x3fb8aa3b, v67
	v_exp_f32_e32 v67, v67
	v_rcp_f32_e32 v70, v66
	v_add_f32_e32 v121, v121, v64
	v_mul_f32_e32 v121, 0x3fb8aa3b, v121
	v_rcp_f32_e32 v71, v67
	v_lshlrev_b32_e32 v122, 16, v214
	v_exp_f32_e32 v121, v121
	v_mul_f32_e32 v70, v70, v122
	v_lshlrev_b32_e32 v122, 16, v213
	v_mul_f32_e32 v66, v66, v122
	v_and_b32_e32 v122, 0xffff0000, v213
	v_and_b32_e32 v123, 0xffff0000, v214
	v_mul_f32_e32 v67, v67, v122
	s_nop 0
	v_add_f32_e32 v120, v120, v65
	v_mul_f32_e32 v71, v71, v123
	v_cvt_pk_bf16_f32 v66, v66, v66
	s_nop 0
	v_mul_f32_e32 v120, 0x3fb8aa3b, v120
	v_rcp_f32_e32 v123, v121
	v_lshrrev_b32_e32 v66, 16, v66
	v_cvt_pk_bf16_f32 v67, v67, v67
	v_exp_f32_e32 v120, v120
	v_and_or_b32 v66, v67, s63, v66
	s_nop 0
	v_cvt_pk_bf16_f32 v67, v70, v70
	s_nop 0
	v_lshlrev_b32_e32 v213, 16, v212
	v_and_b32_e32 v212, 0xffff0000, v212
	v_lshrrev_b32_e32 v67, 16, v67
	v_cvt_pk_bf16_f32 v122, v71, v71
	v_mul_f32_e32 v123, v123, v212
	v_lshlrev_b32_e32 v212, 16, v211
	v_and_or_b32 v67, v122, s63, v67
	v_rcp_f32_e32 v122, v120
	v_mul_f32_e32 v120, v120, v212
	v_and_b32_e32 v211, 0xffff0000, v211
	v_mul_f32_e32 v121, v121, v211
	s_nop 0
	v_cvt_pk_bf16_f32 v120, v120, v120
	s_nop 0
	v_lshrrev_b32_e32 v120, 16, v120
	v_cvt_pk_bf16_f32 v121, v121, v121
	v_mul_f32_e32 v122, v122, v213
	v_and_or_b32 v120, v121, s63, v120
	ds_write2_b32 v137, v66, v120 offset1:68
	s_nop 0
	v_cvt_pk_bf16_f32 v66, v122, v122
	s_nop 0
	v_lshrrev_b32_e32 v66, 16, v66
	v_cvt_pk_bf16_f32 v120, v123, v123
	v_mul_f32_e32 v70, v68, v70
	v_and_or_b32 v66, v120, s63, v66
	v_add_u32_e32 v120, 0x4400, v137
	ds_write2_b32 v120, v67, v66 offset1:68
	v_mul_f32_e32 v66, v68, v122
	s_nop 0
	v_cvt_pk_bf16_f32 v70, v70, v70
	s_nop 0
	v_mul_f32_e32 v67, v69, v123
	v_lshrrev_b32_e32 v70, 16, v70
	v_cvt_pk_bf16_f32 v66, v66, v66
	v_and_or_b32 v66, v66, s63, v70
	s_nop 0
	v_cvt_pk_bf16_f32 v67, v67, v67
	v_add_f32_e32 v70, v118, v65
	v_mul_f32_e32 v71, v69, v71
	v_mul_f32_e32 v70, 0x3fb8aa3b, v70
	ds_write_b32 v74, v66 offset:34816
	s_nop 0
	v_exp_f32_e32 v70, v70
	v_cvt_pk_bf16_f32 v66, v71, v71
	v_lshrrev_b32_e32 v66, 16, v66
	v_add_f32_e32 v71, v119, v64
	v_and_or_b32 v66, v67, s63, v66
	v_mul_f32_e32 v71, 0x3fb8aa3b, v71
	ds_write_b32 v74, v66 offset:34960
	v_rcp_f32_e32 v66, v70
	v_exp_f32_e32 v71, v71
	v_lshlrev_b32_e32 v118, 16, v210
	v_add_f32_e32 v116, v116, v65
	v_mul_f32_e32 v66, v66, v118
	v_lshlrev_b32_e32 v118, 16, v209
	v_rcp_f32_e32 v67, v71
	v_mul_f32_e32 v70, v70, v118
	v_and_b32_e32 v118, 0xffff0000, v209
	v_mul_f32_e32 v71, v71, v118
	s_nop 0
	v_cvt_pk_bf16_f32 v70, v70, v70
	s_nop 0
	v_mul_f32_e32 v116, 0x3fb8aa3b, v116
	v_and_b32_e32 v119, 0xffff0000, v210
	v_lshrrev_b32_e32 v70, 16, v70
	v_cvt_pk_bf16_f32 v71, v71, v71
	v_exp_f32_e32 v116, v116
	v_mul_f32_e32 v67, v67, v119
	v_and_or_b32 v70, v71, s63, v70
	s_nop 0
	v_cvt_pk_bf16_f32 v71, v66, v66
	s_nop 0
	v_lshrrev_b32_e32 v71, 16, v71
	v_cvt_pk_bf16_f32 v118, v67, v67
	v_and_or_b32 v71, v118, s63, v71
	v_add_f32_e32 v117, v117, v64
	v_rcp_f32_e32 v118, v116
	v_mul_f32_e32 v117, 0x3fb8aa3b, v117
	v_exp_f32_e32 v117, v117
	v_lshlrev_b32_e32 v121, 16, v208
	v_mul_f32_e32 v118, v118, v121
	v_lshlrev_b32_e32 v121, 16, v207
	v_mul_f32_e32 v116, v116, v121
	v_and_b32_e32 v121, 0xffff0000, v207
	v_rcp_f32_e32 v119, v117
	v_mul_f32_e32 v117, v117, v121
	s_nop 0
	v_cvt_pk_bf16_f32 v116, v116, v116
	s_nop 0
	v_lshrrev_b32_e32 v116, 16, v116
	v_cvt_pk_bf16_f32 v117, v117, v117
	v_and_b32_e32 v122, 0xffff0000, v208
	v_and_or_b32 v116, v117, s63, v116
	v_mul_f32_e32 v119, v119, v122
	ds_write2_b32 v137, v70, v116 offset0:136 offset1:204
	s_nop 0
	v_cvt_pk_bf16_f32 v70, v118, v118
	s_nop 0
	v_lshrrev_b32_e32 v70, 16, v70
	v_cvt_pk_bf16_f32 v116, v119, v119
	v_mul_f32_e32 v66, v68, v66
	v_and_or_b32 v70, v116, s63, v70
	ds_write2_b32 v120, v71, v70 offset0:136 offset1:204
	v_mul_f32_e32 v70, v68, v118
	s_nop 0
	v_cvt_pk_bf16_f32 v66, v66, v66
	s_nop 0
	v_lshrrev_b32_e32 v66, 16, v66
	v_cvt_pk_bf16_f32 v70, v70, v70
	v_and_or_b32 v66, v70, s63, v66
	v_add_f32_e32 v70, v114, v65
	v_mul_f32_e32 v67, v69, v67
	v_mul_f32_e32 v70, 0x3fb8aa3b, v70
	v_mul_f32_e32 v71, v69, v119
	ds_write_b32 v74, v66 offset:34820
	s_nop 0
	v_exp_f32_e32 v70, v70
	v_cvt_pk_bf16_f32 v66, v67, v67
	s_nop 0
	v_lshrrev_b32_e32 v66, 16, v66
	v_cvt_pk_bf16_f32 v67, v71, v71
	v_add_f32_e32 v71, v115, v64
	v_and_or_b32 v66, v67, s63, v66
	v_mul_f32_e32 v71, 0x3fb8aa3b, v71
	ds_write_b32 v74, v66 offset:34964
	v_rcp_f32_e32 v66, v70
	v_exp_f32_e32 v71, v71
	v_lshlrev_b32_e32 v114, 16, v206
	v_add_f32_e32 v112, v112, v65
	v_mul_f32_e32 v66, v66, v114
	v_lshlrev_b32_e32 v114, 16, v205
	v_rcp_f32_e32 v67, v71
	v_mul_f32_e32 v70, v70, v114
	v_and_b32_e32 v114, 0xffff0000, v205
	v_mul_f32_e32 v71, v71, v114
	s_nop 0
	v_cvt_pk_bf16_f32 v70, v70, v70
	s_nop 0
	v_mul_f32_e32 v112, 0x3fb8aa3b, v112
	v_and_b32_e32 v115, 0xffff0000, v206
	v_lshrrev_b32_e32 v70, 16, v70
	v_cvt_pk_bf16_f32 v71, v71, v71
	v_exp_f32_e32 v112, v112
	v_mul_f32_e32 v67, v67, v115
	v_and_or_b32 v70, v71, s63, v70
	s_nop 0
	v_cvt_pk_bf16_f32 v71, v66, v66
	s_nop 0
	v_lshrrev_b32_e32 v71, 16, v71
	v_cvt_pk_bf16_f32 v114, v67, v67
	v_and_or_b32 v71, v114, s63, v71
	v_add_f32_e32 v113, v113, v64
	v_rcp_f32_e32 v114, v112
	v_mul_f32_e32 v113, 0x3fb8aa3b, v113
	v_exp_f32_e32 v113, v113
	v_lshlrev_b32_e32 v116, 16, v204
	v_mul_f32_e32 v114, v114, v116
	v_lshlrev_b32_e32 v116, 16, v203
	v_mul_f32_e32 v112, v112, v116
	v_and_b32_e32 v116, 0xffff0000, v203
	v_rcp_f32_e32 v115, v113
	v_mul_f32_e32 v113, v113, v116
	s_nop 0
	v_cvt_pk_bf16_f32 v112, v112, v112
	s_nop 0
	v_lshrrev_b32_e32 v112, 16, v112
	v_cvt_pk_bf16_f32 v113, v113, v113
	v_and_b32_e32 v117, 0xffff0000, v204
	v_and_or_b32 v112, v113, s63, v112
	v_add_u32_e32 v113, 0x400, v137
	v_mul_f32_e32 v115, v115, v117
	ds_write2_b32 v113, v70, v112 offset0:16 offset1:84
	s_nop 0
	v_cvt_pk_bf16_f32 v70, v114, v114
	s_nop 0
	v_lshrrev_b32_e32 v70, 16, v70
	v_cvt_pk_bf16_f32 v112, v115, v115
	v_mul_f32_e32 v66, v68, v66
	v_and_or_b32 v70, v112, s63, v70
	v_add_u32_e32 v112, 0x4800, v137
	ds_write2_b32 v112, v71, v70 offset0:16 offset1:84
	v_mul_f32_e32 v70, v68, v114
	s_nop 0
	v_cvt_pk_bf16_f32 v66, v66, v66
	s_nop 0
	v_lshrrev_b32_e32 v66, 16, v66
	v_cvt_pk_bf16_f32 v70, v70, v70
	v_and_or_b32 v66, v70, s63, v66
	v_add_f32_e32 v70, v110, v65
	v_mul_f32_e32 v67, v69, v67
	v_mul_f32_e32 v70, 0x3fb8aa3b, v70
	v_mul_f32_e32 v71, v69, v115
	ds_write_b32 v74, v66 offset:34824
	s_nop 0
	v_exp_f32_e32 v70, v70
	v_cvt_pk_bf16_f32 v66, v67, v67
	s_nop 0
	v_lshrrev_b32_e32 v66, 16, v66
	v_cvt_pk_bf16_f32 v67, v71, v71
	v_add_f32_e32 v71, v111, v64
	v_and_or_b32 v66, v67, s63, v66
	v_mul_f32_e32 v71, 0x3fb8aa3b, v71
	ds_write_b32 v74, v66 offset:34968
	v_rcp_f32_e32 v66, v70
	v_exp_f32_e32 v71, v71
	v_lshlrev_b32_e32 v110, 16, v202
	v_add_f32_e32 v108, v108, v65
	v_mul_f32_e32 v66, v66, v110
	v_lshlrev_b32_e32 v110, 16, v201
	v_rcp_f32_e32 v67, v71
	v_mul_f32_e32 v70, v70, v110
	v_and_b32_e32 v110, 0xffff0000, v201
	v_mul_f32_e32 v71, v71, v110
	s_nop 0
	v_cvt_pk_bf16_f32 v70, v70, v70
	s_nop 0
	v_mul_f32_e32 v108, 0x3fb8aa3b, v108
	v_and_b32_e32 v111, 0xffff0000, v202
	v_lshrrev_b32_e32 v70, 16, v70
	v_cvt_pk_bf16_f32 v71, v71, v71
	v_exp_f32_e32 v108, v108
	v_mul_f32_e32 v67, v67, v111
	v_and_or_b32 v70, v71, s63, v70
	s_nop 0
	v_cvt_pk_bf16_f32 v71, v66, v66
	s_nop 0
	v_lshrrev_b32_e32 v71, 16, v71
	v_cvt_pk_bf16_f32 v110, v67, v67
	v_and_or_b32 v71, v110, s63, v71
	v_add_f32_e32 v109, v109, v64
	v_rcp_f32_e32 v110, v108
	v_mul_f32_e32 v109, 0x3fb8aa3b, v109
	v_exp_f32_e32 v109, v109
	v_lshlrev_b32_e32 v114, 16, v200
	v_mul_f32_e32 v110, v110, v114
	v_lshlrev_b32_e32 v114, 16, v199
	v_mul_f32_e32 v108, v108, v114
	v_and_b32_e32 v114, 0xffff0000, v199
	v_rcp_f32_e32 v111, v109
	v_mul_f32_e32 v109, v109, v114
	s_nop 0
	v_cvt_pk_bf16_f32 v108, v108, v108
	s_nop 0
	v_lshrrev_b32_e32 v108, 16, v108
	v_cvt_pk_bf16_f32 v109, v109, v109
	v_and_b32_e32 v115, 0xffff0000, v200
	v_and_or_b32 v108, v109, s63, v108
	v_mul_f32_e32 v111, v111, v115
	ds_write2_b32 v113, v70, v108 offset0:152 offset1:220
	s_nop 0
	v_cvt_pk_bf16_f32 v70, v110, v110
	s_nop 0
	v_lshrrev_b32_e32 v70, 16, v70
	v_cvt_pk_bf16_f32 v108, v111, v111
	v_mul_f32_e32 v66, v68, v66
	v_and_or_b32 v70, v108, s63, v70
	ds_write2_b32 v112, v71, v70 offset0:152 offset1:220
	v_mul_f32_e32 v70, v68, v110
	s_nop 0
	v_cvt_pk_bf16_f32 v66, v66, v66
	s_nop 0
	v_lshrrev_b32_e32 v66, 16, v66
	v_cvt_pk_bf16_f32 v70, v70, v70
	v_and_or_b32 v66, v70, s63, v66
	v_add_f32_e32 v70, v106, v65
	v_mul_f32_e32 v67, v69, v67
	v_mul_f32_e32 v70, 0x3fb8aa3b, v70
	v_mul_f32_e32 v71, v69, v111
	ds_write_b32 v74, v66 offset:34828
	s_nop 0
	v_exp_f32_e32 v70, v70
	v_cvt_pk_bf16_f32 v66, v67, v67
	s_nop 0
	v_lshrrev_b32_e32 v66, 16, v66
	v_cvt_pk_bf16_f32 v67, v71, v71
	v_add_f32_e32 v71, v107, v64
	v_and_or_b32 v66, v67, s63, v66
	v_mul_f32_e32 v71, 0x3fb8aa3b, v71
	ds_write_b32 v74, v66 offset:34972
	v_rcp_f32_e32 v66, v70
	v_exp_f32_e32 v71, v71
	v_lshlrev_b32_e32 v106, 16, v196
	v_add_f32_e32 v104, v104, v65
	v_mul_f32_e32 v66, v66, v106
	v_lshlrev_b32_e32 v106, 16, v195
	v_rcp_f32_e32 v67, v71
	v_mul_f32_e32 v70, v70, v106
	v_and_b32_e32 v106, 0xffff0000, v195
	v_mul_f32_e32 v71, v71, v106
	s_nop 0
	v_cvt_pk_bf16_f32 v70, v70, v70
	s_nop 0
	v_mul_f32_e32 v104, 0x3fb8aa3b, v104
	v_and_b32_e32 v107, 0xffff0000, v196
	v_lshrrev_b32_e32 v70, 16, v70
	v_cvt_pk_bf16_f32 v71, v71, v71
	v_exp_f32_e32 v104, v104
	v_mul_f32_e32 v67, v67, v107
	v_and_or_b32 v70, v71, s63, v70
	s_nop 0
	v_cvt_pk_bf16_f32 v71, v66, v66
	s_nop 0
	v_lshrrev_b32_e32 v71, 16, v71
	v_cvt_pk_bf16_f32 v106, v67, v67
	v_and_or_b32 v71, v106, s63, v71
	v_add_f32_e32 v105, v105, v64
	v_rcp_f32_e32 v106, v104
	v_mul_f32_e32 v105, 0x3fb8aa3b, v105
	v_exp_f32_e32 v105, v105
	v_lshlrev_b32_e32 v108, 16, v194
	v_mul_f32_e32 v106, v106, v108
	v_lshlrev_b32_e32 v108, 16, v193
	v_mul_f32_e32 v104, v104, v108
	v_and_b32_e32 v108, 0xffff0000, v193
	v_rcp_f32_e32 v107, v105
	v_mul_f32_e32 v105, v105, v108
	s_nop 0
	v_cvt_pk_bf16_f32 v104, v104, v104
	s_nop 0
	v_lshrrev_b32_e32 v104, 16, v104
	v_cvt_pk_bf16_f32 v105, v105, v105
	v_and_b32_e32 v109, 0xffff0000, v194
	v_and_or_b32 v104, v105, s63, v104
	v_add_u32_e32 v105, 0x800, v137
	v_mul_f32_e32 v107, v107, v109
	ds_write2_b32 v105, v70, v104 offset0:32 offset1:100
	s_nop 0
	v_cvt_pk_bf16_f32 v70, v106, v106
	s_nop 0
	v_lshrrev_b32_e32 v70, 16, v70
	v_cvt_pk_bf16_f32 v104, v107, v107
	v_mul_f32_e32 v66, v68, v66
	v_and_or_b32 v70, v104, s63, v70
	v_add_u32_e32 v104, 0x4c00, v137
	ds_write2_b32 v104, v71, v70 offset0:32 offset1:100
	v_mul_f32_e32 v70, v68, v106
	s_nop 0
	v_cvt_pk_bf16_f32 v66, v66, v66
	s_nop 0
	v_lshrrev_b32_e32 v66, 16, v66
	v_cvt_pk_bf16_f32 v70, v70, v70
	v_and_or_b32 v66, v70, s63, v66
	v_add_f32_e32 v70, v102, v65
	v_mul_f32_e32 v67, v69, v67
	v_mul_f32_e32 v70, 0x3fb8aa3b, v70
	v_mul_f32_e32 v71, v69, v107
	ds_write_b32 v74, v66 offset:34832
	s_nop 0
	v_exp_f32_e32 v70, v70
	v_cvt_pk_bf16_f32 v66, v67, v67
	s_nop 0
	v_lshrrev_b32_e32 v66, 16, v66
	v_cvt_pk_bf16_f32 v67, v71, v71
	v_add_f32_e32 v71, v103, v64
	v_and_or_b32 v66, v67, s63, v66
	v_mul_f32_e32 v71, 0x3fb8aa3b, v71
	ds_write_b32 v74, v66 offset:34976
	v_rcp_f32_e32 v66, v70
	v_exp_f32_e32 v71, v71
	v_lshlrev_b32_e32 v102, 16, v190
	v_add_f32_e32 v100, v100, v65
	v_mul_f32_e32 v66, v66, v102
	v_lshlrev_b32_e32 v102, 16, v189
	v_rcp_f32_e32 v67, v71
	v_mul_f32_e32 v70, v70, v102
	v_and_b32_e32 v102, 0xffff0000, v189
	v_mul_f32_e32 v71, v71, v102
	s_nop 0
	v_cvt_pk_bf16_f32 v70, v70, v70
	s_nop 0
	v_mul_f32_e32 v100, 0x3fb8aa3b, v100
	v_and_b32_e32 v103, 0xffff0000, v190
	v_lshrrev_b32_e32 v70, 16, v70
	v_cvt_pk_bf16_f32 v71, v71, v71
	v_exp_f32_e32 v100, v100
	v_mul_f32_e32 v67, v67, v103
	v_and_or_b32 v70, v71, s63, v70
	s_nop 0
	v_cvt_pk_bf16_f32 v71, v66, v66
	s_nop 0
	v_lshrrev_b32_e32 v71, 16, v71
	v_cvt_pk_bf16_f32 v102, v67, v67
	v_and_or_b32 v71, v102, s63, v71
	v_add_f32_e32 v101, v101, v64
	v_rcp_f32_e32 v102, v100
	v_mul_f32_e32 v101, 0x3fb8aa3b, v101
	v_exp_f32_e32 v101, v101
	s_waitcnt vmcnt(19)
	v_lshlrev_b32_e32 v106, 16, v198
	v_mul_f32_e32 v102, v102, v106
	s_waitcnt vmcnt(18)
	v_lshlrev_b32_e32 v106, 16, v197
	v_mul_f32_e32 v100, v100, v106
	v_and_b32_e32 v106, 0xffff0000, v197
	v_rcp_f32_e32 v103, v101
	v_mul_f32_e32 v101, v101, v106
	s_nop 0
	v_cvt_pk_bf16_f32 v100, v100, v100
	s_nop 0
	v_lshrrev_b32_e32 v100, 16, v100
	v_cvt_pk_bf16_f32 v101, v101, v101
	v_and_b32_e32 v107, 0xffff0000, v198
	v_and_or_b32 v100, v101, s63, v100
	v_mul_f32_e32 v103, v103, v107
	ds_write2_b32 v105, v70, v100 offset0:168 offset1:236
	s_nop 0
	v_cvt_pk_bf16_f32 v70, v102, v102
	s_nop 0
	v_lshrrev_b32_e32 v70, 16, v70
	v_cvt_pk_bf16_f32 v100, v103, v103
	v_mul_f32_e32 v66, v68, v66
	v_and_or_b32 v70, v100, s63, v70
	ds_write2_b32 v104, v71, v70 offset0:168 offset1:236
	v_mul_f32_e32 v70, v68, v102
	s_nop 0
	v_cvt_pk_bf16_f32 v66, v66, v66
	s_nop 0
	v_lshrrev_b32_e32 v66, 16, v66
	v_cvt_pk_bf16_f32 v70, v70, v70
	v_and_or_b32 v66, v70, s63, v66
	v_add_f32_e32 v70, v98, v65
	v_mul_f32_e32 v67, v69, v67
	v_mul_f32_e32 v70, 0x3fb8aa3b, v70
	v_mul_f32_e32 v71, v69, v103
	ds_write_b32 v74, v66 offset:34836
	s_nop 0
	v_exp_f32_e32 v70, v70
	v_cvt_pk_bf16_f32 v66, v67, v67
	s_nop 0
	v_lshrrev_b32_e32 v66, 16, v66
	v_cvt_pk_bf16_f32 v67, v71, v71
	v_add_f32_e32 v71, v99, v64
	v_and_or_b32 v66, v67, s63, v66
	v_mul_f32_e32 v71, 0x3fb8aa3b, v71
	ds_write_b32 v74, v66 offset:34980
	v_rcp_f32_e32 v66, v70
	v_exp_f32_e32 v71, v71
	s_waitcnt vmcnt(15)
	v_lshlrev_b32_e32 v98, 16, v192
	v_add_f32_e32 v96, v96, v65
	v_mul_f32_e32 v66, v66, v98
	s_waitcnt vmcnt(14)
	v_lshlrev_b32_e32 v98, 16, v191
	v_rcp_f32_e32 v67, v71
	v_mul_f32_e32 v70, v70, v98
	v_and_b32_e32 v98, 0xffff0000, v191
	v_mul_f32_e32 v71, v71, v98
	s_nop 0
	v_cvt_pk_bf16_f32 v70, v70, v70
	s_nop 0
	v_mul_f32_e32 v96, 0x3fb8aa3b, v96
	v_and_b32_e32 v99, 0xffff0000, v192
	v_lshrrev_b32_e32 v70, 16, v70
	v_cvt_pk_bf16_f32 v71, v71, v71
	v_exp_f32_e32 v96, v96
	v_mul_f32_e32 v67, v67, v99
	v_and_or_b32 v70, v71, s63, v70
	s_nop 0
	v_cvt_pk_bf16_f32 v71, v66, v66
	s_nop 0
	v_lshrrev_b32_e32 v71, 16, v71
	v_cvt_pk_bf16_f32 v98, v67, v67
	v_and_or_b32 v71, v98, s63, v71
	v_add_f32_e32 v97, v97, v64
	v_rcp_f32_e32 v98, v96
	v_mul_f32_e32 v97, 0x3fb8aa3b, v97
	v_exp_f32_e32 v97, v97
	s_waitcnt vmcnt(11)
	v_lshlrev_b32_e32 v100, 16, v188
	v_mul_f32_e32 v98, v98, v100
	s_waitcnt vmcnt(10)
	v_lshlrev_b32_e32 v100, 16, v187
	v_mul_f32_e32 v96, v96, v100
	v_and_b32_e32 v100, 0xffff0000, v187
	v_rcp_f32_e32 v99, v97
	v_mul_f32_e32 v97, v97, v100
	s_nop 0
	v_cvt_pk_bf16_f32 v96, v96, v96
	s_nop 0
	v_lshrrev_b32_e32 v96, 16, v96
	v_cvt_pk_bf16_f32 v97, v97, v97
	v_and_b32_e32 v101, 0xffff0000, v188
	v_and_or_b32 v96, v97, s63, v96
	v_add_u32_e32 v97, 0xc00, v137
	v_mul_f32_e32 v99, v99, v101
	ds_write2_b32 v97, v70, v96 offset0:48 offset1:116
	s_nop 0
	v_cvt_pk_bf16_f32 v70, v98, v98
	s_nop 0
	v_lshrrev_b32_e32 v70, 16, v70
	v_cvt_pk_bf16_f32 v96, v99, v99
	v_mul_f32_e32 v66, v68, v66
	v_and_or_b32 v70, v96, s63, v70
	v_add_u32_e32 v96, 0x5000, v137
	ds_write2_b32 v96, v71, v70 offset0:48 offset1:116
	v_mul_f32_e32 v70, v68, v98
	s_nop 0
	v_cvt_pk_bf16_f32 v66, v66, v66
	s_nop 0
	v_lshrrev_b32_e32 v66, 16, v66
	v_cvt_pk_bf16_f32 v70, v70, v70
	v_and_or_b32 v66, v70, s63, v66
	v_add_f32_e32 v70, v94, v65
	v_mul_f32_e32 v67, v69, v67
	v_mul_f32_e32 v70, 0x3fb8aa3b, v70
	v_mul_f32_e32 v71, v69, v99
	ds_write_b32 v74, v66 offset:34840
	s_nop 0
	v_exp_f32_e32 v70, v70
	v_cvt_pk_bf16_f32 v66, v67, v67
	s_nop 0
	v_lshrrev_b32_e32 v66, 16, v66
	v_cvt_pk_bf16_f32 v67, v71, v71
	v_add_f32_e32 v71, v95, v64
	v_and_or_b32 v66, v67, s63, v66
	v_mul_f32_e32 v71, 0x3fb8aa3b, v71
	ds_write_b32 v74, v66 offset:34984
	v_rcp_f32_e32 v66, v70
	v_exp_f32_e32 v71, v71
	s_waitcnt vmcnt(7)
	v_lshlrev_b32_e32 v94, 16, v186
	v_add_f32_e32 v65, v92, v65
	v_mul_f32_e32 v66, v66, v94
	s_waitcnt vmcnt(6)
	v_lshlrev_b32_e32 v94, 16, v185
	v_mul_f32_e32 v65, 0x3fb8aa3b, v65
	v_rcp_f32_e32 v67, v71
	v_mul_f32_e32 v70, v70, v94
	v_and_b32_e32 v94, 0xffff0000, v185
	v_exp_f32_e32 v65, v65
	v_mul_f32_e32 v71, v71, v94
	s_nop 0
	v_cvt_pk_bf16_f32 v70, v70, v70
	s_nop 0
	v_and_b32_e32 v95, 0xffff0000, v186
	v_lshrrev_b32_e32 v70, 16, v70
	v_cvt_pk_bf16_f32 v71, v71, v71
	v_mul_f32_e32 v67, v67, v95
	v_and_or_b32 v70, v71, s63, v70
	s_nop 0
	v_add_f32_e32 v64, v93, v64
	v_rcp_f32_e32 v92, v65
	v_cvt_pk_bf16_f32 v71, v66, v66
	s_nop 0
	v_mul_f32_e32 v64, 0x3fb8aa3b, v64
	v_lshrrev_b32_e32 v71, 16, v71
	v_cvt_pk_bf16_f32 v94, v67, v67
	v_exp_f32_e32 v64, v64
	v_and_or_b32 v71, v94, s63, v71
	s_waitcnt vmcnt(3)
	v_lshlrev_b32_e32 v94, 16, v184
	v_mul_f32_e32 v92, v92, v94
	s_waitcnt vmcnt(2)
	v_lshlrev_b32_e32 v94, 16, v183
	v_mul_f32_e32 v65, v65, v94
	v_and_b32_e32 v94, 0xffff0000, v183
	v_rcp_f32_e32 v93, v64
	v_mul_f32_e32 v64, v64, v94
	s_nop 0
	v_cvt_pk_bf16_f32 v65, v65, v65
	s_nop 0
	v_lshrrev_b32_e32 v65, 16, v65
	v_cvt_pk_bf16_f32 v64, v64, v64
	v_and_b32_e32 v95, 0xffff0000, v184
	v_and_or_b32 v64, v64, s63, v65
	v_mul_f32_e32 v93, v93, v95
	ds_write2_b32 v97, v70, v64 offset0:184 offset1:252
	s_nop 0
	v_cvt_pk_bf16_f32 v64, v92, v92
	s_nop 0
	v_lshrrev_b32_e32 v64, 16, v64
	v_cvt_pk_bf16_f32 v65, v93, v93
	v_mul_f32_e32 v66, v68, v66
	v_and_or_b32 v64, v65, s63, v64
	ds_write2_b32 v96, v71, v64 offset0:184 offset1:252
	v_mul_f32_e32 v64, v68, v92
	s_nop 0
	v_cvt_pk_bf16_f32 v66, v66, v66
	s_nop 0
	v_lshrrev_b32_e32 v66, 16, v66
	v_cvt_pk_bf16_f32 v64, v64, v64
	v_mul_f32_e32 v67, v69, v67
	v_and_or_b32 v64, v64, s63, v66
	v_mul_f32_e32 v65, v69, v93
	ds_write_b32 v74, v64 offset:34844
	s_nop 0
	v_cvt_pk_bf16_f32 v64, v67, v67
	s_nop 0
	v_lshrrev_b32_e32 v64, 16, v64
	v_cvt_pk_bf16_f32 v65, v65, v65
	v_and_or_b32 v64, v65, s63, v64
	v_add_u32_e32 v104, s71, v131
	ds_write_b32 v74, v64 offset:34988
	s_waitcnt lgkmcnt(0)
	s_barrier
	ds_read_b128 v[64:67], v104
	ds_read_b128 v[68:71], v135 offset:17408
	ds_read_b128 v[92:95], v104 offset:64
	ds_read_b128 v[96:99], v135 offset:17472
	ds_read_b128 v[106:109], v135 offset:21760
	ds_read_b128 v[110:113], v135 offset:21824
	s_waitcnt lgkmcnt(4)
	v_mfma_f32_16x16x32_bf16 v[100:103], v[64:67], v[68:71], 0
	ds_read_b128 v[114:117], v104 offset:4352
	ds_read_b128 v[118:121], v104 offset:4416
	v_add_u32_e32 v105, s69, v130
	v_add_u32_e32 v201, s70, v130
	s_waitcnt lgkmcnt(3)
	v_mfma_f32_16x16x32_bf16 v[64:67], v[64:67], v[106:109], 0
	s_sub_i32 s73, s73, 64
	v_mfma_f32_16x16x32_bf16 v[100:103], v[92:95], v[96:99], v[100:103]
	s_waitcnt lgkmcnt(2)
	v_mfma_f32_16x16x32_bf16 v[64:67], v[92:95], v[110:113], v[64:67]
	ds_read_b128 v[92:95], v104 offset:128
	s_waitcnt lgkmcnt(2)
	v_mfma_f32_16x16x32_bf16 v[68:71], v[114:117], v[68:71], 0
	v_mfma_f32_16x16x32_bf16 v[106:109], v[114:117], v[106:109], 0
	s_waitcnt lgkmcnt(1)
	v_mfma_f32_16x16x32_bf16 v[68:71], v[118:121], v[96:99], v[68:71]
	v_mfma_f32_16x16x32_bf16 v[96:99], v[118:121], v[110:113], v[106:109]
	s_nop 4
	ds_read_b128 v[106:109], v135 offset:17536
	ds_read_b128 v[110:113], v104 offset:192
	ds_read_b128 v[114:117], v135 offset:17600
	ds_read_b128 v[118:121], v135 offset:21888
	ds_read_b128 v[184:187], v135 offset:21952
	s_waitcnt lgkmcnt(4)
	v_mfma_f32_16x16x32_bf16 v[100:103], v[92:95], v[106:109], v[100:103]
	s_waitcnt lgkmcnt(1)
	v_mfma_f32_16x16x32_bf16 v[64:67], v[92:95], v[118:121], v[64:67]
	ds_read_b128 v[92:95], v104 offset:4480
	ds_read_b128 v[188:191], v104 offset:4544
	s_waitcnt lgkmcnt(0)
	s_barrier
	v_mfma_f32_16x16x32_bf16 v[68:71], v[92:95], v[106:109], v[68:71]
	v_add_u32_e32 v106, v134, v138
	v_add_u32_e32 v107, s74, v139
	v_mfma_f32_16x16x32_bf16 v[92:95], v[92:95], v[118:121], v[96:99]
	v_add_u32_e32 v199, 18, v107
	s_add_i32 s74, s74, 64
	s_cmpk_lg_i32 s74, 0x200
	v_mfma_f32_16x16x32_bf16 v[96:99], v[110:113], v[114:117], v[100:103]
	v_mfma_f32_16x16x32_bf16 v[64:67], v[110:113], v[184:187], v[64:67]
	v_mfma_f32_16x16x32_bf16 v[68:71], v[188:191], v[114:117], v[68:71]
	s_nop 5
	s_nop 0
	v_cvt_pk_bf16_f32 v96, v96, v96
	v_lshrrev_b32_e32 v96, 16, v96
	v_cndmask_b32_e64 v96, v96, 0, s[14:15]
	ds_write_b16 v141, v96 offset:17408
	s_nop 0
	v_cvt_pk_bf16_f32 v96, v97, v97
	v_lshrrev_b32_e32 v96, 16, v96
	v_cndmask_b32_e64 v96, v96, 0, s[16:17]
	ds_write_b16 v141, v96 offset:17552
	s_nop 0
	v_cvt_pk_bf16_f32 v96, v98, v98
	v_lshrrev_b32_e32 v96, 16, v96
	v_cndmask_b32_e64 v96, v96, 0, s[18:19]
	ds_write_b16 v141, v96 offset:17696
	s_nop 0
	v_cvt_pk_bf16_f32 v96, v99, v99
	v_lshrrev_b32_e32 v96, 16, v96
	v_cndmask_b32_e64 v96, v96, 0, s[20:21]
	ds_write_b16 v141, v96 offset:17840
	s_nop 0
	v_cvt_pk_bf16_f32 v64, v64, v64
	v_lshrrev_b32_e32 v64, 16, v64
	v_cndmask_b32_e64 v64, v64, 0, s[22:23]
	ds_write_b16 v141, v64 offset:17440
	s_nop 0
	v_cvt_pk_bf16_f32 v64, v65, v65
	v_lshrrev_b32_e32 v64, 16, v64
	v_cndmask_b32_e64 v64, v64, 0, s[24:25]
	ds_write_b16 v141, v64 offset:17584
	s_nop 0
	v_cvt_pk_bf16_f32 v64, v66, v66
	v_lshrrev_b32_e32 v64, 16, v64
	v_cndmask_b32_e64 v64, v64, 0, s[26:27]
	ds_write_b16 v141, v64 offset:17728
	s_nop 0
	v_cvt_pk_bf16_f32 v64, v67, v67
	v_lshrrev_b32_e32 v64, 16, v64
	v_cndmask_b32_e64 v64, v64, 0, s[28:29]
	ds_write_b16 v141, v64 offset:17872
	s_nop 0
	v_cvt_pk_bf16_f32 v64, v68, v68
	v_lshrrev_b32_e32 v64, 16, v64
	v_cndmask_b32_e64 v64, v64, 0, s[30:31]
	ds_write_b16 v141, v64 offset:19712
	s_nop 0
	v_cvt_pk_bf16_f32 v64, v69, v69
	v_lshrrev_b32_e32 v64, 16, v64
	v_cndmask_b32_e64 v64, v64, 0, s[34:35]
	ds_write_b16 v141, v64 offset:19856
	s_nop 0
	v_cvt_pk_bf16_f32 v64, v70, v70
	v_lshrrev_b32_e32 v64, 16, v64
	v_cndmask_b32_e64 v64, v64, 0, s[36:37]
	v_mfma_f32_16x16x32_bf16 v[92:95], v[188:191], v[184:187], v[92:95]
	ds_write_b16 v141, v64 offset:20000
	s_nop 0
	v_cvt_pk_bf16_f32 v64, v71, v71
	v_lshrrev_b32_e32 v64, 16, v64
	v_cndmask_b32_e64 v64, v64, 0, s[38:39]
	ds_write_b16 v141, v64 offset:20144
	s_nop 1
	s_nop 0
	v_cvt_pk_bf16_f32 v64, v92, v92
	v_lshrrev_b32_e32 v64, 16, v64
	v_cndmask_b32_e64 v64, v64, 0, s[14:15]
	ds_write_b16 v141, v64 offset:19744
	s_nop 0
	v_cvt_pk_bf16_f32 v64, v93, v93
	v_lshrrev_b32_e32 v64, 16, v64
	v_cndmask_b32_e64 v64, v64, 0, s[40:41]
	ds_write_b16 v141, v64 offset:19888
	s_nop 0
	v_cvt_pk_bf16_f32 v64, v94, v94
	v_lshrrev_b32_e32 v64, 16, v64
	v_cndmask_b32_e64 v64, v64, 0, s[42:43]
	ds_write_b16 v141, v64 offset:20032
	s_nop 0
	v_cvt_pk_bf16_f32 v64, v95, v95
	v_lshrrev_b32_e32 v64, 16, v64
	v_cndmask_b32_e64 v64, v64, 0, s[44:45]
	ds_write_b16 v141, v64 offset:20176
	s_nop 0
	v_cvt_pk_bf16_f32 v64, v24, v24
	ds_write_b16_d16_hi v106, v64 offset:62464
	s_nop 0
	v_cvt_pk_bf16_f32 v64, v25, v25
	ds_write_b16_d16_hi v106, v64 offset:62736
	s_nop 0
	v_cvt_pk_bf16_f32 v64, v26, v26
	ds_write_b16_d16_hi v106, v64 offset:63008
	s_nop 0
	v_cvt_pk_bf16_f32 v64, v27, v27
	ds_write_b16_d16_hi v106, v64 offset:63280
	s_nop 0
	v_cvt_pk_bf16_f32 v64, v4, v4
	ds_write_b16_d16_hi v106, v64 offset:62496
	s_nop 0
	v_cvt_pk_bf16_f32 v64, v5, v5
	ds_write_b16_d16_hi v106, v64 offset:62768
	s_nop 0
	v_cvt_pk_bf16_f32 v64, v6, v6
	ds_write_b16_d16_hi v106, v64 offset:63040
	s_nop 0
	v_cvt_pk_bf16_f32 v64, v7, v7
	ds_write_b16_d16_hi v106, v64 offset:63312
	s_nop 0
	v_cvt_pk_bf16_f32 v64, v8, v8
	ds_write_b16_d16_hi v106, v64 offset:62528
	s_nop 0
	v_cvt_pk_bf16_f32 v64, v9, v9
	ds_write_b16_d16_hi v106, v64 offset:62800
	s_nop 0
	v_cvt_pk_bf16_f32 v64, v10, v10
	ds_write_b16_d16_hi v106, v64 offset:63072
	s_nop 0
	v_cvt_pk_bf16_f32 v64, v11, v11
	ds_write_b16_d16_hi v106, v64 offset:63344
	s_nop 0
	v_cvt_pk_bf16_f32 v64, v0, v0
	ds_write_b16_d16_hi v106, v64 offset:62560
	s_nop 0
	v_cvt_pk_bf16_f32 v64, v1, v1
	ds_write_b16_d16_hi v106, v64 offset:62832
	s_nop 0
	v_cvt_pk_bf16_f32 v64, v2, v2
	ds_write_b16_d16_hi v106, v64 offset:63104
	s_nop 0
	v_cvt_pk_bf16_f32 v64, v3, v3
	ds_write_b16_d16_hi v106, v64 offset:63376
	s_nop 0
	v_cvt_pk_bf16_f32 v64, v12, v12
	ds_write_b16_d16_hi v142, v64 offset:62464
	s_nop 0
	v_cvt_pk_bf16_f32 v64, v13, v13
	ds_write_b16_d16_hi v143, v64 offset:62464
	s_nop 0
	v_cvt_pk_bf16_f32 v64, v14, v14
	ds_write_b16_d16_hi v145, v64 offset:62464
	s_nop 0
	v_cvt_pk_bf16_f32 v64, v15, v15
	ds_write_b16_d16_hi v146, v64 offset:62464
	s_nop 0
	v_cvt_pk_bf16_f32 v64, v16, v16
	ds_write_b16_d16_hi v142, v64 offset:62496
	s_nop 0
	v_cvt_pk_bf16_f32 v64, v17, v17
	ds_write_b16_d16_hi v143, v64 offset:62496
	s_nop 0
	v_cvt_pk_bf16_f32 v64, v18, v18
	ds_write_b16_d16_hi v145, v64 offset:62496
	s_nop 0
	v_cvt_pk_bf16_f32 v64, v19, v19
	ds_write_b16_d16_hi v146, v64 offset:62496
	s_nop 0
	v_cvt_pk_bf16_f32 v64, v20, v20
	ds_write_b16_d16_hi v142, v64 offset:62528
	s_nop 0
	v_cvt_pk_bf16_f32 v64, v21, v21
	ds_write_b16_d16_hi v143, v64 offset:62528
	s_nop 0
	v_cvt_pk_bf16_f32 v64, v22, v22
	ds_write_b16_d16_hi v145, v64 offset:62528
	s_nop 0
	v_cvt_pk_bf16_f32 v64, v23, v23
	ds_write_b16_d16_hi v146, v64 offset:62528
	s_nop 0
	v_cvt_pk_bf16_f32 v64, v40, v40
	ds_write_b16_d16_hi v142, v64 offset:62560
	s_nop 0
	v_cvt_pk_bf16_f32 v64, v41, v41
	ds_write_b16_d16_hi v143, v64 offset:62560
	s_nop 0
	v_cvt_pk_bf16_f32 v64, v42, v42
	ds_write_b16_d16_hi v145, v64 offset:62560
	s_nop 0
	v_cvt_pk_bf16_f32 v64, v43, v43
	ds_write_b16_d16_hi v146, v64 offset:62560
	v_lshlrev_b32_e32 v64, 16, v166
	v_lshlrev_b32_e32 v65, 16, v170
	v_lshlrev_b32_e32 v66, 16, v172
	v_lshlrev_b32_e32 v67, 16, v174
	v_lshlrev_b32_e32 v68, 16, v176
	v_lshlrev_b32_e32 v69, 16, v178
	v_lshlrev_b32_e32 v70, 16, v180
	s_waitcnt vmcnt(1)
	v_lshlrev_b32_e32 v71, 16, v182
	v_or_b32_sdwa v64, v64, v165 dst_sel:DWORD dst_unused:UNUSED_PAD src0_sel:DWORD src1_sel:WORD_0
	v_or_b32_sdwa v65, v65, v167 dst_sel:DWORD dst_unused:UNUSED_PAD src0_sel:DWORD src1_sel:WORD_0
	v_or_b32_sdwa v66, v66, v171 dst_sel:DWORD dst_unused:UNUSED_PAD src0_sel:DWORD src1_sel:WORD_0
	v_or_b32_sdwa v67, v67, v173 dst_sel:DWORD dst_unused:UNUSED_PAD src0_sel:DWORD src1_sel:WORD_0
	v_or_b32_sdwa v68, v68, v175 dst_sel:DWORD dst_unused:UNUSED_PAD src0_sel:DWORD src1_sel:WORD_0
	v_or_b32_sdwa v69, v69, v177 dst_sel:DWORD dst_unused:UNUSED_PAD src0_sel:DWORD src1_sel:WORD_0
	v_or_b32_sdwa v70, v70, v179 dst_sel:DWORD dst_unused:UNUSED_PAD src0_sel:DWORD src1_sel:WORD_0
	v_or_b32_sdwa v71, v71, v181 dst_sel:DWORD dst_unused:UNUSED_PAD src0_sel:DWORD src1_sel:WORD_0
	ds_write_b128 v147, v[64:67] offset:53248
	ds_write_b128 v147, v[68:71] offset:53264
	s_waitcnt lgkmcnt(0)
	s_barrier
	ds_read_b128 v[64:67], v104
	ds_read_b128 v[68:71], v135 offset:62464
	ds_read_b128 v[92:95], v104 offset:64
	ds_read_b128 v[96:99], v135 offset:62528
	ds_read_b128 v[108:111], v136 offset:4352
	ds_read_b128 v[112:115], v136 offset:4416
	s_waitcnt lgkmcnt(4)
	v_mfma_f32_16x16x32_bf16 v[100:103], v[64:67], v[68:71], 0
	ds_read_b128 v[116:119], v104 offset:4352
	ds_read_b128 v[120:123], v104 offset:4416
	v_add_u32_e32 v167, s72, v130
	v_add_u32_e32 v165, s66, v140
	s_waitcnt lgkmcnt(3)
	v_mfma_f32_16x16x32_bf16 v[64:67], v[64:67], v[108:111], 0
	v_add_u32_e32 v200, 0x1fed, v165
	v_subrev_u32_e32 v140, 64, v140
	v_mfma_f32_16x16x32_bf16 v[100:103], v[92:95], v[96:99], v[100:103]
	s_waitcnt lgkmcnt(2)
	v_mfma_f32_16x16x32_bf16 v[64:67], v[92:95], v[112:115], v[64:67]
	ds_read_b128 v[92:95], v104 offset:128
	s_waitcnt lgkmcnt(2)
	v_mfma_f32_16x16x32_bf16 v[68:71], v[116:119], v[68:71], 0
	v_mfma_f32_16x16x32_bf16 v[108:111], v[116:119], v[108:111], 0
	s_waitcnt lgkmcnt(1)
	v_mfma_f32_16x16x32_bf16 v[68:71], v[120:123], v[96:99], v[68:71]
	v_mfma_f32_16x16x32_bf16 v[96:99], v[120:123], v[112:115], v[108:111]
	s_nop 4
	ds_read_b128 v[108:111], v135 offset:62592
	ds_read_b128 v[112:115], v104 offset:192
	ds_read_b128 v[116:119], v135 offset:62656
	ds_read_b128 v[120:123], v136 offset:4480
	ds_read_b128 v[170:173], v136 offset:4544
	s_waitcnt lgkmcnt(4)
	v_mfma_f32_16x16x32_bf16 v[100:103], v[92:95], v[108:111], v[100:103]
	s_waitcnt lgkmcnt(1)
	v_mfma_f32_16x16x32_bf16 v[64:67], v[92:95], v[120:123], v[64:67]
	ds_read_b128 v[92:95], v104 offset:4480
	ds_read_b128 v[174:177], v104 offset:4544
	s_waitcnt lgkmcnt(1)
	v_mfma_f32_16x16x32_bf16 v[68:71], v[92:95], v[108:111], v[68:71]
	v_mfma_f32_16x16x32_bf16 v[92:95], v[92:95], v[120:123], v[96:99]
	v_mfma_f32_16x16x32_bf16 v[96:99], v[112:115], v[116:119], v[100:103]
	s_nop 2
	ds_read_b128 v[100:103], v105 offset:17408
	v_mfma_f32_16x16x32_bf16 v[64:67], v[112:115], v[170:173], v[64:67]
	s_waitcnt lgkmcnt(1)
	v_mfma_f32_16x16x32_bf16 v[68:71], v[174:177], v[116:119], v[68:71]
	ds_read_b128 v[108:111], v167 offset:53248
	ds_read_b128 v[112:115], v105 offset:17472
	ds_read_b128 v[116:119], v167 offset:53312
	v_mfma_f32_16x16x32_bf16 v[92:95], v[174:177], v[170:173], v[92:95]
	ds_read_b128 v[120:123], v167 offset:55552
	ds_read_b128 v[170:173], v167 offset:55616
	s_waitcnt lgkmcnt(4)
	v_mfma_f32_16x16x32_bf16 v[96:99], v[100:103], v[108:111], v[96:99]
	s_waitcnt lgkmcnt(1)
	v_mfma_f32_16x16x32_bf16 v[64:67], v[100:103], v[120:123], v[64:67]
	ds_read_b128 v[100:103], v105 offset:19712
	ds_read_b128 v[174:177], v105 offset:19776
	s_waitcnt lgkmcnt(1)
	v_mfma_f32_16x16x32_bf16 v[92:95], v[100:103], v[120:123], v[92:95]
	v_mfma_f32_16x16x32_bf16 v[68:71], v[100:103], v[108:111], v[68:71]
	v_mfma_f32_16x16x32_bf16 v[108:111], v[112:115], v[116:119], v[96:99]
	v_mfma_f32_16x16x32_bf16 v[112:115], v[112:115], v[170:173], v[64:67]
	s_waitcnt lgkmcnt(0)
	v_mfma_f32_16x16x32_bf16 v[64:67], v[174:177], v[170:173], v[92:95]
	s_nop 2
	v_add_u32_e32 v92, 0x1fff, v165
	v_cndmask_b32_e64 v92, v92, v107, s[6:7]
	v_add_u32_e32 v92, s67, v92
	v_ashrrev_i32_e32 v93, 31, v92
	v_lshlrev_b64 v[92:93], 11, v[92:93]
	v_lshl_add_u64 v[100:101], v[88:89], 0, v[92:93]
	s_nop 0
	v_cvt_pk_bf16_f32 v92, v108, v108
	global_store_short_d16_hi v[100:101], v92, off
	s_nop 0
	v_cvt_pk_bf16_f32 v92, v112, v112
	global_store_short_d16_hi v[100:101], v92, off offset:32
	v_add_u32_e32 v92, 1, v107
	v_add_u32_e32 v93, 0x1ffe, v165
	v_cndmask_b32_e64 v92, v93, v92, s[6:7]
	v_add_u32_e32 v92, s67, v92
	v_ashrrev_i32_e32 v93, 31, v92
	v_lshlrev_b64 v[92:93], 11, v[92:93]
	v_lshl_add_u64 v[102:103], v[88:89], 0, v[92:93]
	s_nop 0
	v_cvt_pk_bf16_f32 v92, v109, v109
	global_store_short_d16_hi v[102:103], v92, off
	s_nop 0
	v_cvt_pk_bf16_f32 v92, v113, v113
	global_store_short_d16_hi v[102:103], v92, off offset:32
	v_add_u32_e32 v92, 2, v107
	v_add_u32_e32 v93, 0x1ffd, v165
	v_cndmask_b32_e64 v92, v93, v92, s[6:7]
	v_add_u32_e32 v92, s67, v92
	v_ashrrev_i32_e32 v93, 31, v92
	v_lshlrev_b64 v[92:93], 11, v[92:93]
	v_lshl_add_u64 v[98:99], v[88:89], 0, v[92:93]
	s_nop 0
	v_cvt_pk_bf16_f32 v92, v110, v110
	global_store_short_d16_hi v[98:99], v92, off
	s_nop 0
	v_cvt_pk_bf16_f32 v92, v114, v114
	global_store_short_d16_hi v[98:99], v92, off offset:32
	v_add_u32_e32 v92, 3, v107
	v_add_u32_e32 v93, 0x1ffc, v165
	v_cndmask_b32_e64 v92, v93, v92, s[6:7]
	v_add_u32_e32 v92, s67, v92
	v_ashrrev_i32_e32 v93, 31, v92
	v_lshlrev_b64 v[92:93], 11, v[92:93]
	s_nop 0
	v_lshl_add_u64 v[92:93], v[88:89], 0, v[92:93]
	v_cvt_pk_bf16_f32 v94, v111, v111
	global_store_short_d16_hi v[92:93], v94, off
	s_nop 0
	v_cvt_pk_bf16_f32 v94, v115, v115
	v_mfma_f32_16x16x32_bf16 v[68:71], v[174:177], v[116:119], v[68:71]
	global_store_short_d16_hi v[92:93], v94, off offset:32
	v_add_u32_e32 v94, 16, v107
	v_add_u32_e32 v95, 0x1fef, v165
	v_cndmask_b32_e64 v94, v95, v94, s[6:7]
	v_add_u32_e32 v94, s67, v94
	v_ashrrev_i32_e32 v95, 31, v94
	v_lshlrev_b64 v[94:95], 11, v[94:95]
	s_nop 0
	s_nop 0
	v_lshl_add_u64 v[94:95], v[88:89], 0, v[94:95]
	v_cvt_pk_bf16_f32 v68, v68, v68
	global_store_short_d16_hi v[94:95], v68, off
	s_nop 0
	v_cvt_pk_bf16_f32 v64, v64, v64
	global_store_short_d16_hi v[94:95], v64, off offset:32
	v_add_u32_e32 v64, 17, v107
	v_add_u32_e32 v68, 0x1fee, v165
	v_cndmask_b32_e64 v64, v68, v64, s[6:7]
	v_add_u32_e32 v96, s67, v64
	v_ashrrev_i32_e32 v97, 31, v96
	v_lshlrev_b64 v[96:97], 11, v[96:97]
	s_nop 0
	v_lshl_add_u64 v[96:97], v[88:89], 0, v[96:97]
	v_cvt_pk_bf16_f32 v64, v69, v69
	ds_read2_b32 v[68:69], v148 offset1:16
	global_store_short_d16_hi v[96:97], v64, off
	s_nop 0
	v_cvt_pk_bf16_f32 v64, v65, v65
	global_store_short_d16_hi v[96:97], v64, off offset:32
	ds_read2_b32 v[64:65], v148 offset0:32 offset1:48
	s_waitcnt lgkmcnt(1)
	v_pk_mul_f32 v[26:27], v[26:27], v[68:69] op_sel_hi:[1,0]
	v_pk_mul_f32 v[24:25], v[24:25], v[68:69] op_sel_hi:[1,0]
	v_pk_mul_f32 v[14:15], v[14:15], v[68:69] op_sel_hi:[1,0]
	v_pk_mul_f32 v[12:13], v[12:13], v[68:69] op_sel_hi:[1,0]
	v_cndmask_b32_e64 v68, v200, v199, s[6:7]
	v_add_u32_e32 v68, s67, v68
	v_mov_b32_e32 v166, v69
	v_ashrrev_i32_e32 v69, 31, v68
	s_waitcnt lgkmcnt(0)
	v_pk_mul_f32 v[10:11], v[10:11], v[64:65] op_sel_hi:[1,0]
	v_pk_mul_f32 v[8:9], v[8:9], v[64:65] op_sel_hi:[1,0]
	v_mov_b32_e32 v198, v65
	v_pk_mul_f32 v[22:23], v[22:23], v[64:65] op_sel_hi:[1,0]
	v_pk_mul_f32 v[20:21], v[20:21], v[64:65] op_sel_hi:[1,0]
	v_lshlrev_b64 v[64:65], 11, v[68:69]
	s_nop 0
	v_lshl_add_u64 v[64:65], v[88:89], 0, v[64:65]
	v_cvt_pk_bf16_f32 v68, v70, v70
	ds_read_b128 v[108:111], v105 offset:53248
	ds_read_b128 v[112:115], v201 offset:34816
	ds_read_b128 v[116:119], v201 offset:37120
	ds_read_b128 v[120:123], v105 offset:53312
	ds_read_b128 v[170:173], v201 offset:34880
	ds_read_b128 v[174:177], v201 offset:39424
	ds_read_b128 v[178:181], v201 offset:37184
	ds_read_b128 v[182:185], v105 offset:55552
	ds_read_b128 v[186:189], v201 offset:41728
	ds_read_b128 v[190:193], v201 offset:39488
	global_store_short_d16_hi v[64:65], v68, off
	s_nop 0
	v_cvt_pk_bf16_f32 v66, v66, v66
	global_store_short_d16_hi v[64:65], v66, off offset:32
	v_add_u32_e32 v66, 19, v107
	v_add_u32_e32 v68, 0x1fec, v165
	v_cndmask_b32_e64 v66, v68, v66, s[6:7]
	v_add_u32_e32 v68, s67, v66
	v_ashrrev_i32_e32 v69, 31, v68
	v_lshlrev_b64 v[68:69], 11, v[68:69]
	s_nop 0
	v_lshl_add_u64 v[68:69], v[88:89], 0, v[68:69]
	v_cvt_pk_bf16_f32 v66, v71, v71
	global_store_short_d16_hi v[68:69], v66, off
	s_nop 0
	v_cvt_pk_bf16_f32 v66, v67, v67
	global_store_short_d16_hi v[68:69], v66, off offset:32
	s_nop 0
	v_pk_mul_f32 v[6:7], v[6:7], v[166:167] op_sel_hi:[1,0]
	v_pk_mul_f32 v[4:5], v[4:5], v[166:167] op_sel_hi:[1,0]
	v_pk_mul_f32 v[2:3], v[2:3], v[198:199] op_sel_hi:[1,0]
	v_pk_mul_f32 v[0:1], v[0:1], v[198:199] op_sel_hi:[1,0]
	v_cvt_pk_bf16_f32 v66, v48, v48
	s_waitcnt lgkmcnt(8)
	v_mfma_f32_16x16x32_bf16 v[24:27], v[108:111], v[112:115], v[24:27]
	ds_read_b128 v[194:197], v201 offset:41792
	v_pk_mul_f32 v[18:19], v[18:19], v[166:167] op_sel_hi:[1,0]
	v_pk_mul_f32 v[16:17], v[16:17], v[166:167] op_sel_hi:[1,0]
	s_waitcnt lgkmcnt(8)
	v_mfma_f32_16x16x32_bf16 v[4:7], v[108:111], v[116:119], v[4:7]
	v_mul_f32_e64 v42, v42, v198
	v_mul_f32_e64 v43, v43, v198
	v_pk_mul_f32 v[40:41], v[40:41], v[198:199] op_sel_hi:[1,0]
	s_waitcnt lgkmcnt(5)
	v_mfma_f32_16x16x32_bf16 v[8:11], v[108:111], v[174:177], v[8:11]
	s_waitcnt lgkmcnt(2)
	v_mfma_f32_16x16x32_bf16 v[0:3], v[108:111], v[186:189], v[0:3]
	ds_read_b128 v[108:111], v105 offset:55616
	s_waitcnt lgkmcnt(0)
	s_barrier
	ds_write_b16_d16_hi v106, v66 offset:62464
	s_nop 0
	v_cvt_pk_bf16_f32 v66, v49, v49
	ds_write_b16_d16_hi v106, v66 offset:62736
	s_nop 0
	v_cvt_pk_bf16_f32 v66, v50, v50
	ds_write_b16_d16_hi v106, v66 offset:63008
	s_nop 0
	v_cvt_pk_bf16_f32 v66, v51, v51
	ds_write_b16_d16_hi v106, v66 offset:63280
	s_nop 0
	v_cvt_pk_bf16_f32 v66, v32, v32
	ds_write_b16_d16_hi v106, v66 offset:62496
	s_nop 0
	v_cvt_pk_bf16_f32 v66, v33, v33
	ds_write_b16_d16_hi v106, v66 offset:62768
	s_nop 0
	v_cvt_pk_bf16_f32 v66, v34, v34
	ds_write_b16_d16_hi v106, v66 offset:63040
	s_nop 0
	v_cvt_pk_bf16_f32 v66, v35, v35
	ds_write_b16_d16_hi v106, v66 offset:63312
	s_nop 0
	v_cvt_pk_bf16_f32 v66, v36, v36
	ds_write_b16_d16_hi v106, v66 offset:62528
	s_nop 0
	v_cvt_pk_bf16_f32 v66, v37, v37
	ds_write_b16_d16_hi v106, v66 offset:62800
	s_nop 0
	v_cvt_pk_bf16_f32 v66, v38, v38
	ds_write_b16_d16_hi v106, v66 offset:63072
	s_nop 0
	v_cvt_pk_bf16_f32 v66, v39, v39
	ds_write_b16_d16_hi v106, v66 offset:63344
	s_nop 0
	v_cvt_pk_bf16_f32 v66, v28, v28
	ds_write_b16_d16_hi v106, v66 offset:62560
	s_nop 0
	v_cvt_pk_bf16_f32 v66, v29, v29
	ds_write_b16_d16_hi v106, v66 offset:62832
	s_nop 0
	v_cvt_pk_bf16_f32 v66, v30, v30
	ds_write_b16_d16_hi v106, v66 offset:63104
	s_nop 0
	v_cvt_pk_bf16_f32 v66, v31, v31
	ds_write_b16_d16_hi v106, v66 offset:63376
	s_nop 0
	v_cvt_pk_bf16_f32 v66, v44, v44
	ds_write_b16_d16_hi v142, v66 offset:62464
	s_nop 0
	v_cvt_pk_bf16_f32 v66, v45, v45
	ds_write_b16_d16_hi v143, v66 offset:62464
	s_nop 0
	v_cvt_pk_bf16_f32 v66, v46, v46
	ds_write_b16_d16_hi v145, v66 offset:62464
	s_nop 0
	v_cvt_pk_bf16_f32 v66, v47, v47
	ds_write_b16_d16_hi v146, v66 offset:62464
	s_nop 0
	v_cvt_pk_bf16_f32 v66, v52, v52
	ds_write_b16_d16_hi v142, v66 offset:62496
	s_nop 0
	v_cvt_pk_bf16_f32 v66, v53, v53
	ds_write_b16_d16_hi v143, v66 offset:62496
	s_nop 0
	v_cvt_pk_bf16_f32 v66, v54, v54
	ds_write_b16_d16_hi v145, v66 offset:62496
	s_nop 0
	v_cvt_pk_bf16_f32 v66, v55, v55
	ds_write_b16_d16_hi v146, v66 offset:62496
	s_nop 0
	v_cvt_pk_bf16_f32 v66, v56, v56
	ds_write_b16_d16_hi v142, v66 offset:62528
	s_nop 0
	v_cvt_pk_bf16_f32 v66, v57, v57
	ds_write_b16_d16_hi v143, v66 offset:62528
	s_nop 0
	v_cvt_pk_bf16_f32 v66, v58, v58
	ds_write_b16_d16_hi v145, v66 offset:62528
	s_nop 0
	v_cvt_pk_bf16_f32 v66, v59, v59
	ds_write_b16_d16_hi v146, v66 offset:62528
	s_nop 0
	v_cvt_pk_bf16_f32 v66, v60, v60
	ds_write_b16_d16_hi v142, v66 offset:62560
	s_nop 0
	v_cvt_pk_bf16_f32 v66, v61, v61
	ds_write_b16_d16_hi v143, v66 offset:62560
	s_nop 0
	v_cvt_pk_bf16_f32 v66, v62, v62
	ds_write_b16_d16_hi v145, v66 offset:62560
	s_nop 0
	v_cvt_pk_bf16_f32 v66, v63, v63
	ds_write_b16_d16_hi v146, v66 offset:62560
	v_lshlrev_b32_e32 v66, 16, v150
	v_mfma_f32_16x16x32_bf16 v[12:15], v[182:185], v[112:115], v[12:15]
	v_or_b32_sdwa v112, v66, v149 dst_sel:DWORD dst_unused:UNUSED_PAD src0_sel:DWORD src1_sel:WORD_0
	v_lshlrev_b32_e32 v66, 16, v152
	v_or_b32_sdwa v113, v66, v151 dst_sel:DWORD dst_unused:UNUSED_PAD src0_sel:DWORD src1_sel:WORD_0
	v_lshlrev_b32_e32 v66, 16, v154
	v_or_b32_sdwa v114, v66, v153 dst_sel:DWORD dst_unused:UNUSED_PAD src0_sel:DWORD src1_sel:WORD_0
	v_lshlrev_b32_e32 v66, 16, v156
	v_or_b32_sdwa v115, v66, v155 dst_sel:DWORD dst_unused:UNUSED_PAD src0_sel:DWORD src1_sel:WORD_0
	v_lshlrev_b32_e32 v66, 16, v158
	v_mfma_f32_16x16x32_bf16 v[16:19], v[182:185], v[116:119], v[16:19]
	v_or_b32_sdwa v116, v66, v157 dst_sel:DWORD dst_unused:UNUSED_PAD src0_sel:DWORD src1_sel:WORD_0
	v_lshlrev_b32_e32 v66, 16, v160
	v_or_b32_sdwa v117, v66, v159 dst_sel:DWORD dst_unused:UNUSED_PAD src0_sel:DWORD src1_sel:WORD_0
	v_lshlrev_b32_e32 v66, 16, v162
	v_or_b32_sdwa v118, v66, v161 dst_sel:DWORD dst_unused:UNUSED_PAD src0_sel:DWORD src1_sel:WORD_0
	s_waitcnt vmcnt(16)
	v_lshlrev_b32_e32 v66, 16, v164
	v_or_b32_sdwa v119, v66, v163 dst_sel:DWORD dst_unused:UNUSED_PAD src0_sel:DWORD src1_sel:WORD_0
	ds_write_b128 v147, v[112:115] offset:53248
	ds_write_b128 v147, v[116:119] offset:53264
	s_waitcnt lgkmcnt(0)
	s_barrier
	ds_read_b128 v[112:115], v104
	v_mfma_f32_16x16x32_bf16 v[20:23], v[182:185], v[174:177], v[20:23]
	v_mfma_f32_16x16x32_bf16 v[40:43], v[182:185], v[186:189], v[40:43]
	v_mfma_f32_16x16x32_bf16 v[24:27], v[120:123], v[170:173], v[24:27]
	v_mfma_f32_16x16x32_bf16 v[4:7], v[120:123], v[178:181], v[4:7]
	v_mfma_f32_16x16x32_bf16 v[8:11], v[120:123], v[190:193], v[8:11]
	v_mfma_f32_16x16x32_bf16 v[0:3], v[120:123], v[194:197], v[0:3]
	v_mfma_f32_16x16x32_bf16 v[12:15], v[108:111], v[170:173], v[12:15]
	v_mfma_f32_16x16x32_bf16 v[16:19], v[108:111], v[178:181], v[16:19]
	v_mfma_f32_16x16x32_bf16 v[20:23], v[108:111], v[190:193], v[20:23]
	v_mfma_f32_16x16x32_bf16 v[40:43], v[108:111], v[194:197], v[40:43]
	ds_read_b128 v[106:109], v135 offset:62464
	ds_read_b128 v[116:119], v104 offset:64
	ds_read_b128 v[120:123], v135 offset:62528
	ds_read_b128 v[154:157], v136 offset:4352
	ds_read_b128 v[158:161], v136 offset:4416
	ds_read_b128 v[162:165], v104 offset:4352
	ds_read_b128 v[170:173], v104 offset:4416
	s_waitcnt lgkmcnt(6)
	v_mfma_f32_16x16x32_bf16 v[150:153], v[112:115], v[106:109], 0
	s_waitcnt lgkmcnt(3)
	v_mfma_f32_16x16x32_bf16 v[110:113], v[112:115], v[154:157], 0
	v_mfma_f32_16x16x32_bf16 v[150:153], v[116:119], v[120:123], v[150:153]
	s_waitcnt lgkmcnt(2)
	v_mfma_f32_16x16x32_bf16 v[110:113], v[116:119], v[158:161], v[110:113]
	ds_read_b128 v[114:117], v104 offset:128
	s_waitcnt lgkmcnt(2)
	v_mfma_f32_16x16x32_bf16 v[106:109], v[162:165], v[106:109], 0
	v_mfma_f32_16x16x32_bf16 v[154:157], v[162:165], v[154:157], 0
	s_waitcnt lgkmcnt(1)
	v_mfma_f32_16x16x32_bf16 v[106:109], v[170:173], v[120:123], v[106:109]
	v_mfma_f32_16x16x32_bf16 v[118:121], v[170:173], v[158:161], v[154:157]
	s_nop 4
	ds_read_b128 v[154:157], v135 offset:62592
	ds_read_b128 v[158:161], v104 offset:192
	ds_read_b128 v[162:165], v135 offset:62656
	ds_read_b128 v[170:173], v136 offset:4480
	ds_read_b128 v[174:177], v136 offset:4544
	s_waitcnt lgkmcnt(4)
	v_mfma_f32_16x16x32_bf16 v[150:153], v[114:117], v[154:157], v[150:153]
	s_waitcnt lgkmcnt(1)
	v_mfma_f32_16x16x32_bf16 v[110:113], v[114:117], v[170:173], v[110:113]
	ds_read_b128 v[114:117], v104 offset:4480
	ds_read_b128 v[178:181], v104 offset:4544
	s_waitcnt lgkmcnt(1)
	v_mfma_f32_16x16x32_bf16 v[106:109], v[114:117], v[154:157], v[106:109]
	v_mfma_f32_16x16x32_bf16 v[114:117], v[114:117], v[170:173], v[118:121]
	v_mfma_f32_16x16x32_bf16 v[118:121], v[158:161], v[162:165], v[150:153]
	s_nop 2
	ds_read_b128 v[150:153], v105 offset:17408
	v_mfma_f32_16x16x32_bf16 v[110:113], v[158:161], v[174:177], v[110:113]
	s_waitcnt lgkmcnt(1)
	v_mfma_f32_16x16x32_bf16 v[106:109], v[178:181], v[162:165], v[106:109]
	ds_read_b128 v[154:157], v167 offset:53248
	ds_read_b128 v[158:161], v105 offset:17472
	ds_read_b128 v[162:165], v167 offset:53312
	v_mfma_f32_16x16x32_bf16 v[114:117], v[178:181], v[174:177], v[114:117]
	ds_read_b128 v[170:173], v167 offset:55552
	ds_read_b128 v[174:177], v167 offset:55616
	s_waitcnt lgkmcnt(4)
	v_mfma_f32_16x16x32_bf16 v[118:121], v[150:153], v[154:157], v[118:121]
	s_waitcnt lgkmcnt(1)
	v_mfma_f32_16x16x32_bf16 v[110:113], v[150:153], v[170:173], v[110:113]
	ds_read_b128 v[150:153], v105 offset:19712
	ds_read_b128 v[178:181], v105 offset:19776
	v_mfma_f32_16x16x32_bf16 v[118:121], v[158:161], v[162:165], v[118:121]
	s_waitcnt lgkmcnt(2)
	v_mfma_f32_16x16x32_bf16 v[110:113], v[158:161], v[174:177], v[110:113]
	s_waitcnt lgkmcnt(1)
	v_mfma_f32_16x16x32_bf16 v[106:109], v[150:153], v[154:157], v[106:109]
	s_nop 3
	s_nop 0
	v_cvt_pk_bf16_f32 v66, v118, v118
	global_store_short_d16_hi v[100:101], v66, off offset:128
	s_nop 0
	v_cvt_pk_bf16_f32 v66, v110, v110
	global_store_short_d16_hi v[100:101], v66, off offset:160
	s_nop 0
	v_cvt_pk_bf16_f32 v66, v119, v119
	global_store_short_d16_hi v[102:103], v66, off offset:128
	s_nop 0
	v_cvt_pk_bf16_f32 v66, v111, v111
	global_store_short_d16_hi v[102:103], v66, off offset:160
	s_nop 0
	v_cvt_pk_bf16_f32 v66, v120, v120
	global_store_short_d16_hi v[98:99], v66, off offset:128
	s_nop 0
	v_cvt_pk_bf16_f32 v70, v112, v112
	ds_read2_b32 v[66:67], v148 offset1:16
	v_mfma_f32_16x16x32_bf16 v[114:117], v[150:153], v[170:173], v[114:117]
	global_store_short_d16_hi v[98:99], v70, off offset:160
	s_nop 0
	ds_read_b128 v[98:101], v105 offset:53248
	v_cvt_pk_bf16_f32 v70, v121, v121
	s_waitcnt lgkmcnt(2)
	v_mfma_f32_16x16x32_bf16 v[106:109], v[178:181], v[162:165], v[106:109]
	global_store_short_d16_hi v[92:93], v70, off offset:128
	ds_read2_b32 v[70:71], v148 offset0:32 offset1:48
	s_waitcnt lgkmcnt(2)
	v_pk_mul_f32 v[50:51], v[50:51], v[66:67] op_sel_hi:[1,0]
	v_mfma_f32_16x16x32_bf16 v[114:117], v[178:181], v[174:177], v[114:117]
	v_mul_f32_e64 v48, v48, v66
	v_mul_f32_e64 v49, v49, v66
	ds_read_b128 v[118:121], v201 offset:34816
	v_pk_mul_f32 v[46:47], v[46:47], v[66:67] op_sel_hi:[1,0]
	v_pk_mul_f32 v[44:45], v[44:45], v[66:67] op_sel_hi:[1,0]
	s_nop 0
	ds_read_b128 v[150:153], v201 offset:37120
	ds_read_b128 v[154:157], v105 offset:53312
	ds_read_b128 v[158:161], v201 offset:34880
	ds_read_b128 v[162:165], v201 offset:39424
	ds_read_b128 v[170:173], v201 offset:37184
	ds_read_b128 v[174:177], v105 offset:55552
	ds_read_b128 v[178:181], v201 offset:41728
	ds_read_b128 v[182:185], v201 offset:39488
	v_cvt_pk_bf16_f32 v66, v113, v113
	global_store_short_d16_hi v[92:93], v66, off offset:160
	s_nop 0
	v_mov_b32_e32 v102, v67
	s_waitcnt lgkmcnt(9)
	v_mov_b32_e32 v104, v71
	v_cvt_pk_bf16_f32 v66, v106, v106
	v_pk_mul_f32 v[34:35], v[34:35], v[102:103] op_sel_hi:[1,0]
	v_pk_mul_f32 v[32:33], v[32:33], v[102:103] op_sel_hi:[1,0]
	v_pk_mul_f32 v[38:39], v[38:39], v[70:71] op_sel_hi:[1,0]
	v_pk_mul_f32 v[36:37], v[36:37], v[70:71] op_sel_hi:[1,0]
	v_pk_mul_f32 v[30:31], v[30:31], v[104:105] op_sel_hi:[1,0]
	v_pk_mul_f32 v[28:29], v[28:29], v[104:105] op_sel_hi:[1,0]
	global_store_short_d16_hi v[94:95], v66, off offset:128
	s_nop 0
	s_waitcnt lgkmcnt(8)
	v_mfma_f32_16x16x32_bf16 v[48:51], v[98:101], v[118:121], v[48:51]
	ds_read_b128 v[186:189], v201 offset:41792
	v_cvt_pk_bf16_f32 v66, v114, v114
	global_store_short_d16_hi v[94:95], v66, off offset:160
	s_waitcnt lgkmcnt(8)
	v_mfma_f32_16x16x32_bf16 v[32:35], v[98:101], v[150:153], v[32:35]
	s_nop 0
	v_cvt_pk_bf16_f32 v66, v107, v107
	global_store_short_d16_hi v[96:97], v66, off offset:128
	s_waitcnt lgkmcnt(5)
	v_mfma_f32_16x16x32_bf16 v[36:39], v[98:101], v[162:165], v[36:39]
	s_nop 0
	v_pk_mul_f32 v[54:55], v[54:55], v[102:103] op_sel_hi:[1,0]
	v_pk_mul_f32 v[52:53], v[52:53], v[102:103] op_sel_hi:[1,0]
	s_waitcnt lgkmcnt(2)
	v_mfma_f32_16x16x32_bf16 v[28:31], v[98:101], v[178:181], v[28:31]
	ds_read_b128 v[98:101], v105 offset:55616
	v_pk_mul_f32 v[58:59], v[58:59], v[70:71] op_sel_hi:[1,0]
	v_pk_mul_f32 v[56:57], v[56:57], v[70:71] op_sel_hi:[1,0]
	v_pk_mul_f32 v[62:63], v[62:63], v[104:105] op_sel_hi:[1,0]
	v_pk_mul_f32 v[60:61], v[60:61], v[104:105] op_sel_hi:[1,0]
	v_cvt_pk_bf16_f32 v66, v115, v115
	v_mfma_f32_16x16x32_bf16 v[44:47], v[174:177], v[118:121], v[44:47]
	global_store_short_d16_hi v[96:97], v66, off offset:160
	s_nop 0
	v_cvt_pk_bf16_f32 v66, v108, v108
	v_mfma_f32_16x16x32_bf16 v[52:55], v[174:177], v[150:153], v[52:55]
	global_store_short_d16_hi v[64:65], v66, off offset:128
	s_nop 0
	v_cvt_pk_bf16_f32 v66, v116, v116
	v_mfma_f32_16x16x32_bf16 v[56:59], v[174:177], v[162:165], v[56:59]
	global_store_short_d16_hi v[64:65], v66, off offset:160
	s_nop 0
	v_cvt_pk_bf16_f32 v64, v109, v109
	v_mfma_f32_16x16x32_bf16 v[60:63], v[174:177], v[178:181], v[60:63]
	global_store_short_d16_hi v[68:69], v64, off offset:128
	s_nop 0
	v_cvt_pk_bf16_f32 v64, v117, v117
	v_mfma_f32_16x16x32_bf16 v[48:51], v[154:157], v[158:161], v[48:51]
	global_store_short_d16_hi v[68:69], v64, off offset:160
	v_mfma_f32_16x16x32_bf16 v[32:35], v[154:157], v[170:173], v[32:35]
	s_waitcnt lgkmcnt(2)
	v_mfma_f32_16x16x32_bf16 v[36:39], v[154:157], v[182:185], v[36:39]
	s_waitcnt lgkmcnt(1)
	v_mfma_f32_16x16x32_bf16 v[28:31], v[154:157], v[186:189], v[28:31]
	s_waitcnt lgkmcnt(0)
	v_mfma_f32_16x16x32_bf16 v[44:47], v[98:101], v[158:161], v[44:47]
	v_mfma_f32_16x16x32_bf16 v[52:55], v[98:101], v[170:173], v[52:55]
	v_mfma_f32_16x16x32_bf16 v[56:59], v[98:101], v[182:185], v[56:59]
	v_mfma_f32_16x16x32_bf16 v[60:63], v[98:101], v[186:189], v[60:63]
	s_cbranch_scc0 .LBB0_332

.LBB0_394:
	v_ashrrev_i32_e32 v31, 31, v30
	v_lshlrev_b64 v[14:15], 11, v[30:31]
	v_lshl_or_b32 v14, v32, 1, v14
	s_waitcnt lgkmcnt(0)
	v_lshl_add_u64 v[48:49], s[12:13], 0, v[14:15]
	v_lshl_add_u64 v[50:51], s[14:15], 0, v[14:15]
	v_lshl_add_u64 v[52:53], s[16:17], 0, v[14:15]
	global_load_dwordx4 v[40:43], v[48:49], off
	global_load_dwordx4 v[44:47], v[50:51], off
	global_load_dwordx4 v[18:21], v[52:53], off
	v_lshl_add_u64 v[38:39], s[18:19], 0, v[14:15]
	global_load_dwordx4 v[26:29], v[48:49], off offset:1024
	global_load_dwordx4 v[22:25], v[50:51], off offset:1024
	global_load_dwordx4 v[14:17], v[52:53], off offset:1024
	v_add_u32_e32 v30, s3, v30
	s_waitcnt vmcnt(5)
	v_lshlrev_b32_e32 v49, 16, v41
	v_lshlrev_b32_e32 v48, 16, v40
	s_waitcnt vmcnt(4)
	v_lshlrev_b32_e32 v51, 16, v45
	v_lshlrev_b32_e32 v50, 16, v44
	s_waitcnt vmcnt(3)
	v_lshlrev_b32_e32 v55, 16, v19
	v_lshlrev_b32_e32 v54, 16, v18
	v_and_b32_e32 v41, 0xffff0000, v41
	v_and_b32_e32 v40, 0xffff0000, v40
	v_and_b32_e32 v53, 0xffff0000, v45
	v_and_b32_e32 v52, 0xffff0000, v44
	v_and_b32_e32 v57, 0xffff0000, v19
	v_and_b32_e32 v56, 0xffff0000, v18
	v_lshlrev_b32_e32 v19, 16, v43
	v_lshlrev_b32_e32 v18, 16, v42
	v_lshlrev_b32_e32 v63, 16, v47
	v_lshlrev_b32_e32 v62, 16, v46
	v_and_b32_e32 v65, 0xffff0000, v43
	v_and_b32_e32 v64, 0xffff0000, v42
	v_and_b32_e32 v47, 0xffff0000, v47
	v_and_b32_e32 v46, 0xffff0000, v46
	v_pk_add_f32 v[44:45], v[48:49], v[50:51]
	v_mul_f32_e32 v31, 0xbfb8aa3b, v54
	v_mul_f32_e32 v49, 0xbfb8aa3b, v55
	v_pk_add_f32 v[42:43], v[40:41], v[52:53]
	v_pk_add_f32 v[40:41], v[18:19], v[62:63]
	v_pk_add_f32 v[18:19], v[64:65], v[46:47]
	v_exp_f32_e32 v46, v31
	v_exp_f32_e32 v47, v49
	v_mul_f32_e32 v48, 0xbfb8aa3b, v56
	v_mul_f32_e32 v50, 0xbfb8aa3b, v57
	v_exp_f32_e32 v48, v48
	v_exp_f32_e32 v49, v50
	v_pk_add_f32 v[46:47], v[46:47], 1.0 op_sel_hi:[1,0]
	v_lshlrev_b32_e32 v67, 16, v21
	v_div_scale_f32 v31, s[6:7], v47, v47, 1.0
	v_pk_add_f32 v[48:49], v[48:49], 1.0 op_sel_hi:[1,0]
	v_div_scale_f32 v53, s[6:7], v46, v46, 1.0
	v_rcp_f32_e32 v68, v31
	v_div_scale_f32 v63, s[8:9], v49, v49, 1.0
	v_rcp_f32_e32 v69, v53
	v_div_scale_f32 v65, s[10:11], v48, v48, 1.0
	v_rcp_f32_e32 v70, v63
	v_rcp_f32_e32 v71, v65
	v_fma_f32 v72, -v31, v68, 1.0
	v_div_scale_f32 v52, vcc, 1.0, v47, 1.0
	v_fma_f32 v73, -v53, v69, 1.0
	v_fmac_f32_e32 v68, v72, v68
	v_div_scale_f32 v62, s[6:7], 1.0, v46, 1.0
	v_fma_f32 v74, -v63, v70, 1.0
	v_fmac_f32_e32 v69, v73, v69
	v_mul_f32_e32 v72, v52, v68
	v_div_scale_f32 v64, s[8:9], 1.0, v49, 1.0
	v_fma_f32 v75, -v65, v71, 1.0
	v_fmac_f32_e32 v70, v74, v70
	v_mul_f32_e32 v73, v62, v69
	v_fma_f32 v76, -v31, v72, v52
	v_div_scale_f32 v66, s[10:11], 1.0, v48, 1.0
	v_fmac_f32_e32 v71, v75, v71
	v_mul_f32_e32 v74, v64, v70
	v_fma_f32 v77, -v53, v73, v62
	v_fmac_f32_e32 v72, v76, v68
	v_mul_f32_e32 v75, v66, v71
	v_fma_f32 v78, -v63, v74, v64
	v_fmac_f32_e32 v73, v77, v69
	v_fma_f32 v31, -v31, v72, v52
	v_fma_f32 v79, -v65, v75, v66
	v_fmac_f32_e32 v74, v78, v70
	v_fma_f32 v52, -v53, v73, v62
	v_div_fmas_f32 v31, v31, v68, v72
	s_mov_b64 vcc, s[6:7]
	v_fmac_f32_e32 v75, v79, v71
	v_fma_f32 v53, -v63, v74, v64
	v_div_fixup_f32 v47, v31, v47, 1.0
	v_div_fmas_f32 v31, v52, v69, v73
	s_mov_b64 vcc, s[8:9]
	v_fma_f32 v62, -v65, v75, v66
	v_div_fixup_f32 v46, v31, v46, 1.0
	v_div_fmas_f32 v31, v53, v70, v74
	s_mov_b64 vcc, s[10:11]
	v_div_fixup_f32 v49, v31, v49, 1.0
	v_div_fmas_f32 v31, v62, v71, v75
	v_lshlrev_b32_e32 v66, 16, v20
	v_div_fixup_f32 v48, v31, v48, 1.0
	v_mul_f32_e32 v31, 0xbfb8aa3b, v66
	v_exp_f32_e32 v52, v31
	v_mul_f32_e32 v31, 0xbfb8aa3b, v67
	v_exp_f32_e32 v53, v31
	v_pk_mul_f32 v[46:47], v[46:47], v[54:55]
	v_pk_mul_f32 v[54:55], v[40:41], v[40:41]
	v_pk_mul_f32 v[48:49], v[48:49], v[56:57]
	v_pk_add_f32 v[52:53], v[52:53], 1.0 op_sel_hi:[1,0]
	v_pk_fma_f32 v[56:57], v[18:19], v[18:19], v[54:55]
	v_and_b32_e32 v55, 0xffff0000, v21
	v_div_scale_f32 v21, s[6:7], v53, v53, 1.0
	v_rcp_f32_e32 v31, v21
	v_and_b32_e32 v54, 0xffff0000, v20
	v_mul_f32_e32 v20, 0xbfb8aa3b, v54
	v_exp_f32_e32 v20, v20
	v_fma_f32 v62, -v21, v31, 1.0
	v_fmac_f32_e32 v31, v62, v31
	v_div_scale_f32 v62, vcc, 1.0, v53, 1.0
	v_mul_f32_e32 v63, v62, v31
	v_fma_f32 v64, -v21, v63, v62
	v_fmac_f32_e32 v63, v64, v31
	v_fma_f32 v21, -v21, v63, v62
	v_div_scale_f32 v62, s[6:7], v52, v52, 1.0
	v_rcp_f32_e32 v64, v62
	v_div_fmas_f32 v21, v21, v31, v63
	v_div_fixup_f32 v53, v21, v53, 1.0
	v_div_scale_f32 v31, vcc, 1.0, v52, 1.0
	v_fma_f32 v21, -v62, v64, 1.0
	v_fmac_f32_e32 v64, v21, v64
	v_mul_f32_e32 v21, 0xbfb8aa3b, v55
	v_exp_f32_e32 v21, v21
	v_mul_f32_e32 v65, v31, v64
	v_fma_f32 v63, -v62, v65, v31
	v_fmac_f32_e32 v65, v63, v64
	v_fma_f32 v31, -v62, v65, v31
	v_pk_add_f32 v[62:63], v[20:21], 1.0 op_sel_hi:[1,0]
	v_div_fmas_f32 v20, v31, v64, v65
	v_div_scale_f32 v68, s[6:7], v63, v63, 1.0
	v_rcp_f32_e32 v69, v68
	v_div_fixup_f32 v52, v20, v52, 1.0
	v_pk_mul_f32 v[20:21], v[52:53], v[66:67]
	v_div_scale_f32 v64, s[6:7], v62, v62, 1.0
	v_fma_f32 v31, -v68, v69, 1.0
	v_fmac_f32_e32 v69, v31, v69
	v_div_scale_f32 v31, vcc, 1.0, v63, 1.0
	v_mul_f32_e32 v52, v31, v69
	v_fma_f32 v53, -v68, v52, v31
	v_rcp_f32_e32 v65, v64
	v_fmac_f32_e32 v52, v53, v69
	v_fma_f32 v31, -v68, v52, v31
	v_div_fmas_f32 v31, v31, v69, v52
	v_div_fixup_f32 v53, v31, v63, 1.0
	v_fma_f32 v31, -v64, v65, 1.0
	v_fmac_f32_e32 v65, v31, v65
	v_div_scale_f32 v31, vcc, 1.0, v62, 1.0
	v_mul_f32_e32 v52, v31, v65
	v_fma_f32 v63, -v64, v52, v31
	v_fmac_f32_e32 v52, v63, v65
	v_fma_f32 v31, -v64, v52, v31
	v_div_fmas_f32 v31, v31, v65, v52
	v_div_fixup_f32 v52, v31, v62, 1.0
	v_pk_mul_f32 v[54:55], v[52:53], v[54:55]
	s_waitcnt vmcnt(2)
	v_lshlrev_b32_e32 v53, 16, v27
	v_lshlrev_b32_e32 v52, 16, v26
	s_waitcnt vmcnt(1)
	v_lshlrev_b32_e32 v63, 16, v23
	v_lshlrev_b32_e32 v62, 16, v22
	v_and_b32_e32 v27, 0xffff0000, v27
	v_and_b32_e32 v26, 0xffff0000, v26
	v_and_b32_e32 v23, 0xffff0000, v23
	v_and_b32_e32 v22, 0xffff0000, v22
	v_pk_add_f32 v[22:23], v[26:27], v[22:23]
	s_waitcnt vmcnt(0)
	v_lshlrev_b32_e32 v26, 16, v14
	v_lshlrev_b32_e32 v27, 16, v15
	v_mul_f32_e32 v31, 0xbfb8aa3b, v26
	v_pk_add_f32 v[52:53], v[52:53], v[62:63]
	v_exp_f32_e32 v62, v31
	v_mul_f32_e32 v31, 0xbfb8aa3b, v27
	v_exp_f32_e32 v63, v31
	v_and_b32_e32 v67, 0xffff0000, v15
	v_and_b32_e32 v66, 0xffff0000, v14
	v_mul_f32_e32 v14, 0xbfb8aa3b, v66
	v_pk_add_f32 v[62:63], v[62:63], 1.0 op_sel_hi:[1,0]
	v_exp_f32_e32 v14, v14
	v_div_scale_f32 v15, s[6:7], v63, v63, 1.0
	v_rcp_f32_e32 v31, v15
	v_pk_mul_f32 v[50:51], v[44:45], v[44:45]
	v_pk_mul_f32 v[64:65], v[52:53], v[52:53]
	v_pk_fma_f32 v[50:51], v[42:43], v[42:43], v[50:51]
	v_fma_f32 v68, -v15, v31, 1.0
	v_fmac_f32_e32 v31, v68, v31
	v_div_scale_f32 v68, vcc, 1.0, v63, 1.0
	v_mul_f32_e32 v69, v68, v31
	v_fma_f32 v70, -v15, v69, v68
	v_fmac_f32_e32 v69, v70, v31
	v_fma_f32 v15, -v15, v69, v68
	v_div_scale_f32 v68, s[6:7], v62, v62, 1.0
	v_rcp_f32_e32 v70, v68
	v_div_fmas_f32 v15, v15, v31, v69
	v_div_fixup_f32 v63, v15, v63, 1.0
	v_div_scale_f32 v31, vcc, 1.0, v62, 1.0
	v_fma_f32 v15, -v68, v70, 1.0
	v_fmac_f32_e32 v70, v15, v70
	v_mul_f32_e32 v15, 0xbfb8aa3b, v67
	v_exp_f32_e32 v15, v15
	v_mul_f32_e32 v71, v31, v70
	v_fma_f32 v69, -v68, v71, v31
	v_fmac_f32_e32 v71, v69, v70
	v_fma_f32 v31, -v68, v71, v31
	v_pk_add_f32 v[68:69], v[14:15], 1.0 op_sel_hi:[1,0]
	v_div_fmas_f32 v14, v31, v70, v71
	v_div_scale_f32 v72, s[6:7], v69, v69, 1.0
	v_rcp_f32_e32 v73, v72
	v_div_fixup_f32 v62, v14, v62, 1.0
	v_pk_mul_f32 v[14:15], v[62:63], v[26:27]
	v_pk_fma_f32 v[64:65], v[22:23], v[22:23], v[64:65]
	v_fma_f32 v26, -v72, v73, 1.0
	v_fmac_f32_e32 v73, v26, v73
	v_div_scale_f32 v26, vcc, 1.0, v69, 1.0
	v_mul_f32_e32 v27, v26, v73
	v_fma_f32 v31, -v72, v27, v26
	v_fmac_f32_e32 v27, v31, v73
	v_div_scale_f32 v31, s[6:7], v68, v68, 1.0
	v_rcp_f32_e32 v62, v31
	v_fma_f32 v26, -v72, v27, v26
	v_div_fmas_f32 v26, v26, v73, v27
	v_div_fixup_f32 v27, v26, v69, 1.0
	v_fma_f32 v26, -v31, v62, 1.0
	v_fmac_f32_e32 v62, v26, v62
	v_div_scale_f32 v26, vcc, 1.0, v68, 1.0
	v_mul_f32_e32 v63, v26, v62
	v_fma_f32 v69, -v31, v63, v26
	v_fmac_f32_e32 v63, v69, v62
	v_fma_f32 v26, -v31, v63, v26
	v_div_fmas_f32 v26, v26, v62, v63
	v_div_fixup_f32 v26, v26, v68, 1.0
	v_pk_mul_f32 v[26:27], v[26:27], v[66:67]
	v_lshlrev_b32_e32 v63, 16, v29
	v_lshlrev_b32_e32 v62, 16, v28
	v_lshlrev_b32_e32 v67, 16, v25
	v_lshlrev_b32_e32 v66, 16, v24
	v_and_b32_e32 v29, 0xffff0000, v29
	v_and_b32_e32 v28, 0xffff0000, v28
	v_and_b32_e32 v25, 0xffff0000, v25
	v_and_b32_e32 v24, 0xffff0000, v24
	v_pk_add_f32 v[24:25], v[28:29], v[24:25]
	v_lshlrev_b32_e32 v28, 16, v16
	v_lshlrev_b32_e32 v29, 16, v17
	v_mul_f32_e32 v31, 0xbfb8aa3b, v28
	v_pk_add_f32 v[62:63], v[62:63], v[66:67]
	v_exp_f32_e32 v66, v31
	v_mul_f32_e32 v31, 0xbfb8aa3b, v29
	v_exp_f32_e32 v67, v31
	v_pk_mul_f32 v[68:69], v[62:63], v[62:63]
	v_and_b32_e32 v17, 0xffff0000, v17
	v_pk_fma_f32 v[68:69], v[24:25], v[24:25], v[68:69]
	v_pk_add_f32 v[66:67], v[66:67], 1.0 op_sel_hi:[1,0]
	v_and_b32_e32 v16, 0xffff0000, v16
	v_div_scale_f32 v31, s[6:7], v67, v67, 1.0
	v_rcp_f32_e32 v71, v31
	v_mul_f32_e32 v70, 0xbfb8aa3b, v16
	v_exp_f32_e32 v70, v70
	v_fma_f32 v72, -v31, v71, 1.0
	v_fmac_f32_e32 v71, v72, v71
	v_div_scale_f32 v72, vcc, 1.0, v67, 1.0
	v_mul_f32_e32 v73, v72, v71
	v_fma_f32 v74, -v31, v73, v72
	v_fmac_f32_e32 v73, v74, v71
	v_fma_f32 v31, -v31, v73, v72
	v_div_scale_f32 v72, s[6:7], v66, v66, 1.0
	v_rcp_f32_e32 v74, v72
	v_div_fmas_f32 v31, v31, v71, v73
	v_div_fixup_f32 v67, v31, v67, 1.0
	v_mul_f32_e32 v71, 0xbfb8aa3b, v17
	v_fma_f32 v31, -v72, v74, 1.0
	v_fmac_f32_e32 v74, v31, v74
	v_div_scale_f32 v31, vcc, 1.0, v66, 1.0
	v_mul_f32_e32 v73, v31, v74
	v_fma_f32 v75, -v72, v73, v31
	v_fmac_f32_e32 v73, v75, v74
	v_fma_f32 v31, -v72, v73, v31
	v_div_fmas_f32 v31, v31, v74, v73
	v_div_fixup_f32 v66, v31, v66, 1.0
	v_pk_mul_f32 v[28:29], v[66:67], v[28:29]
	v_mov_b32_e32 v66, v64
	v_mov_b32_e32 v67, v50
	v_mov_b32_e32 v50, v65
	v_pk_add_f32 v[50:51], v[66:67], v[50:51]
	v_mov_b32_e32 v64, v68
	v_mov_b32_e32 v65, v56
	v_pk_add_f32 v[50:51], v[50:51], v[64:65]
	v_mov_b32_e32 v56, v69
	v_pk_add_f32 v[50:51], v[50:51], v[56:57]
	ds_bpermute_b32 v57, v33, v51
	ds_bpermute_b32 v56, v33, v50
	v_exp_f32_e32 v71, v71
	s_waitcnt lgkmcnt(0)
	v_pk_add_f32 v[50:51], v[50:51], v[56:57]
	ds_bpermute_b32 v57, v35, v51
	ds_bpermute_b32 v56, v35, v50
	v_pk_add_f32 v[70:71], v[70:71], 1.0 op_sel_hi:[1,0]
	s_waitcnt lgkmcnt(0)
	v_pk_add_f32 v[50:51], v[50:51], v[56:57]
	v_div_scale_f32 v72, s[6:7], v71, v71, 1.0
	ds_bpermute_b32 v57, v58, v51
	ds_bpermute_b32 v56, v58, v50
	v_rcp_f32_e32 v75, v72
	s_waitcnt lgkmcnt(0)
	v_pk_add_f32 v[50:51], v[50:51], v[56:57]
	v_fma_f32 v31, -v72, v75, 1.0
	v_fmac_f32_e32 v75, v31, v75
	v_div_scale_f32 v31, vcc, 1.0, v71, 1.0
	ds_bpermute_b32 v57, v59, v51
	ds_bpermute_b32 v56, v59, v50
	v_mul_f32_e32 v64, v31, v75
	v_fma_f32 v65, -v72, v64, v31
	v_fmac_f32_e32 v64, v65, v75
	v_fma_f32 v31, -v72, v64, v31
	v_div_fmas_f32 v31, v31, v75, v64
	s_waitcnt lgkmcnt(0)
	v_pk_add_f32 v[50:51], v[50:51], v[56:57]
	v_div_fixup_f32 v65, v31, v71, 1.0
	v_div_scale_f32 v31, s[6:7], v70, v70, 1.0
	ds_bpermute_b32 v57, v60, v51
	ds_bpermute_b32 v56, v60, v50
	v_rcp_f32_e32 v64, v31
	s_waitcnt lgkmcnt(0)
	v_pk_add_f32 v[50:51], v[50:51], v[56:57]
	v_fma_f32 v66, -v31, v64, 1.0
	v_fmac_f32_e32 v64, v66, v64
	v_div_scale_f32 v66, vcc, 1.0, v70, 1.0
	v_pk_fma_f32 v[50:51], v[50:51], s[24:25], v[34:35] op_sel_hi:[1,0,0]
	v_mul_f32_e32 v67, v66, v64
	v_mul_f32_e32 v56, 0x4b800000, v51
	v_cmp_gt_f32_e64 s[6:7], s25, v51
	v_fma_f32 v68, -v31, v67, v66
	v_fmac_f32_e32 v67, v68, v64
	v_cndmask_b32_e64 v51, v51, v56, s[6:7]
	v_rsq_f32_e32 v51, v51
	v_fma_f32 v31, -v31, v67, v66
	v_div_fmas_f32 v31, v31, v64, v67
	v_div_fixup_f32 v64, v31, v70, 1.0
	v_pk_mul_f32 v[56:57], v[64:65], v[16:17]
	v_mul_f32_e32 v16, 0x45800000, v51
	v_cndmask_b32_e64 v64, v51, v16, s[6:7]
	v_pk_mul_f32 v[16:17], v[44:45], v[64:65] op_sel_hi:[1,0]
	v_pk_mul_f32 v[42:43], v[42:43], v[64:65] op_sel_hi:[1,0]
	v_pk_mul_f32 v[16:17], v[0:1], v[16:17]
	v_pk_mul_f32 v[42:43], v[36:37], v[42:43]
	v_pk_mul_f32 v[16:17], v[46:47], v[16:17]
	v_pk_mul_f32 v[42:43], v[48:49], v[42:43]
	s_nop 0
	v_cvt_pk_bf16_f32 v17, v17, v17
	s_nop 0
	v_pk_mul_f32 v[40:41], v[40:41], v[64:65] op_sel_hi:[1,0]
	v_cvt_pk_bf16_f32 v31, v43, v43
	v_pk_mul_f32 v[40:41], v[4:5], v[40:41]
	v_pk_mul_f32 v[18:19], v[18:19], v[64:65] op_sel_hi:[1,0]
	v_and_b32_e32 v31, 0xffff0000, v31
	v_pk_mul_f32 v[20:21], v[20:21], v[40:41]
	v_pk_mul_f32 v[18:19], v[2:3], v[18:19]
	v_or_b32_sdwa v17, v31, v17 dst_sel:DWORD dst_unused:UNUSED_PAD src0_sel:DWORD src1_sel:WORD_1
	v_pk_mul_f32 v[18:19], v[54:55], v[18:19]
	s_nop 0
	v_cvt_pk_bf16_f32 v21, v21, v21
	s_nop 0
	v_cvt_pk_bf16_f32 v19, v19, v19
	v_mul_f32_e32 v31, 0x4b800000, v50
	v_cmp_gt_f32_e32 vcc, s25, v50
	s_nop 0
	s_nop 0
	v_cndmask_b32_e32 v31, v50, v31, vcc
	v_cvt_pk_bf16_f32 v16, v16, v16
	v_and_b32_sdwa v44, v42, v61 dst_sel:DWORD dst_unused:UNUSED_PAD src0_sel:WORD_1 src1_sel:DWORD
	v_cvt_pk_bf16_f32 v20, v20, v20
	v_and_b32_sdwa v40, v18, v61 dst_sel:DWORD dst_unused:UNUSED_PAD src0_sel:WORD_1 src1_sel:DWORD
	v_rsq_f32_e32 v31, v31
	v_cvt_pk_bf16_f32 v42, v42, v42
	v_cvt_pk_bf16_f32 v18, v18, v18
	v_and_b32_e32 v42, 0xffff0000, v42
	v_and_b32_e32 v19, 0xffff0000, v19
	v_and_b32_e32 v18, 0xffff0000, v18
	v_or_b32_sdwa v16, v42, v16 dst_sel:DWORD dst_unused:UNUSED_PAD src0_sel:DWORD src1_sel:WORD_1
	v_or_b32_sdwa v19, v19, v21 dst_sel:DWORD dst_unused:UNUSED_PAD src0_sel:DWORD src1_sel:WORD_1
	v_or_b32_sdwa v18, v18, v20 dst_sel:DWORD dst_unused:UNUSED_PAD src0_sel:DWORD src1_sel:WORD_1
	global_store_dwordx4 v[38:39], v[16:19], off
	s_nop 1
	v_mul_f32_e32 v16, 0x45800000, v31
	v_cndmask_b32_e32 v16, v31, v16, vcc
	v_pk_mul_f32 v[18:19], v[52:53], v[16:17] op_sel_hi:[1,0]
	v_cmp_lt_i32_e32 vcc, s27, v30
	v_pk_mul_f32 v[18:19], v[8:9], v[18:19]
	s_or_b64 s[22:23], vcc, s[22:23]
	v_pk_mul_f32 v[14:15], v[14:15], v[18:19]
	v_pk_mul_f32 v[18:19], v[22:23], v[16:17] op_sel_hi:[1,0]
	s_nop 0
	v_pk_mul_f32 v[18:19], v[6:7], v[18:19]
	s_nop 0
	v_pk_mul_f32 v[18:19], v[26:27], v[18:19]
	v_cvt_pk_bf16_f32 v14, v14, v14
	v_cvt_pk_bf16_f32 v15, v15, v15
	s_nop 0
	s_nop 0
	v_cvt_pk_bf16_f32 v17, v19, v19
	v_cvt_pk_bf16_f32 v18, v18, v18
	v_and_b32_e32 v17, 0xffff0000, v17
	v_and_b32_e32 v18, 0xffff0000, v18
	v_or_b32_sdwa v14, v18, v14 dst_sel:DWORD dst_unused:UNUSED_PAD src0_sel:DWORD src1_sel:WORD_1
	v_pk_mul_f32 v[18:19], v[62:63], v[16:17] op_sel_hi:[1,0]
	v_or_b32_sdwa v15, v17, v15 dst_sel:DWORD dst_unused:UNUSED_PAD src0_sel:DWORD src1_sel:WORD_1
	v_pk_mul_f32 v[18:19], v[12:13], v[18:19]
	v_pk_mul_f32 v[16:17], v[24:25], v[16:17] op_sel_hi:[1,0]
	v_pk_mul_f32 v[18:19], v[28:29], v[18:19]
	v_pk_mul_f32 v[16:17], v[10:11], v[16:17]
	s_nop 0
	v_pk_mul_f32 v[16:17], v[56:57], v[16:17]
	s_nop 0
	v_cvt_pk_bf16_f32 v18, v18, v18
	v_cvt_pk_bf16_f32 v19, v19, v19
	s_nop 0
	s_nop 0
	v_cvt_pk_bf16_f32 v17, v17, v17
	v_cvt_pk_bf16_f32 v16, v16, v16
	v_and_b32_e32 v17, 0xffff0000, v17
	v_and_b32_e32 v16, 0xffff0000, v16
	v_or_b32_sdwa v17, v17, v19 dst_sel:DWORD dst_unused:UNUSED_PAD src0_sel:DWORD src1_sel:WORD_1
	v_or_b32_sdwa v16, v16, v18 dst_sel:DWORD dst_unused:UNUSED_PAD src0_sel:DWORD src1_sel:WORD_1
	global_store_dwordx4 v[38:39], v[14:17], off offset:1024
	s_andn2_b64 exec, exec, s[22:23]
	s_cbranch_execnz .LBB0_394

.Lp6a_ep:
	global_load_dwordx4 v[128:131], v244, s[22:23]
	global_load_dwordx4 v[132:135], v244, s[22:23] offset:64
	global_load_dwordx4 v[136:139], v244, s[22:23] offset:128
	global_load_dwordx4 v[140:143], v244, s[22:23] offset:192
	s_lshl_b32 s71, s83, 25
	s_add_u32 s84, s24, s71
	s_addc_u32 s85, s25, 0
	s_waitcnt vmcnt(0)
	v_add_f32_e32 v148, v0, v128
	v_add_f32_e32 v149, v1, v129
	v_add_f32_e32 v150, v2, v130
	v_add_f32_e32 v151, v3, v131
	v_add_f32_e32 v152, v4, v132
	v_add_f32_e32 v153, v5, v133
	v_add_f32_e32 v154, v6, v134
	v_add_f32_e32 v155, v7, v135
	v_mul_f32_e32 v148, 0xbfb8aa3b, v148
	v_mul_f32_e32 v149, 0xbfb8aa3b, v149
	v_mul_f32_e32 v150, 0xbfb8aa3b, v150
	v_mul_f32_e32 v151, 0xbfb8aa3b, v151
	v_mul_f32_e32 v152, 0xbfb8aa3b, v152
	v_mul_f32_e32 v153, 0xbfb8aa3b, v153
	v_mul_f32_e32 v154, 0xbfb8aa3b, v154
	v_mul_f32_e32 v155, 0xbfb8aa3b, v155
	v_exp_f32_e32 v156, v148
	v_exp_f32_e32 v157, v149
	v_exp_f32_e32 v158, v150
	v_exp_f32_e32 v159, v151
	v_exp_f32_e32 v160, v152
	v_exp_f32_e32 v161, v153
	v_exp_f32_e32 v162, v154
	v_exp_f32_e32 v163, v155
	v_add_f32_e32 v156, 1.0, v156
	v_add_f32_e32 v157, 1.0, v157
	v_add_f32_e32 v158, 1.0, v158
	v_add_f32_e32 v159, 1.0, v159
	v_add_f32_e32 v160, 1.0, v160
	v_add_f32_e32 v161, 1.0, v161
	v_add_f32_e32 v162, 1.0, v162
	v_add_f32_e32 v163, 1.0, v163
	v_div_scale_f32 v164, s[76:77], v156, v156, 1.0
	v_div_scale_f32 v165, s[76:77], v157, v157, 1.0
	v_div_scale_f32 v166, s[76:77], v158, v158, 1.0
	v_div_scale_f32 v167, s[76:77], v159, v159, 1.0
	v_div_scale_f32 v172, s[76:77], v160, v160, 1.0
	v_div_scale_f32 v173, s[76:77], v161, v161, 1.0
	v_div_scale_f32 v174, s[76:77], v162, v162, 1.0
	v_div_scale_f32 v175, s[76:77], v163, v163, 1.0
	v_rcp_f32_e32 v176, v164
	v_rcp_f32_e32 v177, v165
	v_rcp_f32_e32 v178, v166
	v_rcp_f32_e32 v179, v167
	v_rcp_f32_e32 v180, v172
	v_rcp_f32_e32 v181, v173
	v_rcp_f32_e32 v182, v174
	v_rcp_f32_e32 v183, v175
	v_fma_f32 v148, -v164, v176, 1.0
	v_fma_f32 v149, -v165, v177, 1.0
	v_fma_f32 v150, -v166, v178, 1.0
	v_fma_f32 v151, -v167, v179, 1.0
	v_fma_f32 v152, -v172, v180, 1.0
	v_fma_f32 v153, -v173, v181, 1.0
	v_fma_f32 v154, -v174, v182, 1.0
	v_fma_f32 v155, -v175, v183, 1.0
	v_fmac_f32_e32 v176, v148, v176
	v_fmac_f32_e32 v177, v149, v177
	v_fmac_f32_e32 v178, v150, v178
	v_fmac_f32_e32 v179, v151, v179
	v_fmac_f32_e32 v180, v152, v180
	v_fmac_f32_e32 v181, v153, v181
	v_fmac_f32_e32 v182, v154, v182
	v_fmac_f32_e32 v183, v155, v183
	v_div_scale_f32 v184, vcc, 1.0, v156, 1.0
	v_mul_f32_e32 v192, v184, v176
	v_fma_f32 v148, -v164, v192, v184
	v_fmac_f32_e32 v192, v148, v176
	v_fma_f32 v184, -v164, v192, v184
	v_div_fmas_f32 v184, v184, v176, v192
	v_div_fixup_f32 v148, v184, v156, 1.0
	v_div_scale_f32 v185, vcc, 1.0, v157, 1.0
	v_mul_f32_e32 v193, v185, v177
	v_fma_f32 v149, -v165, v193, v185
	v_fmac_f32_e32 v193, v149, v177
	v_fma_f32 v185, -v165, v193, v185
	v_div_fmas_f32 v185, v185, v177, v193
	v_div_fixup_f32 v149, v185, v157, 1.0
	v_div_scale_f32 v186, vcc, 1.0, v158, 1.0
	v_mul_f32_e32 v194, v186, v178
	v_fma_f32 v150, -v166, v194, v186
	v_fmac_f32_e32 v194, v150, v178
	v_fma_f32 v186, -v166, v194, v186
	v_div_fmas_f32 v186, v186, v178, v194
	v_div_fixup_f32 v150, v186, v158, 1.0
	v_div_scale_f32 v187, vcc, 1.0, v159, 1.0
	v_mul_f32_e32 v195, v187, v179
	v_fma_f32 v151, -v167, v195, v187
	v_fmac_f32_e32 v195, v151, v179
	v_fma_f32 v187, -v167, v195, v187
	v_div_fmas_f32 v187, v187, v179, v195
	v_div_fixup_f32 v151, v187, v159, 1.0
	v_div_scale_f32 v188, vcc, 1.0, v160, 1.0
	v_mul_f32_e32 v196, v188, v180
	v_fma_f32 v152, -v172, v196, v188
	v_fmac_f32_e32 v196, v152, v180
	v_fma_f32 v188, -v172, v196, v188
	v_div_fmas_f32 v188, v188, v180, v196
	v_div_fixup_f32 v152, v188, v160, 1.0
	v_div_scale_f32 v189, vcc, 1.0, v161, 1.0
	v_mul_f32_e32 v197, v189, v181
	v_fma_f32 v153, -v173, v197, v189
	v_fmac_f32_e32 v197, v153, v181
	v_fma_f32 v189, -v173, v197, v189
	v_div_fmas_f32 v189, v189, v181, v197
	v_div_fixup_f32 v153, v189, v161, 1.0
	v_div_scale_f32 v190, vcc, 1.0, v162, 1.0
	v_mul_f32_e32 v198, v190, v182
	v_fma_f32 v154, -v174, v198, v190
	v_fmac_f32_e32 v198, v154, v182
	v_fma_f32 v190, -v174, v198, v190
	v_div_fmas_f32 v190, v190, v182, v198
	v_div_fixup_f32 v154, v190, v162, 1.0
	v_div_scale_f32 v191, vcc, 1.0, v163, 1.0
	v_mul_f32_e32 v199, v191, v183
	v_fma_f32 v155, -v175, v199, v191
	v_fmac_f32_e32 v199, v155, v183
	v_fma_f32 v191, -v175, v199, v191
	v_div_fmas_f32 v191, v191, v183, v199
	v_div_fixup_f32 v155, v191, v163, 1.0
	v_cvt_pk_bf16_f32 v200, v148, v149
	v_cvt_pk_bf16_f32 v201, v150, v151
	v_cvt_pk_bf16_f32 v202, v152, v153
	v_cvt_pk_bf16_f32 v203, v154, v155
	global_store_dwordx4 v243, v[200:203], s[84:85]
	s_add_u32 s84, s84, 0x1000
	s_addc_u32 s85, s85, 0
	v_add_f32_e32 v148, v8, v136
	v_add_f32_e32 v149, v9, v137
	v_add_f32_e32 v150, v10, v138
	v_add_f32_e32 v151, v11, v139
	v_add_f32_e32 v152, v12, v140
	v_add_f32_e32 v153, v13, v141
	v_add_f32_e32 v154, v14, v142
	v_add_f32_e32 v155, v15, v143
	v_mul_f32_e32 v148, 0xbfb8aa3b, v148
	v_mul_f32_e32 v149, 0xbfb8aa3b, v149
	v_mul_f32_e32 v150, 0xbfb8aa3b, v150
	v_mul_f32_e32 v151, 0xbfb8aa3b, v151
	v_mul_f32_e32 v152, 0xbfb8aa3b, v152
	v_mul_f32_e32 v153, 0xbfb8aa3b, v153
	v_mul_f32_e32 v154, 0xbfb8aa3b, v154
	v_mul_f32_e32 v155, 0xbfb8aa3b, v155
	v_exp_f32_e32 v156, v148
	v_exp_f32_e32 v157, v149
	v_exp_f32_e32 v158, v150
	v_exp_f32_e32 v159, v151
	v_exp_f32_e32 v160, v152
	v_exp_f32_e32 v161, v153
	v_exp_f32_e32 v162, v154
	v_exp_f32_e32 v163, v155
	v_add_f32_e32 v156, 1.0, v156
	v_add_f32_e32 v157, 1.0, v157
	v_add_f32_e32 v158, 1.0, v158
	v_add_f32_e32 v159, 1.0, v159
	v_add_f32_e32 v160, 1.0, v160
	v_add_f32_e32 v161, 1.0, v161
	v_add_f32_e32 v162, 1.0, v162
	v_add_f32_e32 v163, 1.0, v163
	v_div_scale_f32 v164, s[76:77], v156, v156, 1.0
	v_div_scale_f32 v165, s[76:77], v157, v157, 1.0
	v_div_scale_f32 v166, s[76:77], v158, v158, 1.0
	v_div_scale_f32 v167, s[76:77], v159, v159, 1.0
	v_div_scale_f32 v172, s[76:77], v160, v160, 1.0
	v_div_scale_f32 v173, s[76:77], v161, v161, 1.0
	v_div_scale_f32 v174, s[76:77], v162, v162, 1.0
	v_div_scale_f32 v175, s[76:77], v163, v163, 1.0
	v_rcp_f32_e32 v176, v164
	v_rcp_f32_e32 v177, v165
	v_rcp_f32_e32 v178, v166
	v_rcp_f32_e32 v179, v167
	v_rcp_f32_e32 v180, v172
	v_rcp_f32_e32 v181, v173
	v_rcp_f32_e32 v182, v174
	v_rcp_f32_e32 v183, v175
	v_fma_f32 v148, -v164, v176, 1.0
	v_fma_f32 v149, -v165, v177, 1.0
	v_fma_f32 v150, -v166, v178, 1.0
	v_fma_f32 v151, -v167, v179, 1.0
	v_fma_f32 v152, -v172, v180, 1.0
	v_fma_f32 v153, -v173, v181, 1.0
	v_fma_f32 v154, -v174, v182, 1.0
	v_fma_f32 v155, -v175, v183, 1.0
	v_fmac_f32_e32 v176, v148, v176
	v_fmac_f32_e32 v177, v149, v177
	v_fmac_f32_e32 v178, v150, v178
	v_fmac_f32_e32 v179, v151, v179
	v_fmac_f32_e32 v180, v152, v180
	v_fmac_f32_e32 v181, v153, v181
	v_fmac_f32_e32 v182, v154, v182
	v_fmac_f32_e32 v183, v155, v183
	v_div_scale_f32 v184, vcc, 1.0, v156, 1.0
	v_mul_f32_e32 v192, v184, v176
	v_fma_f32 v148, -v164, v192, v184
	v_fmac_f32_e32 v192, v148, v176
	v_fma_f32 v184, -v164, v192, v184
	v_div_fmas_f32 v184, v184, v176, v192
	v_div_fixup_f32 v148, v184, v156, 1.0
	v_div_scale_f32 v185, vcc, 1.0, v157, 1.0
	v_mul_f32_e32 v193, v185, v177
	v_fma_f32 v149, -v165, v193, v185
	v_fmac_f32_e32 v193, v149, v177
	v_fma_f32 v185, -v165, v193, v185
	v_div_fmas_f32 v185, v185, v177, v193
	v_div_fixup_f32 v149, v185, v157, 1.0
	v_div_scale_f32 v186, vcc, 1.0, v158, 1.0
	v_mul_f32_e32 v194, v186, v178
	v_fma_f32 v150, -v166, v194, v186
	v_fmac_f32_e32 v194, v150, v178
	v_fma_f32 v186, -v166, v194, v186
	v_div_fmas_f32 v186, v186, v178, v194
	v_div_fixup_f32 v150, v186, v158, 1.0
	v_div_scale_f32 v187, vcc, 1.0, v159, 1.0
	v_mul_f32_e32 v195, v187, v179
	v_fma_f32 v151, -v167, v195, v187
	v_fmac_f32_e32 v195, v151, v179
	v_fma_f32 v187, -v167, v195, v187
	v_div_fmas_f32 v187, v187, v179, v195
	v_div_fixup_f32 v151, v187, v159, 1.0
	v_div_scale_f32 v188, vcc, 1.0, v160, 1.0
	v_mul_f32_e32 v196, v188, v180
	v_fma_f32 v152, -v172, v196, v188
	v_fmac_f32_e32 v196, v152, v180
	v_fma_f32 v188, -v172, v196, v188
	v_div_fmas_f32 v188, v188, v180, v196
	v_div_fixup_f32 v152, v188, v160, 1.0
	v_div_scale_f32 v189, vcc, 1.0, v161, 1.0
	v_mul_f32_e32 v197, v189, v181
	v_fma_f32 v153, -v173, v197, v189
	v_fmac_f32_e32 v197, v153, v181
	v_fma_f32 v189, -v173, v197, v189
	v_div_fmas_f32 v189, v189, v181, v197
	v_div_fixup_f32 v153, v189, v161, 1.0
	v_div_scale_f32 v190, vcc, 1.0, v162, 1.0
	v_mul_f32_e32 v198, v190, v182
	v_fma_f32 v154, -v174, v198, v190
	v_fmac_f32_e32 v198, v154, v182
	v_fma_f32 v190, -v174, v198, v190
	v_div_fmas_f32 v190, v190, v182, v198
	v_div_fixup_f32 v154, v190, v162, 1.0
	v_div_scale_f32 v191, vcc, 1.0, v163, 1.0
	v_mul_f32_e32 v199, v191, v183
	v_fma_f32 v155, -v175, v199, v191
	v_fmac_f32_e32 v199, v155, v183
	v_fma_f32 v191, -v175, v199, v191
	v_div_fmas_f32 v191, v191, v183, v199
	v_div_fixup_f32 v155, v191, v163, 1.0
	v_cvt_pk_bf16_f32 v204, v148, v149
	v_cvt_pk_bf16_f32 v205, v150, v151
	v_cvt_pk_bf16_f32 v206, v152, v153
	v_cvt_pk_bf16_f32 v207, v154, v155
	global_store_dwordx4 v243, v[204:207], s[84:85]
	s_add_u32 s84, s84, 0x1000
	s_addc_u32 s85, s85, 0
	v_add_f32_e32 v148, v16, v128
	v_add_f32_e32 v149, v17, v129
	v_add_f32_e32 v150, v18, v130
	v_add_f32_e32 v151, v19, v131
	v_add_f32_e32 v152, v20, v132
	v_add_f32_e32 v153, v21, v133
	v_add_f32_e32 v154, v22, v134
	v_add_f32_e32 v155, v23, v135
	v_mul_f32_e32 v148, 0xbfb8aa3b, v148
	v_mul_f32_e32 v149, 0xbfb8aa3b, v149
	v_mul_f32_e32 v150, 0xbfb8aa3b, v150
	v_mul_f32_e32 v151, 0xbfb8aa3b, v151
	v_mul_f32_e32 v152, 0xbfb8aa3b, v152
	v_mul_f32_e32 v153, 0xbfb8aa3b, v153
	v_mul_f32_e32 v154, 0xbfb8aa3b, v154
	v_mul_f32_e32 v155, 0xbfb8aa3b, v155
	v_exp_f32_e32 v156, v148
	v_exp_f32_e32 v157, v149
	v_exp_f32_e32 v158, v150
	v_exp_f32_e32 v159, v151
	v_exp_f32_e32 v160, v152
	v_exp_f32_e32 v161, v153
	v_exp_f32_e32 v162, v154
	v_exp_f32_e32 v163, v155
	v_add_f32_e32 v156, 1.0, v156
	v_add_f32_e32 v157, 1.0, v157
	v_add_f32_e32 v158, 1.0, v158
	v_add_f32_e32 v159, 1.0, v159
	v_add_f32_e32 v160, 1.0, v160
	v_add_f32_e32 v161, 1.0, v161
	v_add_f32_e32 v162, 1.0, v162
	v_add_f32_e32 v163, 1.0, v163
	v_div_scale_f32 v164, s[76:77], v156, v156, 1.0
	v_div_scale_f32 v165, s[76:77], v157, v157, 1.0
	v_div_scale_f32 v166, s[76:77], v158, v158, 1.0
	v_div_scale_f32 v167, s[76:77], v159, v159, 1.0
	v_div_scale_f32 v172, s[76:77], v160, v160, 1.0
	v_div_scale_f32 v173, s[76:77], v161, v161, 1.0
	v_div_scale_f32 v174, s[76:77], v162, v162, 1.0
	v_div_scale_f32 v175, s[76:77], v163, v163, 1.0
	v_rcp_f32_e32 v176, v164
	v_rcp_f32_e32 v177, v165
	v_rcp_f32_e32 v178, v166
	v_rcp_f32_e32 v179, v167
	v_rcp_f32_e32 v180, v172
	v_rcp_f32_e32 v181, v173
	v_rcp_f32_e32 v182, v174
	v_rcp_f32_e32 v183, v175
	v_fma_f32 v148, -v164, v176, 1.0
	v_fma_f32 v149, -v165, v177, 1.0
	v_fma_f32 v150, -v166, v178, 1.0
	v_fma_f32 v151, -v167, v179, 1.0
	v_fma_f32 v152, -v172, v180, 1.0
	v_fma_f32 v153, -v173, v181, 1.0
	v_fma_f32 v154, -v174, v182, 1.0
	v_fma_f32 v155, -v175, v183, 1.0
	v_fmac_f32_e32 v176, v148, v176
	v_fmac_f32_e32 v177, v149, v177
	v_fmac_f32_e32 v178, v150, v178
	v_fmac_f32_e32 v179, v151, v179
	v_fmac_f32_e32 v180, v152, v180
	v_fmac_f32_e32 v181, v153, v181
	v_fmac_f32_e32 v182, v154, v182
	v_fmac_f32_e32 v183, v155, v183
	v_div_scale_f32 v184, vcc, 1.0, v156, 1.0
	v_mul_f32_e32 v192, v184, v176
	v_fma_f32 v148, -v164, v192, v184
	v_fmac_f32_e32 v192, v148, v176
	v_fma_f32 v184, -v164, v192, v184
	v_div_fmas_f32 v184, v184, v176, v192
	v_div_fixup_f32 v148, v184, v156, 1.0
	v_div_scale_f32 v185, vcc, 1.0, v157, 1.0
	v_mul_f32_e32 v193, v185, v177
	v_fma_f32 v149, -v165, v193, v185
	v_fmac_f32_e32 v193, v149, v177
	v_fma_f32 v185, -v165, v193, v185
	v_div_fmas_f32 v185, v185, v177, v193
	v_div_fixup_f32 v149, v185, v157, 1.0
	v_div_scale_f32 v186, vcc, 1.0, v158, 1.0
	v_mul_f32_e32 v194, v186, v178
	v_fma_f32 v150, -v166, v194, v186
	v_fmac_f32_e32 v194, v150, v178
	v_fma_f32 v186, -v166, v194, v186
	v_div_fmas_f32 v186, v186, v178, v194
	v_div_fixup_f32 v150, v186, v158, 1.0
	v_div_scale_f32 v187, vcc, 1.0, v159, 1.0
	v_mul_f32_e32 v195, v187, v179
	v_fma_f32 v151, -v167, v195, v187
	v_fmac_f32_e32 v195, v151, v179
	v_fma_f32 v187, -v167, v195, v187
	v_div_fmas_f32 v187, v187, v179, v195
	v_div_fixup_f32 v151, v187, v159, 1.0
	v_div_scale_f32 v188, vcc, 1.0, v160, 1.0
	v_mul_f32_e32 v196, v188, v180
	v_fma_f32 v152, -v172, v196, v188
	v_fmac_f32_e32 v196, v152, v180
	v_fma_f32 v188, -v172, v196, v188
	v_div_fmas_f32 v188, v188, v180, v196
	v_div_fixup_f32 v152, v188, v160, 1.0
	v_div_scale_f32 v189, vcc, 1.0, v161, 1.0
	v_mul_f32_e32 v197, v189, v181
	v_fma_f32 v153, -v173, v197, v189
	v_fmac_f32_e32 v197, v153, v181
	v_fma_f32 v189, -v173, v197, v189
	v_div_fmas_f32 v189, v189, v181, v197
	v_div_fixup_f32 v153, v189, v161, 1.0
	v_div_scale_f32 v190, vcc, 1.0, v162, 1.0
	v_mul_f32_e32 v198, v190, v182
	v_fma_f32 v154, -v174, v198, v190
	v_fmac_f32_e32 v198, v154, v182
	v_fma_f32 v190, -v174, v198, v190
	v_div_fmas_f32 v190, v190, v182, v198
	v_div_fixup_f32 v154, v190, v162, 1.0
	v_div_scale_f32 v191, vcc, 1.0, v163, 1.0
	v_mul_f32_e32 v199, v191, v183
	v_fma_f32 v155, -v175, v199, v191
	v_fmac_f32_e32 v199, v155, v183
	v_fma_f32 v191, -v175, v199, v191
	v_div_fmas_f32 v191, v191, v183, v199
	v_div_fixup_f32 v155, v191, v163, 1.0
	v_cvt_pk_bf16_f32 v200, v148, v149
	v_cvt_pk_bf16_f32 v201, v150, v151
	v_cvt_pk_bf16_f32 v202, v152, v153
	v_cvt_pk_bf16_f32 v203, v154, v155
	global_store_dwordx4 v243, v[200:203], s[84:85]
	s_add_u32 s84, s84, 0x1000
	s_addc_u32 s85, s85, 0
	v_add_f32_e32 v148, v24, v136
	v_add_f32_e32 v149, v25, v137
	v_add_f32_e32 v150, v26, v138
	v_add_f32_e32 v151, v27, v139
	v_add_f32_e32 v152, v28, v140
	v_add_f32_e32 v153, v29, v141
	v_add_f32_e32 v154, v30, v142
	v_add_f32_e32 v155, v31, v143
	v_mul_f32_e32 v148, 0xbfb8aa3b, v148
	v_mul_f32_e32 v149, 0xbfb8aa3b, v149
	v_mul_f32_e32 v150, 0xbfb8aa3b, v150
	v_mul_f32_e32 v151, 0xbfb8aa3b, v151
	v_mul_f32_e32 v152, 0xbfb8aa3b, v152
	v_mul_f32_e32 v153, 0xbfb8aa3b, v153
	v_mul_f32_e32 v154, 0xbfb8aa3b, v154
	v_mul_f32_e32 v155, 0xbfb8aa3b, v155
	v_exp_f32_e32 v156, v148
	v_exp_f32_e32 v157, v149
	v_exp_f32_e32 v158, v150
	v_exp_f32_e32 v159, v151
	v_exp_f32_e32 v160, v152
	v_exp_f32_e32 v161, v153
	v_exp_f32_e32 v162, v154
	v_exp_f32_e32 v163, v155
	v_add_f32_e32 v156, 1.0, v156
	v_add_f32_e32 v157, 1.0, v157
	v_add_f32_e32 v158, 1.0, v158
	v_add_f32_e32 v159, 1.0, v159
	v_add_f32_e32 v160, 1.0, v160
	v_add_f32_e32 v161, 1.0, v161
	v_add_f32_e32 v162, 1.0, v162
	v_add_f32_e32 v163, 1.0, v163
	v_div_scale_f32 v164, s[76:77], v156, v156, 1.0
	v_div_scale_f32 v165, s[76:77], v157, v157, 1.0
	v_div_scale_f32 v166, s[76:77], v158, v158, 1.0
	v_div_scale_f32 v167, s[76:77], v159, v159, 1.0
	v_div_scale_f32 v172, s[76:77], v160, v160, 1.0
	v_div_scale_f32 v173, s[76:77], v161, v161, 1.0
	v_div_scale_f32 v174, s[76:77], v162, v162, 1.0
	v_div_scale_f32 v175, s[76:77], v163, v163, 1.0
	v_rcp_f32_e32 v176, v164
	v_rcp_f32_e32 v177, v165
	v_rcp_f32_e32 v178, v166
	v_rcp_f32_e32 v179, v167
	v_rcp_f32_e32 v180, v172
	v_rcp_f32_e32 v181, v173
	v_rcp_f32_e32 v182, v174
	v_rcp_f32_e32 v183, v175
	v_fma_f32 v148, -v164, v176, 1.0
	v_fma_f32 v149, -v165, v177, 1.0
	v_fma_f32 v150, -v166, v178, 1.0
	v_fma_f32 v151, -v167, v179, 1.0
	v_fma_f32 v152, -v172, v180, 1.0
	v_fma_f32 v153, -v173, v181, 1.0
	v_fma_f32 v154, -v174, v182, 1.0
	v_fma_f32 v155, -v175, v183, 1.0
	v_fmac_f32_e32 v176, v148, v176
	v_fmac_f32_e32 v177, v149, v177
	v_fmac_f32_e32 v178, v150, v178
	v_fmac_f32_e32 v179, v151, v179
	v_fmac_f32_e32 v180, v152, v180
	v_fmac_f32_e32 v181, v153, v181
	v_fmac_f32_e32 v182, v154, v182
	v_fmac_f32_e32 v183, v155, v183
	v_div_scale_f32 v184, vcc, 1.0, v156, 1.0
	v_mul_f32_e32 v192, v184, v176
	v_fma_f32 v148, -v164, v192, v184
	v_fmac_f32_e32 v192, v148, v176
	v_fma_f32 v184, -v164, v192, v184
	v_div_fmas_f32 v184, v184, v176, v192
	v_div_fixup_f32 v148, v184, v156, 1.0
	v_div_scale_f32 v185, vcc, 1.0, v157, 1.0
	v_mul_f32_e32 v193, v185, v177
	v_fma_f32 v149, -v165, v193, v185
	v_fmac_f32_e32 v193, v149, v177
	v_fma_f32 v185, -v165, v193, v185
	v_div_fmas_f32 v185, v185, v177, v193
	v_div_fixup_f32 v149, v185, v157, 1.0
	v_div_scale_f32 v186, vcc, 1.0, v158, 1.0
	v_mul_f32_e32 v194, v186, v178
	v_fma_f32 v150, -v166, v194, v186
	v_fmac_f32_e32 v194, v150, v178
	v_fma_f32 v186, -v166, v194, v186
	v_div_fmas_f32 v186, v186, v178, v194
	v_div_fixup_f32 v150, v186, v158, 1.0
	v_div_scale_f32 v187, vcc, 1.0, v159, 1.0
	v_mul_f32_e32 v195, v187, v179
	v_fma_f32 v151, -v167, v195, v187
	v_fmac_f32_e32 v195, v151, v179
	v_fma_f32 v187, -v167, v195, v187
	v_div_fmas_f32 v187, v187, v179, v195
	v_div_fixup_f32 v151, v187, v159, 1.0
	v_div_scale_f32 v188, vcc, 1.0, v160, 1.0
	v_mul_f32_e32 v196, v188, v180
	v_fma_f32 v152, -v172, v196, v188
	v_fmac_f32_e32 v196, v152, v180
	v_fma_f32 v188, -v172, v196, v188
	v_div_fmas_f32 v188, v188, v180, v196
	v_div_fixup_f32 v152, v188, v160, 1.0
	v_div_scale_f32 v189, vcc, 1.0, v161, 1.0
	v_mul_f32_e32 v197, v189, v181
	v_fma_f32 v153, -v173, v197, v189
	v_fmac_f32_e32 v197, v153, v181
	v_fma_f32 v189, -v173, v197, v189
	v_div_fmas_f32 v189, v189, v181, v197
	v_div_fixup_f32 v153, v189, v161, 1.0
	v_div_scale_f32 v190, vcc, 1.0, v162, 1.0
	v_mul_f32_e32 v198, v190, v182
	v_fma_f32 v154, -v174, v198, v190
	v_fmac_f32_e32 v198, v154, v182
	v_fma_f32 v190, -v174, v198, v190
	v_div_fmas_f32 v190, v190, v182, v198
	v_div_fixup_f32 v154, v190, v162, 1.0
	v_div_scale_f32 v191, vcc, 1.0, v163, 1.0
	v_mul_f32_e32 v199, v191, v183
	v_fma_f32 v155, -v175, v199, v191
	v_fmac_f32_e32 v199, v155, v183
	v_fma_f32 v191, -v175, v199, v191
	v_div_fmas_f32 v191, v191, v183, v199
	v_div_fixup_f32 v155, v191, v163, 1.0
	v_cvt_pk_bf16_f32 v204, v148, v149
	v_cvt_pk_bf16_f32 v205, v150, v151
	v_cvt_pk_bf16_f32 v206, v152, v153
	v_cvt_pk_bf16_f32 v207, v154, v155
	global_store_dwordx4 v243, v[204:207], s[84:85]
	s_add_u32 s84, s84, 0x1000
	s_addc_u32 s85, s85, 0
	v_add_f32_e32 v148, v32, v128
	v_add_f32_e32 v149, v33, v129
	v_add_f32_e32 v150, v34, v130
	v_add_f32_e32 v151, v35, v131
	v_add_f32_e32 v152, v36, v132
	v_add_f32_e32 v153, v37, v133
	v_add_f32_e32 v154, v38, v134
	v_add_f32_e32 v155, v39, v135
	v_mul_f32_e32 v148, 0xbfb8aa3b, v148
	v_mul_f32_e32 v149, 0xbfb8aa3b, v149
	v_mul_f32_e32 v150, 0xbfb8aa3b, v150
	v_mul_f32_e32 v151, 0xbfb8aa3b, v151
	v_mul_f32_e32 v152, 0xbfb8aa3b, v152
	v_mul_f32_e32 v153, 0xbfb8aa3b, v153
	v_mul_f32_e32 v154, 0xbfb8aa3b, v154
	v_mul_f32_e32 v155, 0xbfb8aa3b, v155
	v_exp_f32_e32 v156, v148
	v_exp_f32_e32 v157, v149
	v_exp_f32_e32 v158, v150
	v_exp_f32_e32 v159, v151
	v_exp_f32_e32 v160, v152
	v_exp_f32_e32 v161, v153
	v_exp_f32_e32 v162, v154
	v_exp_f32_e32 v163, v155
	v_add_f32_e32 v156, 1.0, v156
	v_add_f32_e32 v157, 1.0, v157
	v_add_f32_e32 v158, 1.0, v158
	v_add_f32_e32 v159, 1.0, v159
	v_add_f32_e32 v160, 1.0, v160
	v_add_f32_e32 v161, 1.0, v161
	v_add_f32_e32 v162, 1.0, v162
	v_add_f32_e32 v163, 1.0, v163
	v_div_scale_f32 v164, s[76:77], v156, v156, 1.0
	v_div_scale_f32 v165, s[76:77], v157, v157, 1.0
	v_div_scale_f32 v166, s[76:77], v158, v158, 1.0
	v_div_scale_f32 v167, s[76:77], v159, v159, 1.0
	v_div_scale_f32 v172, s[76:77], v160, v160, 1.0
	v_div_scale_f32 v173, s[76:77], v161, v161, 1.0
	v_div_scale_f32 v174, s[76:77], v162, v162, 1.0
	v_div_scale_f32 v175, s[76:77], v163, v163, 1.0
	v_rcp_f32_e32 v176, v164
	v_rcp_f32_e32 v177, v165
	v_rcp_f32_e32 v178, v166
	v_rcp_f32_e32 v179, v167
	v_rcp_f32_e32 v180, v172
	v_rcp_f32_e32 v181, v173
	v_rcp_f32_e32 v182, v174
	v_rcp_f32_e32 v183, v175
	v_fma_f32 v148, -v164, v176, 1.0
	v_fma_f32 v149, -v165, v177, 1.0
	v_fma_f32 v150, -v166, v178, 1.0
	v_fma_f32 v151, -v167, v179, 1.0
	v_fma_f32 v152, -v172, v180, 1.0
	v_fma_f32 v153, -v173, v181, 1.0
	v_fma_f32 v154, -v174, v182, 1.0
	v_fma_f32 v155, -v175, v183, 1.0
	v_fmac_f32_e32 v176, v148, v176
	v_fmac_f32_e32 v177, v149, v177
	v_fmac_f32_e32 v178, v150, v178
	v_fmac_f32_e32 v179, v151, v179
	v_fmac_f32_e32 v180, v152, v180
	v_fmac_f32_e32 v181, v153, v181
	v_fmac_f32_e32 v182, v154, v182
	v_fmac_f32_e32 v183, v155, v183
	v_div_scale_f32 v184, vcc, 1.0, v156, 1.0
	v_mul_f32_e32 v192, v184, v176
	v_fma_f32 v148, -v164, v192, v184
	v_fmac_f32_e32 v192, v148, v176
	v_fma_f32 v184, -v164, v192, v184
	v_div_fmas_f32 v184, v184, v176, v192
	v_div_fixup_f32 v148, v184, v156, 1.0
	v_div_scale_f32 v185, vcc, 1.0, v157, 1.0
	v_mul_f32_e32 v193, v185, v177
	v_fma_f32 v149, -v165, v193, v185
	v_fmac_f32_e32 v193, v149, v177
	v_fma_f32 v185, -v165, v193, v185
	v_div_fmas_f32 v185, v185, v177, v193
	v_div_fixup_f32 v149, v185, v157, 1.0
	v_div_scale_f32 v186, vcc, 1.0, v158, 1.0
	v_mul_f32_e32 v194, v186, v178
	v_fma_f32 v150, -v166, v194, v186
	v_fmac_f32_e32 v194, v150, v178
	v_fma_f32 v186, -v166, v194, v186
	v_div_fmas_f32 v186, v186, v178, v194
	v_div_fixup_f32 v150, v186, v158, 1.0
	v_div_scale_f32 v187, vcc, 1.0, v159, 1.0
	v_mul_f32_e32 v195, v187, v179
	v_fma_f32 v151, -v167, v195, v187
	v_fmac_f32_e32 v195, v151, v179
	v_fma_f32 v187, -v167, v195, v187
	v_div_fmas_f32 v187, v187, v179, v195
	v_div_fixup_f32 v151, v187, v159, 1.0
	v_div_scale_f32 v188, vcc, 1.0, v160, 1.0
	v_mul_f32_e32 v196, v188, v180
	v_fma_f32 v152, -v172, v196, v188
	v_fmac_f32_e32 v196, v152, v180
	v_fma_f32 v188, -v172, v196, v188
	v_div_fmas_f32 v188, v188, v180, v196
	v_div_fixup_f32 v152, v188, v160, 1.0
	v_div_scale_f32 v189, vcc, 1.0, v161, 1.0
	v_mul_f32_e32 v197, v189, v181
	v_fma_f32 v153, -v173, v197, v189
	v_fmac_f32_e32 v197, v153, v181
	v_fma_f32 v189, -v173, v197, v189
	v_div_fmas_f32 v189, v189, v181, v197
	v_div_fixup_f32 v153, v189, v161, 1.0
	v_div_scale_f32 v190, vcc, 1.0, v162, 1.0
	v_mul_f32_e32 v198, v190, v182
	v_fma_f32 v154, -v174, v198, v190
	v_fmac_f32_e32 v198, v154, v182
	v_fma_f32 v190, -v174, v198, v190
	v_div_fmas_f32 v190, v190, v182, v198
	v_div_fixup_f32 v154, v190, v162, 1.0
	v_div_scale_f32 v191, vcc, 1.0, v163, 1.0
	v_mul_f32_e32 v199, v191, v183
	v_fma_f32 v155, -v175, v199, v191
	v_fmac_f32_e32 v199, v155, v183
	v_fma_f32 v191, -v175, v199, v191
	v_div_fmas_f32 v191, v191, v183, v199
	v_div_fixup_f32 v155, v191, v163, 1.0
	v_cvt_pk_bf16_f32 v200, v148, v149
	v_cvt_pk_bf16_f32 v201, v150, v151
	v_cvt_pk_bf16_f32 v202, v152, v153
	v_cvt_pk_bf16_f32 v203, v154, v155
	global_store_dwordx4 v243, v[200:203], s[84:85]
	s_add_u32 s84, s84, 0x1000
	s_addc_u32 s85, s85, 0
	v_add_f32_e32 v148, v40, v136
	v_add_f32_e32 v149, v41, v137
	v_add_f32_e32 v150, v42, v138
	v_add_f32_e32 v151, v43, v139
	v_add_f32_e32 v152, v44, v140
	v_add_f32_e32 v153, v45, v141
	v_add_f32_e32 v154, v46, v142
	v_add_f32_e32 v155, v47, v143
	v_mul_f32_e32 v148, 0xbfb8aa3b, v148
	v_mul_f32_e32 v149, 0xbfb8aa3b, v149
	v_mul_f32_e32 v150, 0xbfb8aa3b, v150
	v_mul_f32_e32 v151, 0xbfb8aa3b, v151
	v_mul_f32_e32 v152, 0xbfb8aa3b, v152
	v_mul_f32_e32 v153, 0xbfb8aa3b, v153
	v_mul_f32_e32 v154, 0xbfb8aa3b, v154
	v_mul_f32_e32 v155, 0xbfb8aa3b, v155
	v_exp_f32_e32 v156, v148
	v_exp_f32_e32 v157, v149
	v_exp_f32_e32 v158, v150
	v_exp_f32_e32 v159, v151
	v_exp_f32_e32 v160, v152
	v_exp_f32_e32 v161, v153
	v_exp_f32_e32 v162, v154
	v_exp_f32_e32 v163, v155
	v_add_f32_e32 v156, 1.0, v156
	v_add_f32_e32 v157, 1.0, v157
	v_add_f32_e32 v158, 1.0, v158
	v_add_f32_e32 v159, 1.0, v159
	v_add_f32_e32 v160, 1.0, v160
	v_add_f32_e32 v161, 1.0, v161
	v_add_f32_e32 v162, 1.0, v162
	v_add_f32_e32 v163, 1.0, v163
	v_div_scale_f32 v164, s[76:77], v156, v156, 1.0
	v_div_scale_f32 v165, s[76:77], v157, v157, 1.0
	v_div_scale_f32 v166, s[76:77], v158, v158, 1.0
	v_div_scale_f32 v167, s[76:77], v159, v159, 1.0
	v_div_scale_f32 v172, s[76:77], v160, v160, 1.0
	v_div_scale_f32 v173, s[76:77], v161, v161, 1.0
	v_div_scale_f32 v174, s[76:77], v162, v162, 1.0
	v_div_scale_f32 v175, s[76:77], v163, v163, 1.0
	v_rcp_f32_e32 v176, v164
	v_rcp_f32_e32 v177, v165
	v_rcp_f32_e32 v178, v166
	v_rcp_f32_e32 v179, v167
	v_rcp_f32_e32 v180, v172
	v_rcp_f32_e32 v181, v173
	v_rcp_f32_e32 v182, v174
	v_rcp_f32_e32 v183, v175
	v_fma_f32 v148, -v164, v176, 1.0
	v_fma_f32 v149, -v165, v177, 1.0
	v_fma_f32 v150, -v166, v178, 1.0
	v_fma_f32 v151, -v167, v179, 1.0
	v_fma_f32 v152, -v172, v180, 1.0
	v_fma_f32 v153, -v173, v181, 1.0
	v_fma_f32 v154, -v174, v182, 1.0
	v_fma_f32 v155, -v175, v183, 1.0
	v_fmac_f32_e32 v176, v148, v176
	v_fmac_f32_e32 v177, v149, v177
	v_fmac_f32_e32 v178, v150, v178
	v_fmac_f32_e32 v179, v151, v179
	v_fmac_f32_e32 v180, v152, v180
	v_fmac_f32_e32 v181, v153, v181
	v_fmac_f32_e32 v182, v154, v182
	v_fmac_f32_e32 v183, v155, v183
	v_div_scale_f32 v184, vcc, 1.0, v156, 1.0
	v_mul_f32_e32 v192, v184, v176
	v_fma_f32 v148, -v164, v192, v184
	v_fmac_f32_e32 v192, v148, v176
	v_fma_f32 v184, -v164, v192, v184
	v_div_fmas_f32 v184, v184, v176, v192
	v_div_fixup_f32 v148, v184, v156, 1.0
	v_div_scale_f32 v185, vcc, 1.0, v157, 1.0
	v_mul_f32_e32 v193, v185, v177
	v_fma_f32 v149, -v165, v193, v185
	v_fmac_f32_e32 v193, v149, v177
	v_fma_f32 v185, -v165, v193, v185
	v_div_fmas_f32 v185, v185, v177, v193
	v_div_fixup_f32 v149, v185, v157, 1.0
	v_div_scale_f32 v186, vcc, 1.0, v158, 1.0
	v_mul_f32_e32 v194, v186, v178
	v_fma_f32 v150, -v166, v194, v186
	v_fmac_f32_e32 v194, v150, v178
	v_fma_f32 v186, -v166, v194, v186
	v_div_fmas_f32 v186, v186, v178, v194
	v_div_fixup_f32 v150, v186, v158, 1.0
	v_div_scale_f32 v187, vcc, 1.0, v159, 1.0
	v_mul_f32_e32 v195, v187, v179
	v_fma_f32 v151, -v167, v195, v187
	v_fmac_f32_e32 v195, v151, v179
	v_fma_f32 v187, -v167, v195, v187
	v_div_fmas_f32 v187, v187, v179, v195
	v_div_fixup_f32 v151, v187, v159, 1.0
	v_div_scale_f32 v188, vcc, 1.0, v160, 1.0
	v_mul_f32_e32 v196, v188, v180
	v_fma_f32 v152, -v172, v196, v188
	v_fmac_f32_e32 v196, v152, v180
	v_fma_f32 v188, -v172, v196, v188
	v_div_fmas_f32 v188, v188, v180, v196
	v_div_fixup_f32 v152, v188, v160, 1.0
	v_div_scale_f32 v189, vcc, 1.0, v161, 1.0
	v_mul_f32_e32 v197, v189, v181
	v_fma_f32 v153, -v173, v197, v189
	v_fmac_f32_e32 v197, v153, v181
	v_fma_f32 v189, -v173, v197, v189
	v_div_fmas_f32 v189, v189, v181, v197
	v_div_fixup_f32 v153, v189, v161, 1.0
	v_div_scale_f32 v190, vcc, 1.0, v162, 1.0
	v_mul_f32_e32 v198, v190, v182
	v_fma_f32 v154, -v174, v198, v190
	v_fmac_f32_e32 v198, v154, v182
	v_fma_f32 v190, -v174, v198, v190
	v_div_fmas_f32 v190, v190, v182, v198
	v_div_fixup_f32 v154, v190, v162, 1.0
	v_div_scale_f32 v191, vcc, 1.0, v163, 1.0
	v_mul_f32_e32 v199, v191, v183
	v_fma_f32 v155, -v175, v199, v191
	v_fmac_f32_e32 v199, v155, v183
	v_fma_f32 v191, -v175, v199, v191
	v_div_fmas_f32 v191, v191, v183, v199
	v_div_fixup_f32 v155, v191, v163, 1.0
	v_cvt_pk_bf16_f32 v204, v148, v149
	v_cvt_pk_bf16_f32 v205, v150, v151
	v_cvt_pk_bf16_f32 v206, v152, v153
	v_cvt_pk_bf16_f32 v207, v154, v155
	global_store_dwordx4 v243, v[204:207], s[84:85]
	s_add_u32 s84, s84, 0x1000
	s_addc_u32 s85, s85, 0
	v_add_f32_e32 v148, v48, v128
	v_add_f32_e32 v149, v49, v129
	v_add_f32_e32 v150, v50, v130
	v_add_f32_e32 v151, v51, v131
	v_add_f32_e32 v152, v52, v132
	v_add_f32_e32 v153, v53, v133
	v_add_f32_e32 v154, v54, v134
	v_add_f32_e32 v155, v55, v135
	v_mul_f32_e32 v148, 0xbfb8aa3b, v148
	v_mul_f32_e32 v149, 0xbfb8aa3b, v149
	v_mul_f32_e32 v150, 0xbfb8aa3b, v150
	v_mul_f32_e32 v151, 0xbfb8aa3b, v151
	v_mul_f32_e32 v152, 0xbfb8aa3b, v152
	v_mul_f32_e32 v153, 0xbfb8aa3b, v153
	v_mul_f32_e32 v154, 0xbfb8aa3b, v154
	v_mul_f32_e32 v155, 0xbfb8aa3b, v155
	v_exp_f32_e32 v156, v148
	v_exp_f32_e32 v157, v149
	v_exp_f32_e32 v158, v150
	v_exp_f32_e32 v159, v151
	v_exp_f32_e32 v160, v152
	v_exp_f32_e32 v161, v153
	v_exp_f32_e32 v162, v154
	v_exp_f32_e32 v163, v155
	v_add_f32_e32 v156, 1.0, v156
	v_add_f32_e32 v157, 1.0, v157
	v_add_f32_e32 v158, 1.0, v158
	v_add_f32_e32 v159, 1.0, v159
	v_add_f32_e32 v160, 1.0, v160
	v_add_f32_e32 v161, 1.0, v161
	v_add_f32_e32 v162, 1.0, v162
	v_add_f32_e32 v163, 1.0, v163
	v_div_scale_f32 v164, s[76:77], v156, v156, 1.0
	v_div_scale_f32 v165, s[76:77], v157, v157, 1.0
	v_div_scale_f32 v166, s[76:77], v158, v158, 1.0
	v_div_scale_f32 v167, s[76:77], v159, v159, 1.0
	v_div_scale_f32 v172, s[76:77], v160, v160, 1.0
	v_div_scale_f32 v173, s[76:77], v161, v161, 1.0
	v_div_scale_f32 v174, s[76:77], v162, v162, 1.0
	v_div_scale_f32 v175, s[76:77], v163, v163, 1.0
	v_rcp_f32_e32 v176, v164
	v_rcp_f32_e32 v177, v165
	v_rcp_f32_e32 v178, v166
	v_rcp_f32_e32 v179, v167
	v_rcp_f32_e32 v180, v172
	v_rcp_f32_e32 v181, v173
	v_rcp_f32_e32 v182, v174
	v_rcp_f32_e32 v183, v175
	v_fma_f32 v148, -v164, v176, 1.0
	v_fma_f32 v149, -v165, v177, 1.0
	v_fma_f32 v150, -v166, v178, 1.0
	v_fma_f32 v151, -v167, v179, 1.0
	v_fma_f32 v152, -v172, v180, 1.0
	v_fma_f32 v153, -v173, v181, 1.0
	v_fma_f32 v154, -v174, v182, 1.0
	v_fma_f32 v155, -v175, v183, 1.0
	v_fmac_f32_e32 v176, v148, v176
	v_fmac_f32_e32 v177, v149, v177
	v_fmac_f32_e32 v178, v150, v178
	v_fmac_f32_e32 v179, v151, v179
	v_fmac_f32_e32 v180, v152, v180
	v_fmac_f32_e32 v181, v153, v181
	v_fmac_f32_e32 v182, v154, v182
	v_fmac_f32_e32 v183, v155, v183
	v_div_scale_f32 v184, vcc, 1.0, v156, 1.0
	v_mul_f32_e32 v192, v184, v176
	v_fma_f32 v148, -v164, v192, v184
	v_fmac_f32_e32 v192, v148, v176
	v_fma_f32 v184, -v164, v192, v184
	v_div_fmas_f32 v184, v184, v176, v192
	v_div_fixup_f32 v148, v184, v156, 1.0
	v_div_scale_f32 v185, vcc, 1.0, v157, 1.0
	v_mul_f32_e32 v193, v185, v177
	v_fma_f32 v149, -v165, v193, v185
	v_fmac_f32_e32 v193, v149, v177
	v_fma_f32 v185, -v165, v193, v185
	v_div_fmas_f32 v185, v185, v177, v193
	v_div_fixup_f32 v149, v185, v157, 1.0
	v_div_scale_f32 v186, vcc, 1.0, v158, 1.0
	v_mul_f32_e32 v194, v186, v178
	v_fma_f32 v150, -v166, v194, v186
	v_fmac_f32_e32 v194, v150, v178
	v_fma_f32 v186, -v166, v194, v186
	v_div_fmas_f32 v186, v186, v178, v194
	v_div_fixup_f32 v150, v186, v158, 1.0
	v_div_scale_f32 v187, vcc, 1.0, v159, 1.0
	v_mul_f32_e32 v195, v187, v179
	v_fma_f32 v151, -v167, v195, v187
	v_fmac_f32_e32 v195, v151, v179
	v_fma_f32 v187, -v167, v195, v187
	v_div_fmas_f32 v187, v187, v179, v195
	v_div_fixup_f32 v151, v187, v159, 1.0
	v_div_scale_f32 v188, vcc, 1.0, v160, 1.0
	v_mul_f32_e32 v196, v188, v180
	v_fma_f32 v152, -v172, v196, v188
	v_fmac_f32_e32 v196, v152, v180
	v_fma_f32 v188, -v172, v196, v188
	v_div_fmas_f32 v188, v188, v180, v196
	v_div_fixup_f32 v152, v188, v160, 1.0
	v_div_scale_f32 v189, vcc, 1.0, v161, 1.0
	v_mul_f32_e32 v197, v189, v181
	v_fma_f32 v153, -v173, v197, v189
	v_fmac_f32_e32 v197, v153, v181
	v_fma_f32 v189, -v173, v197, v189
	v_div_fmas_f32 v189, v189, v181, v197
	v_div_fixup_f32 v153, v189, v161, 1.0
	v_div_scale_f32 v190, vcc, 1.0, v162, 1.0
	v_mul_f32_e32 v198, v190, v182
	v_fma_f32 v154, -v174, v198, v190
	v_fmac_f32_e32 v198, v154, v182
	v_fma_f32 v190, -v174, v198, v190
	v_div_fmas_f32 v190, v190, v182, v198
	v_div_fixup_f32 v154, v190, v162, 1.0
	v_div_scale_f32 v191, vcc, 1.0, v163, 1.0
	v_mul_f32_e32 v199, v191, v183
	v_fma_f32 v155, -v175, v199, v191
	v_fmac_f32_e32 v199, v155, v183
	v_fma_f32 v191, -v175, v199, v191
	v_div_fmas_f32 v191, v191, v183, v199
	v_div_fixup_f32 v155, v191, v163, 1.0
	v_cvt_pk_bf16_f32 v200, v148, v149
	v_cvt_pk_bf16_f32 v201, v150, v151
	v_cvt_pk_bf16_f32 v202, v152, v153
	v_cvt_pk_bf16_f32 v203, v154, v155
	global_store_dwordx4 v243, v[200:203], s[84:85]
	s_add_u32 s84, s84, 0x1000
	s_addc_u32 s85, s85, 0
	v_add_f32_e32 v148, v56, v136
	v_add_f32_e32 v149, v57, v137
	v_add_f32_e32 v150, v58, v138
	v_add_f32_e32 v151, v59, v139
	v_add_f32_e32 v152, v60, v140
	v_add_f32_e32 v153, v61, v141
	v_add_f32_e32 v154, v62, v142
	v_add_f32_e32 v155, v63, v143
	v_mul_f32_e32 v148, 0xbfb8aa3b, v148
	v_mul_f32_e32 v149, 0xbfb8aa3b, v149
	v_mul_f32_e32 v150, 0xbfb8aa3b, v150
	v_mul_f32_e32 v151, 0xbfb8aa3b, v151
	v_mul_f32_e32 v152, 0xbfb8aa3b, v152
	v_mul_f32_e32 v153, 0xbfb8aa3b, v153
	v_mul_f32_e32 v154, 0xbfb8aa3b, v154
	v_mul_f32_e32 v155, 0xbfb8aa3b, v155
	v_exp_f32_e32 v156, v148
	v_exp_f32_e32 v157, v149
	v_exp_f32_e32 v158, v150
	v_exp_f32_e32 v159, v151
	v_exp_f32_e32 v160, v152
	v_exp_f32_e32 v161, v153
	v_exp_f32_e32 v162, v154
	v_exp_f32_e32 v163, v155
	v_add_f32_e32 v156, 1.0, v156
	v_add_f32_e32 v157, 1.0, v157
	v_add_f32_e32 v158, 1.0, v158
	v_add_f32_e32 v159, 1.0, v159
	v_add_f32_e32 v160, 1.0, v160
	v_add_f32_e32 v161, 1.0, v161
	v_add_f32_e32 v162, 1.0, v162
	v_add_f32_e32 v163, 1.0, v163
	v_div_scale_f32 v164, s[76:77], v156, v156, 1.0
	v_div_scale_f32 v165, s[76:77], v157, v157, 1.0
	v_div_scale_f32 v166, s[76:77], v158, v158, 1.0
	v_div_scale_f32 v167, s[76:77], v159, v159, 1.0
	v_div_scale_f32 v172, s[76:77], v160, v160, 1.0
	v_div_scale_f32 v173, s[76:77], v161, v161, 1.0
	v_div_scale_f32 v174, s[76:77], v162, v162, 1.0
	v_div_scale_f32 v175, s[76:77], v163, v163, 1.0
	v_rcp_f32_e32 v176, v164
	v_rcp_f32_e32 v177, v165
	v_rcp_f32_e32 v178, v166
	v_rcp_f32_e32 v179, v167
	v_rcp_f32_e32 v180, v172
	v_rcp_f32_e32 v181, v173
	v_rcp_f32_e32 v182, v174
	v_rcp_f32_e32 v183, v175
	v_fma_f32 v148, -v164, v176, 1.0
	v_fma_f32 v149, -v165, v177, 1.0
	v_fma_f32 v150, -v166, v178, 1.0
	v_fma_f32 v151, -v167, v179, 1.0
	v_fma_f32 v152, -v172, v180, 1.0
	v_fma_f32 v153, -v173, v181, 1.0
	v_fma_f32 v154, -v174, v182, 1.0
	v_fma_f32 v155, -v175, v183, 1.0
	v_fmac_f32_e32 v176, v148, v176
	v_fmac_f32_e32 v177, v149, v177
	v_fmac_f32_e32 v178, v150, v178
	v_fmac_f32_e32 v179, v151, v179
	v_fmac_f32_e32 v180, v152, v180
	v_fmac_f32_e32 v181, v153, v181
	v_fmac_f32_e32 v182, v154, v182
	v_fmac_f32_e32 v183, v155, v183
	v_div_scale_f32 v184, vcc, 1.0, v156, 1.0
	v_mul_f32_e32 v192, v184, v176
	v_fma_f32 v148, -v164, v192, v184
	v_fmac_f32_e32 v192, v148, v176
	v_fma_f32 v184, -v164, v192, v184
	v_div_fmas_f32 v184, v184, v176, v192
	v_div_fixup_f32 v148, v184, v156, 1.0
	v_div_scale_f32 v185, vcc, 1.0, v157, 1.0
	v_mul_f32_e32 v193, v185, v177
	v_fma_f32 v149, -v165, v193, v185
	v_fmac_f32_e32 v193, v149, v177
	v_fma_f32 v185, -v165, v193, v185
	v_div_fmas_f32 v185, v185, v177, v193
	v_div_fixup_f32 v149, v185, v157, 1.0
	v_div_scale_f32 v186, vcc, 1.0, v158, 1.0
	v_mul_f32_e32 v194, v186, v178
	v_fma_f32 v150, -v166, v194, v186
	v_fmac_f32_e32 v194, v150, v178
	v_fma_f32 v186, -v166, v194, v186
	v_div_fmas_f32 v186, v186, v178, v194
	v_div_fixup_f32 v150, v186, v158, 1.0
	v_div_scale_f32 v187, vcc, 1.0, v159, 1.0
	v_mul_f32_e32 v195, v187, v179
	v_fma_f32 v151, -v167, v195, v187
	v_fmac_f32_e32 v195, v151, v179
	v_fma_f32 v187, -v167, v195, v187
	v_div_fmas_f32 v187, v187, v179, v195
	v_div_fixup_f32 v151, v187, v159, 1.0
	v_div_scale_f32 v188, vcc, 1.0, v160, 1.0
	v_mul_f32_e32 v196, v188, v180
	v_fma_f32 v152, -v172, v196, v188
	v_fmac_f32_e32 v196, v152, v180
	v_fma_f32 v188, -v172, v196, v188
	v_div_fmas_f32 v188, v188, v180, v196
	v_div_fixup_f32 v152, v188, v160, 1.0
	v_div_scale_f32 v189, vcc, 1.0, v161, 1.0
	v_mul_f32_e32 v197, v189, v181
	v_fma_f32 v153, -v173, v197, v189
	v_fmac_f32_e32 v197, v153, v181
	v_fma_f32 v189, -v173, v197, v189
	v_div_fmas_f32 v189, v189, v181, v197
	v_div_fixup_f32 v153, v189, v161, 1.0
	v_div_scale_f32 v190, vcc, 1.0, v162, 1.0
	v_mul_f32_e32 v198, v190, v182
	v_fma_f32 v154, -v174, v198, v190
	v_fmac_f32_e32 v198, v154, v182
	v_fma_f32 v190, -v174, v198, v190
	v_div_fmas_f32 v190, v190, v182, v198
	v_div_fixup_f32 v154, v190, v162, 1.0
	v_div_scale_f32 v191, vcc, 1.0, v163, 1.0
	v_mul_f32_e32 v199, v191, v183
	v_fma_f32 v155, -v175, v199, v191
	v_fmac_f32_e32 v199, v155, v183
	v_fma_f32 v191, -v175, v199, v191
	v_div_fmas_f32 v191, v191, v183, v199
	v_div_fixup_f32 v155, v191, v163, 1.0
	v_cvt_pk_bf16_f32 v204, v148, v149
	v_cvt_pk_bf16_f32 v205, v150, v151
	v_cvt_pk_bf16_f32 v206, v152, v153
	v_cvt_pk_bf16_f32 v207, v154, v155
	global_store_dwordx4 v243, v[204:207], s[84:85]
	s_add_u32 s84, s84, 0x1000
	s_addc_u32 s85, s85, 0
	s_cmp_eq_u32 s83, 1
	s_cbranch_scc1 .Lp6a_epdone
	s_cmp_eq_u32 s95, 1
	s_cbranch_scc0 .Lp6a_epdone
	v_mov_b32_e32 v0, v64
	v_mov_b32_e32 v1, v65
	v_mov_b32_e32 v2, v66
	v_mov_b32_e32 v3, v67
	v_mov_b32_e32 v4, v68
	v_mov_b32_e32 v5, v69
	v_mov_b32_e32 v6, v70
	v_mov_b32_e32 v7, v71
	v_mov_b32_e32 v8, v72
	v_mov_b32_e32 v9, v73
	v_mov_b32_e32 v10, v74
	v_mov_b32_e32 v11, v75
	v_mov_b32_e32 v12, v76
	v_mov_b32_e32 v13, v77
	v_mov_b32_e32 v14, v78
	v_mov_b32_e32 v15, v79
	v_mov_b32_e32 v16, v80
	v_mov_b32_e32 v17, v81
	v_mov_b32_e32 v18, v82
	v_mov_b32_e32 v19, v83
	v_mov_b32_e32 v20, v84
	v_mov_b32_e32 v21, v85
	v_mov_b32_e32 v22, v86
	v_mov_b32_e32 v23, v87
	v_mov_b32_e32 v24, v88
	v_mov_b32_e32 v25, v89
	v_mov_b32_e32 v26, v90
	v_mov_b32_e32 v27, v91
	v_mov_b32_e32 v28, v92
	v_mov_b32_e32 v29, v93
	v_mov_b32_e32 v30, v94
	v_mov_b32_e32 v31, v95
	v_mov_b32_e32 v32, v96
	v_mov_b32_e32 v33, v97
	v_mov_b32_e32 v34, v98
	v_mov_b32_e32 v35, v99
	v_mov_b32_e32 v36, v100
	v_mov_b32_e32 v37, v101
	v_mov_b32_e32 v38, v102
	v_mov_b32_e32 v39, v103
	v_mov_b32_e32 v40, v104
	v_mov_b32_e32 v41, v105
	v_mov_b32_e32 v42, v106
	v_mov_b32_e32 v43, v107
	v_mov_b32_e32 v44, v108
	v_mov_b32_e32 v45, v109
	v_mov_b32_e32 v46, v110
	v_mov_b32_e32 v47, v111
	v_mov_b32_e32 v48, v112
	v_mov_b32_e32 v49, v113
	v_mov_b32_e32 v50, v114
	v_mov_b32_e32 v51, v115
	v_mov_b32_e32 v52, v116
	v_mov_b32_e32 v53, v117
	v_mov_b32_e32 v54, v118
	v_mov_b32_e32 v55, v119
	v_mov_b32_e32 v56, v120
	v_mov_b32_e32 v57, v121
	v_mov_b32_e32 v58, v122
	v_mov_b32_e32 v59, v123
	v_mov_b32_e32 v60, v124
	v_mov_b32_e32 v61, v125
	v_mov_b32_e32 v62, v126
	v_mov_b32_e32 v63, v127
	s_mov_b32 s83, 1
	s_branch .Lp6a_ep

.Lp6b_ep:
	s_lshl_b32 s71, s83, 25
	s_add_u32 s86, s24, s71
	s_addc_u32 s87, s25, 0
	s_lshl_b32 s71, s83, 25
	s_add_u32 s84, s24, s71
	s_addc_u32 s85, s25, 0
	global_load_dwordx4 v[128:131], v243, s[86:87]
	s_add_u32 s86, s86, 0x1000
	s_addc_u32 s87, s87, 0
	global_load_dwordx4 v[132:135], v243, s[86:87]
	s_add_u32 s86, s86, 0x1000
	s_addc_u32 s87, s87, 0
	global_load_dwordx4 v[136:139], v243, s[86:87]
	s_add_u32 s86, s86, 0x1000
	s_addc_u32 s87, s87, 0
	global_load_dwordx4 v[140:143], v243, s[86:87]
	s_add_u32 s86, s86, 0x1000
	s_addc_u32 s87, s87, 0
	global_load_dwordx4 v[148:151], v243, s[86:87]
	s_add_u32 s86, s86, 0x1000
	s_addc_u32 s87, s87, 0
	global_load_dwordx4 v[152:155], v243, s[86:87]
	s_add_u32 s86, s86, 0x1000
	s_addc_u32 s87, s87, 0
	global_load_dwordx4 v[156:159], v243, s[86:87]
	s_add_u32 s86, s86, 0x1000
	s_addc_u32 s87, s87, 0
	global_load_dwordx4 v[160:163], v243, s[86:87]
	s_add_u32 s86, s86, 0x1000
	s_addc_u32 s87, s87, 0
	s_waitcnt vmcnt(7)
	v_lshlrev_b32_e32 v164, 16, v128
	v_and_b32_e32 v165, 0xffff0000, v128
	v_lshlrev_b32_e32 v166, 16, v129
	v_and_b32_e32 v167, 0xffff0000, v129
	v_lshlrev_b32_e32 v172, 16, v130
	v_and_b32_e32 v173, 0xffff0000, v130
	v_lshlrev_b32_e32 v174, 16, v131
	v_and_b32_e32 v175, 0xffff0000, v131
	v_mul_f32_e32 v164, v0, v164
	v_mul_f32_e32 v165, v1, v165
	v_mul_f32_e32 v166, v2, v166
	v_mul_f32_e32 v167, v3, v167
	v_mul_f32_e32 v172, v4, v172
	v_mul_f32_e32 v173, v5, v173
	v_mul_f32_e32 v174, v6, v174
	v_mul_f32_e32 v175, v7, v175
	v_cvt_pk_bf16_f32 v184, v164, v165
	v_cvt_pk_bf16_f32 v185, v166, v167
	v_cvt_pk_bf16_f32 v186, v172, v173
	v_cvt_pk_bf16_f32 v187, v174, v175
	global_store_dwordx4 v243, v[184:187], s[84:85]
	s_add_u32 s84, s84, 0x1000
	s_addc_u32 s85, s85, 0
	s_waitcnt vmcnt(7)
	v_lshlrev_b32_e32 v164, 16, v132
	v_and_b32_e32 v165, 0xffff0000, v132
	v_lshlrev_b32_e32 v166, 16, v133
	v_and_b32_e32 v167, 0xffff0000, v133
	v_lshlrev_b32_e32 v172, 16, v134
	v_and_b32_e32 v173, 0xffff0000, v134
	v_lshlrev_b32_e32 v174, 16, v135
	v_and_b32_e32 v175, 0xffff0000, v135
	v_mul_f32_e32 v164, v8, v164
	v_mul_f32_e32 v165, v9, v165
	v_mul_f32_e32 v166, v10, v166
	v_mul_f32_e32 v167, v11, v167
	v_mul_f32_e32 v172, v12, v172
	v_mul_f32_e32 v173, v13, v173
	v_mul_f32_e32 v174, v14, v174
	v_mul_f32_e32 v175, v15, v175
	v_cvt_pk_bf16_f32 v188, v164, v165
	v_cvt_pk_bf16_f32 v189, v166, v167
	v_cvt_pk_bf16_f32 v190, v172, v173
	v_cvt_pk_bf16_f32 v191, v174, v175
	global_store_dwordx4 v243, v[188:191], s[84:85]
	s_add_u32 s84, s84, 0x1000
	s_addc_u32 s85, s85, 0
	s_waitcnt vmcnt(7)
	v_lshlrev_b32_e32 v164, 16, v136
	v_and_b32_e32 v165, 0xffff0000, v136
	v_lshlrev_b32_e32 v166, 16, v137
	v_and_b32_e32 v167, 0xffff0000, v137
	v_lshlrev_b32_e32 v172, 16, v138
	v_and_b32_e32 v173, 0xffff0000, v138
	v_lshlrev_b32_e32 v174, 16, v139
	v_and_b32_e32 v175, 0xffff0000, v139
	v_mul_f32_e32 v164, v16, v164
	v_mul_f32_e32 v165, v17, v165
	v_mul_f32_e32 v166, v18, v166
	v_mul_f32_e32 v167, v19, v167
	v_mul_f32_e32 v172, v20, v172
	v_mul_f32_e32 v173, v21, v173
	v_mul_f32_e32 v174, v22, v174
	v_mul_f32_e32 v175, v23, v175
	v_cvt_pk_bf16_f32 v184, v164, v165
	v_cvt_pk_bf16_f32 v185, v166, v167
	v_cvt_pk_bf16_f32 v186, v172, v173
	v_cvt_pk_bf16_f32 v187, v174, v175
	global_store_dwordx4 v243, v[184:187], s[84:85]
	s_add_u32 s84, s84, 0x1000
	s_addc_u32 s85, s85, 0
	s_waitcnt vmcnt(7)
	v_lshlrev_b32_e32 v164, 16, v140
	v_and_b32_e32 v165, 0xffff0000, v140
	v_lshlrev_b32_e32 v166, 16, v141
	v_and_b32_e32 v167, 0xffff0000, v141
	v_lshlrev_b32_e32 v172, 16, v142
	v_and_b32_e32 v173, 0xffff0000, v142
	v_lshlrev_b32_e32 v174, 16, v143
	v_and_b32_e32 v175, 0xffff0000, v143
	v_mul_f32_e32 v164, v24, v164
	v_mul_f32_e32 v165, v25, v165
	v_mul_f32_e32 v166, v26, v166
	v_mul_f32_e32 v167, v27, v167
	v_mul_f32_e32 v172, v28, v172
	v_mul_f32_e32 v173, v29, v173
	v_mul_f32_e32 v174, v30, v174
	v_mul_f32_e32 v175, v31, v175
	v_cvt_pk_bf16_f32 v188, v164, v165
	v_cvt_pk_bf16_f32 v189, v166, v167
	v_cvt_pk_bf16_f32 v190, v172, v173
	v_cvt_pk_bf16_f32 v191, v174, v175
	global_store_dwordx4 v243, v[188:191], s[84:85]
	s_add_u32 s84, s84, 0x1000
	s_addc_u32 s85, s85, 0
	s_waitcnt vmcnt(7)
	v_lshlrev_b32_e32 v164, 16, v148
	v_and_b32_e32 v165, 0xffff0000, v148
	v_lshlrev_b32_e32 v166, 16, v149
	v_and_b32_e32 v167, 0xffff0000, v149
	v_lshlrev_b32_e32 v172, 16, v150
	v_and_b32_e32 v173, 0xffff0000, v150
	v_lshlrev_b32_e32 v174, 16, v151
	v_and_b32_e32 v175, 0xffff0000, v151
	v_mul_f32_e32 v164, v32, v164
	v_mul_f32_e32 v165, v33, v165
	v_mul_f32_e32 v166, v34, v166
	v_mul_f32_e32 v167, v35, v167
	v_mul_f32_e32 v172, v36, v172
	v_mul_f32_e32 v173, v37, v173
	v_mul_f32_e32 v174, v38, v174
	v_mul_f32_e32 v175, v39, v175
	v_cvt_pk_bf16_f32 v184, v164, v165
	v_cvt_pk_bf16_f32 v185, v166, v167
	v_cvt_pk_bf16_f32 v186, v172, v173
	v_cvt_pk_bf16_f32 v187, v174, v175
	global_store_dwordx4 v243, v[184:187], s[84:85]
	s_add_u32 s84, s84, 0x1000
	s_addc_u32 s85, s85, 0
	s_waitcnt vmcnt(7)
	v_lshlrev_b32_e32 v164, 16, v152
	v_and_b32_e32 v165, 0xffff0000, v152
	v_lshlrev_b32_e32 v166, 16, v153
	v_and_b32_e32 v167, 0xffff0000, v153
	v_lshlrev_b32_e32 v172, 16, v154
	v_and_b32_e32 v173, 0xffff0000, v154
	v_lshlrev_b32_e32 v174, 16, v155
	v_and_b32_e32 v175, 0xffff0000, v155
	v_mul_f32_e32 v164, v40, v164
	v_mul_f32_e32 v165, v41, v165
	v_mul_f32_e32 v166, v42, v166
	v_mul_f32_e32 v167, v43, v167
	v_mul_f32_e32 v172, v44, v172
	v_mul_f32_e32 v173, v45, v173
	v_mul_f32_e32 v174, v46, v174
	v_mul_f32_e32 v175, v47, v175
	v_cvt_pk_bf16_f32 v188, v164, v165
	v_cvt_pk_bf16_f32 v189, v166, v167
	v_cvt_pk_bf16_f32 v190, v172, v173
	v_cvt_pk_bf16_f32 v191, v174, v175
	global_store_dwordx4 v243, v[188:191], s[84:85]
	s_add_u32 s84, s84, 0x1000
	s_addc_u32 s85, s85, 0
	s_waitcnt vmcnt(7)
	v_lshlrev_b32_e32 v164, 16, v156
	v_and_b32_e32 v165, 0xffff0000, v156
	v_lshlrev_b32_e32 v166, 16, v157
	v_and_b32_e32 v167, 0xffff0000, v157
	v_lshlrev_b32_e32 v172, 16, v158
	v_and_b32_e32 v173, 0xffff0000, v158
	v_lshlrev_b32_e32 v174, 16, v159
	v_and_b32_e32 v175, 0xffff0000, v159
	v_mul_f32_e32 v164, v48, v164
	v_mul_f32_e32 v165, v49, v165
	v_mul_f32_e32 v166, v50, v166
	v_mul_f32_e32 v167, v51, v167
	v_mul_f32_e32 v172, v52, v172
	v_mul_f32_e32 v173, v53, v173
	v_mul_f32_e32 v174, v54, v174
	v_mul_f32_e32 v175, v55, v175
	v_cvt_pk_bf16_f32 v184, v164, v165
	v_cvt_pk_bf16_f32 v185, v166, v167
	v_cvt_pk_bf16_f32 v186, v172, v173
	v_cvt_pk_bf16_f32 v187, v174, v175
	global_store_dwordx4 v243, v[184:187], s[84:85]
	s_add_u32 s84, s84, 0x1000
	s_addc_u32 s85, s85, 0
	s_waitcnt vmcnt(7)
	v_lshlrev_b32_e32 v164, 16, v160
	v_and_b32_e32 v165, 0xffff0000, v160
	v_lshlrev_b32_e32 v166, 16, v161
	v_and_b32_e32 v167, 0xffff0000, v161
	v_lshlrev_b32_e32 v172, 16, v162
	v_and_b32_e32 v173, 0xffff0000, v162
	v_lshlrev_b32_e32 v174, 16, v163
	v_and_b32_e32 v175, 0xffff0000, v163
	v_mul_f32_e32 v164, v56, v164
	v_mul_f32_e32 v165, v57, v165
	v_mul_f32_e32 v166, v58, v166
	v_mul_f32_e32 v167, v59, v167
	v_mul_f32_e32 v172, v60, v172
	v_mul_f32_e32 v173, v61, v173
	v_mul_f32_e32 v174, v62, v174
	v_mul_f32_e32 v175, v63, v175
	v_cvt_pk_bf16_f32 v188, v164, v165
	v_cvt_pk_bf16_f32 v189, v166, v167
	v_cvt_pk_bf16_f32 v190, v172, v173
	v_cvt_pk_bf16_f32 v191, v174, v175
	global_store_dwordx4 v243, v[188:191], s[84:85]
	s_add_u32 s84, s84, 0x1000
	s_addc_u32 s85, s85, 0
	s_cmp_eq_u32 s83, 1
	s_cbranch_scc1 .Lp6b_epdone
	s_cmp_eq_u32 s95, 1
	s_cbranch_scc0 .Lp6b_epdone
	v_mov_b32_e32 v0, v64
	v_mov_b32_e32 v1, v65
	v_mov_b32_e32 v2, v66
	v_mov_b32_e32 v3, v67
	v_mov_b32_e32 v4, v68
	v_mov_b32_e32 v5, v69
	v_mov_b32_e32 v6, v70
	v_mov_b32_e32 v7, v71
	v_mov_b32_e32 v8, v72
	v_mov_b32_e32 v9, v73
	v_mov_b32_e32 v10, v74
	v_mov_b32_e32 v11, v75
	v_mov_b32_e32 v12, v76
	v_mov_b32_e32 v13, v77
	v_mov_b32_e32 v14, v78
	v_mov_b32_e32 v15, v79
	v_mov_b32_e32 v16, v80
	v_mov_b32_e32 v17, v81
	v_mov_b32_e32 v18, v82
	v_mov_b32_e32 v19, v83
	v_mov_b32_e32 v20, v84
	v_mov_b32_e32 v21, v85
	v_mov_b32_e32 v22, v86
	v_mov_b32_e32 v23, v87
	v_mov_b32_e32 v24, v88
	v_mov_b32_e32 v25, v89
	v_mov_b32_e32 v26, v90
	v_mov_b32_e32 v27, v91
	v_mov_b32_e32 v28, v92
	v_mov_b32_e32 v29, v93
	v_mov_b32_e32 v30, v94
	v_mov_b32_e32 v31, v95
	v_mov_b32_e32 v32, v96
	v_mov_b32_e32 v33, v97
	v_mov_b32_e32 v34, v98
	v_mov_b32_e32 v35, v99
	v_mov_b32_e32 v36, v100
	v_mov_b32_e32 v37, v101
	v_mov_b32_e32 v38, v102
	v_mov_b32_e32 v39, v103
	v_mov_b32_e32 v40, v104
	v_mov_b32_e32 v41, v105
	v_mov_b32_e32 v42, v106
	v_mov_b32_e32 v43, v107
	v_mov_b32_e32 v44, v108
	v_mov_b32_e32 v45, v109
	v_mov_b32_e32 v46, v110
	v_mov_b32_e32 v47, v111
	v_mov_b32_e32 v48, v112
	v_mov_b32_e32 v49, v113
	v_mov_b32_e32 v50, v114
	v_mov_b32_e32 v51, v115
	v_mov_b32_e32 v52, v116
	v_mov_b32_e32 v53, v117
	v_mov_b32_e32 v54, v118
	v_mov_b32_e32 v55, v119
	v_mov_b32_e32 v56, v120
	v_mov_b32_e32 v57, v121
	v_mov_b32_e32 v58, v122
	v_mov_b32_e32 v59, v123
	v_mov_b32_e32 v60, v124
	v_mov_b32_e32 v61, v125
	v_mov_b32_e32 v62, v126
	v_mov_b32_e32 v63, v127
	s_mov_b32 s83, 1
	s_branch .Lp6b_ep

.Lp6c_ep:
	s_lshl_b32 s71, s83, 25
	s_add_u32 s71, s71, 0x8000
	s_add_u32 s84, s24, s71
	s_addc_u32 s85, s25, 0
	v_cvt_pk_bf16_f32 v136, v0, v1
	v_cvt_pk_bf16_f32 v137, v2, v3
	v_cvt_pk_bf16_f32 v138, v4, v5
	v_cvt_pk_bf16_f32 v139, v6, v7
	global_store_dwordx4 v243, v[136:139], s[84:85]
	s_add_u32 s84, s84, 0x1000
	s_addc_u32 s85, s85, 0
	v_cvt_pk_bf16_f32 v140, v8, v9
	v_cvt_pk_bf16_f32 v141, v10, v11
	v_cvt_pk_bf16_f32 v142, v12, v13
	v_cvt_pk_bf16_f32 v143, v14, v15
	global_store_dwordx4 v243, v[140:143], s[84:85]
	s_add_u32 s84, s84, 0x1000
	s_addc_u32 s85, s85, 0
	v_cvt_pk_bf16_f32 v136, v16, v17
	v_cvt_pk_bf16_f32 v137, v18, v19
	v_cvt_pk_bf16_f32 v138, v20, v21
	v_cvt_pk_bf16_f32 v139, v22, v23
	global_store_dwordx4 v243, v[136:139], s[84:85]
	s_add_u32 s84, s84, 0x1000
	s_addc_u32 s85, s85, 0
	v_cvt_pk_bf16_f32 v140, v24, v25
	v_cvt_pk_bf16_f32 v141, v26, v27
	v_cvt_pk_bf16_f32 v142, v28, v29
	v_cvt_pk_bf16_f32 v143, v30, v31
	global_store_dwordx4 v243, v[140:143], s[84:85]
	s_add_u32 s84, s84, 0x1000
	s_addc_u32 s85, s85, 0
	v_cvt_pk_bf16_f32 v136, v32, v33
	v_cvt_pk_bf16_f32 v137, v34, v35
	v_cvt_pk_bf16_f32 v138, v36, v37
	v_cvt_pk_bf16_f32 v139, v38, v39
	global_store_dwordx4 v243, v[136:139], s[84:85]
	s_add_u32 s84, s84, 0x1000
	s_addc_u32 s85, s85, 0
	v_cvt_pk_bf16_f32 v140, v40, v41
	v_cvt_pk_bf16_f32 v141, v42, v43
	v_cvt_pk_bf16_f32 v142, v44, v45
	v_cvt_pk_bf16_f32 v143, v46, v47
	global_store_dwordx4 v243, v[140:143], s[84:85]
	s_add_u32 s84, s84, 0x1000
	s_addc_u32 s85, s85, 0
	v_cvt_pk_bf16_f32 v136, v48, v49
	v_cvt_pk_bf16_f32 v137, v50, v51
	v_cvt_pk_bf16_f32 v138, v52, v53
	v_cvt_pk_bf16_f32 v139, v54, v55
	global_store_dwordx4 v243, v[136:139], s[84:85]
	s_add_u32 s84, s84, 0x1000
	s_addc_u32 s85, s85, 0
	v_cvt_pk_bf16_f32 v140, v56, v57
	v_cvt_pk_bf16_f32 v141, v58, v59
	v_cvt_pk_bf16_f32 v142, v60, v61
	v_cvt_pk_bf16_f32 v143, v62, v63
	global_store_dwordx4 v243, v[140:143], s[84:85]
	s_add_u32 s84, s84, 0x1000
	s_addc_u32 s85, s85, 0
	s_cmp_eq_u32 s83, 1
	s_cbranch_scc1 .Lp6c_epdone
	s_cmp_eq_u32 s95, 1
	s_cbranch_scc0 .Lp6c_epdone
	v_mov_b32_e32 v0, v64
	v_mov_b32_e32 v1, v65
	v_mov_b32_e32 v2, v66
	v_mov_b32_e32 v3, v67
	v_mov_b32_e32 v4, v68
	v_mov_b32_e32 v5, v69
	v_mov_b32_e32 v6, v70
	v_mov_b32_e32 v7, v71
	v_mov_b32_e32 v8, v72
	v_mov_b32_e32 v9, v73
	v_mov_b32_e32 v10, v74
	v_mov_b32_e32 v11, v75
	v_mov_b32_e32 v12, v76
	v_mov_b32_e32 v13, v77
	v_mov_b32_e32 v14, v78
	v_mov_b32_e32 v15, v79
	v_mov_b32_e32 v16, v80
	v_mov_b32_e32 v17, v81
	v_mov_b32_e32 v18, v82
	v_mov_b32_e32 v19, v83
	v_mov_b32_e32 v20, v84
	v_mov_b32_e32 v21, v85
	v_mov_b32_e32 v22, v86
	v_mov_b32_e32 v23, v87
	v_mov_b32_e32 v24, v88
	v_mov_b32_e32 v25, v89
	v_mov_b32_e32 v26, v90
	v_mov_b32_e32 v27, v91
	v_mov_b32_e32 v28, v92
	v_mov_b32_e32 v29, v93
	v_mov_b32_e32 v30, v94
	v_mov_b32_e32 v31, v95
	v_mov_b32_e32 v32, v96
	v_mov_b32_e32 v33, v97
	v_mov_b32_e32 v34, v98
	v_mov_b32_e32 v35, v99
	v_mov_b32_e32 v36, v100
	v_mov_b32_e32 v37, v101
	v_mov_b32_e32 v38, v102
	v_mov_b32_e32 v39, v103
	v_mov_b32_e32 v40, v104
	v_mov_b32_e32 v41, v105
	v_mov_b32_e32 v42, v106
	v_mov_b32_e32 v43, v107
	v_mov_b32_e32 v44, v108
	v_mov_b32_e32 v45, v109
	v_mov_b32_e32 v46, v110
	v_mov_b32_e32 v47, v111
	v_mov_b32_e32 v48, v112
	v_mov_b32_e32 v49, v113
	v_mov_b32_e32 v50, v114
	v_mov_b32_e32 v51, v115
	v_mov_b32_e32 v52, v116
	v_mov_b32_e32 v53, v117
	v_mov_b32_e32 v54, v118
	v_mov_b32_e32 v55, v119
	v_mov_b32_e32 v56, v120
	v_mov_b32_e32 v57, v121
	v_mov_b32_e32 v58, v122
	v_mov_b32_e32 v59, v123
	v_mov_b32_e32 v60, v124
	v_mov_b32_e32 v61, v125
	v_mov_b32_e32 v62, v126
	v_mov_b32_e32 v63, v127
	s_mov_b32 s83, 1
	s_branch .Lp6c_ep

.Lp6d_ep:
	s_add_u32 s28, s22, 0x1000
	s_addc_u32 s29, s23, 0
	global_load_dwordx4 v[128:131], v244, s[28:29]
	global_load_dwordx4 v[132:135], v244, s[28:29] offset:64
	global_load_dwordx4 v[136:139], v244, s[28:29] offset:128
	global_load_dwordx4 v[140:143], v244, s[28:29] offset:192
	s_cmp_eq_u32 s83, 1
	s_cselect_b32 s75, s97, s70
	v_lshrrev_b32_e32 v249, 1, v168
	v_and_b32_e32 v249, 0x1c0, v249
	v_and_b32_e32 v250, 15, v168
	v_or_b32_e32 v249, v249, v250
	v_lshl_add_u32 v249, s75, 7, v249
	v_lshlrev_b32_e32 v249, 11, v249
	v_bfe_u32 v250, v168, 4, 2
	v_lshlrev_b32_e32 v246, 3, v250
	v_and_b32_e32 v250, 1, v250
	v_mul_u32_u24_e32 v250, 24, v250
	v_add3_u32 v249, v249, v250, v246
	v_bfe_u32 v250, v168, 6, 1
	s_lshl_b32 s71, s74, 8
	v_lshl_add_u32 v245, v250, 7, v249
	v_add_u32_e32 v245, s71, v245
	v_add_u32_e32 v246, 0x8000, v245
	v_add_u32_e32 v247, 0x10000, v245
	v_add_u32_e32 v248, 0x18000, v245
	s_lshl_b32 s71, s83, 25
	s_add_u32 s86, s24, s71
	s_addc_u32 s87, s25, 0
	s_lshl_b32 s71, s83, 25
	s_add_u32 s71, s71, 0x8000
	s_add_u32 s88, s24, s71
	s_addc_u32 s89, s25, 0
	global_load_dwordx4 v[148:151], v243, s[86:87]
	s_add_u32 s86, s86, 0x1000
	s_addc_u32 s87, s87, 0
	global_load_dwordx4 v[164:167], v243, s[88:89]
	s_add_u32 s88, s88, 0x1000
	s_addc_u32 s89, s89, 0
	global_load_dwordx4 v[152:155], v243, s[86:87]
	s_add_u32 s86, s86, 0x1000
	s_addc_u32 s87, s87, 0
	global_load_dwordx4 v[172:175], v243, s[88:89]
	s_add_u32 s88, s88, 0x1000
	s_addc_u32 s89, s89, 0
	global_load_dwordx4 v[156:159], v243, s[86:87]
	s_add_u32 s86, s86, 0x1000
	s_addc_u32 s87, s87, 0
	global_load_dwordx4 v[176:179], v243, s[88:89]
	s_add_u32 s88, s88, 0x1000
	s_addc_u32 s89, s89, 0
	global_load_dwordx4 v[160:163], v243, s[86:87]
	s_add_u32 s86, s86, 0x1000
	s_addc_u32 s87, s87, 0
	global_load_dwordx4 v[180:183], v243, s[88:89]
	s_add_u32 s88, s88, 0x1000
	s_addc_u32 s89, s89, 0
	s_waitcnt vmcnt(6)
	v_add_f32_e32 v184, v0, v128
	v_add_f32_e32 v185, v1, v129
	v_add_f32_e32 v186, v2, v130
	v_add_f32_e32 v187, v3, v131
	v_add_f32_e32 v188, v4, v132
	v_add_f32_e32 v189, v5, v133
	v_add_f32_e32 v190, v6, v134
	v_add_f32_e32 v191, v7, v135
	v_mul_f32_e32 v184, 0xbfb8aa3b, v184
	v_mul_f32_e32 v185, 0xbfb8aa3b, v185
	v_mul_f32_e32 v186, 0xbfb8aa3b, v186
	v_mul_f32_e32 v187, 0xbfb8aa3b, v187
	v_mul_f32_e32 v188, 0xbfb8aa3b, v188
	v_mul_f32_e32 v189, 0xbfb8aa3b, v189
	v_mul_f32_e32 v190, 0xbfb8aa3b, v190
	v_mul_f32_e32 v191, 0xbfb8aa3b, v191
	v_exp_f32_e32 v192, v184
	v_exp_f32_e32 v193, v185
	v_exp_f32_e32 v194, v186
	v_exp_f32_e32 v195, v187
	v_exp_f32_e32 v196, v188
	v_exp_f32_e32 v197, v189
	v_exp_f32_e32 v198, v190
	v_exp_f32_e32 v199, v191
	v_add_f32_e32 v192, 1.0, v192
	v_add_f32_e32 v193, 1.0, v193
	v_add_f32_e32 v194, 1.0, v194
	v_add_f32_e32 v195, 1.0, v195
	v_add_f32_e32 v196, 1.0, v196
	v_add_f32_e32 v197, 1.0, v197
	v_add_f32_e32 v198, 1.0, v198
	v_add_f32_e32 v199, 1.0, v199
	v_div_scale_f32 v200, s[76:77], v192, v192, 1.0
	v_div_scale_f32 v201, s[76:77], v193, v193, 1.0
	v_div_scale_f32 v202, s[76:77], v194, v194, 1.0
	v_div_scale_f32 v203, s[76:77], v195, v195, 1.0
	v_div_scale_f32 v204, s[76:77], v196, v196, 1.0
	v_div_scale_f32 v205, s[76:77], v197, v197, 1.0
	v_div_scale_f32 v206, s[76:77], v198, v198, 1.0
	v_div_scale_f32 v207, s[76:77], v199, v199, 1.0
	v_rcp_f32_e32 v208, v200
	v_rcp_f32_e32 v209, v201
	v_rcp_f32_e32 v210, v202
	v_rcp_f32_e32 v211, v203
	v_rcp_f32_e32 v212, v204
	v_rcp_f32_e32 v213, v205
	v_rcp_f32_e32 v214, v206
	v_rcp_f32_e32 v215, v207
	v_fma_f32 v184, -v200, v208, 1.0
	v_fma_f32 v185, -v201, v209, 1.0
	v_fma_f32 v186, -v202, v210, 1.0
	v_fma_f32 v187, -v203, v211, 1.0
	v_fma_f32 v188, -v204, v212, 1.0
	v_fma_f32 v189, -v205, v213, 1.0
	v_fma_f32 v190, -v206, v214, 1.0
	v_fma_f32 v191, -v207, v215, 1.0
	v_fmac_f32_e32 v208, v184, v208
	v_fmac_f32_e32 v209, v185, v209
	v_fmac_f32_e32 v210, v186, v210
	v_fmac_f32_e32 v211, v187, v211
	v_fmac_f32_e32 v212, v188, v212
	v_fmac_f32_e32 v213, v189, v213
	v_fmac_f32_e32 v214, v190, v214
	v_fmac_f32_e32 v215, v191, v215
	v_div_scale_f32 v216, vcc, 1.0, v192, 1.0
	v_mul_f32_e32 v224, v216, v208
	v_fma_f32 v184, -v200, v224, v216
	v_fmac_f32_e32 v224, v184, v208
	v_fma_f32 v216, -v200, v224, v216
	v_div_fmas_f32 v216, v216, v208, v224
	v_div_fixup_f32 v184, v216, v192, 1.0
	v_div_scale_f32 v217, vcc, 1.0, v193, 1.0
	v_mul_f32_e32 v225, v217, v209
	v_fma_f32 v185, -v201, v225, v217
	v_fmac_f32_e32 v225, v185, v209
	v_fma_f32 v217, -v201, v225, v217
	v_div_fmas_f32 v217, v217, v209, v225
	v_div_fixup_f32 v185, v217, v193, 1.0
	v_div_scale_f32 v218, vcc, 1.0, v194, 1.0
	v_mul_f32_e32 v226, v218, v210
	v_fma_f32 v186, -v202, v226, v218
	v_fmac_f32_e32 v226, v186, v210
	v_fma_f32 v218, -v202, v226, v218
	v_div_fmas_f32 v218, v218, v210, v226
	v_div_fixup_f32 v186, v218, v194, 1.0
	v_div_scale_f32 v219, vcc, 1.0, v195, 1.0
	v_mul_f32_e32 v227, v219, v211
	v_fma_f32 v187, -v203, v227, v219
	v_fmac_f32_e32 v227, v187, v211
	v_fma_f32 v219, -v203, v227, v219
	v_div_fmas_f32 v219, v219, v211, v227
	v_div_fixup_f32 v187, v219, v195, 1.0
	v_div_scale_f32 v220, vcc, 1.0, v196, 1.0
	v_mul_f32_e32 v228, v220, v212
	v_fma_f32 v188, -v204, v228, v220
	v_fmac_f32_e32 v228, v188, v212
	v_fma_f32 v220, -v204, v228, v220
	v_div_fmas_f32 v220, v220, v212, v228
	v_div_fixup_f32 v188, v220, v196, 1.0
	v_div_scale_f32 v221, vcc, 1.0, v197, 1.0
	v_mul_f32_e32 v229, v221, v213
	v_fma_f32 v189, -v205, v229, v221
	v_fmac_f32_e32 v229, v189, v213
	v_fma_f32 v221, -v205, v229, v221
	v_div_fmas_f32 v221, v221, v213, v229
	v_div_fixup_f32 v189, v221, v197, 1.0
	v_div_scale_f32 v222, vcc, 1.0, v198, 1.0
	v_mul_f32_e32 v230, v222, v214
	v_fma_f32 v190, -v206, v230, v222
	v_fmac_f32_e32 v230, v190, v214
	v_fma_f32 v222, -v206, v230, v222
	v_div_fmas_f32 v222, v222, v214, v230
	v_div_fixup_f32 v190, v222, v198, 1.0
	v_div_scale_f32 v223, vcc, 1.0, v199, 1.0
	v_mul_f32_e32 v231, v223, v215
	v_fma_f32 v191, -v207, v231, v223
	v_fmac_f32_e32 v231, v191, v215
	v_fma_f32 v223, -v207, v231, v223
	v_div_fmas_f32 v223, v223, v215, v231
	v_div_fixup_f32 v191, v223, v199, 1.0
	v_lshlrev_b32_e32 v192, 16, v148
	v_and_b32_e32 v193, 0xffff0000, v148
	v_lshlrev_b32_e32 v200, 16, v164
	v_and_b32_e32 v201, 0xffff0000, v164
	v_lshlrev_b32_e32 v194, 16, v149
	v_and_b32_e32 v195, 0xffff0000, v149
	v_lshlrev_b32_e32 v202, 16, v165
	v_and_b32_e32 v203, 0xffff0000, v165
	v_lshlrev_b32_e32 v196, 16, v150
	v_and_b32_e32 v197, 0xffff0000, v150
	v_lshlrev_b32_e32 v204, 16, v166
	v_and_b32_e32 v205, 0xffff0000, v166
	v_lshlrev_b32_e32 v198, 16, v151
	v_and_b32_e32 v199, 0xffff0000, v151
	v_lshlrev_b32_e32 v206, 16, v167
	v_and_b32_e32 v207, 0xffff0000, v167
	v_fma_f32 v184, v184, v200, v192
	v_fma_f32 v185, v185, v201, v193
	v_fma_f32 v186, v186, v202, v194
	v_fma_f32 v187, v187, v203, v195
	v_fma_f32 v188, v188, v204, v196
	v_fma_f32 v189, v189, v205, v197
	v_fma_f32 v190, v190, v206, v198
	v_fma_f32 v191, v191, v207, v199
	v_cvt_pk_bf16_f32 v216, v184, v185
	v_cvt_pk_bf16_f32 v217, v186, v187
	v_cvt_pk_bf16_f32 v218, v188, v189
	v_cvt_pk_bf16_f32 v219, v190, v191
	s_nop 1
	v_permlane16_swap_b32_e32 v216, v218
	v_permlane16_swap_b32_e32 v217, v219
	global_store_dwordx4 v245, v[216:219], s[26:27]
	s_waitcnt vmcnt(5)
	v_add_f32_e32 v184, v8, v136
	v_add_f32_e32 v185, v9, v137
	v_add_f32_e32 v186, v10, v138
	v_add_f32_e32 v187, v11, v139
	v_add_f32_e32 v188, v12, v140
	v_add_f32_e32 v189, v13, v141
	v_add_f32_e32 v190, v14, v142
	v_add_f32_e32 v191, v15, v143
	v_mul_f32_e32 v184, 0xbfb8aa3b, v184
	v_mul_f32_e32 v185, 0xbfb8aa3b, v185
	v_mul_f32_e32 v186, 0xbfb8aa3b, v186
	v_mul_f32_e32 v187, 0xbfb8aa3b, v187
	v_mul_f32_e32 v188, 0xbfb8aa3b, v188
	v_mul_f32_e32 v189, 0xbfb8aa3b, v189
	v_mul_f32_e32 v190, 0xbfb8aa3b, v190
	v_mul_f32_e32 v191, 0xbfb8aa3b, v191
	v_exp_f32_e32 v192, v184
	v_exp_f32_e32 v193, v185
	v_exp_f32_e32 v194, v186
	v_exp_f32_e32 v195, v187
	v_exp_f32_e32 v196, v188
	v_exp_f32_e32 v197, v189
	v_exp_f32_e32 v198, v190
	v_exp_f32_e32 v199, v191
	v_add_f32_e32 v192, 1.0, v192
	v_add_f32_e32 v193, 1.0, v193
	v_add_f32_e32 v194, 1.0, v194
	v_add_f32_e32 v195, 1.0, v195
	v_add_f32_e32 v196, 1.0, v196
	v_add_f32_e32 v197, 1.0, v197
	v_add_f32_e32 v198, 1.0, v198
	v_add_f32_e32 v199, 1.0, v199
	v_div_scale_f32 v200, s[76:77], v192, v192, 1.0
	v_div_scale_f32 v201, s[76:77], v193, v193, 1.0
	v_div_scale_f32 v202, s[76:77], v194, v194, 1.0
	v_div_scale_f32 v203, s[76:77], v195, v195, 1.0
	v_div_scale_f32 v204, s[76:77], v196, v196, 1.0
	v_div_scale_f32 v205, s[76:77], v197, v197, 1.0
	v_div_scale_f32 v206, s[76:77], v198, v198, 1.0
	v_div_scale_f32 v207, s[76:77], v199, v199, 1.0
	v_rcp_f32_e32 v208, v200
	v_rcp_f32_e32 v209, v201
	v_rcp_f32_e32 v210, v202
	v_rcp_f32_e32 v211, v203
	v_rcp_f32_e32 v212, v204
	v_rcp_f32_e32 v213, v205
	v_rcp_f32_e32 v214, v206
	v_rcp_f32_e32 v215, v207
	v_fma_f32 v184, -v200, v208, 1.0
	v_fma_f32 v185, -v201, v209, 1.0
	v_fma_f32 v186, -v202, v210, 1.0
	v_fma_f32 v187, -v203, v211, 1.0
	v_fma_f32 v188, -v204, v212, 1.0
	v_fma_f32 v189, -v205, v213, 1.0
	v_fma_f32 v190, -v206, v214, 1.0
	v_fma_f32 v191, -v207, v215, 1.0
	v_fmac_f32_e32 v208, v184, v208
	v_fmac_f32_e32 v209, v185, v209
	v_fmac_f32_e32 v210, v186, v210
	v_fmac_f32_e32 v211, v187, v211
	v_fmac_f32_e32 v212, v188, v212
	v_fmac_f32_e32 v213, v189, v213
	v_fmac_f32_e32 v214, v190, v214
	v_fmac_f32_e32 v215, v191, v215
	v_div_scale_f32 v216, vcc, 1.0, v192, 1.0
	v_mul_f32_e32 v224, v216, v208
	v_fma_f32 v184, -v200, v224, v216
	v_fmac_f32_e32 v224, v184, v208
	v_fma_f32 v216, -v200, v224, v216
	v_div_fmas_f32 v216, v216, v208, v224
	v_div_fixup_f32 v184, v216, v192, 1.0
	v_div_scale_f32 v217, vcc, 1.0, v193, 1.0
	v_mul_f32_e32 v225, v217, v209
	v_fma_f32 v185, -v201, v225, v217
	v_fmac_f32_e32 v225, v185, v209
	v_fma_f32 v217, -v201, v225, v217
	v_div_fmas_f32 v217, v217, v209, v225
	v_div_fixup_f32 v185, v217, v193, 1.0
	v_div_scale_f32 v218, vcc, 1.0, v194, 1.0
	v_mul_f32_e32 v226, v218, v210
	v_fma_f32 v186, -v202, v226, v218
	v_fmac_f32_e32 v226, v186, v210
	v_fma_f32 v218, -v202, v226, v218
	v_div_fmas_f32 v218, v218, v210, v226
	v_div_fixup_f32 v186, v218, v194, 1.0
	v_div_scale_f32 v219, vcc, 1.0, v195, 1.0
	v_mul_f32_e32 v227, v219, v211
	v_fma_f32 v187, -v203, v227, v219
	v_fmac_f32_e32 v227, v187, v211
	v_fma_f32 v219, -v203, v227, v219
	v_div_fmas_f32 v219, v219, v211, v227
	v_div_fixup_f32 v187, v219, v195, 1.0
	v_div_scale_f32 v220, vcc, 1.0, v196, 1.0
	v_mul_f32_e32 v228, v220, v212
	v_fma_f32 v188, -v204, v228, v220
	v_fmac_f32_e32 v228, v188, v212
	v_fma_f32 v220, -v204, v228, v220
	v_div_fmas_f32 v220, v220, v212, v228
	v_div_fixup_f32 v188, v220, v196, 1.0
	v_div_scale_f32 v221, vcc, 1.0, v197, 1.0
	v_mul_f32_e32 v229, v221, v213
	v_fma_f32 v189, -v205, v229, v221
	v_fmac_f32_e32 v229, v189, v213
	v_fma_f32 v221, -v205, v229, v221
	v_div_fmas_f32 v221, v221, v213, v229
	v_div_fixup_f32 v189, v221, v197, 1.0
	v_div_scale_f32 v222, vcc, 1.0, v198, 1.0
	v_mul_f32_e32 v230, v222, v214
	v_fma_f32 v190, -v206, v230, v222
	v_fmac_f32_e32 v230, v190, v214
	v_fma_f32 v222, -v206, v230, v222
	v_div_fmas_f32 v222, v222, v214, v230
	v_div_fixup_f32 v190, v222, v198, 1.0
	v_div_scale_f32 v223, vcc, 1.0, v199, 1.0
	v_mul_f32_e32 v231, v223, v215
	v_fma_f32 v191, -v207, v231, v223
	v_fmac_f32_e32 v231, v191, v215
	v_fma_f32 v223, -v207, v231, v223
	v_div_fmas_f32 v223, v223, v215, v231
	v_div_fixup_f32 v191, v223, v199, 1.0
	v_lshlrev_b32_e32 v192, 16, v152
	v_and_b32_e32 v193, 0xffff0000, v152
	v_lshlrev_b32_e32 v200, 16, v172
	v_and_b32_e32 v201, 0xffff0000, v172
	v_lshlrev_b32_e32 v194, 16, v153
	v_and_b32_e32 v195, 0xffff0000, v153
	v_lshlrev_b32_e32 v202, 16, v173
	v_and_b32_e32 v203, 0xffff0000, v173
	v_lshlrev_b32_e32 v196, 16, v154
	v_and_b32_e32 v197, 0xffff0000, v154
	v_lshlrev_b32_e32 v204, 16, v174
	v_and_b32_e32 v205, 0xffff0000, v174
	v_lshlrev_b32_e32 v198, 16, v155
	v_and_b32_e32 v199, 0xffff0000, v155
	v_lshlrev_b32_e32 v206, 16, v175
	v_and_b32_e32 v207, 0xffff0000, v175
	v_fma_f32 v184, v184, v200, v192
	v_fma_f32 v185, v185, v201, v193
	v_fma_f32 v186, v186, v202, v194
	v_fma_f32 v187, v187, v203, v195
	v_fma_f32 v188, v188, v204, v196
	v_fma_f32 v189, v189, v205, v197
	v_fma_f32 v190, v190, v206, v198
	v_fma_f32 v191, v191, v207, v199
	v_cvt_pk_bf16_f32 v220, v184, v185
	v_cvt_pk_bf16_f32 v221, v186, v187
	v_cvt_pk_bf16_f32 v222, v188, v189
	v_cvt_pk_bf16_f32 v223, v190, v191
	s_nop 1
	v_permlane16_swap_b32_e32 v220, v222
	v_permlane16_swap_b32_e32 v221, v223
	global_store_dwordx4 v245, v[220:223], s[26:27] offset:64
	s_waitcnt vmcnt(4)
	v_add_f32_e32 v184, v16, v128
	v_add_f32_e32 v185, v17, v129
	v_add_f32_e32 v186, v18, v130
	v_add_f32_e32 v187, v19, v131
	v_add_f32_e32 v188, v20, v132
	v_add_f32_e32 v189, v21, v133
	v_add_f32_e32 v190, v22, v134
	v_add_f32_e32 v191, v23, v135
	v_mul_f32_e32 v184, 0xbfb8aa3b, v184
	v_mul_f32_e32 v185, 0xbfb8aa3b, v185
	v_mul_f32_e32 v186, 0xbfb8aa3b, v186
	v_mul_f32_e32 v187, 0xbfb8aa3b, v187
	v_mul_f32_e32 v188, 0xbfb8aa3b, v188
	v_mul_f32_e32 v189, 0xbfb8aa3b, v189
	v_mul_f32_e32 v190, 0xbfb8aa3b, v190
	v_mul_f32_e32 v191, 0xbfb8aa3b, v191
	v_exp_f32_e32 v192, v184
	v_exp_f32_e32 v193, v185
	v_exp_f32_e32 v194, v186
	v_exp_f32_e32 v195, v187
	v_exp_f32_e32 v196, v188
	v_exp_f32_e32 v197, v189
	v_exp_f32_e32 v198, v190
	v_exp_f32_e32 v199, v191
	v_add_f32_e32 v192, 1.0, v192
	v_add_f32_e32 v193, 1.0, v193
	v_add_f32_e32 v194, 1.0, v194
	v_add_f32_e32 v195, 1.0, v195
	v_add_f32_e32 v196, 1.0, v196
	v_add_f32_e32 v197, 1.0, v197
	v_add_f32_e32 v198, 1.0, v198
	v_add_f32_e32 v199, 1.0, v199
	v_div_scale_f32 v200, s[76:77], v192, v192, 1.0
	v_div_scale_f32 v201, s[76:77], v193, v193, 1.0
	v_div_scale_f32 v202, s[76:77], v194, v194, 1.0
	v_div_scale_f32 v203, s[76:77], v195, v195, 1.0
	v_div_scale_f32 v204, s[76:77], v196, v196, 1.0
	v_div_scale_f32 v205, s[76:77], v197, v197, 1.0
	v_div_scale_f32 v206, s[76:77], v198, v198, 1.0
	v_div_scale_f32 v207, s[76:77], v199, v199, 1.0
	v_rcp_f32_e32 v208, v200
	v_rcp_f32_e32 v209, v201
	v_rcp_f32_e32 v210, v202
	v_rcp_f32_e32 v211, v203
	v_rcp_f32_e32 v212, v204
	v_rcp_f32_e32 v213, v205
	v_rcp_f32_e32 v214, v206
	v_rcp_f32_e32 v215, v207
	v_fma_f32 v184, -v200, v208, 1.0
	v_fma_f32 v185, -v201, v209, 1.0
	v_fma_f32 v186, -v202, v210, 1.0
	v_fma_f32 v187, -v203, v211, 1.0
	v_fma_f32 v188, -v204, v212, 1.0
	v_fma_f32 v189, -v205, v213, 1.0
	v_fma_f32 v190, -v206, v214, 1.0
	v_fma_f32 v191, -v207, v215, 1.0
	v_fmac_f32_e32 v208, v184, v208
	v_fmac_f32_e32 v209, v185, v209
	v_fmac_f32_e32 v210, v186, v210
	v_fmac_f32_e32 v211, v187, v211
	v_fmac_f32_e32 v212, v188, v212
	v_fmac_f32_e32 v213, v189, v213
	v_fmac_f32_e32 v214, v190, v214
	v_fmac_f32_e32 v215, v191, v215
	v_div_scale_f32 v216, vcc, 1.0, v192, 1.0
	v_mul_f32_e32 v224, v216, v208
	v_fma_f32 v184, -v200, v224, v216
	v_fmac_f32_e32 v224, v184, v208
	v_fma_f32 v216, -v200, v224, v216
	v_div_fmas_f32 v216, v216, v208, v224
	v_div_fixup_f32 v184, v216, v192, 1.0
	v_div_scale_f32 v217, vcc, 1.0, v193, 1.0
	v_mul_f32_e32 v225, v217, v209
	v_fma_f32 v185, -v201, v225, v217
	v_fmac_f32_e32 v225, v185, v209
	v_fma_f32 v217, -v201, v225, v217
	v_div_fmas_f32 v217, v217, v209, v225
	v_div_fixup_f32 v185, v217, v193, 1.0
	v_div_scale_f32 v218, vcc, 1.0, v194, 1.0
	v_mul_f32_e32 v226, v218, v210
	v_fma_f32 v186, -v202, v226, v218
	v_fmac_f32_e32 v226, v186, v210
	v_fma_f32 v218, -v202, v226, v218
	v_div_fmas_f32 v218, v218, v210, v226
	v_div_fixup_f32 v186, v218, v194, 1.0
	v_div_scale_f32 v219, vcc, 1.0, v195, 1.0
	v_mul_f32_e32 v227, v219, v211
	v_fma_f32 v187, -v203, v227, v219
	v_fmac_f32_e32 v227, v187, v211
	v_fma_f32 v219, -v203, v227, v219
	v_div_fmas_f32 v219, v219, v211, v227
	v_div_fixup_f32 v187, v219, v195, 1.0
	v_div_scale_f32 v220, vcc, 1.0, v196, 1.0
	v_mul_f32_e32 v228, v220, v212
	v_fma_f32 v188, -v204, v228, v220
	v_fmac_f32_e32 v228, v188, v212
	v_fma_f32 v220, -v204, v228, v220
	v_div_fmas_f32 v220, v220, v212, v228
	v_div_fixup_f32 v188, v220, v196, 1.0
	v_div_scale_f32 v221, vcc, 1.0, v197, 1.0
	v_mul_f32_e32 v229, v221, v213
	v_fma_f32 v189, -v205, v229, v221
	v_fmac_f32_e32 v229, v189, v213
	v_fma_f32 v221, -v205, v229, v221
	v_div_fmas_f32 v221, v221, v213, v229
	v_div_fixup_f32 v189, v221, v197, 1.0
	v_div_scale_f32 v222, vcc, 1.0, v198, 1.0
	v_mul_f32_e32 v230, v222, v214
	v_fma_f32 v190, -v206, v230, v222
	v_fmac_f32_e32 v230, v190, v214
	v_fma_f32 v222, -v206, v230, v222
	v_div_fmas_f32 v222, v222, v214, v230
	v_div_fixup_f32 v190, v222, v198, 1.0
	v_div_scale_f32 v223, vcc, 1.0, v199, 1.0
	v_mul_f32_e32 v231, v223, v215
	v_fma_f32 v191, -v207, v231, v223
	v_fmac_f32_e32 v231, v191, v215
	v_fma_f32 v223, -v207, v231, v223
	v_div_fmas_f32 v223, v223, v215, v231
	v_div_fixup_f32 v191, v223, v199, 1.0
	v_lshlrev_b32_e32 v192, 16, v156
	v_and_b32_e32 v193, 0xffff0000, v156
	v_lshlrev_b32_e32 v200, 16, v176
	v_and_b32_e32 v201, 0xffff0000, v176
	v_lshlrev_b32_e32 v194, 16, v157
	v_and_b32_e32 v195, 0xffff0000, v157
	v_lshlrev_b32_e32 v202, 16, v177
	v_and_b32_e32 v203, 0xffff0000, v177
	v_lshlrev_b32_e32 v196, 16, v158
	v_and_b32_e32 v197, 0xffff0000, v158
	v_lshlrev_b32_e32 v204, 16, v178
	v_and_b32_e32 v205, 0xffff0000, v178
	v_lshlrev_b32_e32 v198, 16, v159
	v_and_b32_e32 v199, 0xffff0000, v159
	v_lshlrev_b32_e32 v206, 16, v179
	v_and_b32_e32 v207, 0xffff0000, v179
	v_fma_f32 v184, v184, v200, v192
	v_fma_f32 v185, v185, v201, v193
	v_fma_f32 v186, v186, v202, v194
	v_fma_f32 v187, v187, v203, v195
	v_fma_f32 v188, v188, v204, v196
	v_fma_f32 v189, v189, v205, v197
	v_fma_f32 v190, v190, v206, v198
	v_fma_f32 v191, v191, v207, v199
	v_cvt_pk_bf16_f32 v216, v184, v185
	v_cvt_pk_bf16_f32 v217, v186, v187
	v_cvt_pk_bf16_f32 v218, v188, v189
	v_cvt_pk_bf16_f32 v219, v190, v191
	s_nop 1
	v_permlane16_swap_b32_e32 v216, v218
	v_permlane16_swap_b32_e32 v217, v219
	global_store_dwordx4 v246, v[216:219], s[26:27]
	s_waitcnt vmcnt(3)
	v_add_f32_e32 v184, v24, v136
	v_add_f32_e32 v185, v25, v137
	v_add_f32_e32 v186, v26, v138
	v_add_f32_e32 v187, v27, v139
	v_add_f32_e32 v188, v28, v140
	v_add_f32_e32 v189, v29, v141
	v_add_f32_e32 v190, v30, v142
	v_add_f32_e32 v191, v31, v143
	v_mul_f32_e32 v184, 0xbfb8aa3b, v184
	v_mul_f32_e32 v185, 0xbfb8aa3b, v185
	v_mul_f32_e32 v186, 0xbfb8aa3b, v186
	v_mul_f32_e32 v187, 0xbfb8aa3b, v187
	v_mul_f32_e32 v188, 0xbfb8aa3b, v188
	v_mul_f32_e32 v189, 0xbfb8aa3b, v189
	v_mul_f32_e32 v190, 0xbfb8aa3b, v190
	v_mul_f32_e32 v191, 0xbfb8aa3b, v191
	v_exp_f32_e32 v192, v184
	v_exp_f32_e32 v193, v185
	v_exp_f32_e32 v194, v186
	v_exp_f32_e32 v195, v187
	v_exp_f32_e32 v196, v188
	v_exp_f32_e32 v197, v189
	v_exp_f32_e32 v198, v190
	v_exp_f32_e32 v199, v191
	v_add_f32_e32 v192, 1.0, v192
	v_add_f32_e32 v193, 1.0, v193
	v_add_f32_e32 v194, 1.0, v194
	v_add_f32_e32 v195, 1.0, v195
	v_add_f32_e32 v196, 1.0, v196
	v_add_f32_e32 v197, 1.0, v197
	v_add_f32_e32 v198, 1.0, v198
	v_add_f32_e32 v199, 1.0, v199
	v_div_scale_f32 v200, s[76:77], v192, v192, 1.0
	v_div_scale_f32 v201, s[76:77], v193, v193, 1.0
	v_div_scale_f32 v202, s[76:77], v194, v194, 1.0
	v_div_scale_f32 v203, s[76:77], v195, v195, 1.0
	v_div_scale_f32 v204, s[76:77], v196, v196, 1.0
	v_div_scale_f32 v205, s[76:77], v197, v197, 1.0
	v_div_scale_f32 v206, s[76:77], v198, v198, 1.0
	v_div_scale_f32 v207, s[76:77], v199, v199, 1.0
	v_rcp_f32_e32 v208, v200
	v_rcp_f32_e32 v209, v201
	v_rcp_f32_e32 v210, v202
	v_rcp_f32_e32 v211, v203
	v_rcp_f32_e32 v212, v204
	v_rcp_f32_e32 v213, v205
	v_rcp_f32_e32 v214, v206
	v_rcp_f32_e32 v215, v207
	v_fma_f32 v184, -v200, v208, 1.0
	v_fma_f32 v185, -v201, v209, 1.0
	v_fma_f32 v186, -v202, v210, 1.0
	v_fma_f32 v187, -v203, v211, 1.0
	v_fma_f32 v188, -v204, v212, 1.0
	v_fma_f32 v189, -v205, v213, 1.0
	v_fma_f32 v190, -v206, v214, 1.0
	v_fma_f32 v191, -v207, v215, 1.0
	v_fmac_f32_e32 v208, v184, v208
	v_fmac_f32_e32 v209, v185, v209
	v_fmac_f32_e32 v210, v186, v210
	v_fmac_f32_e32 v211, v187, v211
	v_fmac_f32_e32 v212, v188, v212
	v_fmac_f32_e32 v213, v189, v213
	v_fmac_f32_e32 v214, v190, v214
	v_fmac_f32_e32 v215, v191, v215
	v_div_scale_f32 v216, vcc, 1.0, v192, 1.0
	v_mul_f32_e32 v224, v216, v208
	v_fma_f32 v184, -v200, v224, v216
	v_fmac_f32_e32 v224, v184, v208
	v_fma_f32 v216, -v200, v224, v216
	v_div_fmas_f32 v216, v216, v208, v224
	v_div_fixup_f32 v184, v216, v192, 1.0
	v_div_scale_f32 v217, vcc, 1.0, v193, 1.0
	v_mul_f32_e32 v225, v217, v209
	v_fma_f32 v185, -v201, v225, v217
	v_fmac_f32_e32 v225, v185, v209
	v_fma_f32 v217, -v201, v225, v217
	v_div_fmas_f32 v217, v217, v209, v225
	v_div_fixup_f32 v185, v217, v193, 1.0
	v_div_scale_f32 v218, vcc, 1.0, v194, 1.0
	v_mul_f32_e32 v226, v218, v210
	v_fma_f32 v186, -v202, v226, v218
	v_fmac_f32_e32 v226, v186, v210
	v_fma_f32 v218, -v202, v226, v218
	v_div_fmas_f32 v218, v218, v210, v226
	v_div_fixup_f32 v186, v218, v194, 1.0
	v_div_scale_f32 v219, vcc, 1.0, v195, 1.0
	v_mul_f32_e32 v227, v219, v211
	v_fma_f32 v187, -v203, v227, v219
	v_fmac_f32_e32 v227, v187, v211
	v_fma_f32 v219, -v203, v227, v219
	v_div_fmas_f32 v219, v219, v211, v227
	v_div_fixup_f32 v187, v219, v195, 1.0
	v_div_scale_f32 v220, vcc, 1.0, v196, 1.0
	v_mul_f32_e32 v228, v220, v212
	v_fma_f32 v188, -v204, v228, v220
	v_fmac_f32_e32 v228, v188, v212
	v_fma_f32 v220, -v204, v228, v220
	v_div_fmas_f32 v220, v220, v212, v228
	v_div_fixup_f32 v188, v220, v196, 1.0
	v_div_scale_f32 v221, vcc, 1.0, v197, 1.0
	v_mul_f32_e32 v229, v221, v213
	v_fma_f32 v189, -v205, v229, v221
	v_fmac_f32_e32 v229, v189, v213
	v_fma_f32 v221, -v205, v229, v221
	v_div_fmas_f32 v221, v221, v213, v229
	v_div_fixup_f32 v189, v221, v197, 1.0
	v_div_scale_f32 v222, vcc, 1.0, v198, 1.0
	v_mul_f32_e32 v230, v222, v214
	v_fma_f32 v190, -v206, v230, v222
	v_fmac_f32_e32 v230, v190, v214
	v_fma_f32 v222, -v206, v230, v222
	v_div_fmas_f32 v222, v222, v214, v230
	v_div_fixup_f32 v190, v222, v198, 1.0
	v_div_scale_f32 v223, vcc, 1.0, v199, 1.0
	v_mul_f32_e32 v231, v223, v215
	v_fma_f32 v191, -v207, v231, v223
	v_fmac_f32_e32 v231, v191, v215
	v_fma_f32 v223, -v207, v231, v223
	v_div_fmas_f32 v223, v223, v215, v231
	v_div_fixup_f32 v191, v223, v199, 1.0
	v_lshlrev_b32_e32 v192, 16, v160
	v_and_b32_e32 v193, 0xffff0000, v160
	v_lshlrev_b32_e32 v200, 16, v180
	v_and_b32_e32 v201, 0xffff0000, v180
	v_lshlrev_b32_e32 v194, 16, v161
	v_and_b32_e32 v195, 0xffff0000, v161
	v_lshlrev_b32_e32 v202, 16, v181
	v_and_b32_e32 v203, 0xffff0000, v181
	v_lshlrev_b32_e32 v196, 16, v162
	v_and_b32_e32 v197, 0xffff0000, v162
	v_lshlrev_b32_e32 v204, 16, v182
	v_and_b32_e32 v205, 0xffff0000, v182
	v_lshlrev_b32_e32 v198, 16, v163
	v_and_b32_e32 v199, 0xffff0000, v163
	v_lshlrev_b32_e32 v206, 16, v183
	v_and_b32_e32 v207, 0xffff0000, v183
	v_fma_f32 v184, v184, v200, v192
	v_fma_f32 v185, v185, v201, v193
	v_fma_f32 v186, v186, v202, v194
	v_fma_f32 v187, v187, v203, v195
	v_fma_f32 v188, v188, v204, v196
	v_fma_f32 v189, v189, v205, v197
	v_fma_f32 v190, v190, v206, v198
	v_fma_f32 v191, v191, v207, v199
	v_cvt_pk_bf16_f32 v220, v184, v185
	v_cvt_pk_bf16_f32 v221, v186, v187
	v_cvt_pk_bf16_f32 v222, v188, v189
	v_cvt_pk_bf16_f32 v223, v190, v191
	s_nop 1
	v_permlane16_swap_b32_e32 v220, v222
	v_permlane16_swap_b32_e32 v221, v223
	global_store_dwordx4 v246, v[220:223], s[26:27] offset:64
	global_load_dwordx4 v[148:151], v243, s[86:87]
	s_add_u32 s86, s86, 0x1000
	s_addc_u32 s87, s87, 0
	global_load_dwordx4 v[164:167], v243, s[88:89]
	s_add_u32 s88, s88, 0x1000
	s_addc_u32 s89, s89, 0
	global_load_dwordx4 v[152:155], v243, s[86:87]
	s_add_u32 s86, s86, 0x1000
	s_addc_u32 s87, s87, 0
	global_load_dwordx4 v[172:175], v243, s[88:89]
	s_add_u32 s88, s88, 0x1000
	s_addc_u32 s89, s89, 0
	global_load_dwordx4 v[156:159], v243, s[86:87]
	s_add_u32 s86, s86, 0x1000
	s_addc_u32 s87, s87, 0
	global_load_dwordx4 v[176:179], v243, s[88:89]
	s_add_u32 s88, s88, 0x1000
	s_addc_u32 s89, s89, 0
	global_load_dwordx4 v[160:163], v243, s[86:87]
	s_add_u32 s86, s86, 0x1000
	s_addc_u32 s87, s87, 0
	global_load_dwordx4 v[180:183], v243, s[88:89]
	s_add_u32 s88, s88, 0x1000
	s_addc_u32 s89, s89, 0
	s_waitcnt vmcnt(6)
	v_add_f32_e32 v184, v32, v128
	v_add_f32_e32 v185, v33, v129
	v_add_f32_e32 v186, v34, v130
	v_add_f32_e32 v187, v35, v131
	v_add_f32_e32 v188, v36, v132
	v_add_f32_e32 v189, v37, v133
	v_add_f32_e32 v190, v38, v134
	v_add_f32_e32 v191, v39, v135
	v_mul_f32_e32 v184, 0xbfb8aa3b, v184
	v_mul_f32_e32 v185, 0xbfb8aa3b, v185
	v_mul_f32_e32 v186, 0xbfb8aa3b, v186
	v_mul_f32_e32 v187, 0xbfb8aa3b, v187
	v_mul_f32_e32 v188, 0xbfb8aa3b, v188
	v_mul_f32_e32 v189, 0xbfb8aa3b, v189
	v_mul_f32_e32 v190, 0xbfb8aa3b, v190
	v_mul_f32_e32 v191, 0xbfb8aa3b, v191
	v_exp_f32_e32 v192, v184
	v_exp_f32_e32 v193, v185
	v_exp_f32_e32 v194, v186
	v_exp_f32_e32 v195, v187
	v_exp_f32_e32 v196, v188
	v_exp_f32_e32 v197, v189
	v_exp_f32_e32 v198, v190
	v_exp_f32_e32 v199, v191
	v_add_f32_e32 v192, 1.0, v192
	v_add_f32_e32 v193, 1.0, v193
	v_add_f32_e32 v194, 1.0, v194
	v_add_f32_e32 v195, 1.0, v195
	v_add_f32_e32 v196, 1.0, v196
	v_add_f32_e32 v197, 1.0, v197
	v_add_f32_e32 v198, 1.0, v198
	v_add_f32_e32 v199, 1.0, v199
	v_div_scale_f32 v200, s[76:77], v192, v192, 1.0
	v_div_scale_f32 v201, s[76:77], v193, v193, 1.0
	v_div_scale_f32 v202, s[76:77], v194, v194, 1.0
	v_div_scale_f32 v203, s[76:77], v195, v195, 1.0
	v_div_scale_f32 v204, s[76:77], v196, v196, 1.0
	v_div_scale_f32 v205, s[76:77], v197, v197, 1.0
	v_div_scale_f32 v206, s[76:77], v198, v198, 1.0
	v_div_scale_f32 v207, s[76:77], v199, v199, 1.0
	v_rcp_f32_e32 v208, v200
	v_rcp_f32_e32 v209, v201
	v_rcp_f32_e32 v210, v202
	v_rcp_f32_e32 v211, v203
	v_rcp_f32_e32 v212, v204
	v_rcp_f32_e32 v213, v205
	v_rcp_f32_e32 v214, v206
	v_rcp_f32_e32 v215, v207
	v_fma_f32 v184, -v200, v208, 1.0
	v_fma_f32 v185, -v201, v209, 1.0
	v_fma_f32 v186, -v202, v210, 1.0
	v_fma_f32 v187, -v203, v211, 1.0
	v_fma_f32 v188, -v204, v212, 1.0
	v_fma_f32 v189, -v205, v213, 1.0
	v_fma_f32 v190, -v206, v214, 1.0
	v_fma_f32 v191, -v207, v215, 1.0
	v_fmac_f32_e32 v208, v184, v208
	v_fmac_f32_e32 v209, v185, v209
	v_fmac_f32_e32 v210, v186, v210
	v_fmac_f32_e32 v211, v187, v211
	v_fmac_f32_e32 v212, v188, v212
	v_fmac_f32_e32 v213, v189, v213
	v_fmac_f32_e32 v214, v190, v214
	v_fmac_f32_e32 v215, v191, v215
	v_div_scale_f32 v216, vcc, 1.0, v192, 1.0
	v_mul_f32_e32 v224, v216, v208
	v_fma_f32 v184, -v200, v224, v216
	v_fmac_f32_e32 v224, v184, v208
	v_fma_f32 v216, -v200, v224, v216
	v_div_fmas_f32 v216, v216, v208, v224
	v_div_fixup_f32 v184, v216, v192, 1.0
	v_div_scale_f32 v217, vcc, 1.0, v193, 1.0
	v_mul_f32_e32 v225, v217, v209
	v_fma_f32 v185, -v201, v225, v217
	v_fmac_f32_e32 v225, v185, v209
	v_fma_f32 v217, -v201, v225, v217
	v_div_fmas_f32 v217, v217, v209, v225
	v_div_fixup_f32 v185, v217, v193, 1.0
	v_div_scale_f32 v218, vcc, 1.0, v194, 1.0
	v_mul_f32_e32 v226, v218, v210
	v_fma_f32 v186, -v202, v226, v218
	v_fmac_f32_e32 v226, v186, v210
	v_fma_f32 v218, -v202, v226, v218
	v_div_fmas_f32 v218, v218, v210, v226
	v_div_fixup_f32 v186, v218, v194, 1.0
	v_div_scale_f32 v219, vcc, 1.0, v195, 1.0
	v_mul_f32_e32 v227, v219, v211
	v_fma_f32 v187, -v203, v227, v219
	v_fmac_f32_e32 v227, v187, v211
	v_fma_f32 v219, -v203, v227, v219
	v_div_fmas_f32 v219, v219, v211, v227
	v_div_fixup_f32 v187, v219, v195, 1.0
	v_div_scale_f32 v220, vcc, 1.0, v196, 1.0
	v_mul_f32_e32 v228, v220, v212
	v_fma_f32 v188, -v204, v228, v220
	v_fmac_f32_e32 v228, v188, v212
	v_fma_f32 v220, -v204, v228, v220
	v_div_fmas_f32 v220, v220, v212, v228
	v_div_fixup_f32 v188, v220, v196, 1.0
	v_div_scale_f32 v221, vcc, 1.0, v197, 1.0
	v_mul_f32_e32 v229, v221, v213
	v_fma_f32 v189, -v205, v229, v221
	v_fmac_f32_e32 v229, v189, v213
	v_fma_f32 v221, -v205, v229, v221
	v_div_fmas_f32 v221, v221, v213, v229
	v_div_fixup_f32 v189, v221, v197, 1.0
	v_div_scale_f32 v222, vcc, 1.0, v198, 1.0
	v_mul_f32_e32 v230, v222, v214
	v_fma_f32 v190, -v206, v230, v222
	v_fmac_f32_e32 v230, v190, v214
	v_fma_f32 v222, -v206, v230, v222
	v_div_fmas_f32 v222, v222, v214, v230
	v_div_fixup_f32 v190, v222, v198, 1.0
	v_div_scale_f32 v223, vcc, 1.0, v199, 1.0
	v_mul_f32_e32 v231, v223, v215
	v_fma_f32 v191, -v207, v231, v223
	v_fmac_f32_e32 v231, v191, v215
	v_fma_f32 v223, -v207, v231, v223
	v_div_fmas_f32 v223, v223, v215, v231
	v_div_fixup_f32 v191, v223, v199, 1.0
	v_lshlrev_b32_e32 v192, 16, v148
	v_and_b32_e32 v193, 0xffff0000, v148
	v_lshlrev_b32_e32 v200, 16, v164
	v_and_b32_e32 v201, 0xffff0000, v164
	v_lshlrev_b32_e32 v194, 16, v149
	v_and_b32_e32 v195, 0xffff0000, v149
	v_lshlrev_b32_e32 v202, 16, v165
	v_and_b32_e32 v203, 0xffff0000, v165
	v_lshlrev_b32_e32 v196, 16, v150
	v_and_b32_e32 v197, 0xffff0000, v150
	v_lshlrev_b32_e32 v204, 16, v166
	v_and_b32_e32 v205, 0xffff0000, v166
	v_lshlrev_b32_e32 v198, 16, v151
	v_and_b32_e32 v199, 0xffff0000, v151
	v_lshlrev_b32_e32 v206, 16, v167
	v_and_b32_e32 v207, 0xffff0000, v167
	v_fma_f32 v184, v184, v200, v192
	v_fma_f32 v185, v185, v201, v193
	v_fma_f32 v186, v186, v202, v194
	v_fma_f32 v187, v187, v203, v195
	v_fma_f32 v188, v188, v204, v196
	v_fma_f32 v189, v189, v205, v197
	v_fma_f32 v190, v190, v206, v198
	v_fma_f32 v191, v191, v207, v199
	v_cvt_pk_bf16_f32 v216, v184, v185
	v_cvt_pk_bf16_f32 v217, v186, v187
	v_cvt_pk_bf16_f32 v218, v188, v189
	v_cvt_pk_bf16_f32 v219, v190, v191
	s_nop 1
	v_permlane16_swap_b32_e32 v216, v218
	v_permlane16_swap_b32_e32 v217, v219
	global_store_dwordx4 v247, v[216:219], s[26:27]
	s_waitcnt vmcnt(5)
	v_add_f32_e32 v184, v40, v136
	v_add_f32_e32 v185, v41, v137
	v_add_f32_e32 v186, v42, v138
	v_add_f32_e32 v187, v43, v139
	v_add_f32_e32 v188, v44, v140
	v_add_f32_e32 v189, v45, v141
	v_add_f32_e32 v190, v46, v142
	v_add_f32_e32 v191, v47, v143
	v_mul_f32_e32 v184, 0xbfb8aa3b, v184
	v_mul_f32_e32 v185, 0xbfb8aa3b, v185
	v_mul_f32_e32 v186, 0xbfb8aa3b, v186
	v_mul_f32_e32 v187, 0xbfb8aa3b, v187
	v_mul_f32_e32 v188, 0xbfb8aa3b, v188
	v_mul_f32_e32 v189, 0xbfb8aa3b, v189
	v_mul_f32_e32 v190, 0xbfb8aa3b, v190
	v_mul_f32_e32 v191, 0xbfb8aa3b, v191
	v_exp_f32_e32 v192, v184
	v_exp_f32_e32 v193, v185
	v_exp_f32_e32 v194, v186
	v_exp_f32_e32 v195, v187
	v_exp_f32_e32 v196, v188
	v_exp_f32_e32 v197, v189
	v_exp_f32_e32 v198, v190
	v_exp_f32_e32 v199, v191
	v_add_f32_e32 v192, 1.0, v192
	v_add_f32_e32 v193, 1.0, v193
	v_add_f32_e32 v194, 1.0, v194
	v_add_f32_e32 v195, 1.0, v195
	v_add_f32_e32 v196, 1.0, v196
	v_add_f32_e32 v197, 1.0, v197
	v_add_f32_e32 v198, 1.0, v198
	v_add_f32_e32 v199, 1.0, v199
	v_div_scale_f32 v200, s[76:77], v192, v192, 1.0
	v_div_scale_f32 v201, s[76:77], v193, v193, 1.0
	v_div_scale_f32 v202, s[76:77], v194, v194, 1.0
	v_div_scale_f32 v203, s[76:77], v195, v195, 1.0
	v_div_scale_f32 v204, s[76:77], v196, v196, 1.0
	v_div_scale_f32 v205, s[76:77], v197, v197, 1.0
	v_div_scale_f32 v206, s[76:77], v198, v198, 1.0
	v_div_scale_f32 v207, s[76:77], v199, v199, 1.0
	v_rcp_f32_e32 v208, v200
	v_rcp_f32_e32 v209, v201
	v_rcp_f32_e32 v210, v202
	v_rcp_f32_e32 v211, v203
	v_rcp_f32_e32 v212, v204
	v_rcp_f32_e32 v213, v205
	v_rcp_f32_e32 v214, v206
	v_rcp_f32_e32 v215, v207
	v_fma_f32 v184, -v200, v208, 1.0
	v_fma_f32 v185, -v201, v209, 1.0
	v_fma_f32 v186, -v202, v210, 1.0
	v_fma_f32 v187, -v203, v211, 1.0
	v_fma_f32 v188, -v204, v212, 1.0
	v_fma_f32 v189, -v205, v213, 1.0
	v_fma_f32 v190, -v206, v214, 1.0
	v_fma_f32 v191, -v207, v215, 1.0
	v_fmac_f32_e32 v208, v184, v208
	v_fmac_f32_e32 v209, v185, v209
	v_fmac_f32_e32 v210, v186, v210
	v_fmac_f32_e32 v211, v187, v211
	v_fmac_f32_e32 v212, v188, v212
	v_fmac_f32_e32 v213, v189, v213
	v_fmac_f32_e32 v214, v190, v214
	v_fmac_f32_e32 v215, v191, v215
	v_div_scale_f32 v216, vcc, 1.0, v192, 1.0
	v_mul_f32_e32 v224, v216, v208
	v_fma_f32 v184, -v200, v224, v216
	v_fmac_f32_e32 v224, v184, v208
	v_fma_f32 v216, -v200, v224, v216
	v_div_fmas_f32 v216, v216, v208, v224
	v_div_fixup_f32 v184, v216, v192, 1.0
	v_div_scale_f32 v217, vcc, 1.0, v193, 1.0
	v_mul_f32_e32 v225, v217, v209
	v_fma_f32 v185, -v201, v225, v217
	v_fmac_f32_e32 v225, v185, v209
	v_fma_f32 v217, -v201, v225, v217
	v_div_fmas_f32 v217, v217, v209, v225
	v_div_fixup_f32 v185, v217, v193, 1.0
	v_div_scale_f32 v218, vcc, 1.0, v194, 1.0
	v_mul_f32_e32 v226, v218, v210
	v_fma_f32 v186, -v202, v226, v218
	v_fmac_f32_e32 v226, v186, v210
	v_fma_f32 v218, -v202, v226, v218
	v_div_fmas_f32 v218, v218, v210, v226
	v_div_fixup_f32 v186, v218, v194, 1.0
	v_div_scale_f32 v219, vcc, 1.0, v195, 1.0
	v_mul_f32_e32 v227, v219, v211
	v_fma_f32 v187, -v203, v227, v219
	v_fmac_f32_e32 v227, v187, v211
	v_fma_f32 v219, -v203, v227, v219
	v_div_fmas_f32 v219, v219, v211, v227
	v_div_fixup_f32 v187, v219, v195, 1.0
	v_div_scale_f32 v220, vcc, 1.0, v196, 1.0
	v_mul_f32_e32 v228, v220, v212
	v_fma_f32 v188, -v204, v228, v220
	v_fmac_f32_e32 v228, v188, v212
	v_fma_f32 v220, -v204, v228, v220
	v_div_fmas_f32 v220, v220, v212, v228
	v_div_fixup_f32 v188, v220, v196, 1.0
	v_div_scale_f32 v221, vcc, 1.0, v197, 1.0
	v_mul_f32_e32 v229, v221, v213
	v_fma_f32 v189, -v205, v229, v221
	v_fmac_f32_e32 v229, v189, v213
	v_fma_f32 v221, -v205, v229, v221
	v_div_fmas_f32 v221, v221, v213, v229
	v_div_fixup_f32 v189, v221, v197, 1.0
	v_div_scale_f32 v222, vcc, 1.0, v198, 1.0
	v_mul_f32_e32 v230, v222, v214
	v_fma_f32 v190, -v206, v230, v222
	v_fmac_f32_e32 v230, v190, v214
	v_fma_f32 v222, -v206, v230, v222
	v_div_fmas_f32 v222, v222, v214, v230
	v_div_fixup_f32 v190, v222, v198, 1.0
	v_div_scale_f32 v223, vcc, 1.0, v199, 1.0
	v_mul_f32_e32 v231, v223, v215
	v_fma_f32 v191, -v207, v231, v223
	v_fmac_f32_e32 v231, v191, v215
	v_fma_f32 v223, -v207, v231, v223
	v_div_fmas_f32 v223, v223, v215, v231
	v_div_fixup_f32 v191, v223, v199, 1.0
	v_lshlrev_b32_e32 v192, 16, v152
	v_and_b32_e32 v193, 0xffff0000, v152
	v_lshlrev_b32_e32 v200, 16, v172
	v_and_b32_e32 v201, 0xffff0000, v172
	v_lshlrev_b32_e32 v194, 16, v153
	v_and_b32_e32 v195, 0xffff0000, v153
	v_lshlrev_b32_e32 v202, 16, v173
	v_and_b32_e32 v203, 0xffff0000, v173
	v_lshlrev_b32_e32 v196, 16, v154
	v_and_b32_e32 v197, 0xffff0000, v154
	v_lshlrev_b32_e32 v204, 16, v174
	v_and_b32_e32 v205, 0xffff0000, v174
	v_lshlrev_b32_e32 v198, 16, v155
	v_and_b32_e32 v199, 0xffff0000, v155
	v_lshlrev_b32_e32 v206, 16, v175
	v_and_b32_e32 v207, 0xffff0000, v175
	v_fma_f32 v184, v184, v200, v192
	v_fma_f32 v185, v185, v201, v193
	v_fma_f32 v186, v186, v202, v194
	v_fma_f32 v187, v187, v203, v195
	v_fma_f32 v188, v188, v204, v196
	v_fma_f32 v189, v189, v205, v197
	v_fma_f32 v190, v190, v206, v198
	v_fma_f32 v191, v191, v207, v199
	v_cvt_pk_bf16_f32 v220, v184, v185
	v_cvt_pk_bf16_f32 v221, v186, v187
	v_cvt_pk_bf16_f32 v222, v188, v189
	v_cvt_pk_bf16_f32 v223, v190, v191
	s_nop 1
	v_permlane16_swap_b32_e32 v220, v222
	v_permlane16_swap_b32_e32 v221, v223
	global_store_dwordx4 v247, v[220:223], s[26:27] offset:64
	s_waitcnt vmcnt(4)
	v_add_f32_e32 v184, v48, v128
	v_add_f32_e32 v185, v49, v129
	v_add_f32_e32 v186, v50, v130
	v_add_f32_e32 v187, v51, v131
	v_add_f32_e32 v188, v52, v132
	v_add_f32_e32 v189, v53, v133
	v_add_f32_e32 v190, v54, v134
	v_add_f32_e32 v191, v55, v135
	v_mul_f32_e32 v184, 0xbfb8aa3b, v184
	v_mul_f32_e32 v185, 0xbfb8aa3b, v185
	v_mul_f32_e32 v186, 0xbfb8aa3b, v186
	v_mul_f32_e32 v187, 0xbfb8aa3b, v187
	v_mul_f32_e32 v188, 0xbfb8aa3b, v188
	v_mul_f32_e32 v189, 0xbfb8aa3b, v189
	v_mul_f32_e32 v190, 0xbfb8aa3b, v190
	v_mul_f32_e32 v191, 0xbfb8aa3b, v191
	v_exp_f32_e32 v192, v184
	v_exp_f32_e32 v193, v185
	v_exp_f32_e32 v194, v186
	v_exp_f32_e32 v195, v187
	v_exp_f32_e32 v196, v188
	v_exp_f32_e32 v197, v189
	v_exp_f32_e32 v198, v190
	v_exp_f32_e32 v199, v191
	v_add_f32_e32 v192, 1.0, v192
	v_add_f32_e32 v193, 1.0, v193
	v_add_f32_e32 v194, 1.0, v194
	v_add_f32_e32 v195, 1.0, v195
	v_add_f32_e32 v196, 1.0, v196
	v_add_f32_e32 v197, 1.0, v197
	v_add_f32_e32 v198, 1.0, v198
	v_add_f32_e32 v199, 1.0, v199
	v_div_scale_f32 v200, s[76:77], v192, v192, 1.0
	v_div_scale_f32 v201, s[76:77], v193, v193, 1.0
	v_div_scale_f32 v202, s[76:77], v194, v194, 1.0
	v_div_scale_f32 v203, s[76:77], v195, v195, 1.0
	v_div_scale_f32 v204, s[76:77], v196, v196, 1.0
	v_div_scale_f32 v205, s[76:77], v197, v197, 1.0
	v_div_scale_f32 v206, s[76:77], v198, v198, 1.0
	v_div_scale_f32 v207, s[76:77], v199, v199, 1.0
	v_rcp_f32_e32 v208, v200
	v_rcp_f32_e32 v209, v201
	v_rcp_f32_e32 v210, v202
	v_rcp_f32_e32 v211, v203
	v_rcp_f32_e32 v212, v204
	v_rcp_f32_e32 v213, v205
	v_rcp_f32_e32 v214, v206
	v_rcp_f32_e32 v215, v207
	v_fma_f32 v184, -v200, v208, 1.0
	v_fma_f32 v185, -v201, v209, 1.0
	v_fma_f32 v186, -v202, v210, 1.0
	v_fma_f32 v187, -v203, v211, 1.0
	v_fma_f32 v188, -v204, v212, 1.0
	v_fma_f32 v189, -v205, v213, 1.0
	v_fma_f32 v190, -v206, v214, 1.0
	v_fma_f32 v191, -v207, v215, 1.0
	v_fmac_f32_e32 v208, v184, v208
	v_fmac_f32_e32 v209, v185, v209
	v_fmac_f32_e32 v210, v186, v210
	v_fmac_f32_e32 v211, v187, v211
	v_fmac_f32_e32 v212, v188, v212
	v_fmac_f32_e32 v213, v189, v213
	v_fmac_f32_e32 v214, v190, v214
	v_fmac_f32_e32 v215, v191, v215
	v_div_scale_f32 v216, vcc, 1.0, v192, 1.0
	v_mul_f32_e32 v224, v216, v208
	v_fma_f32 v184, -v200, v224, v216
	v_fmac_f32_e32 v224, v184, v208
	v_fma_f32 v216, -v200, v224, v216
	v_div_fmas_f32 v216, v216, v208, v224
	v_div_fixup_f32 v184, v216, v192, 1.0
	v_div_scale_f32 v217, vcc, 1.0, v193, 1.0
	v_mul_f32_e32 v225, v217, v209
	v_fma_f32 v185, -v201, v225, v217
	v_fmac_f32_e32 v225, v185, v209
	v_fma_f32 v217, -v201, v225, v217
	v_div_fmas_f32 v217, v217, v209, v225
	v_div_fixup_f32 v185, v217, v193, 1.0
	v_div_scale_f32 v218, vcc, 1.0, v194, 1.0
	v_mul_f32_e32 v226, v218, v210
	v_fma_f32 v186, -v202, v226, v218
	v_fmac_f32_e32 v226, v186, v210
	v_fma_f32 v218, -v202, v226, v218
	v_div_fmas_f32 v218, v218, v210, v226
	v_div_fixup_f32 v186, v218, v194, 1.0
	v_div_scale_f32 v219, vcc, 1.0, v195, 1.0
	v_mul_f32_e32 v227, v219, v211
	v_fma_f32 v187, -v203, v227, v219
	v_fmac_f32_e32 v227, v187, v211
	v_fma_f32 v219, -v203, v227, v219
	v_div_fmas_f32 v219, v219, v211, v227
	v_div_fixup_f32 v187, v219, v195, 1.0
	v_div_scale_f32 v220, vcc, 1.0, v196, 1.0
	v_mul_f32_e32 v228, v220, v212
	v_fma_f32 v188, -v204, v228, v220
	v_fmac_f32_e32 v228, v188, v212
	v_fma_f32 v220, -v204, v228, v220
	v_div_fmas_f32 v220, v220, v212, v228
	v_div_fixup_f32 v188, v220, v196, 1.0
	v_div_scale_f32 v221, vcc, 1.0, v197, 1.0
	v_mul_f32_e32 v229, v221, v213
	v_fma_f32 v189, -v205, v229, v221
	v_fmac_f32_e32 v229, v189, v213
	v_fma_f32 v221, -v205, v229, v221
	v_div_fmas_f32 v221, v221, v213, v229
	v_div_fixup_f32 v189, v221, v197, 1.0
	v_div_scale_f32 v222, vcc, 1.0, v198, 1.0
	v_mul_f32_e32 v230, v222, v214
	v_fma_f32 v190, -v206, v230, v222
	v_fmac_f32_e32 v230, v190, v214
	v_fma_f32 v222, -v206, v230, v222
	v_div_fmas_f32 v222, v222, v214, v230
	v_div_fixup_f32 v190, v222, v198, 1.0
	v_div_scale_f32 v223, vcc, 1.0, v199, 1.0
	v_mul_f32_e32 v231, v223, v215
	v_fma_f32 v191, -v207, v231, v223
	v_fmac_f32_e32 v231, v191, v215
	v_fma_f32 v223, -v207, v231, v223
	v_div_fmas_f32 v223, v223, v215, v231
	v_div_fixup_f32 v191, v223, v199, 1.0
	v_lshlrev_b32_e32 v192, 16, v156
	v_and_b32_e32 v193, 0xffff0000, v156
	v_lshlrev_b32_e32 v200, 16, v176
	v_and_b32_e32 v201, 0xffff0000, v176
	v_lshlrev_b32_e32 v194, 16, v157
	v_and_b32_e32 v195, 0xffff0000, v157
	v_lshlrev_b32_e32 v202, 16, v177
	v_and_b32_e32 v203, 0xffff0000, v177
	v_lshlrev_b32_e32 v196, 16, v158
	v_and_b32_e32 v197, 0xffff0000, v158
	v_lshlrev_b32_e32 v204, 16, v178
	v_and_b32_e32 v205, 0xffff0000, v178
	v_lshlrev_b32_e32 v198, 16, v159
	v_and_b32_e32 v199, 0xffff0000, v159
	v_lshlrev_b32_e32 v206, 16, v179
	v_and_b32_e32 v207, 0xffff0000, v179
	v_fma_f32 v184, v184, v200, v192
	v_fma_f32 v185, v185, v201, v193
	v_fma_f32 v186, v186, v202, v194
	v_fma_f32 v187, v187, v203, v195
	v_fma_f32 v188, v188, v204, v196
	v_fma_f32 v189, v189, v205, v197
	v_fma_f32 v190, v190, v206, v198
	v_fma_f32 v191, v191, v207, v199
	v_cvt_pk_bf16_f32 v216, v184, v185
	v_cvt_pk_bf16_f32 v217, v186, v187
	v_cvt_pk_bf16_f32 v218, v188, v189
	v_cvt_pk_bf16_f32 v219, v190, v191
	s_nop 1
	v_permlane16_swap_b32_e32 v216, v218
	v_permlane16_swap_b32_e32 v217, v219
	global_store_dwordx4 v248, v[216:219], s[26:27]
	s_waitcnt vmcnt(3)
	v_add_f32_e32 v184, v56, v136
	v_add_f32_e32 v185, v57, v137
	v_add_f32_e32 v186, v58, v138
	v_add_f32_e32 v187, v59, v139
	v_add_f32_e32 v188, v60, v140
	v_add_f32_e32 v189, v61, v141
	v_add_f32_e32 v190, v62, v142
	v_add_f32_e32 v191, v63, v143
	v_mul_f32_e32 v184, 0xbfb8aa3b, v184
	v_mul_f32_e32 v185, 0xbfb8aa3b, v185
	v_mul_f32_e32 v186, 0xbfb8aa3b, v186
	v_mul_f32_e32 v187, 0xbfb8aa3b, v187
	v_mul_f32_e32 v188, 0xbfb8aa3b, v188
	v_mul_f32_e32 v189, 0xbfb8aa3b, v189
	v_mul_f32_e32 v190, 0xbfb8aa3b, v190
	v_mul_f32_e32 v191, 0xbfb8aa3b, v191
	v_exp_f32_e32 v192, v184
	v_exp_f32_e32 v193, v185
	v_exp_f32_e32 v194, v186
	v_exp_f32_e32 v195, v187
	v_exp_f32_e32 v196, v188
	v_exp_f32_e32 v197, v189
	v_exp_f32_e32 v198, v190
	v_exp_f32_e32 v199, v191
	v_add_f32_e32 v192, 1.0, v192
	v_add_f32_e32 v193, 1.0, v193
	v_add_f32_e32 v194, 1.0, v194
	v_add_f32_e32 v195, 1.0, v195
	v_add_f32_e32 v196, 1.0, v196
	v_add_f32_e32 v197, 1.0, v197
	v_add_f32_e32 v198, 1.0, v198
	v_add_f32_e32 v199, 1.0, v199
	v_div_scale_f32 v200, s[76:77], v192, v192, 1.0
	v_div_scale_f32 v201, s[76:77], v193, v193, 1.0
	v_div_scale_f32 v202, s[76:77], v194, v194, 1.0
	v_div_scale_f32 v203, s[76:77], v195, v195, 1.0
	v_div_scale_f32 v204, s[76:77], v196, v196, 1.0
	v_div_scale_f32 v205, s[76:77], v197, v197, 1.0
	v_div_scale_f32 v206, s[76:77], v198, v198, 1.0
	v_div_scale_f32 v207, s[76:77], v199, v199, 1.0
	v_rcp_f32_e32 v208, v200
	v_rcp_f32_e32 v209, v201
	v_rcp_f32_e32 v210, v202
	v_rcp_f32_e32 v211, v203
	v_rcp_f32_e32 v212, v204
	v_rcp_f32_e32 v213, v205
	v_rcp_f32_e32 v214, v206
	v_rcp_f32_e32 v215, v207
	v_fma_f32 v184, -v200, v208, 1.0
	v_fma_f32 v185, -v201, v209, 1.0
	v_fma_f32 v186, -v202, v210, 1.0
	v_fma_f32 v187, -v203, v211, 1.0
	v_fma_f32 v188, -v204, v212, 1.0
	v_fma_f32 v189, -v205, v213, 1.0
	v_fma_f32 v190, -v206, v214, 1.0
	v_fma_f32 v191, -v207, v215, 1.0
	v_fmac_f32_e32 v208, v184, v208
	v_fmac_f32_e32 v209, v185, v209
	v_fmac_f32_e32 v210, v186, v210
	v_fmac_f32_e32 v211, v187, v211
	v_fmac_f32_e32 v212, v188, v212
	v_fmac_f32_e32 v213, v189, v213
	v_fmac_f32_e32 v214, v190, v214
	v_fmac_f32_e32 v215, v191, v215
	v_div_scale_f32 v216, vcc, 1.0, v192, 1.0
	v_mul_f32_e32 v224, v216, v208
	v_fma_f32 v184, -v200, v224, v216
	v_fmac_f32_e32 v224, v184, v208
	v_fma_f32 v216, -v200, v224, v216
	v_div_fmas_f32 v216, v216, v208, v224
	v_div_fixup_f32 v184, v216, v192, 1.0
	v_div_scale_f32 v217, vcc, 1.0, v193, 1.0
	v_mul_f32_e32 v225, v217, v209
	v_fma_f32 v185, -v201, v225, v217
	v_fmac_f32_e32 v225, v185, v209
	v_fma_f32 v217, -v201, v225, v217
	v_div_fmas_f32 v217, v217, v209, v225
	v_div_fixup_f32 v185, v217, v193, 1.0
	v_div_scale_f32 v218, vcc, 1.0, v194, 1.0
	v_mul_f32_e32 v226, v218, v210
	v_fma_f32 v186, -v202, v226, v218
	v_fmac_f32_e32 v226, v186, v210
	v_fma_f32 v218, -v202, v226, v218
	v_div_fmas_f32 v218, v218, v210, v226
	v_div_fixup_f32 v186, v218, v194, 1.0
	v_div_scale_f32 v219, vcc, 1.0, v195, 1.0
	v_mul_f32_e32 v227, v219, v211
	v_fma_f32 v187, -v203, v227, v219
	v_fmac_f32_e32 v227, v187, v211
	v_fma_f32 v219, -v203, v227, v219
	v_div_fmas_f32 v219, v219, v211, v227
	v_div_fixup_f32 v187, v219, v195, 1.0
	v_div_scale_f32 v220, vcc, 1.0, v196, 1.0
	v_mul_f32_e32 v228, v220, v212
	v_fma_f32 v188, -v204, v228, v220
	v_fmac_f32_e32 v228, v188, v212
	v_fma_f32 v220, -v204, v228, v220
	v_div_fmas_f32 v220, v220, v212, v228
	v_div_fixup_f32 v188, v220, v196, 1.0
	v_div_scale_f32 v221, vcc, 1.0, v197, 1.0
	v_mul_f32_e32 v229, v221, v213
	v_fma_f32 v189, -v205, v229, v221
	v_fmac_f32_e32 v229, v189, v213
	v_fma_f32 v221, -v205, v229, v221
	v_div_fmas_f32 v221, v221, v213, v229
	v_div_fixup_f32 v189, v221, v197, 1.0
	v_div_scale_f32 v222, vcc, 1.0, v198, 1.0
	v_mul_f32_e32 v230, v222, v214
	v_fma_f32 v190, -v206, v230, v222
	v_fmac_f32_e32 v230, v190, v214
	v_fma_f32 v222, -v206, v230, v222
	v_div_fmas_f32 v222, v222, v214, v230
	v_div_fixup_f32 v190, v222, v198, 1.0
	v_div_scale_f32 v223, vcc, 1.0, v199, 1.0
	v_mul_f32_e32 v231, v223, v215
	v_fma_f32 v191, -v207, v231, v223
	v_fmac_f32_e32 v231, v191, v215
	v_fma_f32 v223, -v207, v231, v223
	v_div_fmas_f32 v223, v223, v215, v231
	v_div_fixup_f32 v191, v223, v199, 1.0
	v_lshlrev_b32_e32 v192, 16, v160
	v_and_b32_e32 v193, 0xffff0000, v160
	v_lshlrev_b32_e32 v200, 16, v180
	v_and_b32_e32 v201, 0xffff0000, v180
	v_lshlrev_b32_e32 v194, 16, v161
	v_and_b32_e32 v195, 0xffff0000, v161
	v_lshlrev_b32_e32 v202, 16, v181
	v_and_b32_e32 v203, 0xffff0000, v181
	v_lshlrev_b32_e32 v196, 16, v162
	v_and_b32_e32 v197, 0xffff0000, v162
	v_lshlrev_b32_e32 v204, 16, v182
	v_and_b32_e32 v205, 0xffff0000, v182
	v_lshlrev_b32_e32 v198, 16, v163
	v_and_b32_e32 v199, 0xffff0000, v163
	v_lshlrev_b32_e32 v206, 16, v183
	v_and_b32_e32 v207, 0xffff0000, v183
	v_fma_f32 v184, v184, v200, v192
	v_fma_f32 v185, v185, v201, v193
	v_fma_f32 v186, v186, v202, v194
	v_fma_f32 v187, v187, v203, v195
	v_fma_f32 v188, v188, v204, v196
	v_fma_f32 v189, v189, v205, v197
	v_fma_f32 v190, v190, v206, v198
	v_fma_f32 v191, v191, v207, v199
	v_cvt_pk_bf16_f32 v220, v184, v185
	v_cvt_pk_bf16_f32 v221, v186, v187
	v_cvt_pk_bf16_f32 v222, v188, v189
	v_cvt_pk_bf16_f32 v223, v190, v191
	s_nop 1
	v_permlane16_swap_b32_e32 v220, v222
	v_permlane16_swap_b32_e32 v221, v223
	global_store_dwordx4 v248, v[220:223], s[26:27] offset:64
	s_cmp_eq_u32 s83, 1
	s_cbranch_scc1 .Lp6d_epdone
	s_cmp_eq_u32 s95, 1
	s_cbranch_scc0 .Lp6d_epdone
	v_mov_b32_e32 v0, v64
	v_mov_b32_e32 v1, v65
	v_mov_b32_e32 v2, v66
	v_mov_b32_e32 v3, v67
	v_mov_b32_e32 v4, v68
	v_mov_b32_e32 v5, v69
	v_mov_b32_e32 v6, v70
	v_mov_b32_e32 v7, v71
	v_mov_b32_e32 v8, v72
	v_mov_b32_e32 v9, v73
	v_mov_b32_e32 v10, v74
	v_mov_b32_e32 v11, v75
	v_mov_b32_e32 v12, v76
	v_mov_b32_e32 v13, v77
	v_mov_b32_e32 v14, v78
	v_mov_b32_e32 v15, v79
	v_mov_b32_e32 v16, v80
	v_mov_b32_e32 v17, v81
	v_mov_b32_e32 v18, v82
	v_mov_b32_e32 v19, v83
	v_mov_b32_e32 v20, v84
	v_mov_b32_e32 v21, v85
	v_mov_b32_e32 v22, v86
	v_mov_b32_e32 v23, v87
	v_mov_b32_e32 v24, v88
	v_mov_b32_e32 v25, v89
	v_mov_b32_e32 v26, v90
	v_mov_b32_e32 v27, v91
	v_mov_b32_e32 v28, v92
	v_mov_b32_e32 v29, v93
	v_mov_b32_e32 v30, v94
	v_mov_b32_e32 v31, v95
	v_mov_b32_e32 v32, v96
	v_mov_b32_e32 v33, v97
	v_mov_b32_e32 v34, v98
	v_mov_b32_e32 v35, v99
	v_mov_b32_e32 v36, v100
	v_mov_b32_e32 v37, v101
	v_mov_b32_e32 v38, v102
	v_mov_b32_e32 v39, v103
	v_mov_b32_e32 v40, v104
	v_mov_b32_e32 v41, v105
	v_mov_b32_e32 v42, v106
	v_mov_b32_e32 v43, v107
	v_mov_b32_e32 v44, v108
	v_mov_b32_e32 v45, v109
	v_mov_b32_e32 v46, v110
	v_mov_b32_e32 v47, v111
	v_mov_b32_e32 v48, v112
	v_mov_b32_e32 v49, v113
	v_mov_b32_e32 v50, v114
	v_mov_b32_e32 v51, v115
	v_mov_b32_e32 v52, v116
	v_mov_b32_e32 v53, v117
	v_mov_b32_e32 v54, v118
	v_mov_b32_e32 v55, v119
	v_mov_b32_e32 v56, v120
	v_mov_b32_e32 v57, v121
	v_mov_b32_e32 v58, v122
	v_mov_b32_e32 v59, v123
	v_mov_b32_e32 v60, v124
	v_mov_b32_e32 v61, v125
	v_mov_b32_e32 v62, v126
	v_mov_b32_e32 v63, v127
	s_mov_b32 s83, 1
	s_branch .Lp6d_ep

.LBB0_600:
	v_ashrrev_i32_e32 v17, 31, v16
	v_lshlrev_b64 v[14:15], 12, v[16:17]
	v_lshl_add_u64 v[14:15], v[18:19], 0, v[14:15]
	global_load_dwordx4 v[32:35], v[14:15], off
	global_load_dwordx4 v[36:39], v[14:15], off offset:1024
	global_load_dwordx4 v[40:43], v[14:15], off offset:2048
	global_load_dwordx4 v[44:47], v[14:15], off offset:3072
	s_add_i32 s6, s6, s52
	s_cmpk_lt_i32 s6, 0x1000
	s_waitcnt vmcnt(3)
	v_mov_b32_e32 v48, v33
	s_waitcnt vmcnt(2)
	v_mov_b32_e32 v49, v37
	v_mov_b32_e32 v14, v32
	v_mov_b32_e32 v15, v36
	s_waitcnt vmcnt(1)
	v_mov_b32_e32 v56, v41
	s_waitcnt vmcnt(0)
	v_mov_b32_e32 v57, v45
	v_pk_mul_f32 v[48:49], v[48:49], v[48:49]
	v_mov_b32_e32 v50, v34
	v_mov_b32_e32 v51, v38
	v_mov_b32_e32 v54, v40
	v_mov_b32_e32 v55, v44
	v_pk_mul_f32 v[56:57], v[56:57], v[56:57]
	v_pk_fma_f32 v[14:15], v[14:15], v[14:15], v[48:49]
	v_mov_b32_e32 v52, v35
	v_mov_b32_e32 v53, v39
	v_mov_b32_e32 v58, v42
	v_mov_b32_e32 v59, v46
	v_pk_fma_f32 v[48:49], v[54:55], v[54:55], v[56:57]
	v_pk_fma_f32 v[14:15], v[50:51], v[50:51], v[14:15]
	v_mov_b32_e32 v60, v43
	v_mov_b32_e32 v61, v47
	v_pk_fma_f32 v[48:49], v[58:59], v[58:59], v[48:49]
	v_pk_fma_f32 v[14:15], v[52:53], v[52:53], v[14:15]
	v_pk_fma_f32 v[48:49], v[60:61], v[60:61], v[48:49]
	v_add_f32_e32 v14, v14, v15
	v_add_f32_e32 v14, v14, v48
	v_add_f32_e32 v14, v14, v49
	ds_bpermute_b32 v15, v26, v14
	s_waitcnt lgkmcnt(0)
	v_add_f32_e32 v14, v14, v15
	ds_bpermute_b32 v15, v27, v14
	s_waitcnt lgkmcnt(0)
	v_add_f32_e32 v48, v14, v15
	ds_bpermute_b32 v49, v28, v48
	v_lshlrev_b64 v[14:15], 11, v[16:17]
	v_lshl_add_u64 v[14:15], v[20:21], 0, v[14:15]
	v_add_u32_e32 v16, s3, v16
	s_waitcnt lgkmcnt(0)
	v_add_f32_e32 v17, v48, v49
	ds_bpermute_b32 v50, v29, v17
	v_mov_b32_e32 v48, v32
	v_mov_b32_e32 v32, v33
	v_mov_b32_e32 v33, v35
	v_mov_b32_e32 v35, v38
	s_waitcnt lgkmcnt(0)
	v_add_f32_e32 v17, v17, v50
	ds_bpermute_b32 v50, v30, v17
	v_mov_b32_e32 v38, v37
	v_mov_b32_e32 v37, v42
	v_mov_b32_e32 v49, v34
	v_mov_b32_e32 v34, v36
	s_waitcnt lgkmcnt(0)
	v_add_f32_e32 v17, v17, v50
	ds_bpermute_b32 v50, v31, v17
	v_mov_b32_e32 v36, v40
	v_mov_b32_e32 v40, v41
	v_mov_b32_e32 v41, v43
	v_mov_b32_e32 v43, v46
	s_waitcnt lgkmcnt(0)
	v_add_f32_e32 v17, v17, v50
	v_fmamk_f32 v17, v17, 0x3a800000, v24
	v_mul_f32_e32 v42, 0x4b800000, v17
	v_cmp_gt_f32_e32 vcc, s8, v17
	v_mov_b32_e32 v46, v45
	s_nop 0
	v_cndmask_b32_e32 v17, v17, v42, vcc
	v_rsq_f32_e32 v17, v17
	v_mov_b32_e32 v42, v44
	v_mul_f32_e32 v44, 0x45800000, v17
	v_cndmask_b32_e32 v44, v17, v44, vcc
	v_pk_mul_f32 v[32:33], v[32:33], v[44:45] op_sel_hi:[1,0]
	v_pk_mul_f32 v[48:49], v[48:49], v[44:45] op_sel_hi:[1,0]
	v_pk_mul_f32 v[34:35], v[34:35], v[44:45] op_sel_hi:[1,0]
	v_pk_mul_f32 v[38:39], v[38:39], v[44:45] op_sel_hi:[1,0]
	v_pk_mul_f32 v[36:37], v[36:37], v[44:45] op_sel_hi:[1,0]
	v_pk_mul_f32 v[40:41], v[40:41], v[44:45] op_sel_hi:[1,0]
	v_pk_mul_f32 v[42:43], v[42:43], v[44:45] op_sel_hi:[1,0]
	v_pk_mul_f32 v[44:45], v[46:47], v[44:45] op_sel_hi:[1,0]
	v_pk_mul_f32 v[32:33], v[22:23], v[32:33]
	v_pk_mul_f32 v[46:47], v[0:1], v[48:49]
	v_pk_mul_f32 v[38:39], v[2:3], v[38:39]
	v_pk_mul_f32 v[40:41], v[40:41], v[6:7]
	v_pk_mul_f32 v[44:45], v[44:45], v[10:11]
	s_nop 0
	s_nop 0
	v_pk_mul_f32 v[34:35], v[4:5], v[34:35]
	v_pk_mul_f32 v[36:37], v[36:37], v[8:9]
	v_pk_mul_f32 v[42:43], v[42:43], v[12:13]
	s_nop 0
	s_nop 0
	s_nop 0
	s_nop 0
	s_nop 0
	s_nop 0
	s_nop 0
	s_nop 0
	v_cvt_pk_bf16_f32 v33, v33, v33
	v_cvt_pk_bf16_f32 v32, v32, v32
	s_nop 0
	s_nop 0
	s_nop 0
	s_nop 0
	s_nop 0
	s_nop 0
	v_cvt_pk_bf16_f32 v46, v46, v46
	v_cvt_pk_bf16_f32 v17, v47, v47
	v_cvt_pk_bf16_f32 v39, v39, v39
	v_cvt_pk_bf16_f32 v38, v38, v38
	v_cvt_pk_bf16_f32 v41, v41, v41
	v_cvt_pk_bf16_f32 v40, v40, v40
	v_cvt_pk_bf16_f32 v45, v45, v45
	v_cvt_pk_bf16_f32 v44, v44, v44
	v_and_b32_e32 v33, 0xffff0000, v33
	v_and_b32_e32 v32, 0xffff0000, v32
	v_cvt_pk_bf16_f32 v34, v34, v34
	v_cvt_pk_bf16_f32 v35, v35, v35
	v_cvt_pk_bf16_f32 v36, v36, v36
	v_cvt_pk_bf16_f32 v37, v37, v37
	v_cvt_pk_bf16_f32 v42, v42, v42
	v_cvt_pk_bf16_f32 v43, v43, v43
	v_and_b32_e32 v39, 0xffff0000, v39
	v_and_b32_e32 v38, 0xffff0000, v38
	v_and_b32_e32 v41, 0xffff0000, v41
	v_and_b32_e32 v40, 0xffff0000, v40
	v_and_b32_e32 v45, 0xffff0000, v45
	v_and_b32_e32 v44, 0xffff0000, v44
	v_or_b32_sdwa v33, v33, v17 dst_sel:DWORD dst_unused:UNUSED_PAD src0_sel:DWORD src1_sel:WORD_1
	v_or_b32_sdwa v32, v32, v46 dst_sel:DWORD dst_unused:UNUSED_PAD src0_sel:DWORD src1_sel:WORD_1
	v_or_b32_sdwa v35, v39, v35 dst_sel:DWORD dst_unused:UNUSED_PAD src0_sel:DWORD src1_sel:WORD_1
	v_or_b32_sdwa v34, v38, v34 dst_sel:DWORD dst_unused:UNUSED_PAD src0_sel:DWORD src1_sel:WORD_1
	v_or_b32_sdwa v37, v41, v37 dst_sel:DWORD dst_unused:UNUSED_PAD src0_sel:DWORD src1_sel:WORD_1
	v_or_b32_sdwa v36, v40, v36 dst_sel:DWORD dst_unused:UNUSED_PAD src0_sel:DWORD src1_sel:WORD_1
	v_or_b32_sdwa v39, v45, v43 dst_sel:DWORD dst_unused:UNUSED_PAD src0_sel:DWORD src1_sel:WORD_1
	v_or_b32_sdwa v38, v44, v42 dst_sel:DWORD dst_unused:UNUSED_PAD src0_sel:DWORD src1_sel:WORD_1
	global_store_dwordx2 v[14:15], v[32:33], off
	global_store_dwordx2 v[14:15], v[34:35], off offset:512
	global_store_dwordx2 v[14:15], v[36:37], off offset:1024
	global_store_dwordx2 v[14:15], v[38:39], off offset:1536
	s_cbranch_scc1 .LBB0_600

.Lgp9_last:
	v_mfma_f32_16x16x32_bf16 v[0:3], v[232:235], v[192:195], v[0:3]
	v_mfma_f32_16x16x32_bf16 v[116:119], v[100:103], v[192:195], v[116:119]
	v_mfma_f32_16x16x32_bf16 v[4:7], v[236:239], v[192:195], v[4:7]
	v_mfma_f32_16x16x32_bf16 v[120:123], v[104:107], v[192:195], v[120:123]
	v_mfma_f32_16x16x32_bf16 v[8:11], v[240:243], v[192:195], v[8:11]
	v_mfma_f32_16x16x32_bf16 v[124:127], v[68:71], v[192:195], v[124:127]
	v_mfma_f32_16x16x32_bf16 v[12:15], v[244:247], v[192:195], v[12:15]
	v_mfma_f32_16x16x32_bf16 v[128:131], v[80:83], v[192:195], v[128:131]
	v_mfma_f32_16x16x32_bf16 v[16:19], v[232:235], v[204:207], v[16:19]
	v_mfma_f32_16x16x32_bf16 v[132:135], v[100:103], v[204:207], v[132:135]
	v_mfma_f32_16x16x32_bf16 v[20:23], v[236:239], v[204:207], v[20:23]
	v_mfma_f32_16x16x32_bf16 v[136:139], v[104:107], v[204:207], v[136:139]
	v_mfma_f32_16x16x32_bf16 v[24:27], v[240:243], v[204:207], v[24:27]
	v_mfma_f32_16x16x32_bf16 v[140:143], v[68:71], v[204:207], v[140:143]
	v_mfma_f32_16x16x32_bf16 v[28:31], v[244:247], v[204:207], v[28:31]
	v_mfma_f32_16x16x32_bf16 v[148:151], v[80:83], v[204:207], v[148:151]
	v_mfma_f32_16x16x32_bf16 v[32:35], v[232:235], v[208:211], v[32:35]
	v_mfma_f32_16x16x32_bf16 v[152:155], v[100:103], v[208:211], v[152:155]
	v_mfma_f32_16x16x32_bf16 v[36:39], v[236:239], v[208:211], v[36:39]
	v_mfma_f32_16x16x32_bf16 v[156:159], v[104:107], v[208:211], v[156:159]
	v_mfma_f32_16x16x32_bf16 v[40:43], v[240:243], v[208:211], v[40:43]
	v_mfma_f32_16x16x32_bf16 v[160:163], v[68:71], v[208:211], v[160:163]
	v_mfma_f32_16x16x32_bf16 v[44:47], v[244:247], v[208:211], v[44:47]
	v_mfma_f32_16x16x32_bf16 v[172:175], v[80:83], v[208:211], v[172:175]
	v_mfma_f32_16x16x32_bf16 v[48:51], v[232:235], v[212:215], v[48:51]
	v_mfma_f32_16x16x32_bf16 v[176:179], v[100:103], v[212:215], v[176:179]
	v_mfma_f32_16x16x32_bf16 v[52:55], v[236:239], v[212:215], v[52:55]
	v_mfma_f32_16x16x32_bf16 v[180:183], v[104:107], v[212:215], v[180:183]
	v_mfma_f32_16x16x32_bf16 v[56:59], v[240:243], v[212:215], v[56:59]
	v_mfma_f32_16x16x32_bf16 v[184:187], v[68:71], v[212:215], v[184:187]
	v_mfma_f32_16x16x32_bf16 v[60:63], v[244:247], v[212:215], v[60:63]
	v_mfma_f32_16x16x32_bf16 v[188:191], v[80:83], v[212:215], v[188:191]
	s_waitcnt lgkmcnt(0)
	v_mfma_f32_16x16x32_bf16 v[0:3], v[248:251], v[216:219], v[0:3]
	v_mfma_f32_16x16x32_bf16 v[116:119], v[200:203], v[216:219], v[116:119]
	v_mfma_f32_16x16x32_bf16 v[4:7], v[252:255], v[216:219], v[4:7]
	v_mfma_f32_16x16x32_bf16 v[120:123], v[164:167], v[216:219], v[120:123]
	v_mfma_f32_16x16x32_bf16 v[8:11], v[92:95], v[216:219], v[8:11]
	v_mfma_f32_16x16x32_bf16 v[124:127], v[112:115], v[216:219], v[124:127]
	v_mfma_f32_16x16x32_bf16 v[12:15], v[96:99], v[216:219], v[12:15]
	v_mfma_f32_16x16x32_bf16 v[128:131], v[76:79], v[216:219], v[128:131]
	v_mfma_f32_16x16x32_bf16 v[16:19], v[248:251], v[220:223], v[16:19]
	v_mfma_f32_16x16x32_bf16 v[132:135], v[200:203], v[220:223], v[132:135]
	v_mfma_f32_16x16x32_bf16 v[20:23], v[252:255], v[220:223], v[20:23]
	v_mfma_f32_16x16x32_bf16 v[136:139], v[164:167], v[220:223], v[136:139]
	v_mfma_f32_16x16x32_bf16 v[24:27], v[92:95], v[220:223], v[24:27]
	v_mfma_f32_16x16x32_bf16 v[140:143], v[112:115], v[220:223], v[140:143]
	v_mfma_f32_16x16x32_bf16 v[28:31], v[96:99], v[220:223], v[28:31]
	v_mfma_f32_16x16x32_bf16 v[148:151], v[76:79], v[220:223], v[148:151]
	v_mfma_f32_16x16x32_bf16 v[32:35], v[248:251], v[224:227], v[32:35]
	v_mfma_f32_16x16x32_bf16 v[152:155], v[200:203], v[224:227], v[152:155]
	v_mfma_f32_16x16x32_bf16 v[36:39], v[252:255], v[224:227], v[36:39]
	v_mfma_f32_16x16x32_bf16 v[156:159], v[164:167], v[224:227], v[156:159]
	v_mfma_f32_16x16x32_bf16 v[40:43], v[92:95], v[224:227], v[40:43]
	v_mfma_f32_16x16x32_bf16 v[160:163], v[112:115], v[224:227], v[160:163]
	v_mfma_f32_16x16x32_bf16 v[44:47], v[96:99], v[224:227], v[44:47]
	v_mfma_f32_16x16x32_bf16 v[172:175], v[76:79], v[224:227], v[172:175]
	v_mfma_f32_16x16x32_bf16 v[48:51], v[248:251], v[228:231], v[48:51]
	v_mfma_f32_16x16x32_bf16 v[176:179], v[200:203], v[228:231], v[176:179]
	v_mfma_f32_16x16x32_bf16 v[52:55], v[252:255], v[228:231], v[52:55]
	v_mfma_f32_16x16x32_bf16 v[180:183], v[164:167], v[228:231], v[180:183]
	v_mfma_f32_16x16x32_bf16 v[56:59], v[92:95], v[228:231], v[56:59]
	v_mfma_f32_16x16x32_bf16 v[184:187], v[112:115], v[228:231], v[184:187]
	v_mfma_f32_16x16x32_bf16 v[60:63], v[96:99], v[228:231], v[60:63]
	v_mfma_f32_16x16x32_bf16 v[188:191], v[76:79], v[228:231], v[188:191]
	s_nop 7
	s_nop 3
	s_load_dwordx2 s[84:85], s[0:1], 0xa0
	v_lshrrev_b32_e32 v220, 1, v168
	v_and_b32_e32 v220, 0x1c0, v220
	v_and_b32_e32 v221, 15, v168
	v_or_b32_e32 v220, v220, v221
	v_lshl_add_u32 v220, s50, 7, v220
	v_lshlrev_b32_e32 v220, 12, v220
	v_bfe_u32 v221, v168, 4, 2
	v_lshlrev_b32_e32 v217, 3, v221
	v_and_b32_e32 v221, 1, v221
	v_mul_u32_u24_e32 v221, 24, v221
	v_add3_u32 v220, v220, v221, v217
	v_bfe_u32 v221, v168, 6, 1
	s_lshl_b32 s87, s48, 8
	v_lshl_add_u32 v216, v221, 7, v220
	v_add_u32_e32 v216, s87, v216
	v_add_u32_e32 v217, 0x10000, v216
	v_add_u32_e32 v218, 0x20000, v216
	v_add_u32_e32 v219, 0x30000, v216
	s_waitcnt lgkmcnt(0)
	v_cvt_pk_bf16_f32 v208, v0, v1
	v_cvt_pk_bf16_f32 v209, v2, v3
	v_cvt_pk_bf16_f32 v210, v4, v5
	v_cvt_pk_bf16_f32 v211, v6, v7
	s_nop 1
	v_permlane16_swap_b32_e32 v208, v210
	v_permlane16_swap_b32_e32 v209, v211
	global_store_dwordx4 v216, v[208:211], s[84:85]
	v_cvt_pk_bf16_f32 v212, v8, v9
	v_cvt_pk_bf16_f32 v213, v10, v11
	v_cvt_pk_bf16_f32 v214, v12, v13
	v_cvt_pk_bf16_f32 v215, v14, v15
	s_nop 1
	v_permlane16_swap_b32_e32 v212, v214
	v_permlane16_swap_b32_e32 v213, v215
	global_store_dwordx4 v216, v[212:215], s[84:85] offset:64
	v_cvt_pk_bf16_f32 v208, v16, v17
	v_cvt_pk_bf16_f32 v209, v18, v19
	v_cvt_pk_bf16_f32 v210, v20, v21
	v_cvt_pk_bf16_f32 v211, v22, v23
	s_nop 1
	v_permlane16_swap_b32_e32 v208, v210
	v_permlane16_swap_b32_e32 v209, v211
	global_store_dwordx4 v217, v[208:211], s[84:85]
	v_cvt_pk_bf16_f32 v212, v24, v25
	v_cvt_pk_bf16_f32 v213, v26, v27
	v_cvt_pk_bf16_f32 v214, v28, v29
	v_cvt_pk_bf16_f32 v215, v30, v31
	s_nop 1
	v_permlane16_swap_b32_e32 v212, v214
	v_permlane16_swap_b32_e32 v213, v215
	global_store_dwordx4 v217, v[212:215], s[84:85] offset:64
	v_cvt_pk_bf16_f32 v208, v32, v33
	v_cvt_pk_bf16_f32 v209, v34, v35
	v_cvt_pk_bf16_f32 v210, v36, v37
	v_cvt_pk_bf16_f32 v211, v38, v39
	s_nop 1
	v_permlane16_swap_b32_e32 v208, v210
	v_permlane16_swap_b32_e32 v209, v211
	global_store_dwordx4 v218, v[208:211], s[84:85]
	v_cvt_pk_bf16_f32 v212, v40, v41
	v_cvt_pk_bf16_f32 v213, v42, v43
	v_cvt_pk_bf16_f32 v214, v44, v45
	v_cvt_pk_bf16_f32 v215, v46, v47
	s_nop 1
	v_permlane16_swap_b32_e32 v212, v214
	v_permlane16_swap_b32_e32 v213, v215
	global_store_dwordx4 v218, v[212:215], s[84:85] offset:64
	v_cvt_pk_bf16_f32 v208, v48, v49
	v_cvt_pk_bf16_f32 v209, v50, v51
	v_cvt_pk_bf16_f32 v210, v52, v53
	v_cvt_pk_bf16_f32 v211, v54, v55
	s_nop 1
	v_permlane16_swap_b32_e32 v208, v210
	v_permlane16_swap_b32_e32 v209, v211
	global_store_dwordx4 v219, v[208:211], s[84:85]
	v_cvt_pk_bf16_f32 v212, v56, v57
	v_cvt_pk_bf16_f32 v213, v58, v59
	v_cvt_pk_bf16_f32 v214, v60, v61
	v_cvt_pk_bf16_f32 v215, v62, v63
	s_nop 1
	v_permlane16_swap_b32_e32 v212, v214
	v_permlane16_swap_b32_e32 v213, v215
	global_store_dwordx4 v219, v[212:215], s[84:85] offset:64
	s_cmp_eq_u32 s95, 1
	s_cbranch_scc0 .Lgp9_single
	s_load_dwordx2 s[84:85], s[0:1], 0xa0
	v_lshrrev_b32_e32 v220, 1, v168
	v_and_b32_e32 v220, 0x1c0, v220
	v_and_b32_e32 v221, 15, v168
	v_or_b32_e32 v220, v220, v221
	v_lshl_add_u32 v220, s50, 7, v220
	v_lshlrev_b32_e32 v220, 12, v220
	v_bfe_u32 v221, v168, 4, 2
	v_lshlrev_b32_e32 v217, 3, v221
	v_and_b32_e32 v221, 1, v221
	v_mul_u32_u24_e32 v221, 24, v221
	v_add3_u32 v220, v220, v221, v217
	v_bfe_u32 v221, v168, 6, 1
	s_lshl_b32 s87, s83, 8
	v_lshl_add_u32 v216, v221, 7, v220
	v_add_u32_e32 v216, s87, v216
	v_add_u32_e32 v217, 0x10000, v216
	v_add_u32_e32 v218, 0x20000, v216
	v_add_u32_e32 v219, 0x30000, v216
	s_waitcnt lgkmcnt(0)
	v_cvt_pk_bf16_f32 v208, v116, v117
	v_cvt_pk_bf16_f32 v209, v118, v119
	v_cvt_pk_bf16_f32 v210, v120, v121
	v_cvt_pk_bf16_f32 v211, v122, v123
	s_nop 1
	v_permlane16_swap_b32_e32 v208, v210
	v_permlane16_swap_b32_e32 v209, v211
	global_store_dwordx4 v216, v[208:211], s[84:85]
	v_cvt_pk_bf16_f32 v212, v124, v125
	v_cvt_pk_bf16_f32 v213, v126, v127
	v_cvt_pk_bf16_f32 v214, v128, v129
	v_cvt_pk_bf16_f32 v215, v130, v131
	s_nop 1
	v_permlane16_swap_b32_e32 v212, v214
	v_permlane16_swap_b32_e32 v213, v215
	global_store_dwordx4 v216, v[212:215], s[84:85] offset:64
	v_cvt_pk_bf16_f32 v208, v132, v133
	v_cvt_pk_bf16_f32 v209, v134, v135
	v_cvt_pk_bf16_f32 v210, v136, v137
	v_cvt_pk_bf16_f32 v211, v138, v139
	s_nop 1
	v_permlane16_swap_b32_e32 v208, v210
	v_permlane16_swap_b32_e32 v209, v211
	global_store_dwordx4 v217, v[208:211], s[84:85]
	v_cvt_pk_bf16_f32 v212, v140, v141
	v_cvt_pk_bf16_f32 v213, v142, v143
	v_cvt_pk_bf16_f32 v214, v148, v149
	v_cvt_pk_bf16_f32 v215, v150, v151
	s_nop 1
	v_permlane16_swap_b32_e32 v212, v214
	v_permlane16_swap_b32_e32 v213, v215
	global_store_dwordx4 v217, v[212:215], s[84:85] offset:64
	v_cvt_pk_bf16_f32 v208, v152, v153
	v_cvt_pk_bf16_f32 v209, v154, v155
	v_cvt_pk_bf16_f32 v210, v156, v157
	v_cvt_pk_bf16_f32 v211, v158, v159
	s_nop 1
	v_permlane16_swap_b32_e32 v208, v210
	v_permlane16_swap_b32_e32 v209, v211
	global_store_dwordx4 v218, v[208:211], s[84:85]
	v_cvt_pk_bf16_f32 v212, v160, v161
	v_cvt_pk_bf16_f32 v213, v162, v163
	v_cvt_pk_bf16_f32 v214, v172, v173
	v_cvt_pk_bf16_f32 v215, v174, v175
	s_nop 1
	v_permlane16_swap_b32_e32 v212, v214
	v_permlane16_swap_b32_e32 v213, v215
	global_store_dwordx4 v218, v[212:215], s[84:85] offset:64
	v_cvt_pk_bf16_f32 v208, v176, v177
	v_cvt_pk_bf16_f32 v209, v178, v179
	v_cvt_pk_bf16_f32 v210, v180, v181
	v_cvt_pk_bf16_f32 v211, v182, v183
	s_nop 1
	v_permlane16_swap_b32_e32 v208, v210
	v_permlane16_swap_b32_e32 v209, v211
	global_store_dwordx4 v219, v[208:211], s[84:85]
	v_cvt_pk_bf16_f32 v212, v184, v185
	v_cvt_pk_bf16_f32 v213, v186, v187
	v_cvt_pk_bf16_f32 v214, v188, v189
	v_cvt_pk_bf16_f32 v215, v190, v191
	s_nop 1
	v_permlane16_swap_b32_e32 v212, v214
	v_permlane16_swap_b32_e32 v213, v215
	global_store_dwordx4 v219, v[212:215], s[84:85] offset:64
	s_add_i32 s61, s61, s60

.LBB0_1047:
	s_waitcnt vmcnt(3)
	ds_bpermute_b32 v44, v142, v139
	ds_bpermute_b32 v45, v143, v139
	ds_bpermute_b32 v46, v144, v139
	ds_bpermute_b32 v47, v145, v139
	v_add_u32_e32 v128, s22, v156
	s_waitcnt lgkmcnt(3)
	v_lshl_or_b32 v44, v44, 11, v141
	s_waitcnt lgkmcnt(2)
	v_lshl_or_b32 v45, v45, 11, v141
	global_load_dwordx4 v[124:127], v44, s[14:15] offset:1024
	global_load_dwordx4 v[120:123], v45, s[14:15] offset:1024
	ds_bpermute_b32 v45, v146, v139
	s_waitcnt lgkmcnt(2)
	v_lshl_or_b32 v44, v46, 11, v141
	s_waitcnt lgkmcnt(1)
	v_lshl_or_b32 v46, v47, 11, v141
	ds_bpermute_b32 v47, v147, v139
	global_load_dwordx4 v[116:119], v44, s[14:15] offset:1024
	global_load_dwordx4 v[112:115], v46, s[14:15] offset:1024
	s_waitcnt lgkmcnt(1)
	v_lshl_or_b32 v44, v45, 11, v141
	ds_bpermute_b32 v45, v148, v139
	v_cmp_gt_u32_e64 s[10:11], s3, v128
	s_waitcnt lgkmcnt(1)
	v_lshl_or_b32 v46, v47, 11, v141
	ds_bpermute_b32 v47, v149, v139
	global_load_dwordx4 v[108:111], v44, s[14:15] offset:1024
	global_load_dwordx4 v[104:107], v46, s[14:15] offset:1024
	s_waitcnt lgkmcnt(1)
	v_lshl_or_b32 v44, v45, 11, v141
	s_waitcnt vmcnt(7)
	ds_bpermute_b32 v45, v142, v138
	v_mov_b32_e32 v161, v157
	s_waitcnt lgkmcnt(1)
	v_lshl_or_b32 v46, v47, 11, v141
	ds_bpermute_b32 v47, v143, v138
	global_load_dwordx4 v[100:103], v44, s[14:15] offset:1024
	global_load_dwordx4 v[96:99], v46, s[14:15] offset:1024
	s_waitcnt lgkmcnt(1)
	v_lshl_or_b32 v44, v45, 11, v141
	ds_bpermute_b32 v45, v144, v138
	v_cndmask_b32_e64 v128, v140, v128, s[10:11]
	s_waitcnt lgkmcnt(1)
	v_lshl_or_b32 v46, v47, 11, v141
	ds_bpermute_b32 v47, v145, v138
	global_load_dwordx4 v[92:95], v44, s[14:15] offset:1024
	global_load_dwordx4 v[88:91], v46, s[14:15] offset:1024
	s_waitcnt lgkmcnt(1)
	v_lshl_or_b32 v44, v45, 11, v141
	ds_bpermute_b32 v45, v146, v138
	v_cvt_pk_f32_fp8_e32 v[162:163], v84
	s_waitcnt lgkmcnt(1)
	v_lshl_or_b32 v46, v47, 11, v141
	ds_bpermute_b32 v47, v147, v138
	global_load_dwordx4 v[80:83], v44, s[14:15] offset:1024
	global_load_dwordx4 v[72:75], v46, s[14:15] offset:1024
	s_waitcnt lgkmcnt(1)
	v_lshl_or_b32 v44, v45, 11, v141
	ds_bpermute_b32 v45, v148, v138
	ds_bpermute_b32 v46, v149, v138
	v_lshlrev_b64 v[138:139], 9, v[128:129]
	ds_bpermute_b32 v128, v142, v161
	v_cvt_pk_f32_fp8_sdwa v[164:165], v84 src0_sel:WORD_1
	v_cvt_pk_f32_fp8_e32 v[166:167], v85
	v_cvt_pk_f32_fp8_sdwa v[84:85], v85 src0_sel:WORD_1
	v_cvt_pk_f32_fp8_e32 v[170:171], v86
	v_cvt_pk_f32_fp8_sdwa v[172:173], v86 src0_sel:WORD_1
	v_cvt_pk_f32_fp8_e32 v[174:175], v87
	v_cvt_pk_f32_fp8_sdwa v[86:87], v87 src0_sel:WORD_1
	s_waitcnt lgkmcnt(0)
	v_pk_fma_f32 v[162:163], v[162:163], v[128:129], 0 op_sel_hi:[1,0,0]
	v_pk_fma_f32 v[164:165], v[128:129], v[164:165], 0 op_sel_hi:[0,1,0]
	v_pk_fma_f32 v[166:167], v[128:129], v[166:167], 0 op_sel_hi:[0,1,0]
	v_pk_fma_f32 v[84:85], v[128:129], v[84:85], 0 op_sel_hi:[0,1,0]
	v_pk_fma_f32 v[170:171], v[128:129], v[170:171], 0 op_sel_hi:[0,1,0]
	v_pk_fma_f32 v[172:173], v[128:129], v[172:173], 0 op_sel_hi:[0,1,0]
	v_pk_fma_f32 v[174:175], v[128:129], v[174:175], 0 op_sel_hi:[0,1,0]
	v_pk_fma_f32 v[86:87], v[128:129], v[86:87], 0 op_sel_hi:[0,1,0]
	ds_bpermute_b32 v128, v143, v161
	v_cvt_pk_f32_fp8_e32 v[176:177], v76
	v_cvt_pk_f32_fp8_sdwa v[178:179], v76 src0_sel:WORD_1
	v_cvt_pk_f32_fp8_e32 v[180:181], v77
	v_cvt_pk_f32_fp8_sdwa v[76:77], v77 src0_sel:WORD_1
	s_waitcnt lgkmcnt(0)
	v_pk_fma_f32 v[162:163], v[176:177], v[128:129], v[162:163] op_sel_hi:[1,0,1]
	v_pk_fma_f32 v[164:165], v[128:129], v[178:179], v[164:165] op_sel_hi:[0,1,1]
	v_cvt_pk_f32_fp8_sdwa v[176:177], v78 src0_sel:WORD_1
	v_pk_fma_f32 v[76:77], v[128:129], v[76:77], v[84:85] op_sel_hi:[0,1,1]
	v_cvt_pk_f32_fp8_e32 v[84:85], v78
	v_cvt_pk_f32_fp8_e32 v[178:179], v79
	v_cvt_pk_f32_fp8_sdwa v[78:79], v79 src0_sel:WORD_1
	v_pk_fma_f32 v[166:167], v[128:129], v[180:181], v[166:167] op_sel_hi:[0,1,1]
	v_pk_fma_f32 v[84:85], v[128:129], v[84:85], v[170:171] op_sel_hi:[0,1,1]
	v_pk_fma_f32 v[170:171], v[128:129], v[176:177], v[172:173] op_sel_hi:[0,1,1]
	v_pk_fma_f32 v[78:79], v[128:129], v[78:79], v[86:87] op_sel_hi:[0,1,1]
	ds_bpermute_b32 v86, v144, v161
	v_pk_fma_f32 v[172:173], v[128:129], v[178:179], v[174:175] op_sel_hi:[0,1,1]
	v_cvt_pk_f32_fp8_e32 v[174:175], v68
	v_cvt_pk_f32_fp8_sdwa v[176:177], v68 src0_sel:WORD_1
	v_cvt_pk_f32_fp8_e32 v[178:179], v69
	v_cvt_pk_f32_fp8_sdwa v[68:69], v69 src0_sel:WORD_1
	s_waitcnt lgkmcnt(0)
	v_pk_fma_f32 v[162:163], v[174:175], v[86:87], v[162:163] op_sel_hi:[1,0,1]
	v_pk_fma_f32 v[164:165], v[86:87], v[176:177], v[164:165] op_sel_hi:[0,1,1]
	v_cvt_pk_f32_fp8_sdwa v[174:175], v70 src0_sel:WORD_1
	v_pk_fma_f32 v[68:69], v[86:87], v[68:69], v[76:77] op_sel_hi:[0,1,1]
	v_cvt_pk_f32_fp8_e32 v[76:77], v70
	v_cvt_pk_f32_fp8_e32 v[176:177], v71
	v_cvt_pk_f32_fp8_sdwa v[70:71], v71 src0_sel:WORD_1
	v_pk_fma_f32 v[166:167], v[86:87], v[178:179], v[166:167] op_sel_hi:[0,1,1]
	v_pk_fma_f32 v[76:77], v[86:87], v[76:77], v[84:85] op_sel_hi:[0,1,1]
	v_pk_fma_f32 v[84:85], v[86:87], v[174:175], v[170:171] op_sel_hi:[0,1,1]
	v_pk_fma_f32 v[70:71], v[86:87], v[70:71], v[78:79] op_sel_hi:[0,1,1]
	ds_bpermute_b32 v78, v145, v161
	v_pk_fma_f32 v[170:171], v[86:87], v[176:177], v[172:173] op_sel_hi:[0,1,1]
	v_cvt_pk_f32_fp8_e32 v[86:87], v60
	v_cvt_pk_f32_fp8_sdwa v[172:173], v60 src0_sel:WORD_1
	v_cvt_pk_f32_fp8_e32 v[174:175], v61
	v_cvt_pk_f32_fp8_sdwa v[60:61], v61 src0_sel:WORD_1
	s_waitcnt lgkmcnt(0)
	v_pk_fma_f32 v[86:87], v[86:87], v[78:79], v[162:163] op_sel_hi:[1,0,1]
	v_pk_fma_f32 v[162:163], v[78:79], v[172:173], v[164:165] op_sel_hi:[0,1,1]
	v_pk_fma_f32 v[164:165], v[78:79], v[174:175], v[166:167] op_sel_hi:[0,1,1]
	v_pk_fma_f32 v[60:61], v[78:79], v[60:61], v[68:69] op_sel_hi:[0,1,1]
	v_cvt_pk_f32_fp8_e32 v[68:69], v62
	v_cvt_pk_f32_fp8_sdwa v[166:167], v62 src0_sel:WORD_1
	v_cvt_pk_f32_fp8_e32 v[172:173], v63
	v_cvt_pk_f32_fp8_sdwa v[62:63], v63 src0_sel:WORD_1
	v_pk_fma_f32 v[68:69], v[78:79], v[68:69], v[76:77] op_sel_hi:[0,1,1]
	v_pk_fma_f32 v[76:77], v[78:79], v[166:167], v[84:85] op_sel_hi:[0,1,1]
	v_pk_fma_f32 v[84:85], v[78:79], v[172:173], v[170:171] op_sel_hi:[0,1,1]
	v_pk_fma_f32 v[62:63], v[78:79], v[62:63], v[70:71] op_sel_hi:[0,1,1]
	ds_bpermute_b32 v70, v146, v161
	v_cvt_pk_f32_fp8_e32 v[78:79], v52
	v_cvt_pk_f32_fp8_sdwa v[166:167], v52 src0_sel:WORD_1
	v_cvt_pk_f32_fp8_e32 v[170:171], v53
	v_cvt_pk_f32_fp8_sdwa v[52:53], v53 src0_sel:WORD_1
	s_waitcnt lgkmcnt(0)
	v_pk_fma_f32 v[78:79], v[78:79], v[70:71], v[86:87] op_sel_hi:[1,0,1]
	v_pk_fma_f32 v[86:87], v[70:71], v[166:167], v[162:163] op_sel_hi:[0,1,1]
	v_pk_fma_f32 v[162:163], v[70:71], v[170:171], v[164:165] op_sel_hi:[0,1,1]
	v_pk_fma_f32 v[52:53], v[70:71], v[52:53], v[60:61] op_sel_hi:[0,1,1]
	v_cvt_pk_f32_fp8_e32 v[60:61], v54
	v_cvt_pk_f32_fp8_sdwa v[164:165], v54 src0_sel:WORD_1
	v_cvt_pk_f32_fp8_e32 v[166:167], v55
	v_cvt_pk_f32_fp8_sdwa v[54:55], v55 src0_sel:WORD_1
	v_pk_fma_f32 v[60:61], v[70:71], v[60:61], v[68:69] op_sel_hi:[0,1,1]
	v_pk_fma_f32 v[68:69], v[70:71], v[164:165], v[76:77] op_sel_hi:[0,1,1]
	v_pk_fma_f32 v[76:77], v[70:71], v[166:167], v[84:85] op_sel_hi:[0,1,1]
	v_pk_fma_f32 v[54:55], v[70:71], v[54:55], v[62:63] op_sel_hi:[0,1,1]
	ds_bpermute_b32 v62, v147, v161
	v_cvt_pk_f32_fp8_e32 v[70:71], v40
	v_cvt_pk_f32_fp8_sdwa v[84:85], v40 src0_sel:WORD_1
	v_cvt_pk_f32_fp8_e32 v[164:165], v41
	v_cvt_pk_f32_fp8_sdwa v[40:41], v41 src0_sel:WORD_1
	s_waitcnt lgkmcnt(0)
	v_pk_fma_f32 v[70:71], v[70:71], v[62:63], v[78:79] op_sel_hi:[1,0,1]
	v_pk_fma_f32 v[78:79], v[62:63], v[84:85], v[86:87] op_sel_hi:[0,1,1]
	v_pk_fma_f32 v[84:85], v[62:63], v[164:165], v[162:163] op_sel_hi:[0,1,1]
	v_pk_fma_f32 v[40:41], v[62:63], v[40:41], v[52:53] op_sel_hi:[0,1,1]
	v_cvt_pk_f32_fp8_e32 v[52:53], v42
	v_cvt_pk_f32_fp8_sdwa v[86:87], v42 src0_sel:WORD_1
	v_cvt_pk_f32_fp8_e32 v[162:163], v43
	v_cvt_pk_f32_fp8_sdwa v[42:43], v43 src0_sel:WORD_1
	v_pk_fma_f32 v[52:53], v[62:63], v[52:53], v[60:61] op_sel_hi:[0,1,1]
	v_pk_fma_f32 v[60:61], v[62:63], v[86:87], v[68:69] op_sel_hi:[0,1,1]
	v_pk_fma_f32 v[68:69], v[62:63], v[162:163], v[76:77] op_sel_hi:[0,1,1]
	v_pk_fma_f32 v[42:43], v[62:63], v[42:43], v[54:55] op_sel_hi:[0,1,1]
	ds_bpermute_b32 v54, v148, v161
	v_cvt_pk_f32_fp8_e32 v[62:63], v36
	v_cvt_pk_f32_fp8_sdwa v[76:77], v36 src0_sel:WORD_1
	v_cvt_pk_f32_fp8_e32 v[86:87], v37
	v_cvt_pk_f32_fp8_sdwa v[36:37], v37 src0_sel:WORD_1
	s_waitcnt lgkmcnt(0)
	v_pk_fma_f32 v[62:63], v[62:63], v[54:55], v[70:71] op_sel_hi:[1,0,1]
	v_pk_fma_f32 v[70:71], v[54:55], v[76:77], v[78:79] op_sel_hi:[0,1,1]
	v_pk_fma_f32 v[76:77], v[54:55], v[86:87], v[84:85] op_sel_hi:[0,1,1]
	v_pk_fma_f32 v[36:37], v[54:55], v[36:37], v[40:41] op_sel_hi:[0,1,1]
	v_cvt_pk_f32_fp8_e32 v[40:41], v38
	v_cvt_pk_f32_fp8_sdwa v[78:79], v38 src0_sel:WORD_1
	v_cvt_pk_f32_fp8_e32 v[84:85], v39
	v_cvt_pk_f32_fp8_sdwa v[38:39], v39 src0_sel:WORD_1
	v_pk_fma_f32 v[40:41], v[54:55], v[40:41], v[52:53] op_sel_hi:[0,1,1]
	v_pk_fma_f32 v[52:53], v[54:55], v[78:79], v[60:61] op_sel_hi:[0,1,1]
	v_pk_fma_f32 v[60:61], v[54:55], v[84:85], v[68:69] op_sel_hi:[0,1,1]
	v_pk_fma_f32 v[38:39], v[54:55], v[38:39], v[42:43] op_sel_hi:[0,1,1]
	ds_bpermute_b32 v42, v149, v161
	v_cvt_pk_f32_fp8_e32 v[54:55], v32
	v_cvt_pk_f32_fp8_sdwa v[68:69], v32 src0_sel:WORD_1
	v_cvt_pk_f32_fp8_e32 v[78:79], v33
	v_cvt_pk_f32_fp8_sdwa v[32:33], v33 src0_sel:WORD_1
	s_waitcnt lgkmcnt(0)
	v_pk_fma_f32 v[54:55], v[54:55], v[42:43], v[62:63] op_sel_hi:[1,0,1]
	v_pk_fma_f32 v[62:63], v[42:43], v[68:69], v[70:71] op_sel_hi:[0,1,1]
	v_pk_fma_f32 v[68:69], v[42:43], v[78:79], v[76:77] op_sel_hi:[0,1,1]
	v_pk_fma_f32 v[32:33], v[42:43], v[32:33], v[36:37] op_sel_hi:[0,1,1]
	v_cvt_pk_f32_fp8_e32 v[36:37], v34
	v_cvt_pk_f32_fp8_sdwa v[70:71], v34 src0_sel:WORD_1
	v_cvt_pk_f32_fp8_e32 v[76:77], v35
	v_cvt_pk_f32_fp8_sdwa v[34:35], v35 src0_sel:WORD_1
	v_pk_fma_f32 v[36:37], v[42:43], v[36:37], v[40:41] op_sel_hi:[0,1,1]
	v_pk_fma_f32 v[40:41], v[42:43], v[70:71], v[52:53] op_sel_hi:[0,1,1]
	v_pk_fma_f32 v[52:53], v[42:43], v[76:77], v[60:61] op_sel_hi:[0,1,1]
	v_pk_fma_f32 v[34:35], v[42:43], v[34:35], v[38:39] op_sel_hi:[0,1,1]
	ds_bpermute_b32 v38, v142, v137
	v_cvt_pk_f32_fp8_e32 v[42:43], v28
	v_cvt_pk_f32_fp8_sdwa v[60:61], v28 src0_sel:WORD_1
	v_cvt_pk_f32_fp8_e32 v[70:71], v29
	v_cvt_pk_f32_fp8_sdwa v[28:29], v29 src0_sel:WORD_1
	s_waitcnt lgkmcnt(0)
	v_pk_fma_f32 v[42:43], v[42:43], v[38:39], v[54:55] op_sel_hi:[1,0,1]
	v_pk_fma_f32 v[54:55], v[38:39], v[60:61], v[62:63] op_sel_hi:[0,1,1]
	v_pk_fma_f32 v[60:61], v[38:39], v[70:71], v[68:69] op_sel_hi:[0,1,1]
	v_pk_fma_f32 v[28:29], v[38:39], v[28:29], v[32:33] op_sel_hi:[0,1,1]
	v_cvt_pk_f32_fp8_e32 v[32:33], v30
	v_cvt_pk_f32_fp8_sdwa v[62:63], v30 src0_sel:WORD_1
	v_cvt_pk_f32_fp8_e32 v[68:69], v31
	v_cvt_pk_f32_fp8_sdwa v[30:31], v31 src0_sel:WORD_1
	v_pk_fma_f32 v[32:33], v[38:39], v[32:33], v[36:37] op_sel_hi:[0,1,1]
	v_pk_fma_f32 v[36:37], v[38:39], v[62:63], v[40:41] op_sel_hi:[0,1,1]
	v_pk_fma_f32 v[40:41], v[38:39], v[68:69], v[52:53] op_sel_hi:[0,1,1]
	v_pk_fma_f32 v[30:31], v[38:39], v[30:31], v[34:35] op_sel_hi:[0,1,1]
	ds_bpermute_b32 v34, v143, v137
	v_cvt_pk_f32_fp8_e32 v[38:39], v24
	v_cvt_pk_f32_fp8_sdwa v[52:53], v24 src0_sel:WORD_1
	v_cvt_pk_f32_fp8_e32 v[62:63], v25
	v_cvt_pk_f32_fp8_sdwa v[24:25], v25 src0_sel:WORD_1
	s_waitcnt lgkmcnt(0)
	v_pk_fma_f32 v[38:39], v[38:39], v[34:35], v[42:43] op_sel_hi:[1,0,1]
	v_pk_fma_f32 v[42:43], v[34:35], v[52:53], v[54:55] op_sel_hi:[0,1,1]
	v_pk_fma_f32 v[52:53], v[34:35], v[62:63], v[60:61] op_sel_hi:[0,1,1]
	v_pk_fma_f32 v[24:25], v[34:35], v[24:25], v[28:29] op_sel_hi:[0,1,1]
	v_cvt_pk_f32_fp8_e32 v[28:29], v26
	v_cvt_pk_f32_fp8_sdwa v[54:55], v26 src0_sel:WORD_1
	v_cvt_pk_f32_fp8_e32 v[60:61], v27
	v_cvt_pk_f32_fp8_sdwa v[26:27], v27 src0_sel:WORD_1
	v_lshl_or_b32 v47, v47, 11, v141
	global_load_dwordx4 v[64:67], v44, s[14:15] offset:1024
	global_load_dwordx4 v[56:59], v47, s[14:15] offset:1024
	v_lshl_or_b32 v44, v45, 11, v141
	v_lshl_or_b32 v45, v46, 11, v141
	v_lshl_add_u64 v[158:159], v[130:131], 0, v[138:139]
	v_pk_fma_f32 v[26:27], v[34:35], v[26:27], v[30:31] op_sel_hi:[0,1,1]
	ds_bpermute_b32 v30, v144, v137
	global_load_dwordx4 v[48:51], v44, s[14:15] offset:1024
	s_nop 0
	global_load_dwordx4 v[44:47], v45, s[14:15] offset:1024
	s_nop 0
	global_load_dword v160, v[158:159], off
	s_nop 0
	global_load_dword v159, v[158:159], off offset:256
	v_pk_fma_f32 v[28:29], v[34:35], v[28:29], v[32:33] op_sel_hi:[0,1,1]
	v_pk_fma_f32 v[32:33], v[34:35], v[54:55], v[36:37] op_sel_hi:[0,1,1]
	v_pk_fma_f32 v[36:37], v[34:35], v[60:61], v[40:41] op_sel_hi:[0,1,1]
	v_cvt_pk_f32_fp8_e32 v[34:35], v20
	v_cvt_pk_f32_fp8_sdwa v[40:41], v20 src0_sel:WORD_1
	v_cvt_pk_f32_fp8_e32 v[54:55], v21
	v_cvt_pk_f32_fp8_sdwa v[20:21], v21 src0_sel:WORD_1
	s_waitcnt lgkmcnt(0)
	v_pk_fma_f32 v[34:35], v[34:35], v[30:31], v[38:39] op_sel_hi:[1,0,1]
	v_pk_fma_f32 v[38:39], v[30:31], v[40:41], v[42:43] op_sel_hi:[0,1,1]
	v_pk_fma_f32 v[40:41], v[30:31], v[54:55], v[52:53] op_sel_hi:[0,1,1]
	v_pk_fma_f32 v[20:21], v[30:31], v[20:21], v[24:25] op_sel_hi:[0,1,1]
	v_cvt_pk_f32_fp8_e32 v[24:25], v22
	v_cvt_pk_f32_fp8_sdwa v[42:43], v22 src0_sel:WORD_1
	v_cvt_pk_f32_fp8_e32 v[52:53], v23
	v_cvt_pk_f32_fp8_sdwa v[22:23], v23 src0_sel:WORD_1
	v_pk_fma_f32 v[24:25], v[30:31], v[24:25], v[28:29] op_sel_hi:[0,1,1]
	v_pk_fma_f32 v[28:29], v[30:31], v[42:43], v[32:33] op_sel_hi:[0,1,1]
	v_pk_fma_f32 v[32:33], v[30:31], v[52:53], v[36:37] op_sel_hi:[0,1,1]
	v_pk_fma_f32 v[22:23], v[30:31], v[22:23], v[26:27] op_sel_hi:[0,1,1]
	ds_bpermute_b32 v26, v145, v137
	v_cvt_pk_f32_fp8_e32 v[30:31], v16
	v_cvt_pk_f32_fp8_sdwa v[36:37], v16 src0_sel:WORD_1
	v_cvt_pk_f32_fp8_e32 v[42:43], v17
	v_cvt_pk_f32_fp8_sdwa v[16:17], v17 src0_sel:WORD_1
	s_waitcnt lgkmcnt(0)
	v_pk_fma_f32 v[30:31], v[30:31], v[26:27], v[34:35] op_sel_hi:[1,0,1]
	v_pk_fma_f32 v[34:35], v[26:27], v[36:37], v[38:39] op_sel_hi:[0,1,1]
	v_pk_fma_f32 v[36:37], v[26:27], v[42:43], v[40:41] op_sel_hi:[0,1,1]
	v_pk_fma_f32 v[16:17], v[26:27], v[16:17], v[20:21] op_sel_hi:[0,1,1]
	v_cvt_pk_f32_fp8_e32 v[20:21], v18
	v_cvt_pk_f32_fp8_sdwa v[38:39], v18 src0_sel:WORD_1
	v_cvt_pk_f32_fp8_e32 v[40:41], v19
	v_cvt_pk_f32_fp8_sdwa v[18:19], v19 src0_sel:WORD_1
	v_pk_fma_f32 v[20:21], v[26:27], v[20:21], v[24:25] op_sel_hi:[0,1,1]
	v_pk_fma_f32 v[24:25], v[26:27], v[38:39], v[28:29] op_sel_hi:[0,1,1]
	v_pk_fma_f32 v[28:29], v[26:27], v[40:41], v[32:33] op_sel_hi:[0,1,1]
	v_pk_fma_f32 v[18:19], v[26:27], v[18:19], v[22:23] op_sel_hi:[0,1,1]
	ds_bpermute_b32 v22, v146, v137
	v_cvt_pk_f32_fp8_e32 v[26:27], v12
	v_cvt_pk_f32_fp8_sdwa v[32:33], v12 src0_sel:WORD_1
	v_cvt_pk_f32_fp8_e32 v[38:39], v13
	v_cvt_pk_f32_fp8_sdwa v[12:13], v13 src0_sel:WORD_1
	s_waitcnt lgkmcnt(0)
	v_pk_fma_f32 v[26:27], v[26:27], v[22:23], v[30:31] op_sel_hi:[1,0,1]
	v_pk_fma_f32 v[30:31], v[22:23], v[32:33], v[34:35] op_sel_hi:[0,1,1]
	v_pk_fma_f32 v[32:33], v[22:23], v[38:39], v[36:37] op_sel_hi:[0,1,1]
	v_pk_fma_f32 v[12:13], v[22:23], v[12:13], v[16:17] op_sel_hi:[0,1,1]
	v_cvt_pk_f32_fp8_e32 v[16:17], v14
	v_cvt_pk_f32_fp8_sdwa v[34:35], v14 src0_sel:WORD_1
	v_cvt_pk_f32_fp8_e32 v[36:37], v15
	v_cvt_pk_f32_fp8_sdwa v[14:15], v15 src0_sel:WORD_1
	v_pk_fma_f32 v[16:17], v[22:23], v[16:17], v[20:21] op_sel_hi:[0,1,1]
	v_pk_fma_f32 v[20:21], v[22:23], v[34:35], v[24:25] op_sel_hi:[0,1,1]
	v_pk_fma_f32 v[24:25], v[22:23], v[36:37], v[28:29] op_sel_hi:[0,1,1]
	v_pk_fma_f32 v[14:15], v[22:23], v[14:15], v[18:19] op_sel_hi:[0,1,1]
	ds_bpermute_b32 v18, v147, v137
	v_cvt_pk_f32_fp8_e32 v[22:23], v8
	v_cvt_pk_f32_fp8_sdwa v[28:29], v8 src0_sel:WORD_1
	v_cvt_pk_f32_fp8_e32 v[34:35], v9
	v_cvt_pk_f32_fp8_sdwa v[8:9], v9 src0_sel:WORD_1
	s_waitcnt lgkmcnt(0)
	v_pk_fma_f32 v[22:23], v[22:23], v[18:19], v[26:27] op_sel_hi:[1,0,1]
	v_pk_fma_f32 v[26:27], v[18:19], v[28:29], v[30:31] op_sel_hi:[0,1,1]
	v_pk_fma_f32 v[28:29], v[18:19], v[34:35], v[32:33] op_sel_hi:[0,1,1]
	v_pk_fma_f32 v[8:9], v[18:19], v[8:9], v[12:13] op_sel_hi:[0,1,1]
	v_cvt_pk_f32_fp8_e32 v[12:13], v10
	v_cvt_pk_f32_fp8_sdwa v[30:31], v10 src0_sel:WORD_1
	v_cvt_pk_f32_fp8_e32 v[32:33], v11
	v_cvt_pk_f32_fp8_sdwa v[10:11], v11 src0_sel:WORD_1
	v_pk_fma_f32 v[12:13], v[18:19], v[12:13], v[16:17] op_sel_hi:[0,1,1]
	v_pk_fma_f32 v[16:17], v[18:19], v[30:31], v[20:21] op_sel_hi:[0,1,1]
	v_pk_fma_f32 v[20:21], v[18:19], v[32:33], v[24:25] op_sel_hi:[0,1,1]
	v_pk_fma_f32 v[10:11], v[18:19], v[10:11], v[14:15] op_sel_hi:[0,1,1]
	ds_bpermute_b32 v14, v148, v137
	v_cvt_pk_f32_fp8_e32 v[18:19], v4
	v_cvt_pk_f32_fp8_sdwa v[24:25], v4 src0_sel:WORD_1
	v_cvt_pk_f32_fp8_e32 v[30:31], v5
	v_cvt_pk_f32_fp8_sdwa v[4:5], v5 src0_sel:WORD_1
	s_waitcnt lgkmcnt(0)
	v_pk_fma_f32 v[18:19], v[18:19], v[14:15], v[22:23] op_sel_hi:[1,0,1]
	v_pk_fma_f32 v[22:23], v[14:15], v[24:25], v[26:27] op_sel_hi:[0,1,1]
	v_pk_fma_f32 v[24:25], v[14:15], v[30:31], v[28:29] op_sel_hi:[0,1,1]
	v_pk_fma_f32 v[4:5], v[14:15], v[4:5], v[8:9] op_sel_hi:[0,1,1]
	v_cvt_pk_f32_fp8_e32 v[8:9], v6
	v_cvt_pk_f32_fp8_sdwa v[26:27], v6 src0_sel:WORD_1
	v_cvt_pk_f32_fp8_e32 v[28:29], v7
	v_cvt_pk_f32_fp8_sdwa v[6:7], v7 src0_sel:WORD_1
	v_pk_fma_f32 v[8:9], v[14:15], v[8:9], v[12:13] op_sel_hi:[0,1,1]
	v_pk_fma_f32 v[12:13], v[14:15], v[26:27], v[16:17] op_sel_hi:[0,1,1]
	v_pk_fma_f32 v[16:17], v[14:15], v[28:29], v[20:21] op_sel_hi:[0,1,1]
	v_pk_fma_f32 v[6:7], v[14:15], v[6:7], v[10:11] op_sel_hi:[0,1,1]
	ds_bpermute_b32 v10, v149, v137
	v_cvt_pk_f32_fp8_e32 v[14:15], v0
	v_cvt_pk_f32_fp8_sdwa v[20:21], v0 src0_sel:WORD_1
	v_cvt_pk_f32_fp8_e32 v[26:27], v1
	v_cvt_pk_f32_fp8_sdwa v[0:1], v1 src0_sel:WORD_1
	s_waitcnt lgkmcnt(0)
	v_pk_fma_f32 v[14:15], v[14:15], v[10:11], v[18:19] op_sel_hi:[1,0,1]
	v_pk_fma_f32 v[18:19], v[10:11], v[20:21], v[22:23] op_sel_hi:[0,1,1]
	v_pk_fma_f32 v[20:21], v[10:11], v[26:27], v[24:25] op_sel_hi:[0,1,1]
	v_pk_fma_f32 v[0:1], v[10:11], v[0:1], v[4:5] op_sel_hi:[0,1,1]
	v_cvt_pk_f32_fp8_e32 v[4:5], v2
	v_cvt_pk_f32_fp8_sdwa v[22:23], v2 src0_sel:WORD_1
	v_cvt_pk_f32_fp8_e32 v[24:25], v3
	v_cvt_pk_f32_fp8_sdwa v[2:3], v3 src0_sel:WORD_1
	v_pk_fma_f32 v[4:5], v[10:11], v[4:5], v[8:9] op_sel_hi:[0,1,1]
	v_pk_fma_f32 v[8:9], v[10:11], v[22:23], v[12:13] op_sel_hi:[0,1,1]
	v_pk_fma_f32 v[12:13], v[10:11], v[24:25], v[16:17] op_sel_hi:[0,1,1]
	v_pk_fma_f32 v[2:3], v[10:11], v[2:3], v[6:7] op_sel_hi:[0,1,1]
	v_cndmask_b32_e32 v6, v14, v4, vcc
	v_cndmask_b32_e32 v7, v15, v5, vcc
	ds_bpermute_b32 v6, v150, v6
	ds_bpermute_b32 v7, v150, v7
	v_cndmask_b32_e32 v10, v18, v8, vcc
	v_cndmask_b32_e32 v11, v19, v9, vcc
	v_cndmask_b32_e32 v16, v20, v12, vcc
	v_cndmask_b32_e32 v17, v21, v13, vcc
	v_cndmask_b32_e32 v22, v0, v2, vcc
	v_cndmask_b32_e32 v23, v1, v3, vcc
	ds_bpermute_b32 v10, v150, v10
	ds_bpermute_b32 v11, v150, v11
	ds_bpermute_b32 v16, v150, v16
	ds_bpermute_b32 v17, v150, v17
	ds_bpermute_b32 v22, v150, v22
	ds_bpermute_b32 v23, v150, v23
	v_cndmask_b32_e32 v5, v5, v15, vcc
	v_cndmask_b32_e32 v4, v4, v14, vcc
	s_waitcnt lgkmcnt(6)
	v_pk_add_f32 v[4:5], v[4:5], v[6:7]
	v_cndmask_b32_e32 v7, v9, v19, vcc
	v_cndmask_b32_e32 v6, v8, v18, vcc
	v_cndmask_b32_e32 v9, v13, v21, vcc
	v_cndmask_b32_e32 v8, v12, v20, vcc
	v_cndmask_b32_e32 v1, v3, v1, vcc
	v_cndmask_b32_e32 v0, v2, v0, vcc
	s_waitcnt lgkmcnt(4)
	v_pk_add_f32 v[6:7], v[6:7], v[10:11]
	s_waitcnt lgkmcnt(2)
	v_pk_add_f32 v[8:9], v[8:9], v[16:17]
	s_waitcnt lgkmcnt(0)
	v_pk_add_f32 v[0:1], v[0:1], v[22:23]
	v_cndmask_b32_e64 v3, v5, v9, s[6:7]
	v_cndmask_b32_e64 v5, v9, v5, s[6:7]
	v_cndmask_b32_e64 v9, v6, v0, s[6:7]
	v_cndmask_b32_e64 v2, v4, v8, s[6:7]
	ds_bpermute_b32 v10, v151, v9
	v_cndmask_b32_e64 v9, v7, v1, s[6:7]
	ds_bpermute_b32 v2, v151, v2
	ds_bpermute_b32 v3, v151, v3
	ds_bpermute_b32 v11, v151, v9
	v_cndmask_b32_e64 v4, v8, v4, s[6:7]
	v_cndmask_b32_e64 v1, v1, v7, s[6:7]
	v_cndmask_b32_e64 v0, v0, v6, s[6:7]
	s_waitcnt lgkmcnt(1)
	v_pk_add_f32 v[2:3], v[4:5], v[2:3]
	s_waitcnt lgkmcnt(0)
	v_pk_add_f32 v[0:1], v[0:1], v[10:11]
	v_add_u32_e32 v157, s23, v156
	v_cndmask_b32_e64 v4, v2, v0, s[8:9]
	v_cndmask_b32_e64 v5, v3, v1, s[8:9]
	ds_bpermute_b32 v4, v152, v4
	ds_bpermute_b32 v5, v152, v5
	v_cndmask_b32_e64 v1, v1, v3, s[8:9]
	v_cndmask_b32_e64 v0, v0, v2, s[8:9]
	v_cmp_gt_u32_e64 s[10:11], s3, v157
	v_mov_b32_e32 v137, v129
	s_waitcnt lgkmcnt(0)
	v_pk_add_f32 v[0:1], v[0:1], v[4:5]
	v_cndmask_b32_e64 v128, v140, v157, s[10:11]
	s_nop 0
	s_nop 0
	v_cvt_pk_bf16_f32 v0, v0, v0
	v_cvt_pk_bf16_f32 v1, v1, v1
	s_waitcnt vmcnt(1)
	ds_bpermute_b32 v2, v142, v160
	v_lshrrev_b32_e32 v0, 16, v0
	ds_bpermute_b32 v3, v143, v160
	v_and_or_b32 v0, v1, s26, v0
	ds_bpermute_b32 v1, v144, v160
	v_lshl_add_u64 v[138:139], v[134:135], 0, v[138:139]
	v_lshl_add_u64 v[6:7], v[136:137], 1, v[132:133]
	v_lshlrev_b64 v[162:163], 9, v[128:129]
	v_lshl_add_u64 v[164:165], v[134:135], 0, v[162:163]
	global_load_dword v157, v[138:139], off
	global_load_dword v137, v[138:139], off offset:256
	global_load_dword v158, v[164:165], off
	v_add_u32_e32 v156, s20, v156
	global_store_dword v[6:7], v0, off
	s_waitcnt lgkmcnt(2)
	v_lshl_or_b32 v0, v2, 11, v141
	s_waitcnt lgkmcnt(1)
	v_lshl_or_b32 v2, v3, 11, v141
	ds_bpermute_b32 v3, v145, v160
	global_load_dwordx4 v[84:87], v0, s[14:15] offset:1024
	global_load_dwordx4 v[76:79], v2, s[14:15] offset:1024
	s_waitcnt lgkmcnt(1)
	v_lshl_or_b32 v0, v1, 11, v141
	ds_bpermute_b32 v1, v146, v160
	v_cmp_gt_u32_e64 s[10:11], s3, v156
	s_waitcnt lgkmcnt(1)
	v_lshl_or_b32 v2, v3, 11, v141
	ds_bpermute_b32 v3, v147, v160
	global_load_dwordx4 v[68:71], v0, s[14:15] offset:1024
	global_load_dwordx4 v[60:63], v2, s[14:15] offset:1024
	s_waitcnt lgkmcnt(1)
	v_lshl_or_b32 v0, v1, 11, v141
	ds_bpermute_b32 v1, v148, v160
	s_waitcnt lgkmcnt(1)
	v_lshl_or_b32 v2, v3, 11, v141
	ds_bpermute_b32 v3, v149, v160
	global_load_dwordx4 v[52:55], v0, s[14:15] offset:1024
	global_load_dwordx4 v[40:43], v2, s[14:15] offset:1024
	s_waitcnt lgkmcnt(1)
	v_lshl_or_b32 v0, v1, 11, v141
	s_waitcnt vmcnt(10)
	ds_bpermute_b32 v1, v142, v159
	v_lshl_add_u64 v[160:161], v[130:131], 0, v[162:163]
	s_waitcnt lgkmcnt(1)
	v_lshl_or_b32 v2, v3, 11, v141
	ds_bpermute_b32 v3, v143, v159
	global_load_dwordx4 v[36:39], v0, s[14:15] offset:1024
	global_load_dwordx4 v[32:35], v2, s[14:15] offset:1024
	s_waitcnt lgkmcnt(1)
	v_lshl_or_b32 v0, v1, 11, v141
	ds_bpermute_b32 v1, v144, v159
	s_waitcnt lgkmcnt(1)
	v_lshl_or_b32 v2, v3, 11, v141
	ds_bpermute_b32 v3, v145, v159
	global_load_dwordx4 v[28:31], v0, s[14:15] offset:1024
	global_load_dwordx4 v[24:27], v2, s[14:15] offset:1024
	s_waitcnt lgkmcnt(1)
	v_lshl_or_b32 v0, v1, 11, v141
	ds_bpermute_b32 v1, v146, v159
	s_waitcnt lgkmcnt(1)
	v_lshl_or_b32 v2, v3, 11, v141
	ds_bpermute_b32 v3, v147, v159
	global_load_dwordx4 v[20:23], v0, s[14:15] offset:1024
	global_load_dwordx4 v[16:19], v2, s[14:15] offset:1024
	s_waitcnt lgkmcnt(1)
	v_lshl_or_b32 v0, v1, 11, v141
	ds_bpermute_b32 v1, v148, v159
	ds_bpermute_b32 v2, v149, v159
	s_waitcnt lgkmcnt(2)
	v_lshl_or_b32 v3, v3, 11, v141
	global_load_dwordx4 v[12:15], v0, s[14:15] offset:1024
	global_load_dwordx4 v[8:11], v3, s[14:15] offset:1024
	s_waitcnt lgkmcnt(1)
	v_lshl_or_b32 v0, v1, 11, v141
	s_waitcnt lgkmcnt(0)
	v_lshl_or_b32 v1, v2, 11, v141
	global_load_dwordx4 v[4:7], v0, s[14:15] offset:1024
	s_nop 0
	global_load_dwordx4 v[0:3], v1, s[14:15] offset:1024
	s_nop 0
	global_load_dword v139, v[160:161], off
	global_load_dword v138, v[160:161], off offset:256
	global_load_dword v159, v[164:165], off offset:256
	s_and_saveexec_b64 s[18:19], s[10:11]
	s_cbranch_execz .LBB0_1046
	ds_bpermute_b32 v128, v142, v155
	v_cvt_pk_f32_fp8_e32 v[160:161], v124
	v_cvt_pk_f32_fp8_sdwa v[162:163], v124 src0_sel:WORD_1
	v_cvt_pk_f32_fp8_e32 v[164:165], v125
	v_cvt_pk_f32_fp8_sdwa v[124:125], v125 src0_sel:WORD_1
	v_cvt_pk_f32_fp8_e32 v[166:167], v126
	v_cvt_pk_f32_fp8_sdwa v[170:171], v126 src0_sel:WORD_1
	v_cvt_pk_f32_fp8_e32 v[172:173], v127
	v_cvt_pk_f32_fp8_sdwa v[126:127], v127 src0_sel:WORD_1
	s_waitcnt lgkmcnt(0)
	v_pk_fma_f32 v[160:161], v[160:161], v[128:129], 0 op_sel_hi:[1,0,0]
	v_pk_fma_f32 v[162:163], v[128:129], v[162:163], 0 op_sel_hi:[0,1,0]
	v_pk_fma_f32 v[164:165], v[128:129], v[164:165], 0 op_sel_hi:[0,1,0]
	v_pk_fma_f32 v[124:125], v[128:129], v[124:125], 0 op_sel_hi:[0,1,0]
	v_pk_fma_f32 v[166:167], v[128:129], v[166:167], 0 op_sel_hi:[0,1,0]
	v_pk_fma_f32 v[170:171], v[128:129], v[170:171], 0 op_sel_hi:[0,1,0]
	v_pk_fma_f32 v[172:173], v[128:129], v[172:173], 0 op_sel_hi:[0,1,0]
	v_pk_fma_f32 v[126:127], v[128:129], v[126:127], 0 op_sel_hi:[0,1,0]
	ds_bpermute_b32 v128, v143, v155
	v_cvt_pk_f32_fp8_e32 v[174:175], v120
	v_cvt_pk_f32_fp8_sdwa v[176:177], v120 src0_sel:WORD_1
	v_cvt_pk_f32_fp8_e32 v[178:179], v121
	v_cvt_pk_f32_fp8_sdwa v[120:121], v121 src0_sel:WORD_1
	s_waitcnt lgkmcnt(0)
	v_pk_fma_f32 v[160:161], v[174:175], v[128:129], v[160:161] op_sel_hi:[1,0,1]
	v_pk_fma_f32 v[162:163], v[128:129], v[176:177], v[162:163] op_sel_hi:[0,1,1]
	v_cvt_pk_f32_fp8_sdwa v[174:175], v122 src0_sel:WORD_1
	v_pk_fma_f32 v[120:121], v[128:129], v[120:121], v[124:125] op_sel_hi:[0,1,1]
	v_cvt_pk_f32_fp8_e32 v[124:125], v122
	v_cvt_pk_f32_fp8_e32 v[176:177], v123
	v_cvt_pk_f32_fp8_sdwa v[122:123], v123 src0_sel:WORD_1
	v_pk_fma_f32 v[164:165], v[128:129], v[178:179], v[164:165] op_sel_hi:[0,1,1]
	v_pk_fma_f32 v[124:125], v[128:129], v[124:125], v[166:167] op_sel_hi:[0,1,1]
	v_pk_fma_f32 v[166:167], v[128:129], v[174:175], v[170:171] op_sel_hi:[0,1,1]
	v_pk_fma_f32 v[122:123], v[128:129], v[122:123], v[126:127] op_sel_hi:[0,1,1]
	ds_bpermute_b32 v126, v144, v155
	v_pk_fma_f32 v[170:171], v[128:129], v[176:177], v[172:173] op_sel_hi:[0,1,1]
	v_cvt_pk_f32_fp8_e32 v[172:173], v116
	v_cvt_pk_f32_fp8_sdwa v[174:175], v116 src0_sel:WORD_1
	v_cvt_pk_f32_fp8_e32 v[176:177], v117
	v_cvt_pk_f32_fp8_sdwa v[116:117], v117 src0_sel:WORD_1
	s_waitcnt lgkmcnt(0)
	v_pk_fma_f32 v[160:161], v[172:173], v[126:127], v[160:161] op_sel_hi:[1,0,1]
	v_pk_fma_f32 v[162:163], v[126:127], v[174:175], v[162:163] op_sel_hi:[0,1,1]
	v_cvt_pk_f32_fp8_sdwa v[172:173], v118 src0_sel:WORD_1
	v_pk_fma_f32 v[116:117], v[126:127], v[116:117], v[120:121] op_sel_hi:[0,1,1]
	v_cvt_pk_f32_fp8_e32 v[120:121], v118
	v_cvt_pk_f32_fp8_e32 v[174:175], v119
	v_cvt_pk_f32_fp8_sdwa v[118:119], v119 src0_sel:WORD_1
	v_pk_fma_f32 v[164:165], v[126:127], v[176:177], v[164:165] op_sel_hi:[0,1,1]
	v_pk_fma_f32 v[120:121], v[126:127], v[120:121], v[124:125] op_sel_hi:[0,1,1]
	v_pk_fma_f32 v[124:125], v[126:127], v[172:173], v[166:167] op_sel_hi:[0,1,1]
	v_pk_fma_f32 v[118:119], v[126:127], v[118:119], v[122:123] op_sel_hi:[0,1,1]
	ds_bpermute_b32 v122, v145, v155
	v_pk_fma_f32 v[166:167], v[126:127], v[174:175], v[170:171] op_sel_hi:[0,1,1]
	v_cvt_pk_f32_fp8_e32 v[126:127], v112
	v_cvt_pk_f32_fp8_sdwa v[170:171], v112 src0_sel:WORD_1
	v_cvt_pk_f32_fp8_e32 v[172:173], v113
	v_cvt_pk_f32_fp8_sdwa v[112:113], v113 src0_sel:WORD_1
	s_waitcnt lgkmcnt(0)
	v_pk_fma_f32 v[126:127], v[126:127], v[122:123], v[160:161] op_sel_hi:[1,0,1]
	v_pk_fma_f32 v[160:161], v[122:123], v[170:171], v[162:163] op_sel_hi:[0,1,1]
	v_pk_fma_f32 v[162:163], v[122:123], v[172:173], v[164:165] op_sel_hi:[0,1,1]
	v_pk_fma_f32 v[112:113], v[122:123], v[112:113], v[116:117] op_sel_hi:[0,1,1]
	v_cvt_pk_f32_fp8_e32 v[116:117], v114
	v_cvt_pk_f32_fp8_sdwa v[164:165], v114 src0_sel:WORD_1
	v_cvt_pk_f32_fp8_e32 v[170:171], v115
	v_cvt_pk_f32_fp8_sdwa v[114:115], v115 src0_sel:WORD_1
	v_pk_fma_f32 v[116:117], v[122:123], v[116:117], v[120:121] op_sel_hi:[0,1,1]
	v_pk_fma_f32 v[120:121], v[122:123], v[164:165], v[124:125] op_sel_hi:[0,1,1]
	v_pk_fma_f32 v[124:125], v[122:123], v[170:171], v[166:167] op_sel_hi:[0,1,1]
	v_pk_fma_f32 v[114:115], v[122:123], v[114:115], v[118:119] op_sel_hi:[0,1,1]
	ds_bpermute_b32 v118, v146, v155
	v_cvt_pk_f32_fp8_e32 v[122:123], v108
	v_cvt_pk_f32_fp8_sdwa v[164:165], v108 src0_sel:WORD_1
	v_cvt_pk_f32_fp8_e32 v[166:167], v109
	v_cvt_pk_f32_fp8_sdwa v[108:109], v109 src0_sel:WORD_1
	s_waitcnt lgkmcnt(0)
	v_pk_fma_f32 v[122:123], v[122:123], v[118:119], v[126:127] op_sel_hi:[1,0,1]
	v_pk_fma_f32 v[126:127], v[118:119], v[164:165], v[160:161] op_sel_hi:[0,1,1]
	v_pk_fma_f32 v[160:161], v[118:119], v[166:167], v[162:163] op_sel_hi:[0,1,1]
	v_pk_fma_f32 v[108:109], v[118:119], v[108:109], v[112:113] op_sel_hi:[0,1,1]
	v_cvt_pk_f32_fp8_e32 v[112:113], v110
	v_cvt_pk_f32_fp8_sdwa v[162:163], v110 src0_sel:WORD_1
	v_cvt_pk_f32_fp8_e32 v[164:165], v111
	v_cvt_pk_f32_fp8_sdwa v[110:111], v111 src0_sel:WORD_1
	v_pk_fma_f32 v[112:113], v[118:119], v[112:113], v[116:117] op_sel_hi:[0,1,1]
	v_pk_fma_f32 v[116:117], v[118:119], v[162:163], v[120:121] op_sel_hi:[0,1,1]
	v_pk_fma_f32 v[120:121], v[118:119], v[164:165], v[124:125] op_sel_hi:[0,1,1]
	v_pk_fma_f32 v[110:111], v[118:119], v[110:111], v[114:115] op_sel_hi:[0,1,1]
	ds_bpermute_b32 v114, v147, v155
	v_cvt_pk_f32_fp8_e32 v[118:119], v104
	v_cvt_pk_f32_fp8_sdwa v[124:125], v104 src0_sel:WORD_1
	v_cvt_pk_f32_fp8_e32 v[162:163], v105
	v_cvt_pk_f32_fp8_sdwa v[104:105], v105 src0_sel:WORD_1
	s_waitcnt lgkmcnt(0)
	v_pk_fma_f32 v[118:119], v[118:119], v[114:115], v[122:123] op_sel_hi:[1,0,1]
	v_pk_fma_f32 v[122:123], v[114:115], v[124:125], v[126:127] op_sel_hi:[0,1,1]
	v_pk_fma_f32 v[124:125], v[114:115], v[162:163], v[160:161] op_sel_hi:[0,1,1]
	v_pk_fma_f32 v[104:105], v[114:115], v[104:105], v[108:109] op_sel_hi:[0,1,1]
	v_cvt_pk_f32_fp8_e32 v[108:109], v106
	v_cvt_pk_f32_fp8_sdwa v[126:127], v106 src0_sel:WORD_1
	v_cvt_pk_f32_fp8_e32 v[160:161], v107
	v_cvt_pk_f32_fp8_sdwa v[106:107], v107 src0_sel:WORD_1
	v_pk_fma_f32 v[108:109], v[114:115], v[108:109], v[112:113] op_sel_hi:[0,1,1]
	v_pk_fma_f32 v[112:113], v[114:115], v[126:127], v[116:117] op_sel_hi:[0,1,1]
	v_pk_fma_f32 v[116:117], v[114:115], v[160:161], v[120:121] op_sel_hi:[0,1,1]
	v_pk_fma_f32 v[106:107], v[114:115], v[106:107], v[110:111] op_sel_hi:[0,1,1]
	ds_bpermute_b32 v110, v148, v155
	v_cvt_pk_f32_fp8_e32 v[114:115], v100
	v_cvt_pk_f32_fp8_sdwa v[120:121], v100 src0_sel:WORD_1
	v_cvt_pk_f32_fp8_e32 v[126:127], v101
	v_cvt_pk_f32_fp8_sdwa v[100:101], v101 src0_sel:WORD_1
	s_waitcnt lgkmcnt(0)
	v_pk_fma_f32 v[114:115], v[114:115], v[110:111], v[118:119] op_sel_hi:[1,0,1]
	v_pk_fma_f32 v[118:119], v[110:111], v[120:121], v[122:123] op_sel_hi:[0,1,1]
	v_pk_fma_f32 v[120:121], v[110:111], v[126:127], v[124:125] op_sel_hi:[0,1,1]
	v_pk_fma_f32 v[100:101], v[110:111], v[100:101], v[104:105] op_sel_hi:[0,1,1]
	v_cvt_pk_f32_fp8_e32 v[104:105], v102
	v_cvt_pk_f32_fp8_sdwa v[122:123], v102 src0_sel:WORD_1
	v_cvt_pk_f32_fp8_e32 v[124:125], v103
	v_cvt_pk_f32_fp8_sdwa v[102:103], v103 src0_sel:WORD_1
	v_pk_fma_f32 v[104:105], v[110:111], v[104:105], v[108:109] op_sel_hi:[0,1,1]
	v_pk_fma_f32 v[108:109], v[110:111], v[122:123], v[112:113] op_sel_hi:[0,1,1]
	v_pk_fma_f32 v[112:113], v[110:111], v[124:125], v[116:117] op_sel_hi:[0,1,1]
	v_pk_fma_f32 v[102:103], v[110:111], v[102:103], v[106:107] op_sel_hi:[0,1,1]
	ds_bpermute_b32 v106, v149, v155
	v_cvt_pk_f32_fp8_e32 v[110:111], v96
	v_cvt_pk_f32_fp8_sdwa v[116:117], v96 src0_sel:WORD_1
	v_cvt_pk_f32_fp8_e32 v[122:123], v97
	v_cvt_pk_f32_fp8_sdwa v[96:97], v97 src0_sel:WORD_1
	s_waitcnt lgkmcnt(0)
	v_pk_fma_f32 v[110:111], v[110:111], v[106:107], v[114:115] op_sel_hi:[1,0,1]
	v_pk_fma_f32 v[114:115], v[106:107], v[116:117], v[118:119] op_sel_hi:[0,1,1]
	v_pk_fma_f32 v[116:117], v[106:107], v[122:123], v[120:121] op_sel_hi:[0,1,1]
	v_pk_fma_f32 v[96:97], v[106:107], v[96:97], v[100:101] op_sel_hi:[0,1,1]
	v_cvt_pk_f32_fp8_e32 v[100:101], v98
	v_cvt_pk_f32_fp8_sdwa v[118:119], v98 src0_sel:WORD_1
	v_cvt_pk_f32_fp8_e32 v[120:121], v99
	v_cvt_pk_f32_fp8_sdwa v[98:99], v99 src0_sel:WORD_1
	v_pk_fma_f32 v[100:101], v[106:107], v[100:101], v[104:105] op_sel_hi:[0,1,1]
	v_pk_fma_f32 v[104:105], v[106:107], v[118:119], v[108:109] op_sel_hi:[0,1,1]
	v_pk_fma_f32 v[108:109], v[106:107], v[120:121], v[112:113] op_sel_hi:[0,1,1]
	v_pk_fma_f32 v[98:99], v[106:107], v[98:99], v[102:103] op_sel_hi:[0,1,1]
	ds_bpermute_b32 v102, v142, v154
	v_cvt_pk_f32_fp8_e32 v[106:107], v92
	v_cvt_pk_f32_fp8_sdwa v[112:113], v92 src0_sel:WORD_1
	v_cvt_pk_f32_fp8_e32 v[118:119], v93
	v_cvt_pk_f32_fp8_sdwa v[92:93], v93 src0_sel:WORD_1
	s_waitcnt lgkmcnt(0)
	v_pk_fma_f32 v[106:107], v[106:107], v[102:103], v[110:111] op_sel_hi:[1,0,1]
	v_pk_fma_f32 v[110:111], v[102:103], v[112:113], v[114:115] op_sel_hi:[0,1,1]
	v_pk_fma_f32 v[112:113], v[102:103], v[118:119], v[116:117] op_sel_hi:[0,1,1]
	v_pk_fma_f32 v[92:93], v[102:103], v[92:93], v[96:97] op_sel_hi:[0,1,1]
	v_cvt_pk_f32_fp8_e32 v[96:97], v94
	v_cvt_pk_f32_fp8_sdwa v[114:115], v94 src0_sel:WORD_1
	v_cvt_pk_f32_fp8_e32 v[116:117], v95
	v_cvt_pk_f32_fp8_sdwa v[94:95], v95 src0_sel:WORD_1
	v_pk_fma_f32 v[96:97], v[102:103], v[96:97], v[100:101] op_sel_hi:[0,1,1]
	v_pk_fma_f32 v[100:101], v[102:103], v[114:115], v[104:105] op_sel_hi:[0,1,1]
	v_pk_fma_f32 v[104:105], v[102:103], v[116:117], v[108:109] op_sel_hi:[0,1,1]
	v_pk_fma_f32 v[94:95], v[102:103], v[94:95], v[98:99] op_sel_hi:[0,1,1]
	ds_bpermute_b32 v98, v143, v154
	v_cvt_pk_f32_fp8_e32 v[102:103], v88
	v_cvt_pk_f32_fp8_sdwa v[108:109], v88 src0_sel:WORD_1
	v_cvt_pk_f32_fp8_e32 v[114:115], v89
	v_cvt_pk_f32_fp8_sdwa v[88:89], v89 src0_sel:WORD_1
	s_waitcnt lgkmcnt(0)
	v_pk_fma_f32 v[102:103], v[102:103], v[98:99], v[106:107] op_sel_hi:[1,0,1]
	v_pk_fma_f32 v[106:107], v[98:99], v[108:109], v[110:111] op_sel_hi:[0,1,1]
	v_pk_fma_f32 v[108:109], v[98:99], v[114:115], v[112:113] op_sel_hi:[0,1,1]
	v_pk_fma_f32 v[88:89], v[98:99], v[88:89], v[92:93] op_sel_hi:[0,1,1]
	v_cvt_pk_f32_fp8_e32 v[92:93], v90
	v_cvt_pk_f32_fp8_sdwa v[110:111], v90 src0_sel:WORD_1
	v_cvt_pk_f32_fp8_e32 v[112:113], v91
	v_cvt_pk_f32_fp8_sdwa v[90:91], v91 src0_sel:WORD_1
	v_pk_fma_f32 v[92:93], v[98:99], v[92:93], v[96:97] op_sel_hi:[0,1,1]
	v_pk_fma_f32 v[96:97], v[98:99], v[110:111], v[100:101] op_sel_hi:[0,1,1]
	v_pk_fma_f32 v[100:101], v[98:99], v[112:113], v[104:105] op_sel_hi:[0,1,1]
	v_pk_fma_f32 v[90:91], v[98:99], v[90:91], v[94:95] op_sel_hi:[0,1,1]
	ds_bpermute_b32 v94, v144, v154
	v_cvt_pk_f32_fp8_e32 v[98:99], v80
	v_cvt_pk_f32_fp8_sdwa v[104:105], v80 src0_sel:WORD_1
	v_cvt_pk_f32_fp8_e32 v[110:111], v81
	v_cvt_pk_f32_fp8_sdwa v[80:81], v81 src0_sel:WORD_1
	s_waitcnt lgkmcnt(0)
	v_pk_fma_f32 v[98:99], v[98:99], v[94:95], v[102:103] op_sel_hi:[1,0,1]
	v_pk_fma_f32 v[102:103], v[94:95], v[104:105], v[106:107] op_sel_hi:[0,1,1]
	v_pk_fma_f32 v[104:105], v[94:95], v[110:111], v[108:109] op_sel_hi:[0,1,1]
	v_pk_fma_f32 v[80:81], v[94:95], v[80:81], v[88:89] op_sel_hi:[0,1,1]
	v_cvt_pk_f32_fp8_e32 v[88:89], v82
	v_cvt_pk_f32_fp8_sdwa v[106:107], v82 src0_sel:WORD_1
	v_cvt_pk_f32_fp8_e32 v[108:109], v83
	v_cvt_pk_f32_fp8_sdwa v[82:83], v83 src0_sel:WORD_1
	v_pk_fma_f32 v[88:89], v[94:95], v[88:89], v[92:93] op_sel_hi:[0,1,1]
	v_pk_fma_f32 v[92:93], v[94:95], v[106:107], v[96:97] op_sel_hi:[0,1,1]
	v_pk_fma_f32 v[96:97], v[94:95], v[108:109], v[100:101] op_sel_hi:[0,1,1]
	v_pk_fma_f32 v[82:83], v[94:95], v[82:83], v[90:91] op_sel_hi:[0,1,1]
	ds_bpermute_b32 v90, v145, v154
	v_cvt_pk_f32_fp8_e32 v[94:95], v72
	v_cvt_pk_f32_fp8_sdwa v[100:101], v72 src0_sel:WORD_1
	v_cvt_pk_f32_fp8_e32 v[106:107], v73
	v_cvt_pk_f32_fp8_sdwa v[72:73], v73 src0_sel:WORD_1
	s_waitcnt lgkmcnt(0)
	v_pk_fma_f32 v[94:95], v[94:95], v[90:91], v[98:99] op_sel_hi:[1,0,1]
	v_pk_fma_f32 v[98:99], v[90:91], v[100:101], v[102:103] op_sel_hi:[0,1,1]
	v_pk_fma_f32 v[100:101], v[90:91], v[106:107], v[104:105] op_sel_hi:[0,1,1]
	v_pk_fma_f32 v[72:73], v[90:91], v[72:73], v[80:81] op_sel_hi:[0,1,1]
	v_cvt_pk_f32_fp8_e32 v[80:81], v74
	v_cvt_pk_f32_fp8_sdwa v[102:103], v74 src0_sel:WORD_1
	v_cvt_pk_f32_fp8_e32 v[104:105], v75
	v_cvt_pk_f32_fp8_sdwa v[74:75], v75 src0_sel:WORD_1
	v_pk_fma_f32 v[80:81], v[90:91], v[80:81], v[88:89] op_sel_hi:[0,1,1]
	v_pk_fma_f32 v[88:89], v[90:91], v[102:103], v[92:93] op_sel_hi:[0,1,1]
	v_pk_fma_f32 v[92:93], v[90:91], v[104:105], v[96:97] op_sel_hi:[0,1,1]
	v_pk_fma_f32 v[74:75], v[90:91], v[74:75], v[82:83] op_sel_hi:[0,1,1]
	ds_bpermute_b32 v82, v146, v154
	v_cvt_pk_f32_fp8_e32 v[90:91], v64
	v_cvt_pk_f32_fp8_sdwa v[96:97], v64 src0_sel:WORD_1
	v_cvt_pk_f32_fp8_e32 v[102:103], v65
	v_cvt_pk_f32_fp8_sdwa v[64:65], v65 src0_sel:WORD_1
	s_waitcnt lgkmcnt(0)
	v_pk_fma_f32 v[90:91], v[90:91], v[82:83], v[94:95] op_sel_hi:[1,0,1]
	v_pk_fma_f32 v[94:95], v[82:83], v[96:97], v[98:99] op_sel_hi:[0,1,1]
	v_pk_fma_f32 v[96:97], v[82:83], v[102:103], v[100:101] op_sel_hi:[0,1,1]
	v_pk_fma_f32 v[64:65], v[82:83], v[64:65], v[72:73] op_sel_hi:[0,1,1]
	v_cvt_pk_f32_fp8_e32 v[72:73], v66
	v_cvt_pk_f32_fp8_sdwa v[98:99], v66 src0_sel:WORD_1
	v_cvt_pk_f32_fp8_e32 v[100:101], v67
	v_cvt_pk_f32_fp8_sdwa v[66:67], v67 src0_sel:WORD_1
	v_pk_fma_f32 v[72:73], v[82:83], v[72:73], v[80:81] op_sel_hi:[0,1,1]
	v_pk_fma_f32 v[80:81], v[82:83], v[98:99], v[88:89] op_sel_hi:[0,1,1]
	v_pk_fma_f32 v[88:89], v[82:83], v[100:101], v[92:93] op_sel_hi:[0,1,1]
	v_pk_fma_f32 v[66:67], v[82:83], v[66:67], v[74:75] op_sel_hi:[0,1,1]
	ds_bpermute_b32 v74, v147, v154
	v_cvt_pk_f32_fp8_e32 v[82:83], v56
	v_cvt_pk_f32_fp8_sdwa v[92:93], v56 src0_sel:WORD_1
	v_cvt_pk_f32_fp8_e32 v[98:99], v57
	v_cvt_pk_f32_fp8_sdwa v[56:57], v57 src0_sel:WORD_1
	s_waitcnt lgkmcnt(0)
	v_pk_fma_f32 v[82:83], v[82:83], v[74:75], v[90:91] op_sel_hi:[1,0,1]
	v_pk_fma_f32 v[90:91], v[74:75], v[92:93], v[94:95] op_sel_hi:[0,1,1]
	v_pk_fma_f32 v[92:93], v[74:75], v[98:99], v[96:97] op_sel_hi:[0,1,1]
	v_pk_fma_f32 v[56:57], v[74:75], v[56:57], v[64:65] op_sel_hi:[0,1,1]
	v_cvt_pk_f32_fp8_e32 v[64:65], v58
	v_cvt_pk_f32_fp8_sdwa v[94:95], v58 src0_sel:WORD_1
	v_cvt_pk_f32_fp8_e32 v[96:97], v59
	v_cvt_pk_f32_fp8_sdwa v[58:59], v59 src0_sel:WORD_1
	v_pk_fma_f32 v[64:65], v[74:75], v[64:65], v[72:73] op_sel_hi:[0,1,1]
	v_pk_fma_f32 v[72:73], v[74:75], v[94:95], v[80:81] op_sel_hi:[0,1,1]
	v_pk_fma_f32 v[80:81], v[74:75], v[96:97], v[88:89] op_sel_hi:[0,1,1]
	v_pk_fma_f32 v[58:59], v[74:75], v[58:59], v[66:67] op_sel_hi:[0,1,1]
	ds_bpermute_b32 v66, v148, v154
	v_cvt_pk_f32_fp8_e32 v[74:75], v48
	v_cvt_pk_f32_fp8_sdwa v[88:89], v48 src0_sel:WORD_1
	v_cvt_pk_f32_fp8_e32 v[94:95], v49
	v_cvt_pk_f32_fp8_sdwa v[48:49], v49 src0_sel:WORD_1
	s_waitcnt lgkmcnt(0)
	v_pk_fma_f32 v[74:75], v[74:75], v[66:67], v[82:83] op_sel_hi:[1,0,1]
	v_pk_fma_f32 v[82:83], v[66:67], v[88:89], v[90:91] op_sel_hi:[0,1,1]
	v_pk_fma_f32 v[88:89], v[66:67], v[94:95], v[92:93] op_sel_hi:[0,1,1]
	v_pk_fma_f32 v[48:49], v[66:67], v[48:49], v[56:57] op_sel_hi:[0,1,1]
	v_cvt_pk_f32_fp8_e32 v[56:57], v50
	v_cvt_pk_f32_fp8_sdwa v[90:91], v50 src0_sel:WORD_1
	v_cvt_pk_f32_fp8_e32 v[92:93], v51
	v_cvt_pk_f32_fp8_sdwa v[50:51], v51 src0_sel:WORD_1
	v_pk_fma_f32 v[56:57], v[66:67], v[56:57], v[64:65] op_sel_hi:[0,1,1]
	v_pk_fma_f32 v[64:65], v[66:67], v[90:91], v[72:73] op_sel_hi:[0,1,1]
	v_pk_fma_f32 v[72:73], v[66:67], v[92:93], v[80:81] op_sel_hi:[0,1,1]
	v_pk_fma_f32 v[50:51], v[66:67], v[50:51], v[58:59] op_sel_hi:[0,1,1]
	ds_bpermute_b32 v58, v149, v154
	v_cvt_pk_f32_fp8_e32 v[66:67], v44
	v_cvt_pk_f32_fp8_sdwa v[80:81], v44 src0_sel:WORD_1
	v_cvt_pk_f32_fp8_e32 v[90:91], v45
	v_cvt_pk_f32_fp8_sdwa v[44:45], v45 src0_sel:WORD_1
	s_waitcnt lgkmcnt(0)
	v_pk_fma_f32 v[66:67], v[66:67], v[58:59], v[74:75] op_sel_hi:[1,0,1]
	v_pk_fma_f32 v[74:75], v[58:59], v[80:81], v[82:83] op_sel_hi:[0,1,1]
	v_pk_fma_f32 v[80:81], v[58:59], v[90:91], v[88:89] op_sel_hi:[0,1,1]
	v_pk_fma_f32 v[44:45], v[58:59], v[44:45], v[48:49] op_sel_hi:[0,1,1]
	v_cvt_pk_f32_fp8_e32 v[48:49], v46
	v_cvt_pk_f32_fp8_sdwa v[82:83], v46 src0_sel:WORD_1
	v_cvt_pk_f32_fp8_e32 v[88:89], v47
	v_cvt_pk_f32_fp8_sdwa v[46:47], v47 src0_sel:WORD_1
	v_pk_fma_f32 v[48:49], v[58:59], v[48:49], v[56:57] op_sel_hi:[0,1,1]
	v_pk_fma_f32 v[56:57], v[58:59], v[82:83], v[64:65] op_sel_hi:[0,1,1]
	v_pk_fma_f32 v[64:65], v[58:59], v[88:89], v[72:73] op_sel_hi:[0,1,1]
	v_pk_fma_f32 v[46:47], v[58:59], v[46:47], v[50:51] op_sel_hi:[0,1,1]
	v_cndmask_b32_e32 v50, v66, v48, vcc
	v_cndmask_b32_e32 v51, v67, v49, vcc
	ds_bpermute_b32 v50, v150, v50
	ds_bpermute_b32 v51, v150, v51
	v_cndmask_b32_e32 v58, v74, v56, vcc
	v_cndmask_b32_e32 v59, v75, v57, vcc
	v_cndmask_b32_e32 v72, v80, v64, vcc
	v_cndmask_b32_e32 v73, v81, v65, vcc
	v_cndmask_b32_e32 v82, v44, v46, vcc
	v_cndmask_b32_e32 v83, v45, v47, vcc
	ds_bpermute_b32 v58, v150, v58
	ds_bpermute_b32 v59, v150, v59
	ds_bpermute_b32 v72, v150, v72
	ds_bpermute_b32 v73, v150, v73
	ds_bpermute_b32 v82, v150, v82
	ds_bpermute_b32 v83, v150, v83
	v_cndmask_b32_e32 v49, v49, v67, vcc
	v_cndmask_b32_e32 v48, v48, v66, vcc
	s_waitcnt lgkmcnt(6)
	v_pk_add_f32 v[48:49], v[48:49], v[50:51]
	v_cndmask_b32_e32 v51, v57, v75, vcc
	v_cndmask_b32_e32 v50, v56, v74, vcc
	v_cndmask_b32_e32 v57, v65, v81, vcc
	v_cndmask_b32_e32 v56, v64, v80, vcc
	v_cndmask_b32_e32 v45, v47, v45, vcc
	v_cndmask_b32_e32 v44, v46, v44, vcc
	s_waitcnt lgkmcnt(4)
	v_pk_add_f32 v[50:51], v[50:51], v[58:59]
	s_waitcnt lgkmcnt(2)
	v_pk_add_f32 v[56:57], v[56:57], v[72:73]
	s_waitcnt lgkmcnt(0)
	v_pk_add_f32 v[44:45], v[44:45], v[82:83]
	v_cndmask_b32_e64 v47, v49, v57, s[6:7]
	v_cndmask_b32_e64 v49, v57, v49, s[6:7]
	v_cndmask_b32_e64 v57, v50, v44, s[6:7]
	v_cndmask_b32_e64 v46, v48, v56, s[6:7]
	ds_bpermute_b32 v58, v151, v57
	v_cndmask_b32_e64 v57, v51, v45, s[6:7]
	ds_bpermute_b32 v46, v151, v46
	ds_bpermute_b32 v47, v151, v47
	ds_bpermute_b32 v59, v151, v57
	v_cndmask_b32_e64 v48, v56, v48, s[6:7]
	v_cndmask_b32_e64 v45, v45, v51, s[6:7]
	v_cndmask_b32_e64 v44, v44, v50, s[6:7]
	s_waitcnt lgkmcnt(1)
	v_pk_add_f32 v[46:47], v[48:49], v[46:47]
	s_waitcnt lgkmcnt(0)
	v_pk_add_f32 v[44:45], v[44:45], v[58:59]
	v_add_u32_e32 v128, s24, v136
	v_cndmask_b32_e64 v48, v46, v44, s[8:9]
	v_cndmask_b32_e64 v49, v47, v45, s[8:9]
	ds_bpermute_b32 v48, v152, v48
	ds_bpermute_b32 v49, v152, v49
	v_cndmask_b32_e64 v45, v45, v47, s[8:9]
	v_cndmask_b32_e64 v44, v44, v46, s[8:9]
	v_lshl_add_u64 v[50:51], v[128:129], 1, v[132:133]
	s_waitcnt lgkmcnt(0)
	v_pk_add_f32 v[44:45], v[44:45], v[48:49]
	s_nop 0
	v_and_b32_sdwa v47, v44, v153 dst_sel:DWORD dst_unused:UNUSED_PAD src0_sel:WORD_1 src1_sel:DWORD
	v_and_b32_sdwa v46, v45, v153 dst_sel:DWORD dst_unused:UNUSED_PAD src0_sel:WORD_1 src1_sel:DWORD
	v_cvt_pk_bf16_f32 v44, v44, v44
	v_cvt_pk_bf16_f32 v45, v45, v45
	v_lshrrev_b32_e32 v44, 16, v44
	v_and_or_b32 v44, v45, s26, v44
	global_store_dword v[50:51], v44, off
	s_branch .LBB0_1046
